# GEMM mainloops: cluster-closing s_barrier issued right after the last MFMA, scalar bookkeeping moved behind it (40 sites)
# speedup vs baseline: 1.0020x; 1.0020x over previous
; #define PG8_STAGE(bufoff, gbase, voff) do { _Pragma("unroll") for (int _i = 0; _i < 2; ++_i) \
;         __builtin_amdgcn_global_load_lds((const unsigned*)((const char*)(gbase) + (voff)[_i]), (LAS unsigned*)(lds + (bufoff) + ldsw + _i * 8192), 16, 0, 0); } while (0)
; #define PG8_LDA(dst, b, h) do { _Pragma("unroll") for (int m = 0; m < 4; ++m) _Pragma("unroll") for (int k = 0; k < 2; ++k) dst[m][k] = *(const LAS bf16x8*)(lds + PG8_SA(b, h) + aoff + m * 2048 + k * 1024); } while (0)
; #define PG8_LDB(dst, b, h) do { _Pragma("unroll") for (int n = 0; n < 2; ++n) _Pragma("unroll") for (int k = 0; k < 2; ++k) dst[n][k] = *(const LAS bf16x8*)(lds + PG8_SB(b, h) + boff + n * 2048 + k * 1024); } while (0)
; #define PG8_MMA(ai, bj, At, Bt) do { __builtin_amdgcn_s_setprio(1); _Pragma("unroll") for (int m = 0; m < 4; ++m) _Pragma("unroll") for (int n = 0; n < 2; ++n) _Pragma("unroll") for (int k = 0; k < 2; ++k) \
;         acc[ai][bj][m][n] = __builtin_amdgcn_mfma_f32_16x16x32_bf16(Bt[n][k], At[m][k], acc[ai][bj][m][n], 0, 0, 0); __builtin_amdgcn_s_setprio(0); } while (0)
; #define PG8_WAIT_V(n) asm volatile("s_waitcnt vmcnt(" #n ")" ::: "memory")
; #define PG8_WAIT_L(n) asm volatile("s_waitcnt lgkmcnt(" #n ")" ::: "memory")
; #define PG8_BAR __builtin_amdgcn_s_barrier()
; #define PG8_SCHED __builtin_amdgcn_sched_barrier(0)
; template <class Epi>
; DEVI void gemm_phase(LAS unsigned char* lds, const Gemm g, const Epi& E) {
;     ...
;             PG8_LDB(B0, 0, 0); PG8_SCHED; PG8_LDA(At, 0, 0); PG8_STAGE(PG8_SA(1, 1), a1 + hstepA, voffA);
;             PG8_WAIT_L(8); PG8_BAR; PG8_WAIT_L(0); PG8_MMA(0, 0, At, B0); PG8_BAR; PG8_SCHED;
;             PG8_LDB(B1, 0, 1); PG8_STAGE(PG8_SB(0, 0), b2, voffB);
;             PG8_BAR; PG8_WAIT_L(0); PG8_MMA(0, 1, At, B1); PG8_BAR;
;             PG8_LDA(At, 0, 1); PG8_STAGE(PG8_SA(0, 0), a2, voffA);
;             PG8_BAR; PG8_WAIT_L(0); PG8_MMA(1, 0, At, B0); PG8_BAR; PG8_SCHED;
;             PG8_STAGE(PG8_SB(0, 1), b2 + hstepB, voffB);
;             PG8_WAIT_V(6); PG8_BAR; PG8_MMA(1, 1, At, B1); PG8_BAR;
.LBB0_187:
	ds_read_b128 v[156:159], v150
	ds_read_b128 v[160:163], v150 offset:1024
	ds_read_b128 v[164:167], v150 offset:2048
	ds_read_b128 v[168:171], v150 offset:3072
	s_add_u32 s26, s0, 0xfffc0080
	s_addc_u32 s27, s1, -1
	s_cmp_eq_u32 s50, 12
	s_cselect_b32 s29, s13, s27
	s_cselect_b32 s28, s15, s26
	s_cselect_b32 s27, s19, s49
	s_cselect_b32 s26, s18, s17
	v_lshl_add_u64 v[204:205], s[0:1], 0, v[138:139]
	s_add_i32 m0, s38, 0xc000
	ds_read_b128 v[172:175], v151
	ds_read_b128 v[176:179], v151 offset:1024
	ds_read_b128 v[180:183], v151 offset:2048
	ds_read_b128 v[184:187], v151 offset:3072
	ds_read_b128 v[188:191], v151 offset:4096
	ds_read_b128 v[192:195], v151 offset:5120
	ds_read_b128 v[196:199], v151 offset:6144
	ds_read_b128 v[200:203], v151 offset:7168
	global_load_lds_dwordx4 v[204:205], off
	s_add_i32 m0, s38, 0xe000
	v_lshl_add_u64 v[204:205], s[0:1], 0, v[140:141]
	global_load_lds_dwordx4 v[204:205], off
	s_waitcnt lgkmcnt(8)
	s_barrier
	s_waitcnt lgkmcnt(0)
	v_mfma_f32_16x16x32_bf16 v[124:127], v[156:159], v[172:175], v[124:127]
	v_mfma_f32_16x16x32_bf16 v[120:123], v[164:167], v[172:175], v[120:123]
	v_mfma_f32_16x16x32_bf16 v[116:119], v[156:159], v[180:183], v[116:119]
	v_mfma_f32_16x16x32_bf16 v[108:111], v[164:167], v[180:183], v[108:111]
	v_mfma_f32_16x16x32_bf16 v[100:103], v[156:159], v[188:191], v[100:103]
	v_mfma_f32_16x16x32_bf16 v[96:99], v[164:167], v[188:191], v[96:99]
	v_mfma_f32_16x16x32_bf16 v[84:87], v[156:159], v[196:199], v[84:87]
	v_mfma_f32_16x16x32_bf16 v[80:83], v[164:167], v[196:199], v[80:83]
	v_mfma_f32_16x16x32_bf16 v[124:127], v[160:163], v[176:179], v[124:127]
	v_mfma_f32_16x16x32_bf16 v[120:123], v[168:171], v[176:179], v[120:123]
	v_mfma_f32_16x16x32_bf16 v[116:119], v[160:163], v[184:187], v[116:119]
	v_mfma_f32_16x16x32_bf16 v[108:111], v[168:171], v[184:187], v[108:111]
	v_mfma_f32_16x16x32_bf16 v[100:103], v[160:163], v[192:195], v[100:103]
	v_mfma_f32_16x16x32_bf16 v[96:99], v[168:171], v[192:195], v[96:99]
	v_mfma_f32_16x16x32_bf16 v[84:87], v[160:163], v[200:203], v[84:87]
	v_mfma_f32_16x16x32_bf16 v[80:83], v[168:171], v[200:203], v[80:83]
	s_barrier
	s_add_i32 s51, s46, s35
	v_lshl_add_u64 v[220:221], s[26:27], 0, v[130:131]
	s_mov_b32 m0, s51
	ds_read_b128 v[204:207], v152
	ds_read_b128 v[208:211], v152 offset:1024
	ds_read_b128 v[212:215], v152 offset:2048
	ds_read_b128 v[216:219], v152 offset:3072
	global_load_lds_dwordx4 v[220:221], off
	s_add_i32 m0, s51, 0x2000
	v_lshl_add_u64 v[222:223], s[26:27], 0, v[134:135]
	global_load_lds_dwordx4 v[222:223], off
	s_barrier
	s_waitcnt lgkmcnt(0)
	v_mfma_f32_16x16x32_bf16 v[112:115], v[204:207], v[172:175], v[112:115]
	v_mfma_f32_16x16x32_bf16 v[104:107], v[212:215], v[172:175], v[104:107]
	v_mfma_f32_16x16x32_bf16 v[92:95], v[204:207], v[180:183], v[92:95]
	v_mfma_f32_16x16x32_bf16 v[88:91], v[212:215], v[180:183], v[88:91]
	v_mfma_f32_16x16x32_bf16 v[76:79], v[204:207], v[188:191], v[76:79]
	v_mfma_f32_16x16x32_bf16 v[72:75], v[212:215], v[188:191], v[72:75]
	v_mfma_f32_16x16x32_bf16 v[68:71], v[204:207], v[196:199], v[68:71]
	v_mfma_f32_16x16x32_bf16 v[64:67], v[212:215], v[196:199], v[64:67]
	v_mfma_f32_16x16x32_bf16 v[112:115], v[208:211], v[176:179], v[112:115]
	v_mfma_f32_16x16x32_bf16 v[104:107], v[216:219], v[176:179], v[104:107]
	v_mfma_f32_16x16x32_bf16 v[92:95], v[208:211], v[184:187], v[92:95]
	v_mfma_f32_16x16x32_bf16 v[88:91], v[216:219], v[184:187], v[88:91]
	v_mfma_f32_16x16x32_bf16 v[76:79], v[208:211], v[192:195], v[76:79]
	v_mfma_f32_16x16x32_bf16 v[72:75], v[216:219], v[192:195], v[72:75]
	v_mfma_f32_16x16x32_bf16 v[68:71], v[208:211], v[200:203], v[68:71]
	v_mfma_f32_16x16x32_bf16 v[64:67], v[216:219], v[200:203], v[64:67]
	s_barrier
	s_mov_b32 m0, s38
	v_lshl_add_u64 v[224:225], s[28:29], 0, v[128:129]
	ds_read_b128 v[172:175], v151 offset:16384
	ds_read_b128 v[176:179], v151 offset:17408
	ds_read_b128 v[180:183], v151 offset:18432
	ds_read_b128 v[184:187], v151 offset:19456
	ds_read_b128 v[188:191], v151 offset:20480
	ds_read_b128 v[192:195], v151 offset:21504
	ds_read_b128 v[196:199], v151 offset:22528
	ds_read_b128 v[200:203], v151 offset:23552
	global_load_lds_dwordx4 v[224:225], off
	s_mov_b32 m0, s39
	v_lshl_add_u64 v[226:227], s[28:29], 0, v[132:133]
	global_load_lds_dwordx4 v[226:227], off
	s_barrier
	s_waitcnt lgkmcnt(0)
	v_mfma_f32_16x16x32_bf16 v[60:63], v[156:159], v[172:175], v[60:63]
	v_mfma_f32_16x16x32_bf16 v[56:59], v[164:167], v[172:175], v[56:59]
	v_mfma_f32_16x16x32_bf16 v[52:55], v[156:159], v[180:183], v[52:55]
	v_mfma_f32_16x16x32_bf16 v[48:51], v[164:167], v[180:183], v[48:51]
	v_mfma_f32_16x16x32_bf16 v[36:39], v[156:159], v[188:191], v[36:39]
	v_mfma_f32_16x16x32_bf16 v[32:35], v[164:167], v[188:191], v[32:35]
	v_mfma_f32_16x16x32_bf16 v[20:23], v[156:159], v[196:199], v[20:23]
	v_mfma_f32_16x16x32_bf16 v[16:19], v[164:167], v[196:199], v[16:19]
	v_mfma_f32_16x16x32_bf16 v[60:63], v[160:163], v[176:179], v[60:63]
	v_mfma_f32_16x16x32_bf16 v[56:59], v[168:171], v[176:179], v[56:59]
	v_mfma_f32_16x16x32_bf16 v[52:55], v[160:163], v[184:187], v[52:55]
	v_mfma_f32_16x16x32_bf16 v[48:51], v[168:171], v[184:187], v[48:51]
	v_mfma_f32_16x16x32_bf16 v[36:39], v[160:163], v[192:195], v[36:39]
	v_mfma_f32_16x16x32_bf16 v[32:35], v[168:171], v[192:195], v[32:35]
	v_mfma_f32_16x16x32_bf16 v[20:23], v[160:163], v[200:203], v[20:23]
	v_mfma_f32_16x16x32_bf16 v[16:19], v[168:171], v[200:203], v[16:19]
	s_barrier
	s_add_u32 s52, s26, 0x40000
	s_addc_u32 s53, s27, 0
	s_add_i32 s51, s47, s35
	s_mov_b32 m0, s51
	v_lshl_add_u64 v[156:157], s[52:53], 0, v[130:131]
	global_load_lds_dwordx4 v[156:157], off
	s_add_i32 m0, s51, 0x2000
	v_lshl_add_u64 v[156:157], s[52:53], 0, v[134:135]
	global_load_lds_dwordx4 v[156:157], off
	s_waitcnt vmcnt(6)
	s_barrier
; #define PG8_STAGE(bufoff, gbase, voff) do { _Pragma("unroll") for (int _i = 0; _i < 2; ++_i) \
;         __builtin_amdgcn_global_load_lds((const unsigned*)((const char*)(gbase) + (voff)[_i]), (LAS unsigned*)(lds + (bufoff) + ldsw + _i * 8192), 16, 0, 0); } while (0)
; #define PG8_LDA(dst, b, h) do { _Pragma("unroll") for (int m = 0; m < 4; ++m) _Pragma("unroll") for (int k = 0; k < 2; ++k) dst[m][k] = *(const LAS bf16x8*)(lds + PG8_SA(b, h) + aoff + m * 2048 + k * 1024); } while (0)
; #define PG8_LDB(dst, b, h) do { _Pragma("unroll") for (int n = 0; n < 2; ++n) _Pragma("unroll") for (int k = 0; k < 2; ++k) dst[n][k] = *(const LAS bf16x8*)(lds + PG8_SB(b, h) + boff + n * 2048 + k * 1024); } while (0)
; #define PG8_MMA(ai, bj, At, Bt) do { __builtin_amdgcn_s_setprio(1); _Pragma("unroll") for (int m = 0; m < 4; ++m) _Pragma("unroll") for (int n = 0; n < 2; ++n) _Pragma("unroll") for (int k = 0; k < 2; ++k) \
;         acc[ai][bj][m][n] = __builtin_amdgcn_mfma_f32_16x16x32_bf16(Bt[n][k], At[m][k], acc[ai][bj][m][n], 0, 0, 0); __builtin_amdgcn_s_setprio(0); } while (0)
; #define PG8_WAIT_V(n) asm volatile("s_waitcnt vmcnt(" #n ")" ::: "memory")
; #define PG8_WAIT_L(n) asm volatile("s_waitcnt lgkmcnt(" #n ")" ::: "memory")
; #define PG8_BAR __builtin_amdgcn_s_barrier()
; #define PG8_SCHED __builtin_amdgcn_sched_barrier(0)
; template <class Epi>
; DEVI void gemm_phase(LAS unsigned char* lds, const Gemm g, const Epi& E) {
;     ...
;             PG8_WAIT_V(6); PG8_BAR; PG8_MMA(1, 1, At, B1); PG8_BAR;
;             PG8_LDB(B0, 1, 0); PG8_SCHED; PG8_LDA(At, 1, 0); PG8_STAGE(PG8_SA(0, 1), a2 + hstepA, voffA);
;             PG8_WAIT_L(8); PG8_BAR; PG8_WAIT_L(0); PG8_MMA(0, 0, At, B0); PG8_BAR; PG8_SCHED;
;             PG8_LDB(B1, 1, 1); PG8_STAGE(PG8_SB(1, 0), b3, voffB);
;             PG8_BAR; PG8_WAIT_L(0); PG8_MMA(0, 1, At, B1); PG8_BAR;
;             PG8_LDA(At, 1, 1); PG8_STAGE(PG8_SA(1, 0), a3, voffA);
;             PG8_BAR; PG8_WAIT_L(0); PG8_MMA(1, 0, At, B0); PG8_BAR; PG8_SCHED;
	v_mfma_f32_16x16x32_bf16 v[44:47], v[204:207], v[172:175], v[44:47]
	v_mfma_f32_16x16x32_bf16 v[40:43], v[212:215], v[172:175], v[40:43]
	v_mfma_f32_16x16x32_bf16 v[28:31], v[204:207], v[180:183], v[28:31]
	v_mfma_f32_16x16x32_bf16 v[24:27], v[212:215], v[180:183], v[24:27]
	v_mfma_f32_16x16x32_bf16 v[12:15], v[204:207], v[188:191], v[12:15]
	v_mfma_f32_16x16x32_bf16 v[8:11], v[212:215], v[188:191], v[8:11]
	v_mfma_f32_16x16x32_bf16 v[4:7], v[204:207], v[196:199], v[4:7]
	v_mfma_f32_16x16x32_bf16 v[0:3], v[212:215], v[196:199], v[0:3]
	v_mfma_f32_16x16x32_bf16 v[44:47], v[208:211], v[176:179], v[44:47]
	v_mfma_f32_16x16x32_bf16 v[40:43], v[216:219], v[176:179], v[40:43]
	v_mfma_f32_16x16x32_bf16 v[28:31], v[208:211], v[184:187], v[28:31]
	v_mfma_f32_16x16x32_bf16 v[24:27], v[216:219], v[184:187], v[24:27]
	v_mfma_f32_16x16x32_bf16 v[12:15], v[208:211], v[192:195], v[12:15]
	v_mfma_f32_16x16x32_bf16 v[8:11], v[216:219], v[192:195], v[8:11]
	v_mfma_f32_16x16x32_bf16 v[4:7], v[208:211], v[200:203], v[4:7]
	v_mfma_f32_16x16x32_bf16 v[0:3], v[216:219], v[200:203], v[0:3]
	s_barrier
	s_add_i32 s51, 0, 0x18000
	v_add_u32_e32 v136, s51, v148
	ds_read_b128 v[156:159], v136
	ds_read_b128 v[160:163], v136 offset:1024
	ds_read_b128 v[164:167], v136 offset:2048
	ds_read_b128 v[168:171], v136 offset:3072
	s_add_u32 s28, s28, 0x40000
	s_addc_u32 s29, s29, 0
	s_mov_b32 m0, s40
	v_lshl_add_u64 v[204:205], s[28:29], 0, v[128:129]
	ds_read_b128 v[172:175], v151 offset:32768
	ds_read_b128 v[176:179], v151 offset:33792
	ds_read_b128 v[180:183], v151 offset:34816
	ds_read_b128 v[184:187], v151 offset:35840
	ds_read_b128 v[188:191], v151 offset:36864
	ds_read_b128 v[192:195], v151 offset:37888
	ds_read_b128 v[196:199], v151 offset:38912
	ds_read_b128 v[200:203], v151 offset:39936
	global_load_lds_dwordx4 v[204:205], off
	s_mov_b32 m0, s41
	v_lshl_add_u64 v[204:205], s[28:29], 0, v[132:133]
	global_load_lds_dwordx4 v[204:205], off
	s_waitcnt lgkmcnt(8)
	s_barrier
	s_waitcnt lgkmcnt(0)
	v_mfma_f32_16x16x32_bf16 v[124:127], v[156:159], v[172:175], v[124:127]
	v_mfma_f32_16x16x32_bf16 v[120:123], v[164:167], v[172:175], v[120:123]
	v_mfma_f32_16x16x32_bf16 v[116:119], v[156:159], v[180:183], v[116:119]
	v_mfma_f32_16x16x32_bf16 v[108:111], v[164:167], v[180:183], v[108:111]
	v_mfma_f32_16x16x32_bf16 v[100:103], v[156:159], v[188:191], v[100:103]
	v_mfma_f32_16x16x32_bf16 v[96:99], v[164:167], v[188:191], v[96:99]
	v_mfma_f32_16x16x32_bf16 v[84:87], v[156:159], v[196:199], v[84:87]
	v_mfma_f32_16x16x32_bf16 v[80:83], v[164:167], v[196:199], v[80:83]
	v_mfma_f32_16x16x32_bf16 v[124:127], v[160:163], v[176:179], v[124:127]
	v_mfma_f32_16x16x32_bf16 v[120:123], v[168:171], v[176:179], v[120:123]
	v_mfma_f32_16x16x32_bf16 v[116:119], v[160:163], v[184:187], v[116:119]
	v_mfma_f32_16x16x32_bf16 v[108:111], v[168:171], v[184:187], v[108:111]
	v_mfma_f32_16x16x32_bf16 v[100:103], v[160:163], v[192:195], v[100:103]
	v_mfma_f32_16x16x32_bf16 v[96:99], v[168:171], v[192:195], v[96:99]
	v_mfma_f32_16x16x32_bf16 v[84:87], v[160:163], v[200:203], v[84:87]
	v_mfma_f32_16x16x32_bf16 v[80:83], v[168:171], v[200:203], v[80:83]
	s_barrier
	s_add_i32 s28, 0, 0x1c000
	s_add_i32 s29, s51, s35
	v_add_u32_e32 v136, s28, v148
	v_lshl_add_u64 v[220:221], v[220:221], 0, s[8:9]
	s_mov_b32 m0, s29
	ds_read_b128 v[204:207], v136
	ds_read_b128 v[208:211], v136 offset:1024
	ds_read_b128 v[212:215], v136 offset:2048
	ds_read_b128 v[216:219], v136 offset:3072
	global_load_lds_dwordx4 v[220:221], off
	s_add_i32 m0, s29, 0x2000
	v_lshl_add_u64 v[220:221], v[222:223], 0, s[8:9]
	global_load_lds_dwordx4 v[220:221], off
	s_barrier
	s_waitcnt lgkmcnt(0)
	v_mfma_f32_16x16x32_bf16 v[112:115], v[204:207], v[172:175], v[112:115]
	v_mfma_f32_16x16x32_bf16 v[104:107], v[212:215], v[172:175], v[104:107]
	v_mfma_f32_16x16x32_bf16 v[92:95], v[204:207], v[180:183], v[92:95]
	v_mfma_f32_16x16x32_bf16 v[88:91], v[212:215], v[180:183], v[88:91]
	v_mfma_f32_16x16x32_bf16 v[76:79], v[204:207], v[188:191], v[76:79]
	v_mfma_f32_16x16x32_bf16 v[72:75], v[212:215], v[188:191], v[72:75]
	v_mfma_f32_16x16x32_bf16 v[68:71], v[204:207], v[196:199], v[68:71]
	v_mfma_f32_16x16x32_bf16 v[64:67], v[212:215], v[196:199], v[64:67]
	v_mfma_f32_16x16x32_bf16 v[112:115], v[208:211], v[176:179], v[112:115]
	v_mfma_f32_16x16x32_bf16 v[104:107], v[216:219], v[176:179], v[104:107]
	v_mfma_f32_16x16x32_bf16 v[92:95], v[208:211], v[184:187], v[92:95]
	v_mfma_f32_16x16x32_bf16 v[88:91], v[216:219], v[184:187], v[88:91]
	v_mfma_f32_16x16x32_bf16 v[76:79], v[208:211], v[192:195], v[76:79]
	v_mfma_f32_16x16x32_bf16 v[72:75], v[216:219], v[192:195], v[72:75]
	v_mfma_f32_16x16x32_bf16 v[68:71], v[208:211], v[200:203], v[68:71]
	v_mfma_f32_16x16x32_bf16 v[64:67], v[216:219], v[200:203], v[64:67]
	s_barrier
	s_mov_b32 m0, s44
	v_lshl_add_u64 v[220:221], v[224:225], 0, s[8:9]
	ds_read_b128 v[172:175], v151 offset:49152
	ds_read_b128 v[176:179], v151 offset:50176
	ds_read_b128 v[180:183], v151 offset:51200
	ds_read_b128 v[184:187], v151 offset:52224
	ds_read_b128 v[188:191], v151 offset:53248
	ds_read_b128 v[192:195], v151 offset:54272
	ds_read_b128 v[196:199], v151 offset:55296
	ds_read_b128 v[200:203], v151 offset:56320
	global_load_lds_dwordx4 v[220:221], off
	s_mov_b32 m0, s45
	v_lshl_add_u64 v[220:221], v[226:227], 0, s[8:9]
	global_load_lds_dwordx4 v[220:221], off
	s_barrier
; #define PG8_STAGE(bufoff, gbase, voff) do { _Pragma("unroll") for (int _i = 0; _i < 2; ++_i) \
;         __builtin_amdgcn_global_load_lds((const unsigned*)((const char*)(gbase) + (voff)[_i]), (LAS unsigned*)(lds + (bufoff) + ldsw + _i * 8192), 16, 0, 0); } while (0)
; #define PG8_MMA(ai, bj, At, Bt) do { __builtin_amdgcn_s_setprio(1); _Pragma("unroll") for (int m = 0; m < 4; ++m) _Pragma("unroll") for (int n = 0; n < 2; ++n) _Pragma("unroll") for (int k = 0; k < 2; ++k) \
;         acc[ai][bj][m][n] = __builtin_amdgcn_mfma_f32_16x16x32_bf16(Bt[n][k], At[m][k], acc[ai][bj][m][n], 0, 0, 0); __builtin_amdgcn_s_setprio(0); } while (0)
; #define PG8_WAIT_V(n) asm volatile("s_waitcnt vmcnt(" #n ")" ::: "memory")
; #define PG8_WAIT_L(n) asm volatile("s_waitcnt lgkmcnt(" #n ")" ::: "memory")
; #define PG8_BAR __builtin_amdgcn_s_barrier()
; #define PG8_SCHED __builtin_amdgcn_sched_barrier(0)
; template <class Epi>
; DEVI void gemm_phase(LAS unsigned char* lds, const Gemm g, const Epi& E) {
;     ...
;             PG8_BAR; PG8_WAIT_L(0); PG8_MMA(1, 0, At, B0); PG8_BAR; PG8_SCHED;
;             PG8_STAGE(PG8_SB(1, 1), b3 + hstepB, voffB);
;             PG8_WAIT_V(6); PG8_BAR; PG8_MMA(1, 1, At, B1); PG8_BAR;
	s_waitcnt lgkmcnt(0)
	v_mfma_f32_16x16x32_bf16 v[60:63], v[156:159], v[172:175], v[60:63]
	v_mfma_f32_16x16x32_bf16 v[56:59], v[164:167], v[172:175], v[56:59]
	v_mfma_f32_16x16x32_bf16 v[52:55], v[156:159], v[180:183], v[52:55]
	v_mfma_f32_16x16x32_bf16 v[48:51], v[164:167], v[180:183], v[48:51]
	v_mfma_f32_16x16x32_bf16 v[36:39], v[156:159], v[188:191], v[36:39]
	v_mfma_f32_16x16x32_bf16 v[32:35], v[164:167], v[188:191], v[32:35]
	v_mfma_f32_16x16x32_bf16 v[20:23], v[156:159], v[196:199], v[20:23]
	v_mfma_f32_16x16x32_bf16 v[16:19], v[164:167], v[196:199], v[16:19]
	v_mfma_f32_16x16x32_bf16 v[60:63], v[160:163], v[176:179], v[60:63]
	v_mfma_f32_16x16x32_bf16 v[56:59], v[168:171], v[176:179], v[56:59]
	v_mfma_f32_16x16x32_bf16 v[52:55], v[160:163], v[184:187], v[52:55]
	v_mfma_f32_16x16x32_bf16 v[48:51], v[168:171], v[184:187], v[48:51]
	v_mfma_f32_16x16x32_bf16 v[36:39], v[160:163], v[192:195], v[36:39]
	v_mfma_f32_16x16x32_bf16 v[32:35], v[168:171], v[192:195], v[32:35]
	v_mfma_f32_16x16x32_bf16 v[20:23], v[160:163], v[200:203], v[20:23]
	v_mfma_f32_16x16x32_bf16 v[16:19], v[168:171], v[200:203], v[16:19]
	s_barrier
	s_add_u32 s26, s26, 0x40080
	s_addc_u32 s27, s27, 0
	s_add_i32 s28, s28, s35
	s_mov_b32 m0, s28
	v_lshl_add_u64 v[156:157], s[26:27], 0, v[130:131]
	global_load_lds_dwordx4 v[156:157], off
	s_add_i32 m0, s28, 0x2000
	v_lshl_add_u64 v[156:157], s[26:27], 0, v[134:135]
	global_load_lds_dwordx4 v[156:157], off
	s_waitcnt vmcnt(6)
	s_barrier
	v_mfma_f32_16x16x32_bf16 v[44:47], v[204:207], v[172:175], v[44:47]
	v_mfma_f32_16x16x32_bf16 v[40:43], v[212:215], v[172:175], v[40:43]
	v_mfma_f32_16x16x32_bf16 v[28:31], v[204:207], v[180:183], v[28:31]
	v_mfma_f32_16x16x32_bf16 v[24:27], v[212:215], v[180:183], v[24:27]
	v_mfma_f32_16x16x32_bf16 v[12:15], v[204:207], v[188:191], v[12:15]
	v_mfma_f32_16x16x32_bf16 v[8:11], v[212:215], v[188:191], v[8:11]
	v_mfma_f32_16x16x32_bf16 v[4:7], v[204:207], v[196:199], v[4:7]
	v_mfma_f32_16x16x32_bf16 v[0:3], v[212:215], v[196:199], v[0:3]
	v_mfma_f32_16x16x32_bf16 v[44:47], v[208:211], v[176:179], v[44:47]
	v_mfma_f32_16x16x32_bf16 v[40:43], v[216:219], v[176:179], v[40:43]
	v_mfma_f32_16x16x32_bf16 v[28:31], v[208:211], v[184:187], v[28:31]
	v_mfma_f32_16x16x32_bf16 v[24:27], v[216:219], v[184:187], v[24:27]
	v_mfma_f32_16x16x32_bf16 v[12:15], v[208:211], v[192:195], v[12:15]
	v_mfma_f32_16x16x32_bf16 v[8:11], v[216:219], v[192:195], v[8:11]
	v_mfma_f32_16x16x32_bf16 v[4:7], v[208:211], v[200:203], v[4:7]
	v_mfma_f32_16x16x32_bf16 v[0:3], v[216:219], v[200:203], v[0:3]
	s_barrier
	s_add_i32 s50, s50, 2
	s_add_u32 s0, s0, 0x100
	s_addc_u32 s1, s1, 0
	s_add_u32 s17, s17, 0x100
	s_addc_u32 s49, s49, 0
	s_cmp_gt_u32 s50, 13
	s_cbranch_scc0 .LBB0_187
;     DEVI f32x4 load(int r, int c) const { const bf16x4 y = *(const bf16x4*)(Y + (size_t)r * DM + c); return (f32x4){bf2f((u16)y[0]), bf2f((u16)y[1]), bf2f((u16)y[2]), bf2f((u16)y[3])}; }
; template <class Epi>
; DEVI void gemm_phase(LAS unsigned char* lds, const Gemm g, const Epi& E) {
;     ...
;             for (int am = 0; am < 4; ++am) {
;                 const int ai = am >> 1, m0 = (am & 1) * 2;
;                 f32x4 pre[2][2][2];
;                 if constexpr (Epi::PRE) {
; #pragma unroll
;                     for (int m = 0; m < 2; ++m)
; #pragma unroll
;                         for (int bj = 0; bj < 2; ++bj)
; #pragma unroll
;                             for (int n = 0; n < 2; ++n) pre[m][bj][n] = E.load(row0 + ai * HALF + (m0 + m) * 16, col0 + bj * HALF + n * NST);
;                 }
; #pragma unroll
;                 for (int mm = 0; mm < 2; ++mm) {
;                     const int m = m0 + mm;
;                     const int r = row0 + ai * HALF + m * 16; float rs = 1.f, part = 0.f;
;                     if constexpr (Epi::RS) rs = rsv[ai * 4 + m];
;                     if constexpr (Epi::PAIR) E.pair8(cur.b, r, cur.pn * HALF + wc * 32 + 8 * fq, acc[ai][0][m][0] * rs, acc[ai][0][m][1] * rs, acc[ai][1][m][0] * rs, acc[ai][1][m][1] * rs);
;                     else
; #pragma unroll
;                     for (int bj = 0; bj < 2; ++bj) {
;                         const int c = col0 + bj * HALF; f32x4 v0 = acc[ai][bj][m][0], v1 = acc[ai][bj][m][1];
;                         if constexpr (Epi::RS) { v0 = v0 * rs; v1 = v1 * rs; }
;                         if constexpr (Epi::PRE) part += E.frag_pre8(cur.b, r, c, v0, v1, pre[mm][bj][0], pre[mm][bj][1]);
;                         else if constexpr (Epi::PERM) E.frag8(cur.b, r, c, v0, v1);
;                         else { E.frag(cur.b, r, c, v0); E.frag(cur.b, r, c + 16, v1); }
;                     }
	s_setprio 0
	v_lshl_add_u32 v156, s48, 8, v147
	v_ashrrev_i32_e32 v157, 31, v156
	v_readlane_b32 s2, v252, 39
	v_lshlrev_b64 v[158:159], 11, v[156:157]
	v_lshl_or_b32 v155, s11, 8, v149
	v_mov_b32_e32 v157, s2
	v_readlane_b32 s2, v252, 37
	s_ashr_i32 s11, s10, 31
	v_cmp_gt_i32_e32 vcc, s42, v155
	v_mov_b32_e32 v162, s2
	v_readlane_b32 s2, v252, 38
	s_lshl_b64 s[0:1], s[10:11], 21
	v_cndmask_b32_e32 v161, v157, v162, vcc
	v_mov_b32_e32 v163, s2
	v_readlane_b32 s2, v252, 36
	v_cvt_pk_bf16_f32 v124, v124, v125
	v_cvt_pk_bf16_f32 v125, v126, v127
	v_mov_b32_e32 v164, s2
	v_cndmask_b32_e32 v160, v163, v164, vcc
	v_cvt_pk_bf16_f32 v126, v120, v121
	v_lshl_add_u64 v[120:121], v[160:161], 0, s[0:1]
	v_and_b32_e32 v136, 0x378, v155
	v_cvt_pk_bf16_f32 v127, v122, v123
	v_lshl_add_u64 v[122:123], v[120:121], 0, v[158:159]
	v_lshlrev_b32_e32 v136, 1, v136
	v_lshl_add_u64 v[122:123], v[122:123], 0, v[136:137]
	global_store_dwordx4 v[122:123], v[124:127], off
	v_or_b32_e32 v122, 0x80, v155
	v_cmp_gt_i32_e32 vcc, s42, v122
	v_cvt_pk_bf16_f32 v112, v112, v113
	v_cvt_pk_bf16_f32 v113, v114, v115
	v_cndmask_b32_e32 v123, v157, v162, vcc
	v_cndmask_b32_e32 v122, v163, v164, vcc
	v_lshl_add_u64 v[122:123], v[122:123], 0, s[0:1]
	s_movk_i32 s0, 0x3f8
	v_cvt_pk_bf16_f32 v115, v106, v107
	v_bitop3_b32 v106, v155, s0, v153 bitop3:0xc8
	v_cvt_pk_bf16_f32 v114, v104, v105
	v_lshl_add_u64 v[104:105], v[122:123], 0, v[158:159]
	v_lshlrev_b32_e32 v124, 1, v106
	v_mov_b32_e32 v125, v137
	v_lshl_add_u64 v[104:105], v[104:105], 0, v[124:125]
	global_store_dwordx4 v[104:105], v[112:115], off
	v_or_b32_e32 v104, 16, v156
	v_ashrrev_i32_e32 v105, 31, v104
	v_lshlrev_b64 v[112:113], 11, v[104:105]
	v_cvt_pk_bf16_f32 v106, v108, v109
	v_lshl_add_u64 v[108:109], v[120:121], 0, v[112:113]
	v_cvt_pk_bf16_f32 v92, v92, v93
	v_cvt_pk_bf16_f32 v93, v94, v95
	v_cvt_pk_bf16_f32 v94, v88, v89
	v_lshl_add_u64 v[88:89], v[122:123], 0, v[112:113]
	v_cvt_pk_bf16_f32 v104, v116, v117
	v_cvt_pk_bf16_f32 v105, v118, v119
	v_cvt_pk_bf16_f32 v107, v110, v111
	v_lshl_add_u64 v[108:109], v[108:109], 0, v[136:137]
	v_cvt_pk_bf16_f32 v95, v90, v91
	v_lshl_add_u64 v[88:89], v[88:89], 0, v[124:125]
	global_store_dwordx4 v[108:109], v[104:107], off
	global_store_dwordx4 v[88:89], v[92:95], off
	v_or_b32_e32 v88, 32, v156
	v_ashrrev_i32_e32 v89, 31, v88
	v_lshlrev_b64 v[92:93], 11, v[88:89]
	v_lshl_add_u64 v[94:95], v[120:121], 0, v[92:93]
	v_cvt_pk_bf16_f32 v76, v76, v77
	v_cvt_pk_bf16_f32 v77, v78, v79
	v_cvt_pk_bf16_f32 v78, v72, v73
	v_lshl_add_u64 v[72:73], v[122:123], 0, v[92:93]
	v_cvt_pk_bf16_f32 v88, v100, v101
	v_cvt_pk_bf16_f32 v89, v102, v103
	v_cvt_pk_bf16_f32 v90, v96, v97
	v_cvt_pk_bf16_f32 v91, v98, v99
	v_lshl_add_u64 v[94:95], v[94:95], 0, v[136:137]
	v_cvt_pk_bf16_f32 v79, v74, v75
	v_lshl_add_u64 v[72:73], v[72:73], 0, v[124:125]
	global_store_dwordx4 v[94:95], v[88:91], off
	global_store_dwordx4 v[72:73], v[76:79], off
	v_or_b32_e32 v72, 48, v156
	v_ashrrev_i32_e32 v73, 31, v72
	v_lshlrev_b64 v[76:77], 11, v[72:73]
	v_lshl_add_u64 v[78:79], v[120:121], 0, v[76:77]
	v_cvt_pk_bf16_f32 v68, v68, v69
	v_cvt_pk_bf16_f32 v69, v70, v71
	v_cvt_pk_bf16_f32 v70, v64, v65
	v_lshl_add_u64 v[64:65], v[122:123], 0, v[76:77]
	v_cvt_pk_bf16_f32 v72, v84, v85
	v_cvt_pk_bf16_f32 v73, v86, v87
	v_cvt_pk_bf16_f32 v74, v80, v81
	v_cvt_pk_bf16_f32 v75, v82, v83
	v_lshl_add_u64 v[78:79], v[78:79], 0, v[136:137]
	v_cvt_pk_bf16_f32 v71, v66, v67
	v_lshl_add_u64 v[64:65], v[64:65], 0, v[124:125]
	s_mov_b64 s[0:1], 0x40000
	global_store_dwordx4 v[78:79], v[72:75], off
	global_store_dwordx4 v[64:65], v[68:71], off
	v_lshl_add_u64 v[64:65], v[158:159], 0, s[0:1]
	v_cvt_pk_bf16_f32 v60, v60, v61
	v_cvt_pk_bf16_f32 v61, v62, v63
	v_cvt_pk_bf16_f32 v62, v56, v57
	v_lshl_add_u64 v[56:57], v[120:121], 0, v[64:65]
	v_cvt_pk_bf16_f32 v44, v44, v45
	v_cvt_pk_bf16_f32 v45, v46, v47
	v_cvt_pk_bf16_f32 v46, v40, v41
	v_lshl_add_u64 v[40:41], v[122:123], 0, v[64:65]
	v_cvt_pk_bf16_f32 v63, v58, v59
	v_lshl_add_u64 v[56:57], v[56:57], 0, v[136:137]
	v_cvt_pk_bf16_f32 v47, v42, v43
	v_lshl_add_u64 v[40:41], v[40:41], 0, v[124:125]
	s_mov_b64 s[0:1], 0x48000
	global_store_dwordx4 v[56:57], v[60:63], off
	global_store_dwordx4 v[40:41], v[44:47], off
	v_cvt_pk_bf16_f32 v28, v28, v29
	v_cvt_pk_bf16_f32 v29, v30, v31
	v_lshl_add_u64 v[44:45], v[158:159], 0, s[0:1]
	v_lshl_add_u64 v[46:47], v[120:121], 0, v[44:45]
	v_cvt_pk_bf16_f32 v30, v24, v25
	v_lshl_add_u64 v[24:25], v[122:123], 0, v[44:45]
	v_cvt_pk_bf16_f32 v40, v52, v53
	v_cvt_pk_bf16_f32 v41, v54, v55
	v_cvt_pk_bf16_f32 v42, v48, v49
	v_cvt_pk_bf16_f32 v43, v50, v51
	v_lshl_add_u64 v[46:47], v[46:47], 0, v[136:137]
	v_cvt_pk_bf16_f32 v31, v26, v27
	v_lshl_add_u64 v[24:25], v[24:25], 0, v[124:125]
	s_mov_b64 s[0:1], 0x50000
	global_store_dwordx4 v[46:47], v[40:43], off
	global_store_dwordx4 v[24:25], v[28:31], off
	v_cvt_pk_bf16_f32 v12, v12, v13
	v_cvt_pk_bf16_f32 v13, v14, v15
	v_lshl_add_u64 v[28:29], v[158:159], 0, s[0:1]
	v_lshl_add_u64 v[30:31], v[120:121], 0, v[28:29]
	v_cvt_pk_bf16_f32 v14, v8, v9
	v_lshl_add_u64 v[8:9], v[122:123], 0, v[28:29]
	v_cvt_pk_bf16_f32 v24, v36, v37
	v_cvt_pk_bf16_f32 v25, v38, v39
	v_cvt_pk_bf16_f32 v26, v32, v33
	v_cvt_pk_bf16_f32 v27, v34, v35
	v_lshl_add_u64 v[30:31], v[30:31], 0, v[136:137]
	v_cvt_pk_bf16_f32 v15, v10, v11
	v_lshl_add_u64 v[8:9], v[8:9], 0, v[124:125]
	s_mov_b64 s[0:1], 0x58000
	global_store_dwordx4 v[30:31], v[24:27], off
	global_store_dwordx4 v[8:9], v[12:15], off
	v_cvt_pk_bf16_f32 v4, v4, v5
	v_cvt_pk_bf16_f32 v5, v6, v7
	v_lshl_add_u64 v[12:13], v[158:159], 0, s[0:1]
	v_lshl_add_u64 v[14:15], v[120:121], 0, v[12:13]
	v_cvt_pk_bf16_f32 v6, v0, v1
	v_lshl_add_u64 v[0:1], v[122:123], 0, v[12:13]
	v_cvt_pk_bf16_f32 v8, v20, v21
	v_cvt_pk_bf16_f32 v9, v22, v23
	v_cvt_pk_bf16_f32 v10, v16, v17
	v_cvt_pk_bf16_f32 v11, v18, v19
	v_lshl_add_u64 v[14:15], v[14:15], 0, v[136:137]
	v_cvt_pk_bf16_f32 v7, v2, v3
	v_lshl_add_u64 v[0:1], v[0:1], 0, v[124:125]
	s_and_b64 vcc, exec, s[4:5]
	s_mov_b32 s10, s12
	s_mov_b32 s11, s14
	s_mov_b32 s48, s16
	s_mov_b64 s[28:29], s[18:19]
	s_mov_b64 s[26:27], s[24:25]
	global_store_dwordx4 v[14:15], v[8:11], off
	global_store_dwordx4 v[0:1], v[4:7], off
	s_cbranch_vccz .LBB0_178
	s_waitcnt vmcnt(0)
	s_cmpk_gt_u32 s34, 0xff
	s_cbranch_scc1 .LBB0_191
	s_barrier

; #define PG8_STAGE(bufoff, gbase, voff) do { _Pragma("unroll") for (int _i = 0; _i < 2; ++_i) \
;         __builtin_amdgcn_global_load_lds((const unsigned*)((const char*)(gbase) + (voff)[_i]), (LAS unsigned*)(lds + (bufoff) + ldsw + _i * 8192), 16, 0, 0); } while (0)
; #define PG8_LDA(dst, b, h) do { _Pragma("unroll") for (int m = 0; m < 4; ++m) _Pragma("unroll") for (int k = 0; k < 2; ++k) dst[m][k] = *(const LAS bf16x8*)(lds + PG8_SA(b, h) + aoff + m * 2048 + k * 1024); } while (0)
; #define PG8_LDB(dst, b, h) do { _Pragma("unroll") for (int n = 0; n < 2; ++n) _Pragma("unroll") for (int k = 0; k < 2; ++k) dst[n][k] = *(const LAS bf16x8*)(lds + PG8_SB(b, h) + boff + n * 2048 + k * 1024); } while (0)
; #define PG8_MMA(ai, bj, At, Bt) do { __builtin_amdgcn_s_setprio(1); _Pragma("unroll") for (int m = 0; m < 4; ++m) _Pragma("unroll") for (int n = 0; n < 2; ++n) _Pragma("unroll") for (int k = 0; k < 2; ++k) \
;         acc[ai][bj][m][n] = __builtin_amdgcn_mfma_f32_16x16x32_bf16(Bt[n][k], At[m][k], acc[ai][bj][m][n], 0, 0, 0); __builtin_amdgcn_s_setprio(0); } while (0)
; #define PG8_WAIT_L(n) asm volatile("s_waitcnt lgkmcnt(" #n ")" ::: "memory")
; #define PG8_BAR __builtin_amdgcn_s_barrier()
; #define PG8_SCHED __builtin_amdgcn_sched_barrier(0)
; template <class Epi>
; DEVI void gemm_phase(LAS unsigned char* lds, const Gemm g, const Epi& E) {
;     ...
;             PG8_LDB(B0, 0, 0); PG8_SCHED; PG8_LDA(At, 0, 0); PG8_STAGE(PG8_SA(1, 1), a1 + hstepA, voffA);
;             PG8_WAIT_L(8); PG8_BAR; PG8_WAIT_L(0); PG8_MMA(0, 0, At, B0); PG8_BAR; PG8_SCHED;
;             PG8_LDB(B1, 0, 1); PG8_STAGE(PG8_SB(0, 0), b2, voffB);
;             PG8_BAR; PG8_WAIT_L(0); PG8_MMA(0, 1, At, B1); PG8_BAR;
;             PG8_LDA(At, 0, 1); PG8_STAGE(PG8_SA(0, 0), a2, voffA);
;             PG8_BAR; PG8_WAIT_L(0); PG8_MMA(1, 0, At, B0); PG8_BAR; PG8_SCHED;
;             PG8_STAGE(PG8_SB(0, 1), b2 + hstepB, voffB);
.LBB0_968:
	s_add_u32 s26, s68, 0xfffc0080
	s_addc_u32 s27, s69, -1
	s_add_i32 s38, 0, 0x10000
	v_add_u32_e32 v142, s38, v193
	ds_read_b128 v[130:133], v142
	ds_read_b128 v[134:137], v142 offset:1024
	ds_read_b128 v[138:141], v142 offset:2048
	ds_read_b128 v[142:145], v142 offset:3072
	s_cmp_eq_u32 s19, 12
	s_cselect_b32 s83, s0, s27
	s_cselect_b32 s82, s1, s26
	s_cselect_b32 s81, s9, s18
	s_cselect_b32 s80, s13, s15
	v_lshl_add_u64 v[162:163], s[68:69], 0, v[178:179]
	s_add_i32 m0, s85, 0xc000
	ds_read_b128 v[146:149], v198
	ds_read_b128 v[182:185], v198 offset:1024
	ds_read_b128 v[186:189], v198 offset:2048
	ds_read_b128 v[200:203], v198 offset:3072
	ds_read_b128 v[204:207], v198 offset:4096
	ds_read_b128 v[214:217], v198 offset:5120
	ds_read_b128 v[218:221], v198 offset:6144
	ds_read_b128 v[222:225], v198 offset:7168
	global_load_lds_dwordx4 v[162:163], off
	s_add_i32 m0, s85, 0xe000
	v_lshl_add_u64 v[162:163], s[68:69], 0, v[180:181]
	global_load_lds_dwordx4 v[162:163], off
	s_waitcnt lgkmcnt(8)
	s_barrier
	s_waitcnt lgkmcnt(0)
	v_mfma_f32_16x16x32_bf16 v[126:129], v[130:133], v[146:149], v[126:129]
	v_mfma_f32_16x16x32_bf16 v[122:125], v[138:141], v[146:149], v[122:125]
	v_mfma_f32_16x16x32_bf16 v[110:113], v[130:133], v[186:189], v[110:113]
	v_mfma_f32_16x16x32_bf16 v[106:109], v[138:141], v[186:189], v[106:109]
	v_mfma_f32_16x16x32_bf16 v[94:97], v[130:133], v[204:207], v[94:97]
	v_mfma_f32_16x16x32_bf16 v[90:93], v[138:141], v[204:207], v[90:93]
	v_mfma_f32_16x16x32_bf16 v[78:81], v[130:133], v[218:221], v[78:81]
	v_mfma_f32_16x16x32_bf16 v[74:77], v[138:141], v[218:221], v[74:77]
	v_mfma_f32_16x16x32_bf16 v[126:129], v[134:137], v[182:185], v[126:129]
	v_mfma_f32_16x16x32_bf16 v[122:125], v[142:145], v[182:185], v[122:125]
	v_mfma_f32_16x16x32_bf16 v[110:113], v[134:137], v[200:203], v[110:113]
	v_mfma_f32_16x16x32_bf16 v[106:109], v[142:145], v[200:203], v[106:109]
	v_mfma_f32_16x16x32_bf16 v[94:97], v[134:137], v[214:217], v[94:97]
	v_mfma_f32_16x16x32_bf16 v[90:93], v[142:145], v[214:217], v[90:93]
	v_mfma_f32_16x16x32_bf16 v[78:81], v[134:137], v[222:225], v[78:81]
	v_mfma_f32_16x16x32_bf16 v[74:77], v[142:145], v[222:225], v[74:77]
	s_barrier
	s_add_i32 s39, 0, 0x14000
	v_add_u32_e32 v162, s39, v193
	s_add_i32 s26, s38, s84
	ds_read_b128 v[226:229], v162
	ds_read_b128 v[230:233], v162 offset:1024
	ds_read_b128 v[234:237], v162 offset:2048
	ds_read_b128 v[238:241], v162 offset:3072
	v_lshl_add_u64 v[162:163], s[80:81], 0, v[8:9]
	s_mov_b32 m0, s26
	v_lshl_add_u64 v[164:165], s[80:81], 0, v[176:177]
	global_load_lds_dwordx4 v[162:163], off
	s_add_i32 m0, s26, 0x2000
	s_nop 0
	global_load_lds_dwordx4 v[164:165], off
	s_barrier
	s_waitcnt lgkmcnt(0)
	v_mfma_f32_16x16x32_bf16 v[118:121], v[226:229], v[146:149], v[118:121]
	v_mfma_f32_16x16x32_bf16 v[114:117], v[234:237], v[146:149], v[114:117]
	v_mfma_f32_16x16x32_bf16 v[102:105], v[226:229], v[186:189], v[102:105]
	v_mfma_f32_16x16x32_bf16 v[98:101], v[234:237], v[186:189], v[98:101]
	v_mfma_f32_16x16x32_bf16 v[86:89], v[226:229], v[204:207], v[86:89]
	v_mfma_f32_16x16x32_bf16 v[82:85], v[234:237], v[204:207], v[82:85]
	v_mfma_f32_16x16x32_bf16 v[70:73], v[226:229], v[218:221], v[70:73]
	v_mfma_f32_16x16x32_bf16 v[66:69], v[234:237], v[218:221], v[66:69]
	v_mfma_f32_16x16x32_bf16 v[118:121], v[230:233], v[182:185], v[118:121]
	v_mfma_f32_16x16x32_bf16 v[114:117], v[238:241], v[182:185], v[114:117]
	v_mfma_f32_16x16x32_bf16 v[102:105], v[230:233], v[200:203], v[102:105]
	v_mfma_f32_16x16x32_bf16 v[98:101], v[238:241], v[200:203], v[98:101]
	v_mfma_f32_16x16x32_bf16 v[86:89], v[230:233], v[214:217], v[86:89]
	v_mfma_f32_16x16x32_bf16 v[82:85], v[238:241], v[214:217], v[82:85]
	v_mfma_f32_16x16x32_bf16 v[70:73], v[230:233], v[222:225], v[70:73]
	v_mfma_f32_16x16x32_bf16 v[66:69], v[238:241], v[222:225], v[66:69]
	s_barrier
	s_mov_b32 m0, s85
	v_lshl_add_u64 v[190:191], s[82:83], 0, v[150:151]
	ds_read_b128 v[146:149], v198 offset:16384
	ds_read_b128 v[182:185], v198 offset:17408
	ds_read_b128 v[186:189], v198 offset:18432
	ds_read_b128 v[200:203], v198 offset:19456
	ds_read_b128 v[204:207], v198 offset:20480
	ds_read_b128 v[214:217], v198 offset:21504
	ds_read_b128 v[218:221], v198 offset:22528
	ds_read_b128 v[222:225], v198 offset:23552
	global_load_lds_dwordx4 v[190:191], off
	s_mov_b32 m0, s86
	v_lshl_add_u64 v[208:209], s[82:83], 0, v[152:153]
	global_load_lds_dwordx4 v[208:209], off
	s_barrier
	s_waitcnt lgkmcnt(0)
	v_mfma_f32_16x16x32_bf16 v[62:65], v[130:133], v[146:149], v[62:65]
	v_mfma_f32_16x16x32_bf16 v[58:61], v[138:141], v[146:149], v[58:61]
	v_mfma_f32_16x16x32_bf16 v[46:49], v[130:133], v[186:189], v[46:49]
	v_mfma_f32_16x16x32_bf16 v[42:45], v[138:141], v[186:189], v[42:45]
	v_mfma_f32_16x16x32_bf16 v[30:33], v[130:133], v[204:207], v[30:33]
	v_mfma_f32_16x16x32_bf16 v[26:29], v[138:141], v[204:207], v[26:29]
	v_mfma_f32_16x16x32_bf16 v[14:17], v[130:133], v[218:221], v[14:17]
	v_mfma_f32_16x16x32_bf16 v[10:13], v[138:141], v[218:221], v[10:13]
	v_mfma_f32_16x16x32_bf16 v[62:65], v[134:137], v[182:185], v[62:65]
	v_mfma_f32_16x16x32_bf16 v[58:61], v[142:145], v[182:185], v[58:61]
	v_mfma_f32_16x16x32_bf16 v[46:49], v[134:137], v[200:203], v[46:49]
	v_mfma_f32_16x16x32_bf16 v[42:45], v[142:145], v[200:203], v[42:45]
	v_mfma_f32_16x16x32_bf16 v[30:33], v[134:137], v[214:217], v[30:33]
	v_mfma_f32_16x16x32_bf16 v[26:29], v[142:145], v[214:217], v[26:29]
	v_mfma_f32_16x16x32_bf16 v[14:17], v[134:137], v[222:225], v[14:17]
	v_mfma_f32_16x16x32_bf16 v[10:13], v[142:145], v[222:225], v[10:13]
	s_barrier
; #define PG8_STAGE(bufoff, gbase, voff) do { _Pragma("unroll") for (int _i = 0; _i < 2; ++_i) \
;         __builtin_amdgcn_global_load_lds((const unsigned*)((const char*)(gbase) + (voff)[_i]), (LAS unsigned*)(lds + (bufoff) + ldsw + _i * 8192), 16, 0, 0); } while (0)
; #define PG8_LDA(dst, b, h) do { _Pragma("unroll") for (int m = 0; m < 4; ++m) _Pragma("unroll") for (int k = 0; k < 2; ++k) dst[m][k] = *(const LAS bf16x8*)(lds + PG8_SA(b, h) + aoff + m * 2048 + k * 1024); } while (0)
; #define PG8_LDB(dst, b, h) do { _Pragma("unroll") for (int n = 0; n < 2; ++n) _Pragma("unroll") for (int k = 0; k < 2; ++k) dst[n][k] = *(const LAS bf16x8*)(lds + PG8_SB(b, h) + boff + n * 2048 + k * 1024); } while (0)
; #define PG8_MMA(ai, bj, At, Bt) do { __builtin_amdgcn_s_setprio(1); _Pragma("unroll") for (int m = 0; m < 4; ++m) _Pragma("unroll") for (int n = 0; n < 2; ++n) _Pragma("unroll") for (int k = 0; k < 2; ++k) \
;         acc[ai][bj][m][n] = __builtin_amdgcn_mfma_f32_16x16x32_bf16(Bt[n][k], At[m][k], acc[ai][bj][m][n], 0, 0, 0); __builtin_amdgcn_s_setprio(0); } while (0)
; #define PG8_WAIT_V(n) asm volatile("s_waitcnt vmcnt(" #n ")" ::: "memory")
; #define PG8_WAIT_L(n) asm volatile("s_waitcnt lgkmcnt(" #n ")" ::: "memory")
; #define PG8_BAR __builtin_amdgcn_s_barrier()
; #define PG8_SCHED __builtin_amdgcn_sched_barrier(0)
; template <class Epi>
; DEVI void gemm_phase(LAS unsigned char* lds, const Gemm g, const Epi& E) {
;     ...
;             PG8_STAGE(PG8_SB(0, 1), b2 + hstepB, voffB);
;             PG8_WAIT_V(6); PG8_BAR; PG8_MMA(1, 1, At, B1); PG8_BAR;
;             PG8_LDB(B0, 1, 0); PG8_SCHED; PG8_LDA(At, 1, 0); PG8_STAGE(PG8_SA(0, 1), a2 + hstepA, voffA);
;             PG8_WAIT_L(8); PG8_BAR; PG8_WAIT_L(0); PG8_MMA(0, 0, At, B0); PG8_BAR; PG8_SCHED;
;             PG8_LDB(B1, 1, 1); PG8_STAGE(PG8_SB(1, 0), b3, voffB);
;             PG8_BAR; PG8_WAIT_L(0); PG8_MMA(0, 1, At, B1); PG8_BAR;
;             PG8_LDA(At, 1, 1); PG8_STAGE(PG8_SA(1, 0), a3, voffA);
	s_add_u32 s26, s80, 0x40000
	s_addc_u32 s27, s81, 0
	s_add_i32 s38, s39, s84
	s_mov_b32 m0, s38
	v_lshl_add_u64 v[130:131], s[26:27], 0, v[8:9]
	global_load_lds_dwordx4 v[130:131], off
	s_add_i32 m0, s38, 0x2000
	v_lshl_add_u64 v[130:131], s[26:27], 0, v[176:177]
	global_load_lds_dwordx4 v[130:131], off
	s_waitcnt vmcnt(6)
	s_barrier
	v_mfma_f32_16x16x32_bf16 v[54:57], v[226:229], v[146:149], v[54:57]
	v_mfma_f32_16x16x32_bf16 v[50:53], v[234:237], v[146:149], v[50:53]
	v_mfma_f32_16x16x32_bf16 v[38:41], v[226:229], v[186:189], v[38:41]
	v_mfma_f32_16x16x32_bf16 v[34:37], v[234:237], v[186:189], v[34:37]
	v_mfma_f32_16x16x32_bf16 v[22:25], v[226:229], v[204:207], v[22:25]
	v_mfma_f32_16x16x32_bf16 v[18:21], v[234:237], v[204:207], v[18:21]
	v_mfma_f32_16x16x32_bf16 v[4:7], v[226:229], v[218:221], v[4:7]
	v_mfma_f32_16x16x32_bf16 v[0:3], v[234:237], v[218:221], v[0:3]
	v_mfma_f32_16x16x32_bf16 v[54:57], v[230:233], v[182:185], v[54:57]
	v_mfma_f32_16x16x32_bf16 v[50:53], v[238:241], v[182:185], v[50:53]
	v_mfma_f32_16x16x32_bf16 v[38:41], v[230:233], v[200:203], v[38:41]
	v_mfma_f32_16x16x32_bf16 v[34:37], v[238:241], v[200:203], v[34:37]
	v_mfma_f32_16x16x32_bf16 v[22:25], v[230:233], v[214:217], v[22:25]
	v_mfma_f32_16x16x32_bf16 v[18:21], v[238:241], v[214:217], v[18:21]
	v_mfma_f32_16x16x32_bf16 v[4:7], v[230:233], v[222:225], v[4:7]
	v_mfma_f32_16x16x32_bf16 v[0:3], v[238:241], v[222:225], v[0:3]
	s_barrier
	s_add_i32 s38, 0, 0x18000
	v_add_u32_e32 v142, s38, v193
	ds_read_b128 v[130:133], v142
	ds_read_b128 v[134:137], v142 offset:1024
	ds_read_b128 v[138:141], v142 offset:2048
	ds_read_b128 v[142:145], v142 offset:3072
	s_add_u32 s26, s82, 0x40000
	s_addc_u32 s27, s83, 0
	s_mov_b32 m0, s87
	v_lshl_add_u64 v[226:227], s[26:27], 0, v[150:151]
	ds_read_b128 v[146:149], v198 offset:32768
	ds_read_b128 v[182:185], v198 offset:33792
	ds_read_b128 v[186:189], v198 offset:34816
	ds_read_b128 v[200:203], v198 offset:35840
	ds_read_b128 v[204:207], v198 offset:36864
	ds_read_b128 v[214:217], v198 offset:37888
	ds_read_b128 v[218:221], v198 offset:38912
	ds_read_b128 v[222:225], v198 offset:39936
	global_load_lds_dwordx4 v[226:227], off
	s_mov_b32 m0, s88
	v_lshl_add_u64 v[226:227], s[26:27], 0, v[152:153]
	global_load_lds_dwordx4 v[226:227], off
	s_waitcnt lgkmcnt(8)
	s_barrier
	s_waitcnt lgkmcnt(0)
	v_mfma_f32_16x16x32_bf16 v[126:129], v[130:133], v[146:149], v[126:129]
	v_mfma_f32_16x16x32_bf16 v[122:125], v[138:141], v[146:149], v[122:125]
	v_mfma_f32_16x16x32_bf16 v[110:113], v[130:133], v[186:189], v[110:113]
	v_mfma_f32_16x16x32_bf16 v[106:109], v[138:141], v[186:189], v[106:109]
	v_mfma_f32_16x16x32_bf16 v[94:97], v[130:133], v[204:207], v[94:97]
	v_mfma_f32_16x16x32_bf16 v[90:93], v[138:141], v[204:207], v[90:93]
	v_mfma_f32_16x16x32_bf16 v[78:81], v[130:133], v[218:221], v[78:81]
	v_mfma_f32_16x16x32_bf16 v[74:77], v[138:141], v[218:221], v[74:77]
	v_mfma_f32_16x16x32_bf16 v[126:129], v[134:137], v[182:185], v[126:129]
	v_mfma_f32_16x16x32_bf16 v[122:125], v[142:145], v[182:185], v[122:125]
	v_mfma_f32_16x16x32_bf16 v[110:113], v[134:137], v[200:203], v[110:113]
	v_mfma_f32_16x16x32_bf16 v[106:109], v[142:145], v[200:203], v[106:109]
	v_mfma_f32_16x16x32_bf16 v[94:97], v[134:137], v[214:217], v[94:97]
	v_mfma_f32_16x16x32_bf16 v[90:93], v[142:145], v[214:217], v[90:93]
	v_mfma_f32_16x16x32_bf16 v[78:81], v[134:137], v[222:225], v[78:81]
	v_mfma_f32_16x16x32_bf16 v[74:77], v[142:145], v[222:225], v[74:77]
	s_barrier
	s_add_i32 s39, 0, 0x1c000
	s_add_i32 s26, s38, s84
	v_add_u32_e32 v199, s39, v193
	v_lshl_add_u64 v[162:163], v[162:163], 0, s[70:71]
	s_mov_b32 m0, s26
	ds_read_b128 v[226:229], v199
	ds_read_b128 v[230:233], v199 offset:1024
	ds_read_b128 v[234:237], v199 offset:2048
	ds_read_b128 v[238:241], v199 offset:3072
	global_load_lds_dwordx4 v[162:163], off
	s_add_i32 m0, s26, 0x2000
	v_lshl_add_u64 v[162:163], v[164:165], 0, s[70:71]
	global_load_lds_dwordx4 v[162:163], off
	s_barrier
	s_waitcnt lgkmcnt(0)
	v_mfma_f32_16x16x32_bf16 v[118:121], v[226:229], v[146:149], v[118:121]
	v_mfma_f32_16x16x32_bf16 v[114:117], v[234:237], v[146:149], v[114:117]
	v_mfma_f32_16x16x32_bf16 v[102:105], v[226:229], v[186:189], v[102:105]
	v_mfma_f32_16x16x32_bf16 v[98:101], v[234:237], v[186:189], v[98:101]
	v_mfma_f32_16x16x32_bf16 v[86:89], v[226:229], v[204:207], v[86:89]
	v_mfma_f32_16x16x32_bf16 v[82:85], v[234:237], v[204:207], v[82:85]
	v_mfma_f32_16x16x32_bf16 v[70:73], v[226:229], v[218:221], v[70:73]
	v_mfma_f32_16x16x32_bf16 v[66:69], v[234:237], v[218:221], v[66:69]
	v_mfma_f32_16x16x32_bf16 v[118:121], v[230:233], v[182:185], v[118:121]
	v_mfma_f32_16x16x32_bf16 v[114:117], v[238:241], v[182:185], v[114:117]
	v_mfma_f32_16x16x32_bf16 v[102:105], v[230:233], v[200:203], v[102:105]
	v_mfma_f32_16x16x32_bf16 v[98:101], v[238:241], v[200:203], v[98:101]
	v_mfma_f32_16x16x32_bf16 v[86:89], v[230:233], v[214:217], v[86:89]
	v_mfma_f32_16x16x32_bf16 v[82:85], v[238:241], v[214:217], v[82:85]
	v_mfma_f32_16x16x32_bf16 v[70:73], v[230:233], v[222:225], v[70:73]
	v_mfma_f32_16x16x32_bf16 v[66:69], v[238:241], v[222:225], v[66:69]
	s_barrier
	s_mov_b32 m0, s89
	v_lshl_add_u64 v[162:163], v[190:191], 0, s[70:71]
	ds_read_b128 v[146:149], v198 offset:49152
	ds_read_b128 v[182:185], v198 offset:50176
	ds_read_b128 v[186:189], v198 offset:51200
	ds_read_b128 v[200:203], v198 offset:52224
	ds_read_b128 v[204:207], v198 offset:53248
	ds_read_b128 v[214:217], v198 offset:54272
	ds_read_b128 v[218:221], v198 offset:55296
	ds_read_b128 v[222:225], v198 offset:56320
	global_load_lds_dwordx4 v[162:163], off
	s_mov_b32 m0, s90
	v_lshl_add_u64 v[162:163], v[208:209], 0, s[70:71]
	global_load_lds_dwordx4 v[162:163], off
	s_barrier
; #define LAS __attribute__((address_space(3)))
;     DEVI f32x4 load(int r, int c) const { const bf16x4 y = *(const bf16x4*)(Y + (size_t)r * DM + c); return (f32x4){bf2f((u16)y[0]), bf2f((u16)y[1]), bf2f((u16)y[2]), bf2f((u16)y[3])}; }
; template <class Epi>
; DEVI void gemm_phase(LAS unsigned char* lds, const Gemm g, const Epi& E) {
;     ...
;             for (int am = 0; am < 4; ++am) {
;                 const int ai = am >> 1, m0 = (am & 1) * 2;
;                 f32x4 pre[2][2][2];
;                 if constexpr (Epi::PRE) {
; #pragma unroll
;                     for (int m = 0; m < 2; ++m)
; #pragma unroll
;                         for (int bj = 0; bj < 2; ++bj)
; #pragma unroll
;                             for (int n = 0; n < 2; ++n) pre[m][bj][n] = E.load(row0 + ai * HALF + (m0 + m) * 16, col0 + bj * HALF + n * NST);
;                 }
; #pragma unroll
;                 for (int mm = 0; mm < 2; ++mm) {
;                     const int m = m0 + mm;
;                     const int r = row0 + ai * HALF + m * 16; float rs = 1.f, part = 0.f;
;                     if constexpr (Epi::RS) rs = rsv[ai * 4 + m];
;                     if constexpr (Epi::PAIR) E.pair8(cur.b, r, cur.pn * HALF + wc * 32 + 8 * fq, acc[ai][0][m][0] * rs, acc[ai][0][m][1] * rs, acc[ai][1][m][0] * rs, acc[ai][1][m][1] * rs);
;                     else
; #pragma unroll
;                     for (int bj = 0; bj < 2; ++bj) {
;                         const int c = col0 + bj * HALF; f32x4 v0 = acc[ai][bj][m][0], v1 = acc[ai][bj][m][1];
;                         if constexpr (Epi::RS) { v0 = v0 * rs; v1 = v1 * rs; }
;                         if constexpr (Epi::PRE) part += E.frag_pre8(cur.b, r, c, v0, v1, pre[mm][bj][0], pre[mm][bj][1]);
;                         else if constexpr (Epi::PERM) E.frag8(cur.b, r, c, v0, v1);
;                         else { E.frag(cur.b, r, c, v0); E.frag(cur.b, r, c + 16, v1); }
;                     }
;                     if constexpr (Epi::SSQ) { part += __shfl_xor(part, 16); part += __shfl_xor(part, 32); if (fq == 0) ((LAS float*)(lds + 131072))[(wr * 4 + wc) * 128 + ai * 64 + m * 16 + fr] = part; }
	s_waitcnt lgkmcnt(0)
	v_mfma_f32_16x16x32_bf16 v[62:65], v[130:133], v[146:149], v[62:65]
	v_mfma_f32_16x16x32_bf16 v[58:61], v[138:141], v[146:149], v[58:61]
	v_mfma_f32_16x16x32_bf16 v[46:49], v[130:133], v[186:189], v[46:49]
	v_mfma_f32_16x16x32_bf16 v[42:45], v[138:141], v[186:189], v[42:45]
	v_mfma_f32_16x16x32_bf16 v[30:33], v[130:133], v[204:207], v[30:33]
	v_mfma_f32_16x16x32_bf16 v[26:29], v[138:141], v[204:207], v[26:29]
	v_mfma_f32_16x16x32_bf16 v[14:17], v[130:133], v[218:221], v[14:17]
	v_mfma_f32_16x16x32_bf16 v[10:13], v[138:141], v[218:221], v[10:13]
	v_mfma_f32_16x16x32_bf16 v[62:65], v[134:137], v[182:185], v[62:65]
	v_mfma_f32_16x16x32_bf16 v[58:61], v[142:145], v[182:185], v[58:61]
	v_mfma_f32_16x16x32_bf16 v[46:49], v[134:137], v[200:203], v[46:49]
	v_mfma_f32_16x16x32_bf16 v[42:45], v[142:145], v[200:203], v[42:45]
	v_mfma_f32_16x16x32_bf16 v[30:33], v[134:137], v[214:217], v[30:33]
	v_mfma_f32_16x16x32_bf16 v[26:29], v[142:145], v[214:217], v[26:29]
	v_mfma_f32_16x16x32_bf16 v[14:17], v[134:137], v[222:225], v[14:17]
	v_mfma_f32_16x16x32_bf16 v[10:13], v[142:145], v[222:225], v[10:13]
	s_barrier
	s_add_u32 s26, s80, 0x40080
	s_addc_u32 s27, s81, 0
	s_add_i32 s38, s39, s84
	s_mov_b32 m0, s38
	v_lshl_add_u64 v[130:131], s[26:27], 0, v[8:9]
	global_load_lds_dwordx4 v[130:131], off
	s_add_i32 m0, s38, 0x2000
	v_lshl_add_u64 v[130:131], s[26:27], 0, v[176:177]
	global_load_lds_dwordx4 v[130:131], off
	s_waitcnt vmcnt(6)
	s_barrier
	v_mfma_f32_16x16x32_bf16 v[54:57], v[226:229], v[146:149], v[54:57]
	v_mfma_f32_16x16x32_bf16 v[50:53], v[234:237], v[146:149], v[50:53]
	v_mfma_f32_16x16x32_bf16 v[38:41], v[226:229], v[186:189], v[38:41]
	v_mfma_f32_16x16x32_bf16 v[34:37], v[234:237], v[186:189], v[34:37]
	v_mfma_f32_16x16x32_bf16 v[22:25], v[226:229], v[204:207], v[22:25]
	v_mfma_f32_16x16x32_bf16 v[18:21], v[234:237], v[204:207], v[18:21]
	v_mfma_f32_16x16x32_bf16 v[4:7], v[226:229], v[218:221], v[4:7]
	v_mfma_f32_16x16x32_bf16 v[0:3], v[234:237], v[218:221], v[0:3]
	v_mfma_f32_16x16x32_bf16 v[54:57], v[230:233], v[182:185], v[54:57]
	v_mfma_f32_16x16x32_bf16 v[50:53], v[238:241], v[182:185], v[50:53]
	v_mfma_f32_16x16x32_bf16 v[38:41], v[230:233], v[200:203], v[38:41]
	v_mfma_f32_16x16x32_bf16 v[34:37], v[238:241], v[200:203], v[34:37]
	v_mfma_f32_16x16x32_bf16 v[22:25], v[230:233], v[214:217], v[22:25]
	v_mfma_f32_16x16x32_bf16 v[18:21], v[238:241], v[214:217], v[18:21]
	v_mfma_f32_16x16x32_bf16 v[4:7], v[230:233], v[222:225], v[4:7]
	v_mfma_f32_16x16x32_bf16 v[0:3], v[238:241], v[222:225], v[0:3]
	s_barrier
	s_add_i32 s19, s19, 2
	s_add_u32 s68, s68, 0x100
	s_addc_u32 s69, s69, 0
	s_add_u32 s15, s15, 0x100
	s_addc_u32 s18, s18, 0
	s_cmp_gt_u32 s19, 13
	s_cbranch_scc0 .LBB0_968
	s_setprio 0
	v_and_b32_e32 v131, 64, v155
	v_xor_b32_e32 v130, 16, v155
	v_add_u32_e32 v131, 64, v131
	v_cmp_lt_i32_e32 vcc, v130, v131
	s_lshl_b32 s9, s46, 8
	v_add_u32_e32 v186, s9, v192
	v_cndmask_b32_e32 v130, v155, v130, vcc
	v_lshlrev_b32_e32 v200, 2, v130
	v_xor_b32_e32 v130, 32, v155
	v_cmp_lt_i32_e32 vcc, v130, v131
	v_lshl_or_b32 v184, s8, 8, v197
	v_ashrrev_i32_e32 v187, 31, v186
	v_cndmask_b32_e32 v130, v155, v130, vcc
	v_lshlrev_b32_e32 v199, 2, v130
	v_lshlrev_b64 v[130:131], 12, v[186:187]
	v_ashrrev_i32_e32 v185, 31, v184
	v_lshl_add_u64 v[130:131], s[78:79], 0, v[130:131]
	v_lshlrev_b64 v[188:189], 2, v[184:185]
	v_lshl_add_u64 v[130:131], v[130:131], 0, v[188:189]
	global_load_dwordx4 v[202:205], v[130:131], off offset:16
	global_load_dwordx4 v[206:209], v[130:131], off
	global_load_dwordx4 v[146:149], v[130:131], off offset:528
	global_load_dwordx4 v[214:217], v[130:131], off offset:512
	v_or_b32_e32 v190, 16, v186
	v_ashrrev_i32_e32 v191, 31, v190
	v_lshlrev_b64 v[130:131], 12, v[190:191]
	v_lshl_add_u64 v[130:131], s[78:79], 0, v[130:131]
	v_lshl_add_u64 v[134:135], v[130:131], 0, v[188:189]
	global_load_dwordx4 v[138:141], v[134:135], off offset:16
	global_load_dwordx4 v[142:145], v[134:135], off
	global_load_dwordx4 v[130:133], v[134:135], off offset:528
	s_nop 0
	global_load_dwordx4 v[134:137], v[134:135], off offset:512
	v_lshlrev_b64 v[162:163], 10, v[186:187]
	v_lshl_add_u64 v[164:165], v[162:163], 0, v[184:185]
	v_or_b32_e32 v182, 0x80, v184
	v_ashrrev_i32_e32 v183, 31, v182
	s_waitcnt vmcnt(0)
	v_pk_add_f32 v[122:123], v[122:123], v[202:203]
	v_pk_add_f32 v[128:129], v[128:129], v[208:209]
	v_pk_add_f32 v[126:127], v[126:127], v[206:207]
	v_lshl_add_u64 v[206:207], v[164:165], 2, s[30:31]
	v_pk_add_f32 v[124:125], v[124:125], v[204:205]
	global_store_dwordx4 v[206:207], v[126:129], off
	global_store_dwordx4 v[206:207], v[122:125], off offset:16
	v_cvt_pk_bf16_f32 v202, v126, v127
	v_cvt_pk_bf16_f32 v204, v122, v123
	v_mul_f32_e32 v127, v127, v127
	v_mul_f32_e32 v123, v123, v123
	v_fmac_f32_e32 v127, v126, v126
	v_mul_f32_e32 v126, v129, v129
	v_fmac_f32_e32 v123, v122, v122
	v_mul_f32_e32 v122, v125, v125
	v_fmac_f32_e32 v126, v128, v128
	v_fmac_f32_e32 v122, v124, v124
	v_cvt_pk_bf16_f32 v203, v128, v129
	v_cvt_pk_bf16_f32 v205, v124, v125
	v_lshl_add_u64 v[164:165], v[164:165], 1, s[28:29]
	v_add_f32_e32 v126, v127, v126
	v_add_f32_e32 v122, v123, v122
	v_pk_add_f32 v[120:121], v[120:121], v[216:217]
	v_pk_add_f32 v[118:119], v[118:119], v[214:215]
	v_pk_add_f32 v[114:115], v[114:115], v[146:147]
	global_store_dwordx4 v[164:165], v[202:205], off
	v_add_f32_e32 v128, v126, v122
	v_pk_add_f32 v[116:117], v[116:117], v[148:149]
	global_store_dwordx4 v[206:207], v[118:121], off offset:512
	global_store_dwordx4 v[206:207], v[114:117], off offset:528
	v_cvt_pk_bf16_f32 v122, v118, v119
	v_cvt_pk_bf16_f32 v124, v114, v115
	v_mul_f32_e32 v119, v119, v119
	v_mul_f32_e32 v115, v115, v115
	v_fmac_f32_e32 v119, v118, v118
	v_mul_f32_e32 v118, v121, v121
	v_fmac_f32_e32 v115, v114, v114
	v_mul_f32_e32 v114, v117, v117
	v_fmac_f32_e32 v118, v120, v120
	v_fmac_f32_e32 v114, v116, v116
	v_add_f32_e32 v118, v119, v118
	v_add_f32_e32 v114, v115, v114
	v_add_f32_e32 v114, v118, v114
	v_add_f32_e32 v114, v128, v114
	ds_bpermute_b32 v115, v200, v114
	v_lshl_add_u64 v[126:127], v[162:163], 0, v[182:183]
	v_cvt_pk_bf16_f32 v123, v120, v121
	v_cvt_pk_bf16_f32 v125, v116, v117
	v_lshl_add_u64 v[126:127], v[126:127], 1, s[28:29]
	s_waitcnt lgkmcnt(0)
	v_add_f32_e32 v114, v114, v115
	ds_bpermute_b32 v115, v199, v114
	global_store_dwordx4 v[126:127], v[122:125], off
	s_and_saveexec_b64 s[46:47], s[2:3]
	s_cbranch_execz .LBB0_971
	s_waitcnt lgkmcnt(0)
	v_add_f32_e32 v114, v114, v115
	ds_write_b32 v194, v114

; #define PG8_STAGE(bufoff, gbase, voff) do { _Pragma("unroll") for (int _i = 0; _i < 2; ++_i) \
;         __builtin_amdgcn_global_load_lds((const unsigned*)((const char*)(gbase) + (voff)[_i]), (LAS unsigned*)(lds + (bufoff) + ldsw + _i * 8192), 16, 0, 0); } while (0)
; #define PG8_LDA(dst, b, h) do { _Pragma("unroll") for (int m = 0; m < 4; ++m) _Pragma("unroll") for (int k = 0; k < 2; ++k) dst[m][k] = *(const LAS bf16x8*)(lds + PG8_SA(b, h) + aoff + m * 2048 + k * 1024); } while (0)
; #define PG8_LDB(dst, b, h) do { _Pragma("unroll") for (int n = 0; n < 2; ++n) _Pragma("unroll") for (int k = 0; k < 2; ++k) dst[n][k] = *(const LAS bf16x8*)(lds + PG8_SB(b, h) + boff + n * 2048 + k * 1024); } while (0)
; #define PG8_MMA(ai, bj, At, Bt) do { __builtin_amdgcn_s_setprio(1); _Pragma("unroll") for (int m = 0; m < 4; ++m) _Pragma("unroll") for (int n = 0; n < 2; ++n) _Pragma("unroll") for (int k = 0; k < 2; ++k) \
;         acc[ai][bj][m][n] = __builtin_amdgcn_mfma_f32_16x16x32_bf16(Bt[n][k], At[m][k], acc[ai][bj][m][n], 0, 0, 0); __builtin_amdgcn_s_setprio(0); } while (0)
; #define PG8_WAIT_L(n) asm volatile("s_waitcnt lgkmcnt(" #n ")" ::: "memory")
; #define PG8_BAR __builtin_amdgcn_s_barrier()
; #define PG8_SCHED __builtin_amdgcn_sched_barrier(0)
; template <class Epi>
; DEVI void gemm_phase(LAS unsigned char* lds, const Gemm g, const Epi& E) {
;     ...
;             PG8_LDB(B0, 0, 0); PG8_SCHED; PG8_LDA(At, 0, 0); PG8_STAGE(PG8_SA(1, 1), a1 + hstepA, voffA);
;             PG8_WAIT_L(8); PG8_BAR; PG8_WAIT_L(0); PG8_MMA(0, 0, At, B0); PG8_BAR; PG8_SCHED;
;             PG8_LDB(B1, 0, 1); PG8_STAGE(PG8_SB(0, 0), b2, voffB);
;             PG8_BAR; PG8_WAIT_L(0); PG8_MMA(0, 1, At, B1); PG8_BAR;
;             PG8_LDA(At, 0, 1); PG8_STAGE(PG8_SA(0, 0), a2, voffA);
;             PG8_BAR; PG8_WAIT_L(0); PG8_MMA(1, 0, At, B0); PG8_BAR; PG8_SCHED;
;             PG8_STAGE(PG8_SB(0, 1), b2 + hstepB, voffB);
.LBB0_1007:
	s_add_u32 s16, s14, 0xfffc0080
	s_addc_u32 s17, s15, -1
	s_add_i32 s26, 0, 0x10000
	v_add_u32_e32 v8, s26, v199
	ds_read_b128 v[130:133], v8
	ds_read_b128 v[134:137], v8 offset:1024
	ds_read_b128 v[138:141], v8 offset:2048
	ds_read_b128 v[142:145], v8 offset:3072
	s_cmp_eq_u32 s19, 12
	s_cselect_b32 s37, s0, s17
	s_cselect_b32 s36, s1, s16
	s_cselect_b32 s17, s5, s18
	s_cselect_b32 s16, s7, s9
	v_lshl_add_u64 v[162:163], s[14:15], 0, v[180:181]
	s_add_i32 m0, s66, 0xc000
	ds_read_b128 v[184:187], v204
	ds_read_b128 v[188:191], v204 offset:1024
	ds_read_b128 v[192:195], v204 offset:2048
	ds_read_b128 v[206:209], v204 offset:3072
	ds_read_b128 v[214:217], v204 offset:4096
	ds_read_b128 v[218:221], v204 offset:5120
	ds_read_b128 v[222:225], v204 offset:6144
	ds_read_b128 v[226:229], v204 offset:7168
	global_load_lds_dwordx4 v[162:163], off
	s_add_i32 m0, s66, 0xe000
	v_lshl_add_u64 v[162:163], s[14:15], 0, v[182:183]
	global_load_lds_dwordx4 v[162:163], off
	s_waitcnt lgkmcnt(8)
	s_barrier
	s_waitcnt lgkmcnt(0)
	v_mfma_f32_16x16x32_bf16 v[126:129], v[130:133], v[184:187], v[126:129]
	v_mfma_f32_16x16x32_bf16 v[122:125], v[138:141], v[184:187], v[122:125]
	v_mfma_f32_16x16x32_bf16 v[114:117], v[130:133], v[192:195], v[114:117]
	v_mfma_f32_16x16x32_bf16 v[106:109], v[138:141], v[192:195], v[106:109]
	v_mfma_f32_16x16x32_bf16 v[102:105], v[130:133], v[214:217], v[102:105]
	v_mfma_f32_16x16x32_bf16 v[94:97], v[138:141], v[214:217], v[94:97]
	v_mfma_f32_16x16x32_bf16 v[82:85], v[130:133], v[222:225], v[82:85]
	v_mfma_f32_16x16x32_bf16 v[74:77], v[138:141], v[222:225], v[74:77]
	v_mfma_f32_16x16x32_bf16 v[126:129], v[134:137], v[188:191], v[126:129]
	v_mfma_f32_16x16x32_bf16 v[122:125], v[142:145], v[188:191], v[122:125]
	v_mfma_f32_16x16x32_bf16 v[114:117], v[134:137], v[206:209], v[114:117]
	v_mfma_f32_16x16x32_bf16 v[106:109], v[142:145], v[206:209], v[106:109]
	v_mfma_f32_16x16x32_bf16 v[102:105], v[134:137], v[218:221], v[102:105]
	v_mfma_f32_16x16x32_bf16 v[94:97], v[142:145], v[218:221], v[94:97]
	v_mfma_f32_16x16x32_bf16 v[82:85], v[134:137], v[226:229], v[82:85]
	v_mfma_f32_16x16x32_bf16 v[74:77], v[142:145], v[226:229], v[74:77]
	s_barrier
	s_add_i32 s38, 0, 0x14000
	s_add_i32 s26, s26, s47
	v_add_u32_e32 v8, s38, v199
	v_lshl_add_u64 v[162:163], s[16:17], 0, v[148:149]
	s_mov_b32 m0, s26
	ds_read_b128 v[230:233], v8
	ds_read_b128 v[234:237], v8 offset:1024
	ds_read_b128 v[238:241], v8 offset:2048
	ds_read_b128 v[242:245], v8 offset:3072
	global_load_lds_dwordx4 v[162:163], off
	s_add_i32 m0, s26, 0x2000
	v_lshl_add_u64 v[164:165], s[16:17], 0, v[152:153]
	global_load_lds_dwordx4 v[164:165], off
	s_barrier
	s_waitcnt lgkmcnt(0)
	v_mfma_f32_16x16x32_bf16 v[118:121], v[230:233], v[184:187], v[118:121]
	v_mfma_f32_16x16x32_bf16 v[110:113], v[238:241], v[184:187], v[110:113]
	v_mfma_f32_16x16x32_bf16 v[98:101], v[230:233], v[192:195], v[98:101]
	v_mfma_f32_16x16x32_bf16 v[90:93], v[238:241], v[192:195], v[90:93]
	v_mfma_f32_16x16x32_bf16 v[86:89], v[230:233], v[214:217], v[86:89]
	v_mfma_f32_16x16x32_bf16 v[78:81], v[238:241], v[214:217], v[78:81]
	v_mfma_f32_16x16x32_bf16 v[54:57], v[230:233], v[222:225], v[54:57]
	v_mfma_f32_16x16x32_bf16 v[34:37], v[238:241], v[222:225], v[34:37]
	v_mfma_f32_16x16x32_bf16 v[118:121], v[234:237], v[188:191], v[118:121]
	v_mfma_f32_16x16x32_bf16 v[110:113], v[242:245], v[188:191], v[110:113]
	v_mfma_f32_16x16x32_bf16 v[98:101], v[234:237], v[206:209], v[98:101]
	v_mfma_f32_16x16x32_bf16 v[90:93], v[242:245], v[206:209], v[90:93]
	v_mfma_f32_16x16x32_bf16 v[86:89], v[234:237], v[218:221], v[86:89]
	v_mfma_f32_16x16x32_bf16 v[78:81], v[242:245], v[218:221], v[78:81]
	v_mfma_f32_16x16x32_bf16 v[54:57], v[234:237], v[226:229], v[54:57]
	v_mfma_f32_16x16x32_bf16 v[34:37], v[242:245], v[226:229], v[34:37]
	s_barrier
	s_mov_b32 m0, s66
	v_lshl_add_u64 v[202:203], s[36:37], 0, v[146:147]
	ds_read_b128 v[184:187], v204 offset:16384
	ds_read_b128 v[188:191], v204 offset:17408
	ds_read_b128 v[192:195], v204 offset:18432
	ds_read_b128 v[206:209], v204 offset:19456
	ds_read_b128 v[214:217], v204 offset:20480
	ds_read_b128 v[218:221], v204 offset:21504
	ds_read_b128 v[222:225], v204 offset:22528
	ds_read_b128 v[226:229], v204 offset:23552
	global_load_lds_dwordx4 v[202:203], off
	s_mov_b32 m0, s68
	v_lshl_add_u64 v[246:247], s[36:37], 0, v[150:151]
	global_load_lds_dwordx4 v[246:247], off
	s_barrier
	s_waitcnt lgkmcnt(0)
	v_mfma_f32_16x16x32_bf16 v[58:61], v[130:133], v[184:187], v[58:61]
	v_mfma_f32_16x16x32_bf16 v[62:65], v[138:141], v[184:187], v[62:65]
	v_mfma_f32_16x16x32_bf16 v[38:41], v[130:133], v[192:195], v[38:41]
	v_mfma_f32_16x16x32_bf16 v[42:45], v[138:141], v[192:195], v[42:45]
	v_mfma_f32_16x16x32_bf16 v[18:21], v[130:133], v[214:217], v[18:21]
	v_mfma_f32_16x16x32_bf16 v[22:25], v[138:141], v[214:217], v[22:25]
	v_mfma_f32_16x16x32_bf16 v[0:3], v[130:133], v[222:225], v[0:3]
	v_mfma_f32_16x16x32_bf16 v[4:7], v[138:141], v[222:225], v[4:7]
	v_mfma_f32_16x16x32_bf16 v[58:61], v[134:137], v[188:191], v[58:61]
	v_mfma_f32_16x16x32_bf16 v[62:65], v[142:145], v[188:191], v[62:65]
	v_mfma_f32_16x16x32_bf16 v[38:41], v[134:137], v[206:209], v[38:41]
	v_mfma_f32_16x16x32_bf16 v[42:45], v[142:145], v[206:209], v[42:45]
	v_mfma_f32_16x16x32_bf16 v[18:21], v[134:137], v[218:221], v[18:21]
	v_mfma_f32_16x16x32_bf16 v[22:25], v[142:145], v[218:221], v[22:25]
	v_mfma_f32_16x16x32_bf16 v[0:3], v[134:137], v[226:229], v[0:3]
	v_mfma_f32_16x16x32_bf16 v[4:7], v[142:145], v[226:229], v[4:7]
	s_barrier
; #define PG8_STAGE(bufoff, gbase, voff) do { _Pragma("unroll") for (int _i = 0; _i < 2; ++_i) \
;         __builtin_amdgcn_global_load_lds((const unsigned*)((const char*)(gbase) + (voff)[_i]), (LAS unsigned*)(lds + (bufoff) + ldsw + _i * 8192), 16, 0, 0); } while (0)
; #define PG8_LDA(dst, b, h) do { _Pragma("unroll") for (int m = 0; m < 4; ++m) _Pragma("unroll") for (int k = 0; k < 2; ++k) dst[m][k] = *(const LAS bf16x8*)(lds + PG8_SA(b, h) + aoff + m * 2048 + k * 1024); } while (0)
; #define PG8_LDB(dst, b, h) do { _Pragma("unroll") for (int n = 0; n < 2; ++n) _Pragma("unroll") for (int k = 0; k < 2; ++k) dst[n][k] = *(const LAS bf16x8*)(lds + PG8_SB(b, h) + boff + n * 2048 + k * 1024); } while (0)
; #define PG8_MMA(ai, bj, At, Bt) do { __builtin_amdgcn_s_setprio(1); _Pragma("unroll") for (int m = 0; m < 4; ++m) _Pragma("unroll") for (int n = 0; n < 2; ++n) _Pragma("unroll") for (int k = 0; k < 2; ++k) \
;         acc[ai][bj][m][n] = __builtin_amdgcn_mfma_f32_16x16x32_bf16(Bt[n][k], At[m][k], acc[ai][bj][m][n], 0, 0, 0); __builtin_amdgcn_s_setprio(0); } while (0)
; #define PG8_WAIT_V(n) asm volatile("s_waitcnt vmcnt(" #n ")" ::: "memory")
; #define PG8_WAIT_L(n) asm volatile("s_waitcnt lgkmcnt(" #n ")" ::: "memory")
; #define PG8_BAR __builtin_amdgcn_s_barrier()
; #define PG8_SCHED __builtin_amdgcn_sched_barrier(0)
; template <class Epi>
; DEVI void gemm_phase(LAS unsigned char* lds, const Gemm g, const Epi& E) {
;     ...
;             PG8_STAGE(PG8_SB(0, 1), b2 + hstepB, voffB);
;             PG8_WAIT_V(6); PG8_BAR; PG8_MMA(1, 1, At, B1); PG8_BAR;
;             PG8_LDB(B0, 1, 0); PG8_SCHED; PG8_LDA(At, 1, 0); PG8_STAGE(PG8_SA(0, 1), a2 + hstepA, voffA);
;             PG8_WAIT_L(8); PG8_BAR; PG8_WAIT_L(0); PG8_MMA(0, 0, At, B0); PG8_BAR; PG8_SCHED;
;             PG8_LDB(B1, 1, 1); PG8_STAGE(PG8_SB(1, 0), b3, voffB);
;             PG8_BAR; PG8_WAIT_L(0); PG8_MMA(0, 1, At, B1); PG8_BAR;
;             PG8_LDA(At, 1, 1); PG8_STAGE(PG8_SA(1, 0), a3, voffA);
	s_add_u32 s26, s16, 0x40000
	s_addc_u32 s27, s17, 0
	s_add_i32 s38, s38, s47
	s_mov_b32 m0, s38
	v_lshl_add_u64 v[130:131], s[26:27], 0, v[148:149]
	global_load_lds_dwordx4 v[130:131], off
	s_add_i32 m0, s38, 0x2000
	v_lshl_add_u64 v[130:131], s[26:27], 0, v[152:153]
	global_load_lds_dwordx4 v[130:131], off
	s_waitcnt vmcnt(6)
	s_barrier
	v_mfma_f32_16x16x32_bf16 v[66:69], v[230:233], v[184:187], v[66:69]
	v_mfma_f32_16x16x32_bf16 v[70:73], v[238:241], v[184:187], v[70:73]
	v_mfma_f32_16x16x32_bf16 v[46:49], v[230:233], v[192:195], v[46:49]
	v_mfma_f32_16x16x32_bf16 v[50:53], v[238:241], v[192:195], v[50:53]
	v_mfma_f32_16x16x32_bf16 v[26:29], v[230:233], v[214:217], v[26:29]
	v_mfma_f32_16x16x32_bf16 v[30:33], v[238:241], v[214:217], v[30:33]
	v_mfma_f32_16x16x32_bf16 v[10:13], v[230:233], v[222:225], v[10:13]
	v_mfma_f32_16x16x32_bf16 v[14:17], v[238:241], v[222:225], v[14:17]
	v_mfma_f32_16x16x32_bf16 v[66:69], v[234:237], v[188:191], v[66:69]
	v_mfma_f32_16x16x32_bf16 v[70:73], v[242:245], v[188:191], v[70:73]
	v_mfma_f32_16x16x32_bf16 v[46:49], v[234:237], v[206:209], v[46:49]
	v_mfma_f32_16x16x32_bf16 v[50:53], v[242:245], v[206:209], v[50:53]
	v_mfma_f32_16x16x32_bf16 v[26:29], v[234:237], v[218:221], v[26:29]
	v_mfma_f32_16x16x32_bf16 v[30:33], v[242:245], v[218:221], v[30:33]
	v_mfma_f32_16x16x32_bf16 v[10:13], v[234:237], v[226:229], v[10:13]
	v_mfma_f32_16x16x32_bf16 v[14:17], v[242:245], v[226:229], v[14:17]
	s_barrier
	s_add_i32 s38, 0, 0x18000
	v_add_u32_e32 v8, s38, v199
	ds_read_b128 v[130:133], v8
	ds_read_b128 v[134:137], v8 offset:1024
	ds_read_b128 v[138:141], v8 offset:2048
	ds_read_b128 v[142:145], v8 offset:3072
	s_add_u32 s26, s36, 0x40000
	s_addc_u32 s27, s37, 0
	s_mov_b32 m0, s69
	v_lshl_add_u64 v[230:231], s[26:27], 0, v[146:147]
	ds_read_b128 v[184:187], v204 offset:32768
	ds_read_b128 v[188:191], v204 offset:33792
	ds_read_b128 v[192:195], v204 offset:34816
	ds_read_b128 v[206:209], v204 offset:35840
	ds_read_b128 v[214:217], v204 offset:36864
	ds_read_b128 v[218:221], v204 offset:37888
	ds_read_b128 v[222:225], v204 offset:38912
	ds_read_b128 v[226:229], v204 offset:39936
	global_load_lds_dwordx4 v[230:231], off
	s_mov_b32 m0, s80
	v_lshl_add_u64 v[230:231], s[26:27], 0, v[150:151]
	global_load_lds_dwordx4 v[230:231], off
	s_waitcnt lgkmcnt(8)
	s_barrier
	s_waitcnt lgkmcnt(0)
	v_mfma_f32_16x16x32_bf16 v[126:129], v[130:133], v[184:187], v[126:129]
	v_mfma_f32_16x16x32_bf16 v[122:125], v[138:141], v[184:187], v[122:125]
	v_mfma_f32_16x16x32_bf16 v[114:117], v[130:133], v[192:195], v[114:117]
	v_mfma_f32_16x16x32_bf16 v[106:109], v[138:141], v[192:195], v[106:109]
	v_mfma_f32_16x16x32_bf16 v[102:105], v[130:133], v[214:217], v[102:105]
	v_mfma_f32_16x16x32_bf16 v[94:97], v[138:141], v[214:217], v[94:97]
	v_mfma_f32_16x16x32_bf16 v[82:85], v[130:133], v[222:225], v[82:85]
	v_mfma_f32_16x16x32_bf16 v[74:77], v[138:141], v[222:225], v[74:77]
	v_mfma_f32_16x16x32_bf16 v[126:129], v[134:137], v[188:191], v[126:129]
	v_mfma_f32_16x16x32_bf16 v[122:125], v[142:145], v[188:191], v[122:125]
	v_mfma_f32_16x16x32_bf16 v[114:117], v[134:137], v[206:209], v[114:117]
	v_mfma_f32_16x16x32_bf16 v[106:109], v[142:145], v[206:209], v[106:109]
	v_mfma_f32_16x16x32_bf16 v[102:105], v[134:137], v[218:221], v[102:105]
	v_mfma_f32_16x16x32_bf16 v[94:97], v[142:145], v[218:221], v[94:97]
	v_mfma_f32_16x16x32_bf16 v[82:85], v[134:137], v[226:229], v[82:85]
	v_mfma_f32_16x16x32_bf16 v[74:77], v[142:145], v[226:229], v[74:77]
	s_barrier
	s_add_i32 s26, 0, 0x1c000
	s_add_i32 s27, s38, s47
	v_add_u32_e32 v8, s26, v199
	v_lshl_add_u64 v[162:163], v[162:163], 0, s[70:71]
	s_mov_b32 m0, s27
	ds_read_b128 v[230:233], v8
	ds_read_b128 v[234:237], v8 offset:1024
	ds_read_b128 v[238:241], v8 offset:2048
	ds_read_b128 v[242:245], v8 offset:3072
	global_load_lds_dwordx4 v[162:163], off
	s_add_i32 m0, s27, 0x2000
	v_lshl_add_u64 v[162:163], v[164:165], 0, s[70:71]
	global_load_lds_dwordx4 v[162:163], off
	s_barrier
	s_waitcnt lgkmcnt(0)
	v_mfma_f32_16x16x32_bf16 v[118:121], v[230:233], v[184:187], v[118:121]
	v_mfma_f32_16x16x32_bf16 v[110:113], v[238:241], v[184:187], v[110:113]
	v_mfma_f32_16x16x32_bf16 v[98:101], v[230:233], v[192:195], v[98:101]
	v_mfma_f32_16x16x32_bf16 v[90:93], v[238:241], v[192:195], v[90:93]
	v_mfma_f32_16x16x32_bf16 v[86:89], v[230:233], v[214:217], v[86:89]
	v_mfma_f32_16x16x32_bf16 v[78:81], v[238:241], v[214:217], v[78:81]
	v_mfma_f32_16x16x32_bf16 v[54:57], v[230:233], v[222:225], v[54:57]
	v_mfma_f32_16x16x32_bf16 v[34:37], v[238:241], v[222:225], v[34:37]
	v_mfma_f32_16x16x32_bf16 v[118:121], v[234:237], v[188:191], v[118:121]
	v_mfma_f32_16x16x32_bf16 v[110:113], v[242:245], v[188:191], v[110:113]
	v_mfma_f32_16x16x32_bf16 v[98:101], v[234:237], v[206:209], v[98:101]
	v_mfma_f32_16x16x32_bf16 v[90:93], v[242:245], v[206:209], v[90:93]
	v_mfma_f32_16x16x32_bf16 v[86:89], v[234:237], v[218:221], v[86:89]
	v_mfma_f32_16x16x32_bf16 v[78:81], v[242:245], v[218:221], v[78:81]
	v_mfma_f32_16x16x32_bf16 v[54:57], v[234:237], v[226:229], v[54:57]
	v_mfma_f32_16x16x32_bf16 v[34:37], v[242:245], v[226:229], v[34:37]
	s_barrier
	s_mov_b32 m0, s81
	v_lshl_add_u64 v[162:163], v[202:203], 0, s[70:71]
	ds_read_b128 v[184:187], v204 offset:49152
	ds_read_b128 v[188:191], v204 offset:50176
	ds_read_b128 v[192:195], v204 offset:51200
	ds_read_b128 v[206:209], v204 offset:52224
	ds_read_b128 v[214:217], v204 offset:53248
	ds_read_b128 v[218:221], v204 offset:54272
	ds_read_b128 v[222:225], v204 offset:55296
	ds_read_b128 v[226:229], v204 offset:56320
	global_load_lds_dwordx4 v[162:163], off
	s_mov_b32 m0, s82
	v_lshl_add_u64 v[162:163], v[246:247], 0, s[70:71]
	global_load_lds_dwordx4 v[162:163], off
	s_barrier
; #define PG8_STAGE(bufoff, gbase, voff) do { _Pragma("unroll") for (int _i = 0; _i < 2; ++_i) \
;         __builtin_amdgcn_global_load_lds((const unsigned*)((const char*)(gbase) + (voff)[_i]), (LAS unsigned*)(lds + (bufoff) + ldsw + _i * 8192), 16, 0, 0); } while (0)
; #define PG8_MMA(ai, bj, At, Bt) do { __builtin_amdgcn_s_setprio(1); _Pragma("unroll") for (int m = 0; m < 4; ++m) _Pragma("unroll") for (int n = 0; n < 2; ++n) _Pragma("unroll") for (int k = 0; k < 2; ++k) \
;         acc[ai][bj][m][n] = __builtin_amdgcn_mfma_f32_16x16x32_bf16(Bt[n][k], At[m][k], acc[ai][bj][m][n], 0, 0, 0); __builtin_amdgcn_s_setprio(0); } while (0)
; #define PG8_WAIT_V(n) asm volatile("s_waitcnt vmcnt(" #n ")" ::: "memory")
; #define PG8_WAIT_L(n) asm volatile("s_waitcnt lgkmcnt(" #n ")" ::: "memory")
; #define PG8_BAR __builtin_amdgcn_s_barrier()
; #define PG8_SCHED __builtin_amdgcn_sched_barrier(0)
; template <class Epi>
; DEVI void gemm_phase(LAS unsigned char* lds, const Gemm g, const Epi& E) {
;     ...
;             PG8_BAR; PG8_WAIT_L(0); PG8_MMA(1, 0, At, B0); PG8_BAR; PG8_SCHED;
;             PG8_STAGE(PG8_SB(1, 1), b3 + hstepB, voffB);
;             PG8_WAIT_V(6); PG8_BAR; PG8_MMA(1, 1, At, B1); PG8_BAR;
;         }
;         {
;             const int row0 = cur.pm * BM + wr * 64 + fr, col0 = cur.pn * BM + wc * 32 + (Epi::PERM ? 8 : 4) * fq; constexpr int NST = Epi::PERM ? 4 : 16;
;             float rsv[8];
;             if constexpr (Epi::RS) { f32x4 q4[8];
; #pragma unroll
;                 for (int i = 0; i < 8; ++i) q4[i] = *(const f32x4*)(E.ssq_in + (size_t)(row0 + (i >> 2) * HALF + (i & 3) * 16) * 4);
; #pragma unroll
;                 for (int i = 0; i < 8; ++i) rsv[i] = rsqrtf((((q4[i][0] + q4[i][1]) + q4[i][2]) + q4[i][3]) * (1.f / DM) + 1e-6f); }
	s_waitcnt lgkmcnt(0)
	v_mfma_f32_16x16x32_bf16 v[58:61], v[130:133], v[184:187], v[58:61]
	v_mfma_f32_16x16x32_bf16 v[62:65], v[138:141], v[184:187], v[62:65]
	v_mfma_f32_16x16x32_bf16 v[38:41], v[130:133], v[192:195], v[38:41]
	v_mfma_f32_16x16x32_bf16 v[42:45], v[138:141], v[192:195], v[42:45]
	v_mfma_f32_16x16x32_bf16 v[18:21], v[130:133], v[214:217], v[18:21]
	v_mfma_f32_16x16x32_bf16 v[22:25], v[138:141], v[214:217], v[22:25]
	v_mfma_f32_16x16x32_bf16 v[0:3], v[130:133], v[222:225], v[0:3]
	v_mfma_f32_16x16x32_bf16 v[4:7], v[138:141], v[222:225], v[4:7]
	v_mfma_f32_16x16x32_bf16 v[58:61], v[134:137], v[188:191], v[58:61]
	v_mfma_f32_16x16x32_bf16 v[62:65], v[142:145], v[188:191], v[62:65]
	v_mfma_f32_16x16x32_bf16 v[38:41], v[134:137], v[206:209], v[38:41]
	v_mfma_f32_16x16x32_bf16 v[42:45], v[142:145], v[206:209], v[42:45]
	v_mfma_f32_16x16x32_bf16 v[18:21], v[134:137], v[218:221], v[18:21]
	v_mfma_f32_16x16x32_bf16 v[22:25], v[142:145], v[218:221], v[22:25]
	v_mfma_f32_16x16x32_bf16 v[0:3], v[134:137], v[226:229], v[0:3]
	v_mfma_f32_16x16x32_bf16 v[4:7], v[142:145], v[226:229], v[4:7]
	s_barrier
	s_add_u32 s16, s16, 0x40080
	s_addc_u32 s17, s17, 0
	s_add_i32 s26, s26, s47
	s_mov_b32 m0, s26
	v_lshl_add_u64 v[130:131], s[16:17], 0, v[148:149]
	global_load_lds_dwordx4 v[130:131], off
	s_add_i32 m0, s26, 0x2000
	v_lshl_add_u64 v[130:131], s[16:17], 0, v[152:153]
	global_load_lds_dwordx4 v[130:131], off
	s_waitcnt vmcnt(6)
	s_barrier
	v_mfma_f32_16x16x32_bf16 v[66:69], v[230:233], v[184:187], v[66:69]
	v_mfma_f32_16x16x32_bf16 v[70:73], v[238:241], v[184:187], v[70:73]
	v_mfma_f32_16x16x32_bf16 v[46:49], v[230:233], v[192:195], v[46:49]
	v_mfma_f32_16x16x32_bf16 v[50:53], v[238:241], v[192:195], v[50:53]
	v_mfma_f32_16x16x32_bf16 v[26:29], v[230:233], v[214:217], v[26:29]
	v_mfma_f32_16x16x32_bf16 v[30:33], v[238:241], v[214:217], v[30:33]
	v_mfma_f32_16x16x32_bf16 v[10:13], v[230:233], v[222:225], v[10:13]
	v_mfma_f32_16x16x32_bf16 v[14:17], v[238:241], v[222:225], v[14:17]
	v_mfma_f32_16x16x32_bf16 v[66:69], v[234:237], v[188:191], v[66:69]
	v_mfma_f32_16x16x32_bf16 v[70:73], v[242:245], v[188:191], v[70:73]
	v_mfma_f32_16x16x32_bf16 v[46:49], v[234:237], v[206:209], v[46:49]
	v_mfma_f32_16x16x32_bf16 v[50:53], v[242:245], v[206:209], v[50:53]
	v_mfma_f32_16x16x32_bf16 v[26:29], v[234:237], v[218:221], v[26:29]
	v_mfma_f32_16x16x32_bf16 v[30:33], v[242:245], v[218:221], v[30:33]
	v_mfma_f32_16x16x32_bf16 v[10:13], v[234:237], v[226:229], v[10:13]
	v_mfma_f32_16x16x32_bf16 v[14:17], v[242:245], v[226:229], v[14:17]
	s_barrier
	s_add_i32 s19, s19, 2
	s_add_u32 s14, s14, 0x100
	s_addc_u32 s15, s15, 0
	s_add_u32 s9, s9, 0x100
	s_addc_u32 s18, s18, 0
	s_cmp_gt_u32 s19, 13
	s_cbranch_scc0 .LBB0_1007
	s_setprio 0
	v_lshl_add_u32 v194, s4, 8, v197
	v_add_u32_e32 v184, 0xb0, v194
	v_ashrrev_i32_e32 v195, 31, v194
	v_ashrrev_i32_e32 v185, 31, v184
	v_lshl_add_u64 v[130:131], v[194:195], 4, s[76:77]
	v_lshl_add_u64 v[134:135], v[184:185], 4, s[76:77]
	global_load_dwordx4 v[206:209], v[130:131], off
	v_or_b32_e32 v192, 48, v194
	global_load_dwordx4 v[134:137], v[134:135], off
	v_or_b32_e32 v130, 16, v194
	v_ashrrev_i32_e32 v131, 31, v130
	v_lshl_add_u64 v[130:131], v[130:131], 4, s[76:77]
	global_load_dwordx4 v[214:217], v[130:131], off
	v_or_b32_e32 v130, 32, v194
	v_ashrrev_i32_e32 v131, 31, v130
	v_lshl_add_u64 v[130:131], v[130:131], 4, s[76:77]
	v_ashrrev_i32_e32 v193, 31, v192
	global_load_dwordx4 v[218:221], v[130:131], off
	v_lshl_add_u64 v[130:131], v[192:193], 4, s[76:77]
	global_load_dwordx4 v[222:225], v[130:131], off
	v_add_u32_e32 v190, 0x80, v194
	v_ashrrev_i32_e32 v191, 31, v190
	v_add_u32_e32 v188, 0x90, v194
	v_lshl_add_u64 v[130:131], v[190:191], 4, s[76:77]
	v_ashrrev_i32_e32 v189, 31, v188
	global_load_dwordx4 v[138:141], v[130:131], off
	v_lshl_add_u64 v[130:131], v[188:189], 4, s[76:77]
	global_load_dwordx4 v[142:145], v[130:131], off
	v_add_u32_e32 v186, 0xa0, v194
	v_ashrrev_i32_e32 v187, 31, v186
	v_lshl_add_u64 v[130:131], v[186:187], 4, s[76:77]
	global_load_dwordx4 v[130:133], v[130:131], off
	s_mov_b32 s0, 0x358637bd
	v_mov_b64_e32 v[202:203], s[0:1]
	s_mov_b64 s[16:17], s[12:13]
	s_mov_b64 s[14:15], s[10:11]
	s_waitcnt vmcnt(0)
; template <class Epi>
; DEVI void gemm_phase(LAS unsigned char* lds, const Gemm g, const Epi& E) {
;     ...
;             if constexpr (Epi::RS) { f32x4 q4[8];
; #pragma unroll
;                 for (int i = 0; i < 8; ++i) q4[i] = *(const f32x4*)(E.ssq_in + (size_t)(row0 + (i >> 2) * HALF + (i & 3) * 16) * 4);
; #pragma unroll
;                 for (int i = 0; i < 8; ++i) rsv[i] = rsqrtf((((q4[i][0] + q4[i][1]) + q4[i][2]) + q4[i][3]) * (1.f / DM) + 1e-6f); }
	v_mov_b32_e32 v163, v206
	v_mov_b32_e32 v165, v208
	v_mov_b32_e32 v162, v214
	v_mov_b32_e32 v206, v215
	v_pk_add_f32 v[162:163], v[162:163], v[206:207]
	v_mov_b32_e32 v164, v216
	v_pk_add_f32 v[162:163], v[164:165], v[162:163]
	v_mov_b32_e32 v208, v217
	v_pk_add_f32 v[162:163], v[208:209], v[162:163]
	v_mov_b32_e32 v164, v224
	v_pk_fma_f32 v[162:163], v[162:163], s[72:73], v[202:203] op_sel_hi:[1,0,0]
	v_mov_b32_e32 v165, v220
	v_mul_f32_e32 v8, 0x4b800000, v163
	v_cmp_gt_f32_e64 s[4:5], s94, v163
	v_cmp_gt_f32_e32 vcc, s94, v162
	v_mov_b32_e32 v220, v225
	v_cndmask_b32_e64 v8, v163, v8, s[4:5]
	v_rsq_f32_e32 v8, v8
	s_nop 0
	v_mul_f32_e32 v163, 0x45800000, v8
	v_cndmask_b32_e64 v198, v8, v163, s[4:5]
	v_mul_f32_e32 v8, 0x4b800000, v162
	v_cndmask_b32_e32 v8, v162, v8, vcc
	v_rsq_f32_e32 v8, v8
	v_mov_b32_e32 v163, v218
	v_mov_b32_e32 v218, v223
	v_pk_mul_f32 v[128:129], v[128:129], v[198:199] op_sel_hi:[1,0]
	v_mul_f32_e32 v162, 0x45800000, v8
	v_cndmask_b32_e32 v8, v8, v162, vcc
	v_mov_b32_e32 v162, v222
	v_pk_add_f32 v[162:163], v[162:163], v[218:219]
	v_pk_mul_f32 v[126:127], v[126:127], v[198:199] op_sel_hi:[1,0]
	v_pk_add_f32 v[162:163], v[164:165], v[162:163]
	v_pk_mul_f32 v[122:123], v[122:123], v[198:199] op_sel_hi:[1,0]
	v_pk_add_f32 v[162:163], v[220:221], v[162:163]
	v_pk_mul_f32 v[120:121], v[120:121], v[198:199] op_sel_hi:[1,0]
	v_pk_fma_f32 v[162:163], v[162:163], s[72:73], v[202:203] op_sel_hi:[1,0,0]
	v_pk_mul_f32 v[118:119], v[118:119], v[198:199] op_sel_hi:[1,0]
	v_mul_f32_e32 v164, 0x4b800000, v163
	v_cmp_gt_f32_e64 s[4:5], s94, v163
	v_cmp_gt_f32_e32 vcc, s94, v162
	v_pk_mul_f32 v[110:111], v[110:111], v[198:199] op_sel_hi:[1,0]
	v_cndmask_b32_e64 v163, v163, v164, s[4:5]
	v_rsq_f32_e32 v163, v163
	v_cvt_pk_bf16_f32 v118, v118, v119
	v_cvt_pk_bf16_f32 v119, v120, v121
	v_cvt_pk_bf16_f32 v120, v110, v111
	v_mul_f32_e32 v164, 0x45800000, v163
	v_cndmask_b32_e64 v200, v163, v164, s[4:5]
	v_mul_f32_e32 v163, 0x4b800000, v162
	v_cndmask_b32_e32 v162, v162, v163, vcc
	v_rsq_f32_e32 v162, v162
	v_pk_mul_f32 v[112:113], v[112:113], v[198:199] op_sel_hi:[1,0]
	v_pk_mul_f32 v[114:115], v[114:115], v[8:9] op_sel_hi:[1,0]
	v_cvt_pk_bf16_f32 v121, v112, v113
	v_mul_f32_e32 v163, 0x45800000, v162
	v_cndmask_b32_e32 v196, v162, v163, vcc
	v_mov_b32_e32 v162, v142
	v_mov_b32_e32 v163, v138
	v_mov_b32_e32 v138, v143
	v_pk_add_f32 v[138:139], v[162:163], v[138:139]
	v_mov_b32_e32 v142, v144
	v_mov_b32_e32 v143, v140
	v_pk_add_f32 v[138:139], v[142:143], v[138:139]
	v_mov_b32_e32 v140, v145
	v_pk_add_f32 v[138:139], v[140:141], v[138:139]
	v_mov_b32_e32 v142, v134
	v_pk_fma_f32 v[140:141], v[138:139], s[72:73], v[202:203] op_sel_hi:[1,0,0]
	v_mov_b32_e32 v143, v130
	v_mul_f32_e32 v138, 0x4b800000, v141
	v_cmp_gt_f32_e64 s[4:5], s94, v141
	v_mov_b32_e32 v130, v135
	v_pk_add_f32 v[130:131], v[142:143], v[130:131]
	v_cndmask_b32_e64 v138, v141, v138, s[4:5]
	v_rsq_f32_e32 v138, v138
	v_mov_b32_e32 v134, v136
	v_mov_b32_e32 v135, v132
	v_pk_add_f32 v[130:131], v[134:135], v[130:131]
	v_mov_b32_e32 v132, v137
	v_pk_add_f32 v[130:131], v[132:133], v[130:131]
	v_mul_f32_e32 v139, 0x45800000, v138
	v_pk_fma_f32 v[130:131], v[130:131], s[72:73], v[202:203] op_sel_hi:[1,0,0]
	v_cmp_gt_f32_e32 vcc, s94, v140
	v_cndmask_b32_e64 v138, v138, v139, s[4:5]
	v_mul_f32_e32 v139, 0x4b800000, v140
	v_mul_f32_e32 v132, 0x4b800000, v131
	v_cmp_gt_f32_e64 s[4:5], s94, v131
	v_cndmask_b32_e32 v139, v140, v139, vcc
	v_rsq_f32_e32 v139, v139
	v_cndmask_b32_e64 v131, v131, v132, s[4:5]
	v_rsq_f32_e32 v131, v131
	v_pk_mul_f32 v[136:137], v[124:125], v[198:199] op_sel_hi:[1,0]
	v_mul_f32_e32 v140, 0x45800000, v139
	v_cndmask_b32_e32 v140, v139, v140, vcc
	v_mul_f32_e32 v132, 0x45800000, v131
	v_cmp_gt_f32_e32 vcc, s94, v130
	v_cndmask_b32_e64 v132, v131, v132, s[4:5]
	v_mul_f32_e32 v131, 0x4b800000, v130
	v_cndmask_b32_e32 v130, v130, v131, vcc
	v_rsq_f32_e32 v130, v130
	v_cvt_pk_bf16_f32 v125, v128, v129
	v_ashrrev_i32_e32 v134, 5, v194
	v_ashrrev_i32_e32 v135, 31, v134
	v_mul_f32_e32 v131, 0x45800000, v130
	v_cndmask_b32_e32 v130, v130, v131, vcc
	v_lshl_or_b32 v131, s84, 8, v201
	v_ashrrev_i32_e32 v128, 4, v131
	v_ashrrev_i32_e32 v129, 31, v128
	v_cvt_pk_bf16_f32 v124, v126, v127
	v_cvt_pk_bf16_f32 v126, v122, v123
	v_lshlrev_b64 v[122:123], 10, v[128:129]
	v_or_b32_e32 v110, 8, v128
	v_cvt_pk_bf16_f32 v127, v136, v137
	v_lshl_add_u64 v[136:137], v[122:123], 0, v[134:135]
	v_ashrrev_i32_e32 v111, 31, v110
	v_mad_u64_u32 v[142:143], s[0:1], v136, s34, v[178:179]
	v_lshlrev_b64 v[110:111], 10, v[110:111]
	v_mad_i32_i24 v143, v137, s34, v143
	v_lshl_add_u64 v[112:113], v[110:111], 0, v[134:135]
	global_store_dwordx4 v[142:143], v[124:127], off
	v_pk_mul_f32 v[100:101], v[100:101], v[8:9] op_sel_hi:[1,0]
	v_pk_mul_f32 v[98:99], v[98:99], v[8:9] op_sel_hi:[1,0]
	v_mad_u64_u32 v[124:125], s[0:1], v112, s34, v[178:179]
	v_mad_i32_i24 v125, v113, s34, v125
	v_pk_mul_f32 v[112:113], v[116:117], v[8:9] op_sel_hi:[1,0]
	v_pk_mul_f32 v[116:117], v[108:109], v[8:9] op_sel_hi:[1,0]
	v_pk_mul_f32 v[108:109], v[106:107], v[8:9] op_sel_hi:[1,0]
	v_cvt_pk_bf16_f32 v106, v114, v115
	v_cvt_pk_bf16_f32 v107, v112, v113
	v_cvt_pk_bf16_f32 v108, v108, v109
	v_cvt_pk_bf16_f32 v109, v116, v117
	global_store_dwordx4 v[142:143], v[106:109], off offset:512
	v_pk_mul_f32 v[94:95], v[94:95], v[200:201] op_sel_hi:[1,0]
	v_pk_mul_f32 v[96:97], v[96:97], v[200:201] op_sel_hi:[1,0]
	v_pk_mul_f32 v[106:107], v[92:93], v[8:9] op_sel_hi:[1,0]
	v_pk_mul_f32 v[92:93], v[90:91], v[8:9] op_sel_hi:[1,0]
	v_cvt_pk_bf16_f32 v90, v98, v99
	v_cvt_pk_bf16_f32 v91, v100, v101
	v_cvt_pk_bf16_f32 v92, v92, v93
; template <class Epi>
; DEVI void gemm_phase(LAS unsigned char* lds, const Gemm g, const Epi& E) {
;     ...
;                 for (int mm = 0; mm < 2; ++mm) {
;                     const int m = m0 + mm;
;                     const int r = row0 + ai * HALF + m * 16; float rs = 1.f, part = 0.f;
;                     if constexpr (Epi::RS) rs = rsv[ai * 4 + m];
;                     if constexpr (Epi::PAIR) E.pair8(cur.b, r, cur.pn * HALF + wc * 32 + 8 * fq, acc[ai][0][m][0] * rs, acc[ai][0][m][1] * rs, acc[ai][1][m][0] * rs, acc[ai][1][m][1] * rs);
;                     else
; #pragma unroll
;                     for (int bj = 0; bj < 2; ++bj) {
;                         const int c = col0 + bj * HALF; f32x4 v0 = acc[ai][bj][m][0], v1 = acc[ai][bj][m][1];
;                         if constexpr (Epi::RS) { v0 = v0 * rs; v1 = v1 * rs; }
;                         if constexpr (Epi::PRE) part += E.frag_pre8(cur.b, r, c, v0, v1, pre[mm][bj][0], pre[mm][bj][1]);
;                         else if constexpr (Epi::PERM) E.frag8(cur.b, r, c, v0, v1);
	v_cvt_pk_bf16_f32 v93, v106, v107
	v_or_b32_e32 v98, 1, v134
	global_store_dwordx4 v[124:125], v[90:93], off offset:512
	v_ashrrev_i32_e32 v99, 31, v98
	v_pk_mul_f32 v[86:87], v[86:87], v[200:201] op_sel_hi:[1,0]
	v_pk_mul_f32 v[92:93], v[104:105], v[200:201] op_sel_hi:[1,0]
	v_pk_mul_f32 v[90:91], v[102:103], v[200:201] op_sel_hi:[1,0]
	v_pk_mul_f32 v[88:89], v[88:89], v[200:201] op_sel_hi:[1,0]
	v_cvt_pk_bf16_f32 v90, v90, v91
	v_cvt_pk_bf16_f32 v91, v92, v93
	v_cvt_pk_bf16_f32 v92, v94, v95
	v_lshl_add_u64 v[94:95], v[122:123], 0, v[98:99]
	v_cvt_pk_bf16_f32 v93, v96, v97
	v_mad_u64_u32 v[96:97], s[0:1], v94, s34, v[178:179]
	v_mad_i32_i24 v97, v95, s34, v97
	global_store_dwordx4 v[96:97], v[90:93], off
	v_lshlrev_b32_e32 v8, 5, v192
	v_and_b32_e32 v8, 0x3e0, v8
	v_pk_mul_f32 v[90:91], v[80:81], v[200:201] op_sel_hi:[1,0]
	v_pk_mul_f32 v[80:81], v[78:79], v[200:201] op_sel_hi:[1,0]
	v_cvt_pk_bf16_f32 v78, v86, v87
	v_lshl_add_u64 v[86:87], v[110:111], 0, v[98:99]
	v_cvt_pk_bf16_f32 v79, v88, v89
	v_mad_u64_u32 v[88:89], s[0:1], v86, s34, v[178:179]
	v_cvt_pk_bf16_f32 v80, v80, v81
	v_cvt_pk_bf16_f32 v81, v90, v91
	v_mad_i32_i24 v89, v87, s34, v89
	global_store_dwordx4 v[88:89], v[78:81], off
	v_pk_mul_f32 v[82:83], v[82:83], v[196:197] op_sel_hi:[1,0]
	v_pk_mul_f32 v[84:85], v[84:85], v[196:197] op_sel_hi:[1,0]
	v_ashrrev_i32_e32 v78, 5, v192
	v_ashrrev_i32_e32 v79, 31, v78
	v_lshl_add_u64 v[80:81], v[176:177], 0, v[8:9]
	v_pk_mul_f32 v[86:87], v[76:77], v[196:197] op_sel_hi:[1,0]
	v_pk_mul_f32 v[76:77], v[74:75], v[196:197] op_sel_hi:[1,0]
	v_cvt_pk_bf16_f32 v74, v82, v83
	v_lshl_add_u64 v[82:83], v[122:123], 0, v[78:79]
	v_cvt_pk_bf16_f32 v75, v84, v85
	v_mad_u64_u32 v[84:85], s[0:1], v82, s34, v[80:81]
	v_cvt_pk_bf16_f32 v76, v76, v77
	v_cvt_pk_bf16_f32 v77, v86, v87
	v_mad_i32_i24 v85, v83, s34, v85
	v_pk_mul_f32 v[54:55], v[54:55], v[196:197] op_sel_hi:[1,0]
	global_store_dwordx4 v[124:125], v[118:121], off
	global_store_dwordx4 v[84:85], v[74:77], off
	v_pk_mul_f32 v[56:57], v[56:57], v[196:197] op_sel_hi:[1,0]
	v_lshlrev_b32_e32 v8, 5, v188
	v_pk_mul_f32 v[74:75], v[36:37], v[196:197] op_sel_hi:[1,0]
	v_pk_mul_f32 v[36:37], v[34:35], v[196:197] op_sel_hi:[1,0]
	v_cvt_pk_bf16_f32 v34, v54, v55
	v_lshl_add_u64 v[54:55], v[110:111], 0, v[78:79]
	v_cvt_pk_bf16_f32 v35, v56, v57
	v_mad_u64_u32 v[56:57], s[0:1], v54, s34, v[80:81]
	v_cvt_pk_bf16_f32 v36, v36, v37
	v_cvt_pk_bf16_f32 v37, v74, v75
	v_mad_i32_i24 v57, v55, s34, v57
	v_ashrrev_i32_e32 v54, 5, v190
	global_store_dwordx4 v[56:57], v[34:37], off
	v_ashrrev_i32_e32 v55, 31, v54
	v_pk_mul_f32 v[56:57], v[64:65], v[138:139] op_sel_hi:[1,0]
	v_pk_mul_f32 v[36:37], v[60:61], v[138:139] op_sel_hi:[1,0]
	v_pk_mul_f32 v[34:35], v[58:59], v[138:139] op_sel_hi:[1,0]
	v_pk_mul_f32 v[58:59], v[62:63], v[138:139] op_sel_hi:[1,0]
	v_cvt_pk_bf16_f32 v34, v34, v35
	v_cvt_pk_bf16_f32 v35, v36, v37
	v_cvt_pk_bf16_f32 v37, v56, v57
	v_lshl_add_u64 v[56:57], v[122:123], 0, v[54:55]
	v_cvt_pk_bf16_f32 v36, v58, v59
	v_mad_u64_u32 v[58:59], s[0:1], v56, s34, v[178:179]
	v_mad_i32_i24 v59, v57, s34, v59
	global_store_dwordx4 v[58:59], v[34:37], off
	v_pk_mul_f32 v[56:57], v[72:73], v[138:139] op_sel_hi:[1,0]
	v_lshl_add_u64 v[54:55], v[110:111], 0, v[54:55]
	v_pk_mul_f32 v[36:37], v[68:69], v[138:139] op_sel_hi:[1,0]
	v_pk_mul_f32 v[34:35], v[66:67], v[138:139] op_sel_hi:[1,0]
	v_pk_mul_f32 v[58:59], v[70:71], v[138:139] op_sel_hi:[1,0]
	v_cvt_pk_bf16_f32 v34, v34, v35
	v_cvt_pk_bf16_f32 v35, v36, v37
	v_cvt_pk_bf16_f32 v37, v56, v57
	v_mad_u64_u32 v[56:57], s[0:1], v54, s34, v[178:179]
	v_cvt_pk_bf16_f32 v36, v58, v59
	v_mad_i32_i24 v57, v55, s34, v57
	v_ashrrev_i32_e32 v54, 5, v188
	global_store_dwordx4 v[56:57], v[34:37], off
	v_ashrrev_i32_e32 v55, 31, v54
; template <class Epi>
; DEVI void gemm_phase(LAS unsigned char* lds, const Gemm g, const Epi& E) {
;     ...
;                 for (int mm = 0; mm < 2; ++mm) {
;                     const int m = m0 + mm;
;                     const int r = row0 + ai * HALF + m * 16; float rs = 1.f, part = 0.f;
;                     if constexpr (Epi::RS) rs = rsv[ai * 4 + m];
;                     if constexpr (Epi::PAIR) E.pair8(cur.b, r, cur.pn * HALF + wc * 32 + 8 * fq, acc[ai][0][m][0] * rs, acc[ai][0][m][1] * rs, acc[ai][1][m][0] * rs, acc[ai][1][m][1] * rs);
;                     else
; #pragma unroll
;                     for (int bj = 0; bj < 2; ++bj) {
;                         const int c = col0 + bj * HALF; f32x4 v0 = acc[ai][bj][m][0], v1 = acc[ai][bj][m][1];
;                         if constexpr (Epi::RS) { v0 = v0 * rs; v1 = v1 * rs; }
;                         if constexpr (Epi::PRE) part += E.frag_pre8(cur.b, r, c, v0, v1, pre[mm][bj][0], pre[mm][bj][1]);
;                         else if constexpr (Epi::PERM) E.frag8(cur.b, r, c, v0, v1);
	v_and_b32_e32 v8, 0x3e0, v8
	v_pk_mul_f32 v[36:37], v[40:41], v[140:141] op_sel_hi:[1,0]
	v_pk_mul_f32 v[34:35], v[38:39], v[140:141] op_sel_hi:[1,0]
	v_pk_mul_f32 v[38:39], v[44:45], v[140:141] op_sel_hi:[1,0]
	v_lshl_add_u64 v[56:57], v[176:177], 0, v[8:9]
	v_pk_mul_f32 v[40:41], v[42:43], v[140:141] op_sel_hi:[1,0]
	v_cvt_pk_bf16_f32 v34, v34, v35
	v_cvt_pk_bf16_f32 v35, v36, v37
	v_cvt_pk_bf16_f32 v37, v38, v39
	v_lshl_add_u64 v[38:39], v[122:123], 0, v[54:55]
	v_cvt_pk_bf16_f32 v36, v40, v41
	v_mad_u64_u32 v[40:41], s[0:1], v38, s34, v[56:57]
	v_mad_i32_i24 v41, v39, s34, v41
	global_store_dwordx4 v[40:41], v[34:37], off
	v_pk_mul_f32 v[38:39], v[52:53], v[140:141] op_sel_hi:[1,0]
	v_pk_mul_f32 v[40:41], v[50:51], v[140:141] op_sel_hi:[1,0]
	v_pk_mul_f32 v[36:37], v[48:49], v[140:141] op_sel_hi:[1,0]
	v_pk_mul_f32 v[34:35], v[46:47], v[140:141] op_sel_hi:[1,0]
	v_pk_mul_f32 v[20:21], v[20:21], v[132:133] op_sel_hi:[1,0]
	v_cvt_pk_bf16_f32 v34, v34, v35
	v_cvt_pk_bf16_f32 v35, v36, v37
	v_cvt_pk_bf16_f32 v37, v38, v39
	v_lshl_add_u64 v[38:39], v[110:111], 0, v[54:55]
	v_cvt_pk_bf16_f32 v36, v40, v41
	v_mad_u64_u32 v[40:41], s[0:1], v38, s34, v[56:57]
	v_mad_i32_i24 v41, v39, s34, v41
	global_store_dwordx4 v[40:41], v[34:37], off
	v_pk_mul_f32 v[18:19], v[18:19], v[132:133] op_sel_hi:[1,0]
	v_pk_mul_f32 v[22:23], v[22:23], v[132:133] op_sel_hi:[1,0]
	v_ashrrev_i32_e32 v34, 5, v186
	v_ashrrev_i32_e32 v35, 31, v34
	v_pk_mul_f32 v[24:25], v[24:25], v[132:133] op_sel_hi:[1,0]
	v_cvt_pk_bf16_f32 v18, v18, v19
	v_cvt_pk_bf16_f32 v19, v20, v21
	v_cvt_pk_bf16_f32 v20, v22, v23
	v_lshl_add_u64 v[22:23], v[122:123], 0, v[34:35]
	v_cvt_pk_bf16_f32 v21, v24, v25
	v_mad_u64_u32 v[24:25], s[0:1], v22, s34, v[178:179]
	v_mad_i32_i24 v25, v23, s34, v25
	global_store_dwordx4 v[24:25], v[18:21], off
	v_pk_mul_f32 v[22:23], v[32:33], v[132:133] op_sel_hi:[1,0]
	v_pk_mul_f32 v[24:25], v[30:31], v[132:133] op_sel_hi:[1,0]
	v_pk_mul_f32 v[20:21], v[28:29], v[132:133] op_sel_hi:[1,0]
	v_pk_mul_f32 v[18:19], v[26:27], v[132:133] op_sel_hi:[1,0]
	v_lshlrev_b32_e32 v8, 5, v184
	v_cvt_pk_bf16_f32 v18, v18, v19
	v_cvt_pk_bf16_f32 v19, v20, v21
	v_cvt_pk_bf16_f32 v21, v22, v23
	v_lshl_add_u64 v[22:23], v[110:111], 0, v[34:35]
	v_cvt_pk_bf16_f32 v20, v24, v25
	v_mad_u64_u32 v[24:25], s[0:1], v22, s34, v[178:179]
	v_mad_i32_i24 v25, v23, s34, v25
	global_store_dwordx4 v[24:25], v[18:21], off
	v_and_b32_e32 v8, 0x3e0, v8
	v_pk_mul_f32 v[2:3], v[2:3], v[130:131] op_sel_hi:[1,0]
	v_ashrrev_i32_e32 v18, 5, v184
	v_ashrrev_i32_e32 v19, 31, v18
	v_pk_mul_f32 v[0:1], v[0:1], v[130:131] op_sel_hi:[1,0]
	v_pk_mul_f32 v[4:5], v[4:5], v[130:131] op_sel_hi:[1,0]
	v_lshl_add_u64 v[20:21], v[176:177], 0, v[8:9]
	v_pk_mul_f32 v[6:7], v[6:7], v[130:131] op_sel_hi:[1,0]
	v_cvt_pk_bf16_f32 v0, v0, v1
	v_cvt_pk_bf16_f32 v1, v2, v3
	v_cvt_pk_bf16_f32 v2, v4, v5
	v_lshl_add_u64 v[4:5], v[122:123], 0, v[18:19]
	v_cvt_pk_bf16_f32 v3, v6, v7
	v_mad_u64_u32 v[6:7], s[0:1], v4, s34, v[20:21]
	v_mad_i32_i24 v7, v5, s34, v7
	global_store_dwordx4 v[6:7], v[0:3], off
	v_pk_mul_f32 v[4:5], v[16:17], v[130:131] op_sel_hi:[1,0]
	v_pk_mul_f32 v[6:7], v[14:15], v[130:131] op_sel_hi:[1,0]
	v_pk_mul_f32 v[2:3], v[12:13], v[130:131] op_sel_hi:[1,0]
	v_pk_mul_f32 v[0:1], v[10:11], v[130:131] op_sel_hi:[1,0]
	s_and_b64 vcc, exec, s[2:3]
	v_cvt_pk_bf16_f32 v0, v0, v1
	v_cvt_pk_bf16_f32 v1, v2, v3
	v_cvt_pk_bf16_f32 v3, v4, v5
	v_lshl_add_u64 v[4:5], v[110:111], 0, v[18:19]
	v_cvt_pk_bf16_f32 v2, v6, v7
	v_mad_u64_u32 v[6:7], s[0:1], v4, s34, v[20:21]
	v_mad_i32_i24 v7, v5, s34, v7
	s_mov_b32 s84, s8
	s_mov_b32 s4, s6
	global_store_dwordx4 v[6:7], v[0:3], off
	s_cbranch_vccz .LBB0_1000
	s_waitcnt vmcnt(0)
	s_cmpk_gt_u32 s46, 0xff
	s_cbranch_scc1 .LBB0_1011
	s_barrier

; #define PG8_STAGE(bufoff, gbase, voff) do { _Pragma("unroll") for (int _i = 0; _i < 2; ++_i) \
;         __builtin_amdgcn_global_load_lds((const unsigned*)((const char*)(gbase) + (voff)[_i]), (LAS unsigned*)(lds + (bufoff) + ldsw + _i * 8192), 16, 0, 0); } while (0)
; #define PG8_LDA(dst, b, h) do { _Pragma("unroll") for (int m = 0; m < 4; ++m) _Pragma("unroll") for (int k = 0; k < 2; ++k) dst[m][k] = *(const LAS bf16x8*)(lds + PG8_SA(b, h) + aoff + m * 2048 + k * 1024); } while (0)
; #define PG8_LDB(dst, b, h) do { _Pragma("unroll") for (int n = 0; n < 2; ++n) _Pragma("unroll") for (int k = 0; k < 2; ++k) dst[n][k] = *(const LAS bf16x8*)(lds + PG8_SB(b, h) + boff + n * 2048 + k * 1024); } while (0)
; #define PG8_MMA(ai, bj, At, Bt) do { __builtin_amdgcn_s_setprio(1); _Pragma("unroll") for (int m = 0; m < 4; ++m) _Pragma("unroll") for (int n = 0; n < 2; ++n) _Pragma("unroll") for (int k = 0; k < 2; ++k) \
;         acc[ai][bj][m][n] = __builtin_amdgcn_mfma_f32_16x16x32_bf16(Bt[n][k], At[m][k], acc[ai][bj][m][n], 0, 0, 0); __builtin_amdgcn_s_setprio(0); } while (0)
; #define PG8_WAIT_L(n) asm volatile("s_waitcnt lgkmcnt(" #n ")" ::: "memory")
; #define PG8_BAR __builtin_amdgcn_s_barrier()
; #define PG8_SCHED __builtin_amdgcn_sched_barrier(0)
; template <class Epi>
; DEVI void gemm_phase(LAS unsigned char* lds, const Gemm g, const Epi& E) {
;     ...
;             PG8_LDB(B0, 0, 0); PG8_SCHED; PG8_LDA(At, 0, 0); PG8_STAGE(PG8_SA(1, 1), a1 + hstepA, voffA);
;             PG8_WAIT_L(8); PG8_BAR; PG8_WAIT_L(0); PG8_MMA(0, 0, At, B0); PG8_BAR; PG8_SCHED;
;             PG8_LDB(B1, 0, 1); PG8_STAGE(PG8_SB(0, 0), b2, voffB);
;             PG8_BAR; PG8_WAIT_L(0); PG8_MMA(0, 1, At, B1); PG8_BAR;
;             PG8_LDA(At, 0, 1); PG8_STAGE(PG8_SA(0, 0), a2, voffA);
;             PG8_BAR; PG8_WAIT_L(0); PG8_MMA(1, 0, At, B0); PG8_BAR; PG8_SCHED;
;             PG8_STAGE(PG8_SB(0, 1), b2 + hstepB, voffB);
.LBB0_1278:
	s_add_u32 s12, s10, 0x100
	s_addc_u32 s13, s11, 0
	s_add_i32 s38, 0, 0x10000
	v_add_u32_e32 v146, s38, v149
	ds_read_b128 v[142:145], v146
	ds_read_b128 v[176:179], v146 offset:1024
	ds_read_b128 v[180:183], v146 offset:2048
	ds_read_b128 v[184:187], v146 offset:3072
	s_cmp_eq_u32 s27, 6
	s_cselect_b32 s17, s5, s13
	s_cselect_b32 s16, s4, s12
	s_cselect_b32 s15, s7, s26
	s_cselect_b32 s14, s6, s19
	v_lshl_add_u64 v[146:147], s[10:11], 0, v[138:139]
	s_add_i32 m0, s46, 0xc000
	ds_read_b128 v[188:191], v151
	ds_read_b128 v[192:195], v151 offset:1024
	ds_read_b128 v[196:199], v151 offset:2048
	ds_read_b128 v[200:203], v151 offset:3072
	ds_read_b128 v[204:207], v151 offset:4096
	ds_read_b128 v[214:217], v151 offset:5120
	ds_read_b128 v[218:221], v151 offset:6144
	ds_read_b128 v[222:225], v151 offset:7168
	global_load_lds_dwordx4 v[146:147], off
	s_add_i32 m0, s46, 0xe000
	v_lshl_add_u64 v[146:147], s[10:11], 0, v[140:141]
	global_load_lds_dwordx4 v[146:147], off
	s_waitcnt lgkmcnt(8)
	s_barrier
	s_waitcnt lgkmcnt(0)
	v_mfma_f32_16x16x32_bf16 v[126:129], v[142:145], v[188:191], v[126:129]
	v_mfma_f32_16x16x32_bf16 v[122:125], v[180:183], v[188:191], v[122:125]
	v_mfma_f32_16x16x32_bf16 v[110:113], v[142:145], v[196:199], v[110:113]
	v_mfma_f32_16x16x32_bf16 v[106:109], v[180:183], v[196:199], v[106:109]
	v_mfma_f32_16x16x32_bf16 v[94:97], v[142:145], v[204:207], v[94:97]
	v_mfma_f32_16x16x32_bf16 v[90:93], v[180:183], v[204:207], v[90:93]
	v_mfma_f32_16x16x32_bf16 v[78:81], v[142:145], v[218:221], v[78:81]
	v_mfma_f32_16x16x32_bf16 v[74:77], v[180:183], v[218:221], v[74:77]
	v_mfma_f32_16x16x32_bf16 v[126:129], v[176:179], v[192:195], v[126:129]
	v_mfma_f32_16x16x32_bf16 v[122:125], v[184:187], v[192:195], v[122:125]
	v_mfma_f32_16x16x32_bf16 v[110:113], v[176:179], v[200:203], v[110:113]
	v_mfma_f32_16x16x32_bf16 v[106:109], v[184:187], v[200:203], v[106:109]
	v_mfma_f32_16x16x32_bf16 v[94:97], v[176:179], v[214:217], v[94:97]
	v_mfma_f32_16x16x32_bf16 v[90:93], v[184:187], v[214:217], v[90:93]
	v_mfma_f32_16x16x32_bf16 v[78:81], v[176:179], v[222:225], v[78:81]
	v_mfma_f32_16x16x32_bf16 v[74:77], v[184:187], v[222:225], v[74:77]
	s_barrier
	s_add_i32 s39, 0, 0x14000
	v_add_u32_e32 v146, s39, v149
	s_add_i32 s10, s38, s37
	ds_read_b128 v[226:229], v146
	ds_read_b128 v[230:233], v146 offset:1024
	ds_read_b128 v[234:237], v146 offset:2048
	ds_read_b128 v[238:241], v146 offset:3072
	v_lshl_add_u64 v[146:147], s[14:15], 0, v[8:9]
	s_mov_b32 m0, s10
	v_lshl_add_u64 v[152:153], s[14:15], 0, v[130:131]
	global_load_lds_dwordx4 v[146:147], off
	s_add_i32 m0, s10, 0x2000
	s_nop 0
	global_load_lds_dwordx4 v[152:153], off
	s_barrier
	s_waitcnt lgkmcnt(0)
	v_mfma_f32_16x16x32_bf16 v[118:121], v[226:229], v[188:191], v[118:121]
	v_mfma_f32_16x16x32_bf16 v[114:117], v[234:237], v[188:191], v[114:117]
	v_mfma_f32_16x16x32_bf16 v[102:105], v[226:229], v[196:199], v[102:105]
	v_mfma_f32_16x16x32_bf16 v[98:101], v[234:237], v[196:199], v[98:101]
	v_mfma_f32_16x16x32_bf16 v[86:89], v[226:229], v[204:207], v[86:89]
	v_mfma_f32_16x16x32_bf16 v[82:85], v[234:237], v[204:207], v[82:85]
	v_mfma_f32_16x16x32_bf16 v[70:73], v[226:229], v[218:221], v[70:73]
	v_mfma_f32_16x16x32_bf16 v[66:69], v[234:237], v[218:221], v[66:69]
	v_mfma_f32_16x16x32_bf16 v[118:121], v[230:233], v[192:195], v[118:121]
	v_mfma_f32_16x16x32_bf16 v[114:117], v[238:241], v[192:195], v[114:117]
	v_mfma_f32_16x16x32_bf16 v[102:105], v[230:233], v[200:203], v[102:105]
	v_mfma_f32_16x16x32_bf16 v[98:101], v[238:241], v[200:203], v[98:101]
	v_mfma_f32_16x16x32_bf16 v[86:89], v[230:233], v[214:217], v[86:89]
	v_mfma_f32_16x16x32_bf16 v[82:85], v[238:241], v[214:217], v[82:85]
	v_mfma_f32_16x16x32_bf16 v[70:73], v[230:233], v[222:225], v[70:73]
	v_mfma_f32_16x16x32_bf16 v[66:69], v[238:241], v[222:225], v[66:69]
	s_barrier
	s_mov_b32 m0, s46
	v_lshl_add_u64 v[162:163], s[16:17], 0, v[134:135]
	ds_read_b128 v[188:191], v151 offset:16384
	ds_read_b128 v[192:195], v151 offset:17408
	ds_read_b128 v[196:199], v151 offset:18432
	ds_read_b128 v[200:203], v151 offset:19456
	ds_read_b128 v[204:207], v151 offset:20480
	ds_read_b128 v[214:217], v151 offset:21504
	ds_read_b128 v[218:221], v151 offset:22528
	ds_read_b128 v[222:225], v151 offset:23552
	global_load_lds_dwordx4 v[162:163], off
	s_mov_b32 m0, s47
	v_lshl_add_u64 v[164:165], s[16:17], 0, v[132:133]
	global_load_lds_dwordx4 v[164:165], off
	s_barrier
	s_waitcnt lgkmcnt(0)
	v_mfma_f32_16x16x32_bf16 v[62:65], v[142:145], v[188:191], v[62:65]
	v_mfma_f32_16x16x32_bf16 v[58:61], v[180:183], v[188:191], v[58:61]
	v_mfma_f32_16x16x32_bf16 v[46:49], v[142:145], v[196:199], v[46:49]
	v_mfma_f32_16x16x32_bf16 v[42:45], v[180:183], v[196:199], v[42:45]
	v_mfma_f32_16x16x32_bf16 v[30:33], v[142:145], v[204:207], v[30:33]
	v_mfma_f32_16x16x32_bf16 v[26:29], v[180:183], v[204:207], v[26:29]
	v_mfma_f32_16x16x32_bf16 v[14:17], v[142:145], v[218:221], v[14:17]
	v_mfma_f32_16x16x32_bf16 v[10:13], v[180:183], v[218:221], v[10:13]
	v_mfma_f32_16x16x32_bf16 v[62:65], v[176:179], v[192:195], v[62:65]
	v_mfma_f32_16x16x32_bf16 v[58:61], v[184:187], v[192:195], v[58:61]
	v_mfma_f32_16x16x32_bf16 v[46:49], v[176:179], v[200:203], v[46:49]
	v_mfma_f32_16x16x32_bf16 v[42:45], v[184:187], v[200:203], v[42:45]
	v_mfma_f32_16x16x32_bf16 v[30:33], v[176:179], v[214:217], v[30:33]
	v_mfma_f32_16x16x32_bf16 v[26:29], v[184:187], v[214:217], v[26:29]
	v_mfma_f32_16x16x32_bf16 v[14:17], v[176:179], v[222:225], v[14:17]
	v_mfma_f32_16x16x32_bf16 v[10:13], v[184:187], v[222:225], v[10:13]
	s_barrier
; #define PG8_STAGE(bufoff, gbase, voff) do { _Pragma("unroll") for (int _i = 0; _i < 2; ++_i) \
;         __builtin_amdgcn_global_load_lds((const unsigned*)((const char*)(gbase) + (voff)[_i]), (LAS unsigned*)(lds + (bufoff) + ldsw + _i * 8192), 16, 0, 0); } while (0)
; #define PG8_LDA(dst, b, h) do { _Pragma("unroll") for (int m = 0; m < 4; ++m) _Pragma("unroll") for (int k = 0; k < 2; ++k) dst[m][k] = *(const LAS bf16x8*)(lds + PG8_SA(b, h) + aoff + m * 2048 + k * 1024); } while (0)
; #define PG8_LDB(dst, b, h) do { _Pragma("unroll") for (int n = 0; n < 2; ++n) _Pragma("unroll") for (int k = 0; k < 2; ++k) dst[n][k] = *(const LAS bf16x8*)(lds + PG8_SB(b, h) + boff + n * 2048 + k * 1024); } while (0)
; #define PG8_MMA(ai, bj, At, Bt) do { __builtin_amdgcn_s_setprio(1); _Pragma("unroll") for (int m = 0; m < 4; ++m) _Pragma("unroll") for (int n = 0; n < 2; ++n) _Pragma("unroll") for (int k = 0; k < 2; ++k) \
;         acc[ai][bj][m][n] = __builtin_amdgcn_mfma_f32_16x16x32_bf16(Bt[n][k], At[m][k], acc[ai][bj][m][n], 0, 0, 0); __builtin_amdgcn_s_setprio(0); } while (0)
; #define PG8_WAIT_V(n) asm volatile("s_waitcnt vmcnt(" #n ")" ::: "memory")
; #define PG8_WAIT_L(n) asm volatile("s_waitcnt lgkmcnt(" #n ")" ::: "memory")
; #define PG8_BAR __builtin_amdgcn_s_barrier()
; #define PG8_SCHED __builtin_amdgcn_sched_barrier(0)
; template <class Epi>
; DEVI void gemm_phase(LAS unsigned char* lds, const Gemm g, const Epi& E) {
;     ...
;             PG8_STAGE(PG8_SB(0, 1), b2 + hstepB, voffB);
;             PG8_WAIT_V(6); PG8_BAR; PG8_MMA(1, 1, At, B1); PG8_BAR;
;             PG8_LDB(B0, 1, 0); PG8_SCHED; PG8_LDA(At, 1, 0); PG8_STAGE(PG8_SA(0, 1), a2 + hstepA, voffA);
;             PG8_WAIT_L(8); PG8_BAR; PG8_WAIT_L(0); PG8_MMA(0, 0, At, B0); PG8_BAR; PG8_SCHED;
;             PG8_LDB(B1, 1, 1); PG8_STAGE(PG8_SB(1, 0), b3, voffB);
;             PG8_BAR; PG8_WAIT_L(0); PG8_MMA(0, 1, At, B1); PG8_BAR;
;             PG8_LDA(At, 1, 1); PG8_STAGE(PG8_SA(1, 0), a3, voffA);
	s_add_u32 s10, s14, 0x28000
	s_addc_u32 s11, s15, 0
	s_add_i32 s38, s39, s37
	s_mov_b32 m0, s38
	v_lshl_add_u64 v[142:143], s[10:11], 0, v[8:9]
	global_load_lds_dwordx4 v[142:143], off
	s_add_i32 m0, s38, 0x2000
	v_lshl_add_u64 v[142:143], s[10:11], 0, v[130:131]
	global_load_lds_dwordx4 v[142:143], off
	s_waitcnt vmcnt(6)
	s_barrier
	v_mfma_f32_16x16x32_bf16 v[54:57], v[226:229], v[188:191], v[54:57]
	v_mfma_f32_16x16x32_bf16 v[50:53], v[234:237], v[188:191], v[50:53]
	v_mfma_f32_16x16x32_bf16 v[38:41], v[226:229], v[196:199], v[38:41]
	v_mfma_f32_16x16x32_bf16 v[34:37], v[234:237], v[196:199], v[34:37]
	v_mfma_f32_16x16x32_bf16 v[22:25], v[226:229], v[204:207], v[22:25]
	v_mfma_f32_16x16x32_bf16 v[18:21], v[234:237], v[204:207], v[18:21]
	v_mfma_f32_16x16x32_bf16 v[4:7], v[226:229], v[218:221], v[4:7]
	v_mfma_f32_16x16x32_bf16 v[0:3], v[234:237], v[218:221], v[0:3]
	v_mfma_f32_16x16x32_bf16 v[54:57], v[230:233], v[192:195], v[54:57]
	v_mfma_f32_16x16x32_bf16 v[50:53], v[238:241], v[192:195], v[50:53]
	v_mfma_f32_16x16x32_bf16 v[38:41], v[230:233], v[200:203], v[38:41]
	v_mfma_f32_16x16x32_bf16 v[34:37], v[238:241], v[200:203], v[34:37]
	v_mfma_f32_16x16x32_bf16 v[22:25], v[230:233], v[214:217], v[22:25]
	v_mfma_f32_16x16x32_bf16 v[18:21], v[238:241], v[214:217], v[18:21]
	v_mfma_f32_16x16x32_bf16 v[4:7], v[230:233], v[222:225], v[4:7]
	v_mfma_f32_16x16x32_bf16 v[0:3], v[238:241], v[222:225], v[0:3]
	s_barrier
	s_add_i32 s38, 0, 0x18000
	v_add_u32_e32 v184, s38, v149
	ds_read_b128 v[142:145], v184
	ds_read_b128 v[176:179], v184 offset:1024
	ds_read_b128 v[180:183], v184 offset:2048
	ds_read_b128 v[184:187], v184 offset:3072
	s_add_u32 s10, s16, 0x28000
	s_addc_u32 s11, s17, 0
	s_mov_b32 m0, s66
	v_lshl_add_u64 v[208:209], s[10:11], 0, v[134:135]
	ds_read_b128 v[188:191], v151 offset:32768
	ds_read_b128 v[192:195], v151 offset:33792
	ds_read_b128 v[196:199], v151 offset:34816
	ds_read_b128 v[200:203], v151 offset:35840
	ds_read_b128 v[204:207], v151 offset:36864
	ds_read_b128 v[214:217], v151 offset:37888
	ds_read_b128 v[218:221], v151 offset:38912
	ds_read_b128 v[222:225], v151 offset:39936
	global_load_lds_dwordx4 v[208:209], off
	s_mov_b32 m0, s68
	v_lshl_add_u64 v[208:209], s[10:11], 0, v[132:133]
	global_load_lds_dwordx4 v[208:209], off
	s_waitcnt lgkmcnt(8)
	s_barrier
	s_waitcnt lgkmcnt(0)
	v_mfma_f32_16x16x32_bf16 v[126:129], v[142:145], v[188:191], v[126:129]
	v_mfma_f32_16x16x32_bf16 v[122:125], v[180:183], v[188:191], v[122:125]
	v_mfma_f32_16x16x32_bf16 v[110:113], v[142:145], v[196:199], v[110:113]
	v_mfma_f32_16x16x32_bf16 v[106:109], v[180:183], v[196:199], v[106:109]
	v_mfma_f32_16x16x32_bf16 v[94:97], v[142:145], v[204:207], v[94:97]
	v_mfma_f32_16x16x32_bf16 v[90:93], v[180:183], v[204:207], v[90:93]
	v_mfma_f32_16x16x32_bf16 v[78:81], v[142:145], v[218:221], v[78:81]
	v_mfma_f32_16x16x32_bf16 v[74:77], v[180:183], v[218:221], v[74:77]
	v_mfma_f32_16x16x32_bf16 v[126:129], v[176:179], v[192:195], v[126:129]
	v_mfma_f32_16x16x32_bf16 v[122:125], v[184:187], v[192:195], v[122:125]
	v_mfma_f32_16x16x32_bf16 v[110:113], v[176:179], v[200:203], v[110:113]
	v_mfma_f32_16x16x32_bf16 v[106:109], v[184:187], v[200:203], v[106:109]
	v_mfma_f32_16x16x32_bf16 v[94:97], v[176:179], v[214:217], v[94:97]
	v_mfma_f32_16x16x32_bf16 v[90:93], v[184:187], v[214:217], v[90:93]
	v_mfma_f32_16x16x32_bf16 v[78:81], v[176:179], v[222:225], v[78:81]
	v_mfma_f32_16x16x32_bf16 v[74:77], v[184:187], v[222:225], v[74:77]
	s_barrier
	s_add_i32 s16, 0, 0x1c000
	s_add_i32 s10, s38, s37
	v_add_u32_e32 v208, s16, v149
	v_lshl_add_u64 v[146:147], v[146:147], 0, s[70:71]
	s_mov_b32 m0, s10
	ds_read_b128 v[226:229], v208
	ds_read_b128 v[230:233], v208 offset:1024
	ds_read_b128 v[234:237], v208 offset:2048
	ds_read_b128 v[238:241], v208 offset:3072
	global_load_lds_dwordx4 v[146:147], off
	s_add_i32 m0, s10, 0x2000
	v_lshl_add_u64 v[146:147], v[152:153], 0, s[70:71]
	global_load_lds_dwordx4 v[146:147], off
	s_barrier
	s_waitcnt lgkmcnt(0)
	v_mfma_f32_16x16x32_bf16 v[118:121], v[226:229], v[188:191], v[118:121]
	v_mfma_f32_16x16x32_bf16 v[114:117], v[234:237], v[188:191], v[114:117]
	v_mfma_f32_16x16x32_bf16 v[102:105], v[226:229], v[196:199], v[102:105]
	v_mfma_f32_16x16x32_bf16 v[98:101], v[234:237], v[196:199], v[98:101]
	v_mfma_f32_16x16x32_bf16 v[86:89], v[226:229], v[204:207], v[86:89]
	v_mfma_f32_16x16x32_bf16 v[82:85], v[234:237], v[204:207], v[82:85]
	v_mfma_f32_16x16x32_bf16 v[70:73], v[226:229], v[218:221], v[70:73]
	v_mfma_f32_16x16x32_bf16 v[66:69], v[234:237], v[218:221], v[66:69]
	v_mfma_f32_16x16x32_bf16 v[118:121], v[230:233], v[192:195], v[118:121]
	v_mfma_f32_16x16x32_bf16 v[114:117], v[238:241], v[192:195], v[114:117]
	v_mfma_f32_16x16x32_bf16 v[102:105], v[230:233], v[200:203], v[102:105]
	v_mfma_f32_16x16x32_bf16 v[98:101], v[238:241], v[200:203], v[98:101]
	v_mfma_f32_16x16x32_bf16 v[86:89], v[230:233], v[214:217], v[86:89]
	v_mfma_f32_16x16x32_bf16 v[82:85], v[238:241], v[214:217], v[82:85]
	v_mfma_f32_16x16x32_bf16 v[70:73], v[230:233], v[222:225], v[70:73]
	v_mfma_f32_16x16x32_bf16 v[66:69], v[238:241], v[222:225], v[66:69]
	s_barrier
	s_mov_b32 m0, s69
	v_lshl_add_u64 v[146:147], v[162:163], 0, s[70:71]
	ds_read_b128 v[188:191], v151 offset:49152
	ds_read_b128 v[192:195], v151 offset:50176
	ds_read_b128 v[196:199], v151 offset:51200
	ds_read_b128 v[200:203], v151 offset:52224
	ds_read_b128 v[204:207], v151 offset:53248
	ds_read_b128 v[214:217], v151 offset:54272
	ds_read_b128 v[218:221], v151 offset:55296
	ds_read_b128 v[222:225], v151 offset:56320
	global_load_lds_dwordx4 v[146:147], off
	s_mov_b32 m0, s80
	v_lshl_add_u64 v[146:147], v[164:165], 0, s[70:71]
	global_load_lds_dwordx4 v[146:147], off
	s_barrier
; DEVI float sigmoidf_(float x) { return __builtin_amdgcn_rcpf(1.f + __expf(-x)); }
; DEVI float siluf_(float x) { return x * __builtin_amdgcn_rcpf(1.f + __expf(-x)); }
; DEVI float logsigf_(float x) { return fminf(x, 0.f) - __logf(1.f + __expf(-fabsf(x))); }
	s_waitcnt lgkmcnt(0)
	v_mfma_f32_16x16x32_bf16 v[62:65], v[142:145], v[188:191], v[62:65]
	v_mfma_f32_16x16x32_bf16 v[58:61], v[180:183], v[188:191], v[58:61]
	v_mfma_f32_16x16x32_bf16 v[46:49], v[142:145], v[196:199], v[46:49]
	v_mfma_f32_16x16x32_bf16 v[42:45], v[180:183], v[196:199], v[42:45]
	v_mfma_f32_16x16x32_bf16 v[30:33], v[142:145], v[204:207], v[30:33]
	v_mfma_f32_16x16x32_bf16 v[26:29], v[180:183], v[204:207], v[26:29]
	v_mfma_f32_16x16x32_bf16 v[14:17], v[142:145], v[218:221], v[14:17]
	v_mfma_f32_16x16x32_bf16 v[10:13], v[180:183], v[218:221], v[10:13]
	v_mfma_f32_16x16x32_bf16 v[62:65], v[176:179], v[192:195], v[62:65]
	v_mfma_f32_16x16x32_bf16 v[58:61], v[184:187], v[192:195], v[58:61]
	v_mfma_f32_16x16x32_bf16 v[46:49], v[176:179], v[200:203], v[46:49]
	v_mfma_f32_16x16x32_bf16 v[42:45], v[184:187], v[200:203], v[42:45]
	v_mfma_f32_16x16x32_bf16 v[30:33], v[176:179], v[214:217], v[30:33]
	v_mfma_f32_16x16x32_bf16 v[26:29], v[184:187], v[214:217], v[26:29]
	v_mfma_f32_16x16x32_bf16 v[14:17], v[176:179], v[222:225], v[14:17]
	v_mfma_f32_16x16x32_bf16 v[10:13], v[184:187], v[222:225], v[10:13]
	s_barrier
	s_add_u32 s10, s14, 0x28080
	s_addc_u32 s11, s15, 0
	s_add_i32 s14, s16, s37
	s_mov_b32 m0, s14
	v_lshl_add_u64 v[142:143], s[10:11], 0, v[8:9]
	global_load_lds_dwordx4 v[142:143], off
	s_add_i32 m0, s14, 0x2000
	v_lshl_add_u64 v[142:143], s[10:11], 0, v[130:131]
	global_load_lds_dwordx4 v[142:143], off
	s_waitcnt vmcnt(6)
	s_barrier
	v_mfma_f32_16x16x32_bf16 v[54:57], v[226:229], v[188:191], v[54:57]
	v_mfma_f32_16x16x32_bf16 v[50:53], v[234:237], v[188:191], v[50:53]
	v_mfma_f32_16x16x32_bf16 v[38:41], v[226:229], v[196:199], v[38:41]
	v_mfma_f32_16x16x32_bf16 v[34:37], v[234:237], v[196:199], v[34:37]
	v_mfma_f32_16x16x32_bf16 v[22:25], v[226:229], v[204:207], v[22:25]
	v_mfma_f32_16x16x32_bf16 v[18:21], v[234:237], v[204:207], v[18:21]
	v_mfma_f32_16x16x32_bf16 v[4:7], v[226:229], v[218:221], v[4:7]
	v_mfma_f32_16x16x32_bf16 v[0:3], v[234:237], v[218:221], v[0:3]
	v_mfma_f32_16x16x32_bf16 v[54:57], v[230:233], v[192:195], v[54:57]
	v_mfma_f32_16x16x32_bf16 v[50:53], v[238:241], v[192:195], v[50:53]
	v_mfma_f32_16x16x32_bf16 v[38:41], v[230:233], v[200:203], v[38:41]
	v_mfma_f32_16x16x32_bf16 v[34:37], v[238:241], v[200:203], v[34:37]
	v_mfma_f32_16x16x32_bf16 v[22:25], v[230:233], v[214:217], v[22:25]
	v_mfma_f32_16x16x32_bf16 v[18:21], v[238:241], v[214:217], v[18:21]
	v_mfma_f32_16x16x32_bf16 v[4:7], v[230:233], v[222:225], v[4:7]
	v_mfma_f32_16x16x32_bf16 v[0:3], v[238:241], v[222:225], v[0:3]
	s_barrier
	s_add_i32 s27, s27, 2
	s_add_u32 s19, s19, 0x100
	s_addc_u32 s26, s26, 0
	s_cmp_gt_u32 s27, 7
	s_mov_b64 s[10:11], s[12:13]
	s_cbranch_scc0 .LBB0_1278
	s_setprio 0
	v_lshl_add_u32 v144, s18, 8, v148
	v_ashrrev_i32_e32 v145, 31, v144
	v_lshlrev_b64 v[142:143], 16, v[144:145]
	v_mul_f32_e32 v145, 0x3d372713, v126
	v_mul_f32_e32 v145, v126, v145
	v_fma_f32 v145, v126, v145, v126
	v_mul_f32_e32 v145, 0x3f4c422a, v145
	v_add_f32_e32 v145, v145, v145
	v_mul_f32_e32 v145, 0xbfb8aa3b, v145
	v_exp_f32_e32 v145, v145
	v_lshl_or_b32 v164, s1, 8, v150
	s_lshl_b32 s0, s0, 4
	s_ashr_i32 s1, s0, 31
	v_add_f32_e32 v145, 1.0, v145
	v_rcp_f32_e32 v152, v145
	v_mul_f32_e32 v145, 0x3d372713, v122
	v_mul_f32_e32 v145, v122, v145
	v_fma_f32 v145, v122, v145, v122
	v_mul_f32_e32 v145, 0x3f4c422a, v145
	v_add_f32_e32 v145, v145, v145
	v_mul_f32_e32 v145, 0xbfb8aa3b, v145
	v_exp_f32_e32 v145, v145
	v_lshl_add_u64 v[146:147], s[0:1], 1, v[136:137]
	v_lshl_add_u64 v[142:143], v[146:147], 0, v[142:143]
	s_mov_b64 s[0:1], 0x800000
	v_add_f32_e32 v145, 1.0, v145
	v_rcp_f32_e32 v162, v145
	v_mul_f32_e32 v145, 0x3d372713, v127
	v_mul_f32_e32 v145, v127, v145
	v_fma_f32 v145, v127, v145, v127
	v_mul_f32_e32 v145, 0x3f4c422a, v145
	v_add_f32_e32 v145, v145, v145
	v_mul_f32_e32 v145, 0xbfb8aa3b, v145
	v_exp_f32_e32 v145, v145
	s_and_b64 vcc, exec, s[2:3]
	s_mov_b32 s18, s82
	s_mov_b64 s[12:13], s[6:7]
	v_add_f32_e32 v145, 1.0, v145
	v_rcp_f32_e32 v153, v145
	v_mul_f32_e32 v145, 0x3d372713, v123
	v_mul_f32_e32 v145, v123, v145
	v_fma_f32 v145, v123, v145, v123
	v_mul_f32_e32 v145, 0x3f4c422a, v145
	v_add_f32_e32 v145, v145, v145
	v_mul_f32_e32 v145, 0xbfb8aa3b, v145
	v_exp_f32_e32 v145, v145
	v_pk_mul_f32 v[126:127], v[126:127], v[152:153]
	s_mov_b64 s[10:11], s[4:5]
	v_add_f32_e32 v145, 1.0, v145
	v_rcp_f32_e32 v163, v145
	v_mul_f32_e32 v145, 0x3d372713, v128
	v_mul_f32_e32 v145, v128, v145
	v_fma_f32 v145, v128, v145, v128
	v_mul_f32_e32 v145, 0x3f4c422a, v145
	v_add_f32_e32 v145, v145, v145
	v_mul_f32_e32 v145, 0xbfb8aa3b, v145
	v_exp_f32_e32 v145, v145
	v_pk_mul_f32 v[122:123], v[122:123], v[162:163]
	v_add_f32_e32 v145, 1.0, v145
	v_rcp_f32_e32 v152, v145
	v_mul_f32_e32 v145, 0x3d372713, v124
	v_mul_f32_e32 v145, v124, v145
	v_fma_f32 v145, v124, v145, v124
	v_mul_f32_e32 v145, 0x3f4c422a, v145
	v_add_f32_e32 v145, v145, v145
	v_mul_f32_e32 v145, 0xbfb8aa3b, v145
	v_exp_f32_e32 v145, v145
	s_nop 0
	v_add_f32_e32 v145, 1.0, v145
	v_rcp_f32_e32 v162, v145
	v_mul_f32_e32 v145, 0x3d372713, v129
	v_mul_f32_e32 v145, v129, v145
	v_fma_f32 v145, v129, v145, v129
	v_mul_f32_e32 v145, 0x3f4c422a, v145
	v_add_f32_e32 v145, v145, v145
	v_mul_f32_e32 v145, 0xbfb8aa3b, v145
	v_exp_f32_e32 v145, v145
	s_nop 0
	v_add_f32_e32 v145, 1.0, v145
	v_rcp_f32_e32 v153, v145
	v_mul_f32_e32 v145, 0x3d372713, v125
	v_mul_f32_e32 v145, v125, v145
	v_fma_f32 v145, v125, v145, v125
	v_mul_f32_e32 v145, 0x3f4c422a, v145
	v_add_f32_e32 v145, v145, v145
	v_mul_f32_e32 v145, 0xbfb8aa3b, v145
	v_exp_f32_e32 v145, v145
	v_pk_mul_f32 v[128:129], v[128:129], v[152:153]
; DEVI float sigmoidf_(float x) { return __builtin_amdgcn_rcpf(1.f + __expf(-x)); }
; DEVI float siluf_(float x) { return x * __builtin_amdgcn_rcpf(1.f + __expf(-x)); }
; DEVI float logsigf_(float x) { return fminf(x, 0.f) - __logf(1.f + __expf(-fabsf(x))); }
	v_add_f32_e32 v145, 1.0, v145
	v_rcp_f32_e32 v163, v145
	s_nop 0
	v_pk_mul_f32 v[152:153], v[124:125], v[162:163]
	v_cvt_pk_bf16_f32 v125, v128, v129
	v_ashrrev_i32_e32 v128, 4, v164
	v_ashrrev_i32_e32 v129, 31, v128
	v_cvt_pk_bf16_f32 v124, v126, v127
	v_cvt_pk_bf16_f32 v126, v122, v123
	v_lshlrev_b64 v[122:123], 11, v[128:129]
	v_cvt_pk_bf16_f32 v127, v152, v153
	v_lshl_add_u64 v[152:153], v[142:143], 0, v[122:123]
	global_store_dwordx4 v[152:153], v[124:127], off
	s_nop 1
	v_mul_f32_e32 v125, 0x3d372713, v114
	v_mul_f32_e32 v125, v114, v125
	v_fma_f32 v125, v114, v125, v114
	v_mul_f32_e32 v125, 0x3f4c422a, v125
	v_add_f32_e32 v125, v125, v125
	v_mul_f32_e32 v125, 0xbfb8aa3b, v125
	v_exp_f32_e32 v125, v125
	v_mul_f32_e32 v124, 0x3d372713, v118
	v_mul_f32_e32 v124, v118, v124
	v_fma_f32 v124, v118, v124, v118
	v_add_f32_e32 v125, 1.0, v125
	v_rcp_f32_e32 v126, v125
	v_mul_f32_e32 v125, 0x3d372713, v119
	v_mul_f32_e32 v125, v119, v125
	v_fma_f32 v125, v119, v125, v119
	v_mul_f32_e32 v124, 0x3f4c422a, v124
	v_mul_f32_e32 v125, 0x3f4c422a, v125
	v_add_f32_e32 v124, v124, v124
	v_add_f32_e32 v125, v125, v125
	v_mul_f32_e32 v124, 0xbfb8aa3b, v124
	v_mul_f32_e32 v125, 0xbfb8aa3b, v125
	v_exp_f32_e32 v124, v124
	v_exp_f32_e32 v125, v125
	v_add_f32_e32 v124, 1.0, v124
	v_add_f32_e32 v125, 1.0, v125
	v_rcp_f32_e32 v124, v124
	v_rcp_f32_e32 v125, v125
	s_nop 0
	v_pk_mul_f32 v[118:119], v[118:119], v[124:125]
	v_mul_f32_e32 v124, 0x3d372713, v115
	v_mul_f32_e32 v124, v115, v124
	v_fma_f32 v124, v115, v124, v115
	v_mul_f32_e32 v124, 0x3f4c422a, v124
	v_add_f32_e32 v124, v124, v124
	v_mul_f32_e32 v125, 0x3d372713, v116
	v_mul_f32_e32 v124, 0xbfb8aa3b, v124
	v_mul_f32_e32 v125, v116, v125
	v_exp_f32_e32 v124, v124
	v_fma_f32 v125, v116, v125, v116
	v_mul_f32_e32 v125, 0x3f4c422a, v125
	v_add_f32_e32 v125, v125, v125
	v_mul_f32_e32 v125, 0xbfb8aa3b, v125
	v_add_f32_e32 v124, 1.0, v124
	v_exp_f32_e32 v125, v125
	v_rcp_f32_e32 v127, v124
	v_mul_f32_e32 v124, 0x3d372713, v120
	v_mul_f32_e32 v124, v120, v124
	v_add_f32_e32 v125, 1.0, v125
	v_pk_mul_f32 v[114:115], v[114:115], v[126:127]
	v_rcp_f32_e32 v126, v125
	v_mul_f32_e32 v125, 0x3d372713, v121
	v_mul_f32_e32 v125, v121, v125
	v_fma_f32 v124, v120, v124, v120
	v_fma_f32 v125, v121, v125, v121
	v_mul_f32_e32 v124, 0x3f4c422a, v124
	v_mul_f32_e32 v125, 0x3f4c422a, v125
	v_add_f32_e32 v124, v124, v124
	v_add_f32_e32 v125, v125, v125
	v_mul_f32_e32 v124, 0xbfb8aa3b, v124
	v_mul_f32_e32 v125, 0xbfb8aa3b, v125
	v_exp_f32_e32 v124, v124
	v_exp_f32_e32 v125, v125
	v_add_f32_e32 v124, 1.0, v124
	v_add_f32_e32 v125, 1.0, v125
	v_rcp_f32_e32 v124, v124
	v_rcp_f32_e32 v125, v125
	s_nop 0
	v_pk_mul_f32 v[120:121], v[120:121], v[124:125]
	v_mul_f32_e32 v124, 0x3d372713, v117
	v_mul_f32_e32 v124, v117, v124
	v_fma_f32 v124, v117, v124, v117
	v_mul_f32_e32 v124, 0x3f4c422a, v124
	v_add_f32_e32 v124, v124, v124
	v_mul_f32_e32 v124, 0xbfb8aa3b, v124
	v_exp_f32_e32 v124, v124
	s_nop 0
	v_add_f32_e32 v124, 1.0, v124
	v_rcp_f32_e32 v127, v124
	s_nop 0
	v_pk_mul_f32 v[124:125], v[116:117], v[126:127]
	v_cvt_pk_bf16_f32 v116, v118, v119
	v_cvt_pk_bf16_f32 v118, v114, v115
	v_or_b32_e32 v114, 8, v128
	v_ashrrev_i32_e32 v115, 31, v114
	v_lshlrev_b64 v[114:115], 11, v[114:115]
	v_cvt_pk_bf16_f32 v117, v120, v121
	v_cvt_pk_bf16_f32 v119, v124, v125
	v_lshl_add_u64 v[120:121], v[142:143], 0, v[114:115]
	global_store_dwordx4 v[120:121], v[116:119], off
	s_nop 1
	v_mul_f32_e32 v119, 0x3d372713, v106
	v_mul_f32_e32 v119, v106, v119
	v_fma_f32 v119, v106, v119, v106
	v_mul_f32_e32 v119, 0x3f4c422a, v119
	v_add_f32_e32 v119, v119, v119
	v_mul_f32_e32 v119, 0xbfb8aa3b, v119
	v_exp_f32_e32 v119, v119
	v_mul_f32_e32 v118, 0x3d372713, v110
	v_mul_f32_e32 v118, v110, v118
	v_fma_f32 v118, v110, v118, v110
	v_add_f32_e32 v119, 1.0, v119
	v_rcp_f32_e32 v120, v119
	v_mul_f32_e32 v119, 0x3d372713, v111
	v_mul_f32_e32 v119, v111, v119
	v_fma_f32 v119, v111, v119, v111
	v_mul_f32_e32 v118, 0x3f4c422a, v118
	v_mul_f32_e32 v119, 0x3f4c422a, v119
	v_add_f32_e32 v118, v118, v118
	v_add_f32_e32 v119, v119, v119
	v_mul_f32_e32 v118, 0xbfb8aa3b, v118
	v_mul_f32_e32 v119, 0xbfb8aa3b, v119
	v_exp_f32_e32 v118, v118
	v_exp_f32_e32 v119, v119
	v_or_b32_e32 v116, 16, v144
	v_ashrrev_i32_e32 v117, 31, v116
	v_add_f32_e32 v118, 1.0, v118
	v_add_f32_e32 v119, 1.0, v119
	v_rcp_f32_e32 v118, v118
	v_rcp_f32_e32 v119, v119
	v_lshlrev_b64 v[116:117], 16, v[116:117]
	v_lshl_add_u64 v[116:117], v[146:147], 0, v[116:117]
	v_pk_mul_f32 v[110:111], v[110:111], v[118:119]
	v_mul_f32_e32 v118, 0x3d372713, v107
	v_mul_f32_e32 v118, v107, v118
	v_fma_f32 v118, v107, v118, v107
	v_mul_f32_e32 v118, 0x3f4c422a, v118
	v_add_f32_e32 v118, v118, v118
	v_mul_f32_e32 v118, 0xbfb8aa3b, v118
	v_exp_f32_e32 v118, v118
	s_nop 0
	v_add_f32_e32 v118, 1.0, v118
	v_rcp_f32_e32 v121, v118
	s_nop 0
	v_pk_mul_f32 v[118:119], v[106:107], v[120:121]
	v_mul_f32_e32 v107, 0x3d372713, v108
	v_mul_f32_e32 v107, v108, v107
	v_fma_f32 v107, v108, v107, v108
	v_mul_f32_e32 v107, 0x3f4c422a, v107
	v_add_f32_e32 v107, v107, v107
	v_mul_f32_e32 v107, 0xbfb8aa3b, v107
	v_exp_f32_e32 v107, v107
	v_mul_f32_e32 v106, 0x3d372713, v112
	v_mul_f32_e32 v106, v112, v106
	v_fma_f32 v106, v112, v106, v112
	v_add_f32_e32 v107, 1.0, v107
	v_rcp_f32_e32 v120, v107
	v_mul_f32_e32 v107, 0x3d372713, v113
	v_mul_f32_e32 v107, v113, v107
	v_fma_f32 v107, v113, v107, v113
	v_mul_f32_e32 v106, 0x3f4c422a, v106
	v_mul_f32_e32 v107, 0x3f4c422a, v107
	v_add_f32_e32 v106, v106, v106
	v_add_f32_e32 v107, v107, v107
	v_mul_f32_e32 v106, 0xbfb8aa3b, v106
	v_mul_f32_e32 v107, 0xbfb8aa3b, v107
	v_exp_f32_e32 v106, v106
; DEVI float sigmoidf_(float x) { return __builtin_amdgcn_rcpf(1.f + __expf(-x)); }
; DEVI float siluf_(float x) { return x * __builtin_amdgcn_rcpf(1.f + __expf(-x)); }
; DEVI float logsigf_(float x) { return fminf(x, 0.f) - __logf(1.f + __expf(-fabsf(x))); }
	v_exp_f32_e32 v107, v107
	v_add_f32_e32 v106, 1.0, v106
	v_add_f32_e32 v107, 1.0, v107
	v_rcp_f32_e32 v106, v106
	v_rcp_f32_e32 v107, v107
	s_nop 0
	v_pk_mul_f32 v[112:113], v[112:113], v[106:107]
	v_mul_f32_e32 v106, 0x3d372713, v109
	v_mul_f32_e32 v106, v109, v106
	v_fma_f32 v106, v109, v106, v109
	v_mul_f32_e32 v106, 0x3f4c422a, v106
	v_add_f32_e32 v106, v106, v106
	v_mul_f32_e32 v106, 0xbfb8aa3b, v106
	v_exp_f32_e32 v106, v106
	v_cvt_pk_bf16_f32 v107, v112, v113
	v_add_f32_e32 v106, 1.0, v106
	v_rcp_f32_e32 v121, v106
	v_cvt_pk_bf16_f32 v106, v110, v111
	v_lshl_add_u64 v[110:111], v[116:117], 0, v[122:123]
	v_pk_mul_f32 v[120:121], v[108:109], v[120:121]
	v_cvt_pk_bf16_f32 v108, v118, v119
	v_cvt_pk_bf16_f32 v109, v120, v121
	global_store_dwordx4 v[110:111], v[106:109], off
	s_nop 1
	v_mul_f32_e32 v107, 0x3d372713, v98
	v_mul_f32_e32 v107, v98, v107
	v_fma_f32 v107, v98, v107, v98
	v_mul_f32_e32 v107, 0x3f4c422a, v107
	v_add_f32_e32 v107, v107, v107
	v_mul_f32_e32 v107, 0xbfb8aa3b, v107
	v_exp_f32_e32 v107, v107
	v_mul_f32_e32 v106, 0x3d372713, v102
	v_mul_f32_e32 v106, v102, v106
	v_fma_f32 v106, v102, v106, v102
	v_add_f32_e32 v107, 1.0, v107
	v_rcp_f32_e32 v108, v107
	v_mul_f32_e32 v107, 0x3d372713, v103
	v_mul_f32_e32 v107, v103, v107
	v_fma_f32 v107, v103, v107, v103
	v_mul_f32_e32 v106, 0x3f4c422a, v106
	v_mul_f32_e32 v107, 0x3f4c422a, v107
	v_add_f32_e32 v106, v106, v106
	v_add_f32_e32 v107, v107, v107
	v_mul_f32_e32 v106, 0xbfb8aa3b, v106
	v_mul_f32_e32 v107, 0xbfb8aa3b, v107
	v_exp_f32_e32 v106, v106
	v_exp_f32_e32 v107, v107
	v_add_f32_e32 v106, 1.0, v106
	v_add_f32_e32 v107, 1.0, v107
	v_rcp_f32_e32 v106, v106
	v_rcp_f32_e32 v107, v107
	s_nop 0
	v_pk_mul_f32 v[102:103], v[102:103], v[106:107]
	v_mul_f32_e32 v106, 0x3d372713, v99
	v_mul_f32_e32 v106, v99, v106
	v_fma_f32 v106, v99, v106, v99
	v_mul_f32_e32 v106, 0x3f4c422a, v106
	v_add_f32_e32 v106, v106, v106
	v_mul_f32_e32 v106, 0xbfb8aa3b, v106
	v_exp_f32_e32 v106, v106
	s_nop 0
	v_add_f32_e32 v106, 1.0, v106
	v_rcp_f32_e32 v109, v106
	s_nop 0
	v_pk_mul_f32 v[106:107], v[98:99], v[108:109]
	v_mul_f32_e32 v99, 0x3d372713, v100
	v_mul_f32_e32 v99, v100, v99
	v_fma_f32 v99, v100, v99, v100
	v_mul_f32_e32 v99, 0x3f4c422a, v99
	v_add_f32_e32 v99, v99, v99
	v_mul_f32_e32 v99, 0xbfb8aa3b, v99
	v_exp_f32_e32 v99, v99
	v_mul_f32_e32 v98, 0x3d372713, v104
	v_mul_f32_e32 v98, v104, v98
	v_fma_f32 v98, v104, v98, v104
	v_add_f32_e32 v99, 1.0, v99
	v_rcp_f32_e32 v108, v99
	v_mul_f32_e32 v99, 0x3d372713, v105
	v_mul_f32_e32 v99, v105, v99
	v_fma_f32 v99, v105, v99, v105
	v_mul_f32_e32 v98, 0x3f4c422a, v98
	v_mul_f32_e32 v99, 0x3f4c422a, v99
	v_add_f32_e32 v98, v98, v98
	v_add_f32_e32 v99, v99, v99
	v_mul_f32_e32 v98, 0xbfb8aa3b, v98
	v_mul_f32_e32 v99, 0xbfb8aa3b, v99
	v_exp_f32_e32 v98, v98
	v_exp_f32_e32 v99, v99
	v_add_f32_e32 v98, 1.0, v98
	v_add_f32_e32 v99, 1.0, v99
	v_rcp_f32_e32 v98, v98
	v_rcp_f32_e32 v99, v99
	s_nop 0
	v_pk_mul_f32 v[104:105], v[104:105], v[98:99]
	v_mul_f32_e32 v98, 0x3d372713, v101
	v_mul_f32_e32 v98, v101, v98
	v_fma_f32 v98, v101, v98, v101
	v_mul_f32_e32 v98, 0x3f4c422a, v98
	v_add_f32_e32 v98, v98, v98
	v_mul_f32_e32 v98, 0xbfb8aa3b, v98
	v_exp_f32_e32 v98, v98
	v_cvt_pk_bf16_f32 v99, v104, v105
	v_add_f32_e32 v98, 1.0, v98
	v_rcp_f32_e32 v109, v98
	v_cvt_pk_bf16_f32 v98, v102, v103
	v_lshl_add_u64 v[102:103], v[116:117], 0, v[114:115]
	v_pk_mul_f32 v[108:109], v[100:101], v[108:109]
	v_cvt_pk_bf16_f32 v100, v106, v107
	v_cvt_pk_bf16_f32 v101, v108, v109
	global_store_dwordx4 v[102:103], v[98:101], off
	s_nop 1
	v_mul_f32_e32 v101, 0x3d372713, v90
	v_mul_f32_e32 v101, v90, v101
	v_fma_f32 v101, v90, v101, v90
	v_mul_f32_e32 v101, 0x3f4c422a, v101
	v_add_f32_e32 v101, v101, v101
	v_mul_f32_e32 v101, 0xbfb8aa3b, v101
	v_exp_f32_e32 v101, v101
	v_mul_f32_e32 v100, 0x3d372713, v94
	v_mul_f32_e32 v100, v94, v100
	v_fma_f32 v100, v94, v100, v94
	v_add_f32_e32 v101, 1.0, v101
	v_rcp_f32_e32 v102, v101
	v_mul_f32_e32 v101, 0x3d372713, v95
	v_mul_f32_e32 v101, v95, v101
	v_fma_f32 v101, v95, v101, v95
	v_mul_f32_e32 v100, 0x3f4c422a, v100
	v_mul_f32_e32 v101, 0x3f4c422a, v101
	v_add_f32_e32 v100, v100, v100
	v_add_f32_e32 v101, v101, v101
	v_mul_f32_e32 v100, 0xbfb8aa3b, v100
	v_mul_f32_e32 v101, 0xbfb8aa3b, v101
	v_exp_f32_e32 v100, v100
	v_exp_f32_e32 v101, v101
	v_or_b32_e32 v98, 32, v144
	v_ashrrev_i32_e32 v99, 31, v98
	v_add_f32_e32 v100, 1.0, v100
	v_add_f32_e32 v101, 1.0, v101
	v_rcp_f32_e32 v100, v100
	v_rcp_f32_e32 v101, v101
	v_lshlrev_b64 v[98:99], 16, v[98:99]
	v_lshl_add_u64 v[98:99], v[146:147], 0, v[98:99]
	v_pk_mul_f32 v[94:95], v[94:95], v[100:101]
	v_mul_f32_e32 v100, 0x3d372713, v91
	v_mul_f32_e32 v100, v91, v100
	v_fma_f32 v100, v91, v100, v91
	v_mul_f32_e32 v100, 0x3f4c422a, v100
	v_add_f32_e32 v100, v100, v100
	v_mul_f32_e32 v100, 0xbfb8aa3b, v100
	v_exp_f32_e32 v100, v100
	s_nop 0
	v_add_f32_e32 v100, 1.0, v100
	v_rcp_f32_e32 v103, v100
	s_nop 0
	v_pk_mul_f32 v[100:101], v[90:91], v[102:103]
	v_mul_f32_e32 v91, 0x3d372713, v92
	v_mul_f32_e32 v91, v92, v91
	v_fma_f32 v91, v92, v91, v92
	v_mul_f32_e32 v91, 0x3f4c422a, v91
	v_add_f32_e32 v91, v91, v91
	v_mul_f32_e32 v91, 0xbfb8aa3b, v91
	v_exp_f32_e32 v91, v91
	v_mul_f32_e32 v90, 0x3d372713, v96
	v_mul_f32_e32 v90, v96, v90
	v_fma_f32 v90, v96, v90, v96
	v_add_f32_e32 v91, 1.0, v91
	v_rcp_f32_e32 v102, v91
	v_mul_f32_e32 v91, 0x3d372713, v97
	v_mul_f32_e32 v91, v97, v91
	v_fma_f32 v91, v97, v91, v97
	v_mul_f32_e32 v90, 0x3f4c422a, v90
	v_mul_f32_e32 v91, 0x3f4c422a, v91
	v_add_f32_e32 v90, v90, v90
	v_add_f32_e32 v91, v91, v91
	v_mul_f32_e32 v90, 0xbfb8aa3b, v90
	v_mul_f32_e32 v91, 0xbfb8aa3b, v91
; DEVI float sigmoidf_(float x) { return __builtin_amdgcn_rcpf(1.f + __expf(-x)); }
; DEVI float siluf_(float x) { return x * __builtin_amdgcn_rcpf(1.f + __expf(-x)); }
; DEVI float logsigf_(float x) { return fminf(x, 0.f) - __logf(1.f + __expf(-fabsf(x))); }
	v_exp_f32_e32 v90, v90
	v_exp_f32_e32 v91, v91
	v_add_f32_e32 v90, 1.0, v90
	v_add_f32_e32 v91, 1.0, v91
	v_rcp_f32_e32 v90, v90
	v_rcp_f32_e32 v91, v91
	s_nop 0
	v_pk_mul_f32 v[96:97], v[96:97], v[90:91]
	v_mul_f32_e32 v90, 0x3d372713, v93
	v_mul_f32_e32 v90, v93, v90
	v_fma_f32 v90, v93, v90, v93
	v_mul_f32_e32 v90, 0x3f4c422a, v90
	v_add_f32_e32 v90, v90, v90
	v_mul_f32_e32 v90, 0xbfb8aa3b, v90
	v_exp_f32_e32 v90, v90
	v_cvt_pk_bf16_f32 v91, v96, v97
	v_add_f32_e32 v90, 1.0, v90
	v_rcp_f32_e32 v103, v90
	v_cvt_pk_bf16_f32 v90, v94, v95
	v_lshl_add_u64 v[94:95], v[98:99], 0, v[122:123]
	v_pk_mul_f32 v[102:103], v[92:93], v[102:103]
	v_cvt_pk_bf16_f32 v92, v100, v101
	v_cvt_pk_bf16_f32 v93, v102, v103
	global_store_dwordx4 v[94:95], v[90:93], off
	s_nop 1
	v_mul_f32_e32 v91, 0x3d372713, v82
	v_mul_f32_e32 v91, v82, v91
	v_fma_f32 v91, v82, v91, v82
	v_mul_f32_e32 v91, 0x3f4c422a, v91
	v_add_f32_e32 v91, v91, v91
	v_mul_f32_e32 v91, 0xbfb8aa3b, v91
	v_exp_f32_e32 v91, v91
	v_mul_f32_e32 v90, 0x3d372713, v86
	v_mul_f32_e32 v90, v86, v90
	v_fma_f32 v90, v86, v90, v86
	v_add_f32_e32 v91, 1.0, v91
	v_rcp_f32_e32 v92, v91
	v_mul_f32_e32 v91, 0x3d372713, v87
	v_mul_f32_e32 v91, v87, v91
	v_fma_f32 v91, v87, v91, v87
	v_mul_f32_e32 v90, 0x3f4c422a, v90
	v_mul_f32_e32 v91, 0x3f4c422a, v91
	v_add_f32_e32 v90, v90, v90
	v_add_f32_e32 v91, v91, v91
	v_mul_f32_e32 v90, 0xbfb8aa3b, v90
	v_mul_f32_e32 v91, 0xbfb8aa3b, v91
	v_exp_f32_e32 v90, v90
	v_exp_f32_e32 v91, v91
	v_add_f32_e32 v90, 1.0, v90
	v_add_f32_e32 v91, 1.0, v91
	v_rcp_f32_e32 v90, v90
	v_rcp_f32_e32 v91, v91
	s_nop 0
	v_pk_mul_f32 v[86:87], v[86:87], v[90:91]
	v_mul_f32_e32 v90, 0x3d372713, v83
	v_mul_f32_e32 v90, v83, v90
	v_fma_f32 v90, v83, v90, v83
	v_mul_f32_e32 v90, 0x3f4c422a, v90
	v_add_f32_e32 v90, v90, v90
	v_mul_f32_e32 v90, 0xbfb8aa3b, v90
	v_exp_f32_e32 v90, v90
	s_nop 0
	v_add_f32_e32 v90, 1.0, v90
	v_rcp_f32_e32 v93, v90
	s_nop 0
	v_pk_mul_f32 v[90:91], v[82:83], v[92:93]
	v_mul_f32_e32 v83, 0x3d372713, v84
	v_mul_f32_e32 v83, v84, v83
	v_fma_f32 v83, v84, v83, v84
	v_mul_f32_e32 v83, 0x3f4c422a, v83
	v_add_f32_e32 v83, v83, v83
	v_mul_f32_e32 v83, 0xbfb8aa3b, v83
	v_exp_f32_e32 v83, v83
	v_mul_f32_e32 v82, 0x3d372713, v88
	v_mul_f32_e32 v82, v88, v82
	v_fma_f32 v82, v88, v82, v88
	v_add_f32_e32 v83, 1.0, v83
	v_rcp_f32_e32 v92, v83
	v_mul_f32_e32 v83, 0x3d372713, v89
	v_mul_f32_e32 v83, v89, v83
	v_fma_f32 v83, v89, v83, v89
	v_mul_f32_e32 v82, 0x3f4c422a, v82
	v_mul_f32_e32 v83, 0x3f4c422a, v83
	v_add_f32_e32 v82, v82, v82
	v_add_f32_e32 v83, v83, v83
	v_mul_f32_e32 v82, 0xbfb8aa3b, v82
	v_mul_f32_e32 v83, 0xbfb8aa3b, v83
	v_exp_f32_e32 v82, v82
	v_exp_f32_e32 v83, v83
	v_add_f32_e32 v82, 1.0, v82
	v_add_f32_e32 v83, 1.0, v83
	v_rcp_f32_e32 v82, v82
	v_rcp_f32_e32 v83, v83
	s_nop 0
	v_pk_mul_f32 v[88:89], v[88:89], v[82:83]
	v_mul_f32_e32 v82, 0x3d372713, v85
	v_mul_f32_e32 v82, v85, v82
	v_fma_f32 v82, v85, v82, v85
	v_mul_f32_e32 v82, 0x3f4c422a, v82
	v_add_f32_e32 v82, v82, v82
	v_mul_f32_e32 v82, 0xbfb8aa3b, v82
	v_exp_f32_e32 v82, v82
	v_cvt_pk_bf16_f32 v83, v88, v89
	v_add_f32_e32 v82, 1.0, v82
	v_rcp_f32_e32 v93, v82
	v_cvt_pk_bf16_f32 v82, v86, v87
	v_lshl_add_u64 v[86:87], v[98:99], 0, v[114:115]
	v_pk_mul_f32 v[92:93], v[84:85], v[92:93]
	v_cvt_pk_bf16_f32 v84, v90, v91
	v_cvt_pk_bf16_f32 v85, v92, v93
	global_store_dwordx4 v[86:87], v[82:85], off
	s_nop 1
	v_mul_f32_e32 v85, 0x3d372713, v74
	v_mul_f32_e32 v85, v74, v85
	v_fma_f32 v85, v74, v85, v74
	v_mul_f32_e32 v85, 0x3f4c422a, v85
	v_add_f32_e32 v85, v85, v85
	v_mul_f32_e32 v85, 0xbfb8aa3b, v85
	v_exp_f32_e32 v85, v85
	v_mul_f32_e32 v84, 0x3d372713, v78
	v_mul_f32_e32 v84, v78, v84
	v_fma_f32 v84, v78, v84, v78
	v_add_f32_e32 v85, 1.0, v85
	v_rcp_f32_e32 v86, v85
	v_mul_f32_e32 v85, 0x3d372713, v79
	v_mul_f32_e32 v85, v79, v85
	v_fma_f32 v85, v79, v85, v79
	v_mul_f32_e32 v84, 0x3f4c422a, v84
	v_mul_f32_e32 v85, 0x3f4c422a, v85
	v_add_f32_e32 v84, v84, v84
	v_add_f32_e32 v85, v85, v85
	v_mul_f32_e32 v84, 0xbfb8aa3b, v84
	v_mul_f32_e32 v85, 0xbfb8aa3b, v85
	v_exp_f32_e32 v84, v84
	v_exp_f32_e32 v85, v85
	v_or_b32_e32 v82, 48, v144
	v_ashrrev_i32_e32 v83, 31, v82
	v_add_f32_e32 v84, 1.0, v84
	v_add_f32_e32 v85, 1.0, v85
	v_rcp_f32_e32 v84, v84
	v_rcp_f32_e32 v85, v85
	v_lshlrev_b64 v[82:83], 16, v[82:83]
	v_lshl_add_u64 v[82:83], v[146:147], 0, v[82:83]
	v_pk_mul_f32 v[78:79], v[78:79], v[84:85]
	v_mul_f32_e32 v84, 0x3d372713, v75
	v_mul_f32_e32 v84, v75, v84
	v_fma_f32 v84, v75, v84, v75
	v_mul_f32_e32 v84, 0x3f4c422a, v84
	v_add_f32_e32 v84, v84, v84
	v_mul_f32_e32 v84, 0xbfb8aa3b, v84
	v_exp_f32_e32 v84, v84
	s_nop 0
	v_add_f32_e32 v84, 1.0, v84
	v_rcp_f32_e32 v87, v84
	s_nop 0
	v_pk_mul_f32 v[84:85], v[74:75], v[86:87]
	v_mul_f32_e32 v75, 0x3d372713, v76
	v_mul_f32_e32 v75, v76, v75
	v_fma_f32 v75, v76, v75, v76
	v_mul_f32_e32 v75, 0x3f4c422a, v75
	v_add_f32_e32 v75, v75, v75
	v_mul_f32_e32 v75, 0xbfb8aa3b, v75
	v_exp_f32_e32 v75, v75
	v_mul_f32_e32 v74, 0x3d372713, v80
	v_mul_f32_e32 v74, v80, v74
	v_fma_f32 v74, v80, v74, v80
	v_add_f32_e32 v75, 1.0, v75
	v_rcp_f32_e32 v86, v75
	v_mul_f32_e32 v75, 0x3d372713, v81
	v_mul_f32_e32 v75, v81, v75
	v_fma_f32 v75, v81, v75, v81
	v_mul_f32_e32 v74, 0x3f4c422a, v74
	v_mul_f32_e32 v75, 0x3f4c422a, v75
	v_add_f32_e32 v74, v74, v74
	v_add_f32_e32 v75, v75, v75
	v_mul_f32_e32 v74, 0xbfb8aa3b, v74
	v_mul_f32_e32 v75, 0xbfb8aa3b, v75
	v_exp_f32_e32 v74, v74
	v_exp_f32_e32 v75, v75
	v_add_f32_e32 v74, 1.0, v74
	v_add_f32_e32 v75, 1.0, v75
	v_rcp_f32_e32 v74, v74
	v_rcp_f32_e32 v75, v75
	s_nop 0
	v_pk_mul_f32 v[80:81], v[80:81], v[74:75]
	v_mul_f32_e32 v74, 0x3d372713, v77
; DEVI float sigmoidf_(float x) { return __builtin_amdgcn_rcpf(1.f + __expf(-x)); }
; DEVI float siluf_(float x) { return x * __builtin_amdgcn_rcpf(1.f + __expf(-x)); }
; DEVI float logsigf_(float x) { return fminf(x, 0.f) - __logf(1.f + __expf(-fabsf(x))); }
	v_mul_f32_e32 v74, v77, v74
	v_fma_f32 v74, v77, v74, v77
	v_mul_f32_e32 v74, 0x3f4c422a, v74
	v_add_f32_e32 v74, v74, v74
	v_mul_f32_e32 v74, 0xbfb8aa3b, v74
	v_exp_f32_e32 v74, v74
	v_cvt_pk_bf16_f32 v75, v80, v81
	v_add_f32_e32 v74, 1.0, v74
	v_rcp_f32_e32 v87, v74
	v_cvt_pk_bf16_f32 v74, v78, v79
	v_lshl_add_u64 v[78:79], v[82:83], 0, v[122:123]
	v_pk_mul_f32 v[86:87], v[76:77], v[86:87]
	v_cvt_pk_bf16_f32 v76, v84, v85
	v_cvt_pk_bf16_f32 v77, v86, v87
	global_store_dwordx4 v[78:79], v[74:77], off
	s_nop 1
	v_mul_f32_e32 v75, 0x3d372713, v66
	v_mul_f32_e32 v75, v66, v75
	v_fma_f32 v75, v66, v75, v66
	v_mul_f32_e32 v75, 0x3f4c422a, v75
	v_add_f32_e32 v75, v75, v75
	v_mul_f32_e32 v75, 0xbfb8aa3b, v75
	v_exp_f32_e32 v75, v75
	v_mul_f32_e32 v74, 0x3d372713, v70
	v_mul_f32_e32 v74, v70, v74
	v_fma_f32 v74, v70, v74, v70
	v_add_f32_e32 v75, 1.0, v75
	v_rcp_f32_e32 v76, v75
	v_mul_f32_e32 v75, 0x3d372713, v71
	v_mul_f32_e32 v75, v71, v75
	v_fma_f32 v75, v71, v75, v71
	v_mul_f32_e32 v74, 0x3f4c422a, v74
	v_mul_f32_e32 v75, 0x3f4c422a, v75
	v_add_f32_e32 v74, v74, v74
	v_add_f32_e32 v75, v75, v75
	v_mul_f32_e32 v74, 0xbfb8aa3b, v74
	v_mul_f32_e32 v75, 0xbfb8aa3b, v75
	v_exp_f32_e32 v74, v74
	v_exp_f32_e32 v75, v75
	v_add_f32_e32 v74, 1.0, v74
	v_add_f32_e32 v75, 1.0, v75
	v_rcp_f32_e32 v74, v74
	v_rcp_f32_e32 v75, v75
	s_nop 0
	v_pk_mul_f32 v[70:71], v[70:71], v[74:75]
	v_mul_f32_e32 v74, 0x3d372713, v67
	v_mul_f32_e32 v74, v67, v74
	v_fma_f32 v74, v67, v74, v67
	v_mul_f32_e32 v74, 0x3f4c422a, v74
	v_add_f32_e32 v74, v74, v74
	v_mul_f32_e32 v74, 0xbfb8aa3b, v74
	v_exp_f32_e32 v74, v74
	s_nop 0
	v_add_f32_e32 v74, 1.0, v74
	v_rcp_f32_e32 v77, v74
	s_nop 0
	v_pk_mul_f32 v[74:75], v[66:67], v[76:77]
	v_mul_f32_e32 v67, 0x3d372713, v68
	v_mul_f32_e32 v67, v68, v67
	v_fma_f32 v67, v68, v67, v68
	v_mul_f32_e32 v67, 0x3f4c422a, v67
	v_add_f32_e32 v67, v67, v67
	v_mul_f32_e32 v67, 0xbfb8aa3b, v67
	v_exp_f32_e32 v67, v67
	v_mul_f32_e32 v66, 0x3d372713, v72
	v_mul_f32_e32 v66, v72, v66
	v_fma_f32 v66, v72, v66, v72
	v_add_f32_e32 v67, 1.0, v67
	v_rcp_f32_e32 v76, v67
	v_mul_f32_e32 v67, 0x3d372713, v73
	v_mul_f32_e32 v67, v73, v67
	v_fma_f32 v67, v73, v67, v73
	v_mul_f32_e32 v66, 0x3f4c422a, v66
	v_mul_f32_e32 v67, 0x3f4c422a, v67
	v_add_f32_e32 v66, v66, v66
	v_add_f32_e32 v67, v67, v67
	v_mul_f32_e32 v66, 0xbfb8aa3b, v66
	v_mul_f32_e32 v67, 0xbfb8aa3b, v67
	v_exp_f32_e32 v66, v66
	v_exp_f32_e32 v67, v67
	v_add_f32_e32 v66, 1.0, v66
	v_add_f32_e32 v67, 1.0, v67
	v_rcp_f32_e32 v66, v66
	v_rcp_f32_e32 v67, v67
	s_nop 0
	v_pk_mul_f32 v[72:73], v[72:73], v[66:67]
	v_mul_f32_e32 v66, 0x3d372713, v69
	v_mul_f32_e32 v66, v69, v66
	v_fma_f32 v66, v69, v66, v69
	v_mul_f32_e32 v66, 0x3f4c422a, v66
	v_add_f32_e32 v66, v66, v66
	v_mul_f32_e32 v66, 0xbfb8aa3b, v66
	v_exp_f32_e32 v66, v66
	v_cvt_pk_bf16_f32 v67, v72, v73
	v_add_f32_e32 v66, 1.0, v66
	v_rcp_f32_e32 v77, v66
	v_cvt_pk_bf16_f32 v66, v70, v71
	v_lshl_add_u64 v[70:71], v[82:83], 0, v[114:115]
	v_pk_mul_f32 v[76:77], v[68:69], v[76:77]
	v_cvt_pk_bf16_f32 v68, v74, v75
	v_cvt_pk_bf16_f32 v69, v76, v77
	global_store_dwordx4 v[70:71], v[66:69], off
	s_nop 1
	v_mul_f32_e32 v69, 0x3d372713, v58
	v_mul_f32_e32 v69, v58, v69
	v_fma_f32 v69, v58, v69, v58
	v_mul_f32_e32 v69, 0x3f4c422a, v69
	v_add_f32_e32 v69, v69, v69
	v_mul_f32_e32 v69, 0xbfb8aa3b, v69
	v_exp_f32_e32 v69, v69
	v_mul_f32_e32 v68, 0x3d372713, v62
	v_mul_f32_e32 v68, v62, v68
	v_fma_f32 v68, v62, v68, v62
	v_add_f32_e32 v69, 1.0, v69
	v_rcp_f32_e32 v70, v69
	v_mul_f32_e32 v69, 0x3d372713, v63
	v_mul_f32_e32 v69, v63, v69
	v_fma_f32 v69, v63, v69, v63
	v_mul_f32_e32 v68, 0x3f4c422a, v68
	v_mul_f32_e32 v69, 0x3f4c422a, v69
	v_add_f32_e32 v68, v68, v68
	v_add_f32_e32 v69, v69, v69
	v_mul_f32_e32 v68, 0xbfb8aa3b, v68
	v_mul_f32_e32 v69, 0xbfb8aa3b, v69
	v_exp_f32_e32 v68, v68
	v_exp_f32_e32 v69, v69
	v_lshl_add_u64 v[66:67], v[142:143], 0, s[0:1]
	s_mov_b64 s[0:1], 0x900000
	v_add_f32_e32 v68, 1.0, v68
	v_add_f32_e32 v69, 1.0, v69
	v_rcp_f32_e32 v68, v68
	v_rcp_f32_e32 v69, v69
	s_nop 0
	v_pk_mul_f32 v[62:63], v[62:63], v[68:69]
	v_mul_f32_e32 v68, 0x3d372713, v59
	v_mul_f32_e32 v68, v59, v68
	v_fma_f32 v68, v59, v68, v59
	v_mul_f32_e32 v68, 0x3f4c422a, v68
	v_add_f32_e32 v68, v68, v68
	v_mul_f32_e32 v68, 0xbfb8aa3b, v68
	v_exp_f32_e32 v68, v68
	s_nop 0
	v_add_f32_e32 v68, 1.0, v68
	v_rcp_f32_e32 v71, v68
	s_nop 0
	v_pk_mul_f32 v[68:69], v[58:59], v[70:71]
	v_mul_f32_e32 v59, 0x3d372713, v60
	v_mul_f32_e32 v59, v60, v59
	v_fma_f32 v59, v60, v59, v60
	v_mul_f32_e32 v59, 0x3f4c422a, v59
	v_add_f32_e32 v59, v59, v59
	v_mul_f32_e32 v59, 0xbfb8aa3b, v59
	v_exp_f32_e32 v59, v59
	v_mul_f32_e32 v58, 0x3d372713, v64
	v_mul_f32_e32 v58, v64, v58
	v_fma_f32 v58, v64, v58, v64
	v_add_f32_e32 v59, 1.0, v59
	v_rcp_f32_e32 v70, v59
	v_mul_f32_e32 v59, 0x3d372713, v65
	v_mul_f32_e32 v59, v65, v59
	v_fma_f32 v59, v65, v59, v65
	v_mul_f32_e32 v58, 0x3f4c422a, v58
	v_mul_f32_e32 v59, 0x3f4c422a, v59
	v_add_f32_e32 v58, v58, v58
	v_add_f32_e32 v59, v59, v59
	v_mul_f32_e32 v58, 0xbfb8aa3b, v58
	v_mul_f32_e32 v59, 0xbfb8aa3b, v59
	v_exp_f32_e32 v58, v58
	v_exp_f32_e32 v59, v59
	v_add_f32_e32 v58, 1.0, v58
	v_add_f32_e32 v59, 1.0, v59
	v_rcp_f32_e32 v58, v58
	v_rcp_f32_e32 v59, v59
	s_nop 0
	v_pk_mul_f32 v[64:65], v[64:65], v[58:59]
	v_mul_f32_e32 v58, 0x3d372713, v61
	v_mul_f32_e32 v58, v61, v58
	v_fma_f32 v58, v61, v58, v61
	v_mul_f32_e32 v58, 0x3f4c422a, v58
	v_add_f32_e32 v58, v58, v58
	v_mul_f32_e32 v58, 0xbfb8aa3b, v58
	v_exp_f32_e32 v58, v58
	v_cvt_pk_bf16_f32 v59, v64, v65
	v_add_f32_e32 v58, 1.0, v58
	v_rcp_f32_e32 v71, v58
	v_cvt_pk_bf16_f32 v58, v62, v63
; DEVI float sigmoidf_(float x) { return __builtin_amdgcn_rcpf(1.f + __expf(-x)); }
; DEVI float siluf_(float x) { return x * __builtin_amdgcn_rcpf(1.f + __expf(-x)); }
; DEVI float logsigf_(float x) { return fminf(x, 0.f) - __logf(1.f + __expf(-fabsf(x))); }
	v_lshl_add_u64 v[62:63], v[66:67], 0, v[122:123]
	v_pk_mul_f32 v[70:71], v[60:61], v[70:71]
	v_cvt_pk_bf16_f32 v60, v68, v69
	v_cvt_pk_bf16_f32 v61, v70, v71
	global_store_dwordx4 v[62:63], v[58:61], off
	s_nop 1
	v_mul_f32_e32 v59, 0x3d372713, v50
	v_mul_f32_e32 v59, v50, v59
	v_fma_f32 v59, v50, v59, v50
	v_mul_f32_e32 v59, 0x3f4c422a, v59
	v_add_f32_e32 v59, v59, v59
	v_mul_f32_e32 v59, 0xbfb8aa3b, v59
	v_exp_f32_e32 v59, v59
	v_mul_f32_e32 v58, 0x3d372713, v54
	v_mul_f32_e32 v58, v54, v58
	v_fma_f32 v58, v54, v58, v54
	v_add_f32_e32 v59, 1.0, v59
	v_rcp_f32_e32 v60, v59
	v_mul_f32_e32 v59, 0x3d372713, v55
	v_mul_f32_e32 v59, v55, v59
	v_fma_f32 v59, v55, v59, v55
	v_mul_f32_e32 v58, 0x3f4c422a, v58
	v_mul_f32_e32 v59, 0x3f4c422a, v59
	v_add_f32_e32 v58, v58, v58
	v_add_f32_e32 v59, v59, v59
	v_mul_f32_e32 v58, 0xbfb8aa3b, v58
	v_mul_f32_e32 v59, 0xbfb8aa3b, v59
	v_exp_f32_e32 v58, v58
	v_exp_f32_e32 v59, v59
	v_add_f32_e32 v58, 1.0, v58
	v_add_f32_e32 v59, 1.0, v59
	v_rcp_f32_e32 v58, v58
	v_rcp_f32_e32 v59, v59
	s_nop 0
	v_pk_mul_f32 v[54:55], v[54:55], v[58:59]
	v_mul_f32_e32 v58, 0x3d372713, v51
	v_mul_f32_e32 v58, v51, v58
	v_fma_f32 v58, v51, v58, v51
	v_mul_f32_e32 v58, 0x3f4c422a, v58
	v_add_f32_e32 v58, v58, v58
	v_mul_f32_e32 v58, 0xbfb8aa3b, v58
	v_exp_f32_e32 v58, v58
	s_nop 0
	v_add_f32_e32 v58, 1.0, v58
	v_rcp_f32_e32 v61, v58
	s_nop 0
	v_pk_mul_f32 v[58:59], v[50:51], v[60:61]
	v_mul_f32_e32 v51, 0x3d372713, v52
	v_mul_f32_e32 v51, v52, v51
	v_fma_f32 v51, v52, v51, v52
	v_mul_f32_e32 v51, 0x3f4c422a, v51
	v_add_f32_e32 v51, v51, v51
	v_mul_f32_e32 v51, 0xbfb8aa3b, v51
	v_exp_f32_e32 v51, v51
	v_mul_f32_e32 v50, 0x3d372713, v56
	v_mul_f32_e32 v50, v56, v50
	v_fma_f32 v50, v56, v50, v56
	v_add_f32_e32 v51, 1.0, v51
	v_rcp_f32_e32 v60, v51
	v_mul_f32_e32 v51, 0x3d372713, v57
	v_mul_f32_e32 v51, v57, v51
	v_fma_f32 v51, v57, v51, v57
	v_mul_f32_e32 v50, 0x3f4c422a, v50
	v_mul_f32_e32 v51, 0x3f4c422a, v51
	v_add_f32_e32 v50, v50, v50
	v_add_f32_e32 v51, v51, v51
	v_mul_f32_e32 v50, 0xbfb8aa3b, v50
	v_mul_f32_e32 v51, 0xbfb8aa3b, v51
	v_exp_f32_e32 v50, v50
	v_exp_f32_e32 v51, v51
	v_add_f32_e32 v50, 1.0, v50
	v_add_f32_e32 v51, 1.0, v51
	v_rcp_f32_e32 v50, v50
	v_rcp_f32_e32 v51, v51
	s_nop 0
	v_pk_mul_f32 v[56:57], v[56:57], v[50:51]
	v_mul_f32_e32 v50, 0x3d372713, v53
	v_mul_f32_e32 v50, v53, v50
	v_fma_f32 v50, v53, v50, v53
	v_mul_f32_e32 v50, 0x3f4c422a, v50
	v_add_f32_e32 v50, v50, v50
	v_mul_f32_e32 v50, 0xbfb8aa3b, v50
	v_exp_f32_e32 v50, v50
	v_cvt_pk_bf16_f32 v51, v56, v57
	v_add_f32_e32 v50, 1.0, v50
	v_rcp_f32_e32 v61, v50
	v_cvt_pk_bf16_f32 v50, v54, v55
	v_lshl_add_u64 v[54:55], v[66:67], 0, v[114:115]
	v_pk_mul_f32 v[60:61], v[52:53], v[60:61]
	v_cvt_pk_bf16_f32 v52, v58, v59
	v_cvt_pk_bf16_f32 v53, v60, v61
	global_store_dwordx4 v[54:55], v[50:53], off
	s_nop 1
	v_mul_f32_e32 v53, 0x3d372713, v42
	v_mul_f32_e32 v53, v42, v53
	v_fma_f32 v53, v42, v53, v42
	v_mul_f32_e32 v53, 0x3f4c422a, v53
	v_add_f32_e32 v53, v53, v53
	v_mul_f32_e32 v53, 0xbfb8aa3b, v53
	v_exp_f32_e32 v53, v53
	v_mul_f32_e32 v52, 0x3d372713, v46
	v_mul_f32_e32 v52, v46, v52
	v_fma_f32 v52, v46, v52, v46
	v_add_f32_e32 v53, 1.0, v53
	v_rcp_f32_e32 v54, v53
	v_mul_f32_e32 v53, 0x3d372713, v47
	v_mul_f32_e32 v53, v47, v53
	v_fma_f32 v53, v47, v53, v47
	v_mul_f32_e32 v52, 0x3f4c422a, v52
	v_mul_f32_e32 v53, 0x3f4c422a, v53
	v_add_f32_e32 v52, v52, v52
	v_add_f32_e32 v53, v53, v53
	v_mul_f32_e32 v52, 0xbfb8aa3b, v52
	v_mul_f32_e32 v53, 0xbfb8aa3b, v53
	v_exp_f32_e32 v52, v52
	v_exp_f32_e32 v53, v53
	v_lshl_add_u64 v[50:51], v[142:143], 0, s[0:1]
	s_mov_b64 s[0:1], 0xa00000
	v_add_f32_e32 v52, 1.0, v52
	v_add_f32_e32 v53, 1.0, v53
	v_rcp_f32_e32 v52, v52
	v_rcp_f32_e32 v53, v53
	s_nop 0
	v_pk_mul_f32 v[46:47], v[46:47], v[52:53]
	v_mul_f32_e32 v52, 0x3d372713, v43
	v_mul_f32_e32 v52, v43, v52
	v_fma_f32 v52, v43, v52, v43
	v_mul_f32_e32 v52, 0x3f4c422a, v52
	v_add_f32_e32 v52, v52, v52
	v_mul_f32_e32 v52, 0xbfb8aa3b, v52
	v_exp_f32_e32 v52, v52
	s_nop 0
	v_add_f32_e32 v52, 1.0, v52
	v_rcp_f32_e32 v55, v52
	s_nop 0
	v_pk_mul_f32 v[52:53], v[42:43], v[54:55]
	v_mul_f32_e32 v43, 0x3d372713, v44
	v_mul_f32_e32 v43, v44, v43
	v_fma_f32 v43, v44, v43, v44
	v_mul_f32_e32 v43, 0x3f4c422a, v43
	v_add_f32_e32 v43, v43, v43
	v_mul_f32_e32 v43, 0xbfb8aa3b, v43
	v_exp_f32_e32 v43, v43
	v_mul_f32_e32 v42, 0x3d372713, v48
	v_mul_f32_e32 v42, v48, v42
	v_fma_f32 v42, v48, v42, v48
	v_add_f32_e32 v43, 1.0, v43
	v_rcp_f32_e32 v54, v43
	v_mul_f32_e32 v43, 0x3d372713, v49
	v_mul_f32_e32 v43, v49, v43
	v_fma_f32 v43, v49, v43, v49
	v_mul_f32_e32 v42, 0x3f4c422a, v42
	v_mul_f32_e32 v43, 0x3f4c422a, v43
	v_add_f32_e32 v42, v42, v42
	v_add_f32_e32 v43, v43, v43
	v_mul_f32_e32 v42, 0xbfb8aa3b, v42
	v_mul_f32_e32 v43, 0xbfb8aa3b, v43
	v_exp_f32_e32 v42, v42
	v_exp_f32_e32 v43, v43
	v_add_f32_e32 v42, 1.0, v42
	v_add_f32_e32 v43, 1.0, v43
	v_rcp_f32_e32 v42, v42
	v_rcp_f32_e32 v43, v43
	s_nop 0
	v_pk_mul_f32 v[48:49], v[48:49], v[42:43]
	v_mul_f32_e32 v42, 0x3d372713, v45
	v_mul_f32_e32 v42, v45, v42
	v_fma_f32 v42, v45, v42, v45
	v_mul_f32_e32 v42, 0x3f4c422a, v42
	v_add_f32_e32 v42, v42, v42
	v_mul_f32_e32 v42, 0xbfb8aa3b, v42
	v_exp_f32_e32 v42, v42
	v_cvt_pk_bf16_f32 v43, v48, v49
	v_add_f32_e32 v42, 1.0, v42
	v_rcp_f32_e32 v55, v42
	v_cvt_pk_bf16_f32 v42, v46, v47
	v_lshl_add_u64 v[46:47], v[50:51], 0, v[122:123]
	v_pk_mul_f32 v[54:55], v[44:45], v[54:55]
	v_cvt_pk_bf16_f32 v44, v52, v53
	v_cvt_pk_bf16_f32 v45, v54, v55
	global_store_dwordx4 v[46:47], v[42:45], off
	s_nop 1
	v_mul_f32_e32 v43, 0x3d372713, v34
	v_mul_f32_e32 v43, v34, v43
	v_fma_f32 v43, v34, v43, v34
; DEVI float sigmoidf_(float x) { return __builtin_amdgcn_rcpf(1.f + __expf(-x)); }
; DEVI float siluf_(float x) { return x * __builtin_amdgcn_rcpf(1.f + __expf(-x)); }
; DEVI float logsigf_(float x) { return fminf(x, 0.f) - __logf(1.f + __expf(-fabsf(x))); }
	v_mul_f32_e32 v43, 0x3f4c422a, v43
	v_add_f32_e32 v43, v43, v43
	v_mul_f32_e32 v43, 0xbfb8aa3b, v43
	v_exp_f32_e32 v43, v43
	v_mul_f32_e32 v42, 0x3d372713, v38
	v_mul_f32_e32 v42, v38, v42
	v_fma_f32 v42, v38, v42, v38
	v_add_f32_e32 v43, 1.0, v43
	v_rcp_f32_e32 v44, v43
	v_mul_f32_e32 v43, 0x3d372713, v39
	v_mul_f32_e32 v43, v39, v43
	v_fma_f32 v43, v39, v43, v39
	v_mul_f32_e32 v42, 0x3f4c422a, v42
	v_mul_f32_e32 v43, 0x3f4c422a, v43
	v_add_f32_e32 v42, v42, v42
	v_add_f32_e32 v43, v43, v43
	v_mul_f32_e32 v42, 0xbfb8aa3b, v42
	v_mul_f32_e32 v43, 0xbfb8aa3b, v43
	v_exp_f32_e32 v42, v42
	v_exp_f32_e32 v43, v43
	v_add_f32_e32 v42, 1.0, v42
	v_add_f32_e32 v43, 1.0, v43
	v_rcp_f32_e32 v42, v42
	v_rcp_f32_e32 v43, v43
	s_nop 0
	v_pk_mul_f32 v[38:39], v[38:39], v[42:43]
	v_mul_f32_e32 v42, 0x3d372713, v35
	v_mul_f32_e32 v42, v35, v42
	v_fma_f32 v42, v35, v42, v35
	v_mul_f32_e32 v42, 0x3f4c422a, v42
	v_add_f32_e32 v42, v42, v42
	v_mul_f32_e32 v42, 0xbfb8aa3b, v42
	v_exp_f32_e32 v42, v42
	s_nop 0
	v_add_f32_e32 v42, 1.0, v42
	v_rcp_f32_e32 v45, v42
	s_nop 0
	v_pk_mul_f32 v[42:43], v[34:35], v[44:45]
	v_mul_f32_e32 v35, 0x3d372713, v36
	v_mul_f32_e32 v35, v36, v35
	v_fma_f32 v35, v36, v35, v36
	v_mul_f32_e32 v35, 0x3f4c422a, v35
	v_add_f32_e32 v35, v35, v35
	v_mul_f32_e32 v35, 0xbfb8aa3b, v35
	v_exp_f32_e32 v35, v35
	v_mul_f32_e32 v34, 0x3d372713, v40
	v_mul_f32_e32 v34, v40, v34
	v_fma_f32 v34, v40, v34, v40
	v_add_f32_e32 v35, 1.0, v35
	v_rcp_f32_e32 v44, v35
	v_mul_f32_e32 v35, 0x3d372713, v41
	v_mul_f32_e32 v35, v41, v35
	v_fma_f32 v35, v41, v35, v41
	v_mul_f32_e32 v34, 0x3f4c422a, v34
	v_mul_f32_e32 v35, 0x3f4c422a, v35
	v_add_f32_e32 v34, v34, v34
	v_add_f32_e32 v35, v35, v35
	v_mul_f32_e32 v34, 0xbfb8aa3b, v34
	v_mul_f32_e32 v35, 0xbfb8aa3b, v35
	v_exp_f32_e32 v34, v34
	v_exp_f32_e32 v35, v35
	v_add_f32_e32 v34, 1.0, v34
	v_add_f32_e32 v35, 1.0, v35
	v_rcp_f32_e32 v34, v34
	v_rcp_f32_e32 v35, v35
	s_nop 0
	v_pk_mul_f32 v[40:41], v[40:41], v[34:35]
	v_mul_f32_e32 v34, 0x3d372713, v37
	v_mul_f32_e32 v34, v37, v34
	v_fma_f32 v34, v37, v34, v37
	v_mul_f32_e32 v34, 0x3f4c422a, v34
	v_add_f32_e32 v34, v34, v34
	v_mul_f32_e32 v34, 0xbfb8aa3b, v34
	v_exp_f32_e32 v34, v34
	v_cvt_pk_bf16_f32 v35, v40, v41
	v_add_f32_e32 v34, 1.0, v34
	v_rcp_f32_e32 v45, v34
	v_cvt_pk_bf16_f32 v34, v38, v39
	v_lshl_add_u64 v[38:39], v[50:51], 0, v[114:115]
	v_pk_mul_f32 v[44:45], v[36:37], v[44:45]
	v_cvt_pk_bf16_f32 v36, v42, v43
	v_cvt_pk_bf16_f32 v37, v44, v45
	global_store_dwordx4 v[38:39], v[34:37], off
	s_nop 1
	v_mul_f32_e32 v37, 0x3d372713, v26
	v_mul_f32_e32 v37, v26, v37
	v_fma_f32 v37, v26, v37, v26
	v_mul_f32_e32 v37, 0x3f4c422a, v37
	v_add_f32_e32 v37, v37, v37
	v_mul_f32_e32 v37, 0xbfb8aa3b, v37
	v_exp_f32_e32 v37, v37
	v_mul_f32_e32 v36, 0x3d372713, v30
	v_mul_f32_e32 v36, v30, v36
	v_fma_f32 v36, v30, v36, v30
	v_add_f32_e32 v37, 1.0, v37
	v_rcp_f32_e32 v38, v37
	v_mul_f32_e32 v37, 0x3d372713, v31
	v_mul_f32_e32 v37, v31, v37
	v_fma_f32 v37, v31, v37, v31
	v_mul_f32_e32 v36, 0x3f4c422a, v36
	v_mul_f32_e32 v37, 0x3f4c422a, v37
	v_add_f32_e32 v36, v36, v36
	v_add_f32_e32 v37, v37, v37
	v_mul_f32_e32 v36, 0xbfb8aa3b, v36
	v_mul_f32_e32 v37, 0xbfb8aa3b, v37
	v_exp_f32_e32 v36, v36
	v_exp_f32_e32 v37, v37
	v_lshl_add_u64 v[34:35], v[142:143], 0, s[0:1]
	s_mov_b64 s[0:1], 0xb00000
	v_add_f32_e32 v36, 1.0, v36
	v_add_f32_e32 v37, 1.0, v37
	v_rcp_f32_e32 v36, v36
	v_rcp_f32_e32 v37, v37
	s_nop 0
	v_pk_mul_f32 v[30:31], v[30:31], v[36:37]
	v_mul_f32_e32 v36, 0x3d372713, v27
	v_mul_f32_e32 v36, v27, v36
	v_fma_f32 v36, v27, v36, v27
	v_mul_f32_e32 v36, 0x3f4c422a, v36
	v_add_f32_e32 v36, v36, v36
	v_mul_f32_e32 v36, 0xbfb8aa3b, v36
	v_exp_f32_e32 v36, v36
	s_nop 0
	v_add_f32_e32 v36, 1.0, v36
	v_rcp_f32_e32 v39, v36
	s_nop 0
	v_pk_mul_f32 v[36:37], v[26:27], v[38:39]
	v_mul_f32_e32 v27, 0x3d372713, v28
	v_mul_f32_e32 v27, v28, v27
	v_fma_f32 v27, v28, v27, v28
	v_mul_f32_e32 v27, 0x3f4c422a, v27
	v_add_f32_e32 v27, v27, v27
	v_mul_f32_e32 v27, 0xbfb8aa3b, v27
	v_exp_f32_e32 v27, v27
	v_mul_f32_e32 v26, 0x3d372713, v32
	v_mul_f32_e32 v26, v32, v26
	v_fma_f32 v26, v32, v26, v32
	v_add_f32_e32 v27, 1.0, v27
	v_rcp_f32_e32 v38, v27
	v_mul_f32_e32 v27, 0x3d372713, v33
	v_mul_f32_e32 v27, v33, v27
	v_fma_f32 v27, v33, v27, v33
	v_mul_f32_e32 v26, 0x3f4c422a, v26
	v_mul_f32_e32 v27, 0x3f4c422a, v27
	v_add_f32_e32 v26, v26, v26
	v_add_f32_e32 v27, v27, v27
	v_mul_f32_e32 v26, 0xbfb8aa3b, v26
	v_mul_f32_e32 v27, 0xbfb8aa3b, v27
	v_exp_f32_e32 v26, v26
	v_exp_f32_e32 v27, v27
	v_add_f32_e32 v26, 1.0, v26
	v_add_f32_e32 v27, 1.0, v27
	v_rcp_f32_e32 v26, v26
	v_rcp_f32_e32 v27, v27
	s_nop 0
	v_pk_mul_f32 v[32:33], v[32:33], v[26:27]
	v_mul_f32_e32 v26, 0x3d372713, v29
	v_mul_f32_e32 v26, v29, v26
	v_fma_f32 v26, v29, v26, v29
	v_mul_f32_e32 v26, 0x3f4c422a, v26
	v_add_f32_e32 v26, v26, v26
	v_mul_f32_e32 v26, 0xbfb8aa3b, v26
	v_exp_f32_e32 v26, v26
	v_cvt_pk_bf16_f32 v27, v32, v33
	v_add_f32_e32 v26, 1.0, v26
	v_rcp_f32_e32 v39, v26
	v_cvt_pk_bf16_f32 v26, v30, v31
	v_lshl_add_u64 v[30:31], v[34:35], 0, v[122:123]
	v_pk_mul_f32 v[38:39], v[28:29], v[38:39]
	v_cvt_pk_bf16_f32 v28, v36, v37
	v_cvt_pk_bf16_f32 v29, v38, v39
	global_store_dwordx4 v[30:31], v[26:29], off
	s_nop 1
	v_mul_f32_e32 v27, 0x3d372713, v18
	v_mul_f32_e32 v27, v18, v27
	v_fma_f32 v27, v18, v27, v18
	v_mul_f32_e32 v27, 0x3f4c422a, v27
	v_add_f32_e32 v27, v27, v27
	v_mul_f32_e32 v27, 0xbfb8aa3b, v27
	v_exp_f32_e32 v27, v27
	v_mul_f32_e32 v26, 0x3d372713, v22
	v_mul_f32_e32 v26, v22, v26
	v_fma_f32 v26, v22, v26, v22
	v_add_f32_e32 v27, 1.0, v27
	v_rcp_f32_e32 v28, v27
	v_mul_f32_e32 v27, 0x3d372713, v23
; DEVI float sigmoidf_(float x) { return __builtin_amdgcn_rcpf(1.f + __expf(-x)); }
; DEVI float siluf_(float x) { return x * __builtin_amdgcn_rcpf(1.f + __expf(-x)); }
; DEVI float logsigf_(float x) { return fminf(x, 0.f) - __logf(1.f + __expf(-fabsf(x))); }
	v_mul_f32_e32 v27, v23, v27
	v_fma_f32 v27, v23, v27, v23
	v_mul_f32_e32 v26, 0x3f4c422a, v26
	v_mul_f32_e32 v27, 0x3f4c422a, v27
	v_add_f32_e32 v26, v26, v26
	v_add_f32_e32 v27, v27, v27
	v_mul_f32_e32 v26, 0xbfb8aa3b, v26
	v_mul_f32_e32 v27, 0xbfb8aa3b, v27
	v_exp_f32_e32 v26, v26
	v_exp_f32_e32 v27, v27
	v_add_f32_e32 v26, 1.0, v26
	v_add_f32_e32 v27, 1.0, v27
	v_rcp_f32_e32 v26, v26
	v_rcp_f32_e32 v27, v27
	s_nop 0
	v_pk_mul_f32 v[22:23], v[22:23], v[26:27]
	v_mul_f32_e32 v26, 0x3d372713, v19
	v_mul_f32_e32 v26, v19, v26
	v_fma_f32 v26, v19, v26, v19
	v_mul_f32_e32 v26, 0x3f4c422a, v26
	v_add_f32_e32 v26, v26, v26
	v_mul_f32_e32 v26, 0xbfb8aa3b, v26
	v_exp_f32_e32 v26, v26
	s_nop 0
	v_add_f32_e32 v26, 1.0, v26
	v_rcp_f32_e32 v29, v26
	s_nop 0
	v_pk_mul_f32 v[26:27], v[18:19], v[28:29]
	v_mul_f32_e32 v19, 0x3d372713, v20
	v_mul_f32_e32 v19, v20, v19
	v_fma_f32 v19, v20, v19, v20
	v_mul_f32_e32 v19, 0x3f4c422a, v19
	v_add_f32_e32 v19, v19, v19
	v_mul_f32_e32 v19, 0xbfb8aa3b, v19
	v_exp_f32_e32 v19, v19
	v_mul_f32_e32 v18, 0x3d372713, v24
	v_mul_f32_e32 v18, v24, v18
	v_fma_f32 v18, v24, v18, v24
	v_add_f32_e32 v19, 1.0, v19
	v_rcp_f32_e32 v28, v19
	v_mul_f32_e32 v19, 0x3d372713, v25
	v_mul_f32_e32 v19, v25, v19
	v_fma_f32 v19, v25, v19, v25
	v_mul_f32_e32 v18, 0x3f4c422a, v18
	v_mul_f32_e32 v19, 0x3f4c422a, v19
	v_add_f32_e32 v18, v18, v18
	v_add_f32_e32 v19, v19, v19
	v_mul_f32_e32 v18, 0xbfb8aa3b, v18
	v_mul_f32_e32 v19, 0xbfb8aa3b, v19
	v_exp_f32_e32 v18, v18
	v_exp_f32_e32 v19, v19
	v_add_f32_e32 v18, 1.0, v18
	v_add_f32_e32 v19, 1.0, v19
	v_rcp_f32_e32 v18, v18
	v_rcp_f32_e32 v19, v19
	s_nop 0
	v_pk_mul_f32 v[24:25], v[24:25], v[18:19]
	v_mul_f32_e32 v18, 0x3d372713, v21
	v_mul_f32_e32 v18, v21, v18
	v_fma_f32 v18, v21, v18, v21
	v_mul_f32_e32 v18, 0x3f4c422a, v18
	v_add_f32_e32 v18, v18, v18
	v_mul_f32_e32 v18, 0xbfb8aa3b, v18
	v_exp_f32_e32 v18, v18
	v_cvt_pk_bf16_f32 v19, v24, v25
	v_add_f32_e32 v18, 1.0, v18
	v_rcp_f32_e32 v29, v18
	v_cvt_pk_bf16_f32 v18, v22, v23
	v_lshl_add_u64 v[22:23], v[34:35], 0, v[114:115]
	v_pk_mul_f32 v[28:29], v[20:21], v[28:29]
	v_cvt_pk_bf16_f32 v20, v26, v27
	v_cvt_pk_bf16_f32 v21, v28, v29
	global_store_dwordx4 v[22:23], v[18:21], off
	s_nop 1
	v_mul_f32_e32 v21, 0x3d372713, v10
	v_mul_f32_e32 v21, v10, v21
	v_fma_f32 v21, v10, v21, v10
	v_mul_f32_e32 v21, 0x3f4c422a, v21
	v_add_f32_e32 v21, v21, v21
	v_mul_f32_e32 v21, 0xbfb8aa3b, v21
	v_exp_f32_e32 v21, v21
	v_mul_f32_e32 v20, 0x3d372713, v14
	v_mul_f32_e32 v20, v14, v20
	v_fma_f32 v20, v14, v20, v14
	v_add_f32_e32 v21, 1.0, v21
	v_rcp_f32_e32 v22, v21
	v_mul_f32_e32 v21, 0x3d372713, v15
	v_mul_f32_e32 v21, v15, v21
	v_fma_f32 v21, v15, v21, v15
	v_mul_f32_e32 v20, 0x3f4c422a, v20
	v_mul_f32_e32 v21, 0x3f4c422a, v21
	v_add_f32_e32 v20, v20, v20
	v_add_f32_e32 v21, v21, v21
	v_mul_f32_e32 v20, 0xbfb8aa3b, v20
	v_mul_f32_e32 v21, 0xbfb8aa3b, v21
	v_exp_f32_e32 v20, v20
	v_exp_f32_e32 v21, v21
	v_lshl_add_u64 v[18:19], v[142:143], 0, s[0:1]
	s_mov_b32 s0, s8
	v_add_f32_e32 v20, 1.0, v20
	v_add_f32_e32 v21, 1.0, v21
	v_rcp_f32_e32 v20, v20
	v_rcp_f32_e32 v21, v21
	s_mov_b32 s1, s9
	v_pk_mul_f32 v[14:15], v[14:15], v[20:21]
	v_mul_f32_e32 v20, 0x3d372713, v11
	v_mul_f32_e32 v20, v11, v20
	v_fma_f32 v20, v11, v20, v11
	v_mul_f32_e32 v20, 0x3f4c422a, v20
	v_add_f32_e32 v20, v20, v20
	v_mul_f32_e32 v20, 0xbfb8aa3b, v20
	v_exp_f32_e32 v20, v20
	s_nop 0
	v_add_f32_e32 v20, 1.0, v20
	v_rcp_f32_e32 v23, v20
	s_nop 0
	v_pk_mul_f32 v[20:21], v[10:11], v[22:23]
	v_mul_f32_e32 v11, 0x3d372713, v12
	v_mul_f32_e32 v11, v12, v11
	v_fma_f32 v11, v12, v11, v12
	v_mul_f32_e32 v11, 0x3f4c422a, v11
	v_add_f32_e32 v11, v11, v11
	v_mul_f32_e32 v11, 0xbfb8aa3b, v11
	v_exp_f32_e32 v11, v11
	v_mul_f32_e32 v10, 0x3d372713, v16
; #define PG8_WAIT_V(n) asm volatile("s_waitcnt vmcnt(" #n ")" ::: "memory")
; #define PG8_BAR __builtin_amdgcn_s_barrier()
; template <class Epi>
; DEVI void gemm_phase(LAS unsigned char* lds, const Gemm g, const Epi& E) {
;     ...
;         if (!has_next) break;
; #pragma unroll
;         for (int a = 0; a < 2; ++a)
; #pragma unroll
;             for (int b = 0; b < 2; ++b)
; #pragma unroll
;                 for (int m = 0; m < 4; ++m)
; #pragma unroll
;                     for (int n = 0; n < 2; ++n) acc[a][b][m][n] = (f32x4){0.f, 0.f, 0.f, 0.f};
;         cur = nxt; cA = nA; cB = nB; ++ui;
;     }
;     PG8_WAIT_V(0);
;     if (wr == 0) PG8_BAR;
;     PG8_BAR;
	v_mul_f32_e32 v10, v16, v10
	v_fma_f32 v10, v16, v10, v16
	v_add_f32_e32 v11, 1.0, v11
	v_rcp_f32_e32 v22, v11
	v_mul_f32_e32 v11, 0x3d372713, v17
	v_mul_f32_e32 v11, v17, v11
	v_fma_f32 v11, v17, v11, v17
	v_mul_f32_e32 v10, 0x3f4c422a, v10
	v_mul_f32_e32 v11, 0x3f4c422a, v11
	v_add_f32_e32 v10, v10, v10
	v_add_f32_e32 v11, v11, v11
	v_mul_f32_e32 v10, 0xbfb8aa3b, v10
	v_mul_f32_e32 v11, 0xbfb8aa3b, v11
	v_exp_f32_e32 v10, v10
	v_exp_f32_e32 v11, v11
	v_add_f32_e32 v10, 1.0, v10
	v_add_f32_e32 v11, 1.0, v11
	v_rcp_f32_e32 v10, v10
	v_rcp_f32_e32 v11, v11
	s_nop 0
	v_pk_mul_f32 v[16:17], v[16:17], v[10:11]
	v_mul_f32_e32 v10, 0x3d372713, v13
	v_mul_f32_e32 v10, v13, v10
	v_fma_f32 v10, v13, v10, v13
	v_mul_f32_e32 v10, 0x3f4c422a, v10
	v_add_f32_e32 v10, v10, v10
	v_mul_f32_e32 v10, 0xbfb8aa3b, v10
	v_exp_f32_e32 v10, v10
	v_cvt_pk_bf16_f32 v11, v16, v17
	v_add_f32_e32 v10, 1.0, v10
	v_rcp_f32_e32 v23, v10
	v_cvt_pk_bf16_f32 v10, v14, v15
	v_lshl_add_u64 v[14:15], v[18:19], 0, v[122:123]
	v_pk_mul_f32 v[22:23], v[12:13], v[22:23]
	v_cvt_pk_bf16_f32 v12, v20, v21
	v_cvt_pk_bf16_f32 v13, v22, v23
	global_store_dwordx4 v[14:15], v[10:13], off
	s_nop 1
	v_mul_f32_e32 v11, 0x3d372713, v0
	v_mul_f32_e32 v11, v0, v11
	v_fma_f32 v11, v0, v11, v0
	v_mul_f32_e32 v11, 0x3f4c422a, v11
	v_add_f32_e32 v11, v11, v11
	v_mul_f32_e32 v11, 0xbfb8aa3b, v11
	v_exp_f32_e32 v11, v11
	v_mul_f32_e32 v10, 0x3d372713, v4
	v_mul_f32_e32 v10, v4, v10
	v_fma_f32 v10, v4, v10, v4
	v_add_f32_e32 v11, 1.0, v11
	v_rcp_f32_e32 v12, v11
	v_mul_f32_e32 v11, 0x3d372713, v5
	v_mul_f32_e32 v11, v5, v11
	v_fma_f32 v11, v5, v11, v5
	v_mul_f32_e32 v10, 0x3f4c422a, v10
	v_mul_f32_e32 v11, 0x3f4c422a, v11
	v_add_f32_e32 v10, v10, v10
	v_add_f32_e32 v11, v11, v11
	v_mul_f32_e32 v10, 0xbfb8aa3b, v10
	v_mul_f32_e32 v11, 0xbfb8aa3b, v11
	v_exp_f32_e32 v10, v10
	v_exp_f32_e32 v11, v11
	v_add_f32_e32 v10, 1.0, v10
	v_add_f32_e32 v11, 1.0, v11
	v_rcp_f32_e32 v10, v10
	v_rcp_f32_e32 v11, v11
	s_nop 0
	v_pk_mul_f32 v[4:5], v[4:5], v[10:11]
	v_mul_f32_e32 v10, 0x3d372713, v1
	v_mul_f32_e32 v10, v1, v10
	v_fma_f32 v10, v1, v10, v1
	v_mul_f32_e32 v10, 0x3f4c422a, v10
	v_add_f32_e32 v10, v10, v10
	v_mul_f32_e32 v10, 0xbfb8aa3b, v10
	v_exp_f32_e32 v10, v10
	s_nop 0
	v_add_f32_e32 v10, 1.0, v10
	v_rcp_f32_e32 v13, v10
	s_nop 0
	v_pk_mul_f32 v[10:11], v[0:1], v[12:13]
	v_mul_f32_e32 v1, 0x3d372713, v2
	v_mul_f32_e32 v1, v2, v1
	v_fma_f32 v1, v2, v1, v2
	v_mul_f32_e32 v1, 0x3f4c422a, v1
	v_add_f32_e32 v1, v1, v1
	v_mul_f32_e32 v1, 0xbfb8aa3b, v1
	v_exp_f32_e32 v1, v1
	v_mul_f32_e32 v0, 0x3d372713, v6
	v_mul_f32_e32 v0, v6, v0
	v_fma_f32 v0, v6, v0, v6
	v_add_f32_e32 v1, 1.0, v1
	v_rcp_f32_e32 v12, v1
	v_mul_f32_e32 v1, 0x3d372713, v7
	v_mul_f32_e32 v1, v7, v1
	v_fma_f32 v1, v7, v1, v7
	v_mul_f32_e32 v0, 0x3f4c422a, v0
	v_mul_f32_e32 v1, 0x3f4c422a, v1
	v_add_f32_e32 v0, v0, v0
	v_add_f32_e32 v1, v1, v1
	v_mul_f32_e32 v0, 0xbfb8aa3b, v0
	v_mul_f32_e32 v1, 0xbfb8aa3b, v1
	v_exp_f32_e32 v0, v0
	v_exp_f32_e32 v1, v1
	v_add_f32_e32 v0, 1.0, v0
	v_add_f32_e32 v1, 1.0, v1
	v_rcp_f32_e32 v0, v0
	v_rcp_f32_e32 v1, v1
	s_nop 0
	v_pk_mul_f32 v[6:7], v[6:7], v[0:1]
	v_mul_f32_e32 v0, 0x3d372713, v3
	v_mul_f32_e32 v0, v3, v0
	v_fma_f32 v0, v3, v0, v3
	v_mul_f32_e32 v0, 0x3f4c422a, v0
	v_add_f32_e32 v0, v0, v0
	v_mul_f32_e32 v0, 0xbfb8aa3b, v0
	v_exp_f32_e32 v0, v0
	v_cvt_pk_bf16_f32 v1, v6, v7
	v_add_f32_e32 v0, 1.0, v0
	v_rcp_f32_e32 v13, v0
	v_cvt_pk_bf16_f32 v0, v4, v5
	v_lshl_add_u64 v[4:5], v[18:19], 0, v[114:115]
	v_pk_mul_f32 v[12:13], v[2:3], v[12:13]
	v_cvt_pk_bf16_f32 v2, v10, v11
	v_cvt_pk_bf16_f32 v3, v12, v13
	global_store_dwordx4 v[4:5], v[0:3], off
	s_cbranch_vccz .LBB0_1271
	s_waitcnt vmcnt(0)
	s_cmpk_gt_u32 s36, 0xff
	s_cbranch_scc1 .LBB0_1282
	s_barrier

; #define PG8_STAGE(bufoff, gbase, voff) do { _Pragma("unroll") for (int _i = 0; _i < 2; ++_i) \
;         __builtin_amdgcn_global_load_lds((const unsigned*)((const char*)(gbase) + (voff)[_i]), (LAS unsigned*)(lds + (bufoff) + ldsw + _i * 8192), 16, 0, 0); } while (0)
; #define PG8_LDA(dst, b, h) do { _Pragma("unroll") for (int m = 0; m < 4; ++m) _Pragma("unroll") for (int k = 0; k < 2; ++k) dst[m][k] = *(const LAS bf16x8*)(lds + PG8_SA(b, h) + aoff + m * 2048 + k * 1024); } while (0)
; #define PG8_WAIT_V(n) asm volatile("s_waitcnt vmcnt(" #n ")" ::: "memory")
; #define PG8_WAIT_L(n) asm volatile("s_waitcnt lgkmcnt(" #n ")" ::: "memory")
; template <class Epi>
; DEVI void gemm_phase(LAS unsigned char* lds, const Gemm g, const Epi& E) {
;     ...
;         for (int t = 0; t < nt; t += 2) {
;             const bool last = (t == nt - 2);
;             const char* a1 = cA + (size_t)(t + 1) * kstep;
;             const char* a2 = last ? nA : cA + (size_t)(t + 2) * kstep; const char* b2 = last ? nB : cB + (size_t)(t + 2) * kstep;
;             const char* a3 = a2 + kstep; const char* b3 = b2 + kstep;
;             PG8_LDB(B0, 0, 0); PG8_SCHED; PG8_LDA(At, 0, 0); PG8_STAGE(PG8_SA(1, 1), a1 + hstepA, voffA);
;             PG8_WAIT_L(8); PG8_BAR; PG8_WAIT_L(0); PG8_MMA(0, 0, At, B0); PG8_BAR; PG8_SCHED;
;             PG8_LDB(B1, 0, 1); PG8_STAGE(PG8_SB(0, 0), b2, voffB);
;             PG8_BAR; PG8_WAIT_L(0); PG8_MMA(0, 1, At, B1); PG8_BAR;
;             PG8_LDA(At, 0, 1); PG8_STAGE(PG8_SA(0, 0), a2, voffA);
;             PG8_BAR; PG8_WAIT_L(0); PG8_MMA(1, 0, At, B0); PG8_BAR; PG8_SCHED;
;             PG8_STAGE(PG8_SB(0, 1), b2 + hstepB, voffB);
;             PG8_WAIT_V(6); PG8_BAR; PG8_MMA(1, 1, At, B1); PG8_BAR;
;             PG8_LDB(B0, 1, 0); PG8_SCHED; PG8_LDA(At, 1, 0); PG8_STAGE(PG8_SA(0, 1), a2 + hstepA, voffA);
;             PG8_WAIT_L(8); PG8_BAR; PG8_WAIT_L(0); PG8_MMA(0, 0, At, B0); PG8_BAR; PG8_SCHED;
;             PG8_LDB(B1, 1, 1); PG8_STAGE(PG8_SB(1, 0), b3, voffB);
;             PG8_BAR; PG8_WAIT_L(0); PG8_MMA(0, 1, At, B1); PG8_BAR;
;             PG8_LDA(At, 1, 1); PG8_STAGE(PG8_SA(1, 0), a3, voffA);
;             PG8_BAR; PG8_WAIT_L(0); PG8_MMA(1, 0, At, B0); PG8_BAR; PG8_SCHED;
;             PG8_STAGE(PG8_SB(1, 1), b3 + hstepB, voffB);
;             PG8_WAIT_V(6); PG8_BAR; PG8_MMA(1, 1, At, B1); PG8_BAR;
;         }
.LBB0_1346:
	s_add_u32 s14, s12, 0xfffc0080
	s_addc_u32 s15, s13, -1
	s_add_i32 s38, 0, 0x10000
	v_add_u32_e32 v152, s38, v185
	ds_read_b128 v[114:117], v152
	ds_read_b128 v[126:129], v152 offset:1024
	ds_read_b128 v[130:133], v152 offset:2048
	ds_read_b128 v[176:179], v152 offset:3072
	s_cmp_eq_u32 s27, 12
	s_cselect_b32 s17, s1, s15
	s_cselect_b32 s16, s3, s14
	s_cselect_b32 s15, s5, s26
	s_cselect_b32 s14, s18, s19
	v_lshl_add_u64 v[152:153], s[12:13], 0, v[148:149]
	s_add_i32 m0, s11, 0xc000
	ds_read_b128 v[180:183], v187
	ds_read_b128 v[188:191], v187 offset:1024
	ds_read_b128 v[192:195], v187 offset:2048
	ds_read_b128 v[196:199], v187 offset:3072
	ds_read_b128 v[200:203], v187 offset:4096
	ds_read_b128 v[204:207], v187 offset:5120
	ds_read_b128 v[214:217], v187 offset:6144
	ds_read_b128 v[218:221], v187 offset:7168
	global_load_lds_dwordx4 v[152:153], off
	s_add_i32 m0, s11, 0xe000
	v_lshl_add_u64 v[152:153], s[12:13], 0, v[150:151]
	global_load_lds_dwordx4 v[152:153], off
	s_waitcnt lgkmcnt(8)
	s_barrier
	s_waitcnt lgkmcnt(0)
	v_mfma_f32_16x16x32_bf16 v[138:141], v[114:117], v[180:183], v[138:141]
	v_mfma_f32_16x16x32_bf16 v[134:137], v[130:133], v[180:183], v[134:137]
	v_mfma_f32_16x16x32_bf16 v[110:113], v[114:117], v[192:195], v[110:113]
	v_mfma_f32_16x16x32_bf16 v[106:109], v[130:133], v[192:195], v[106:109]
	v_mfma_f32_16x16x32_bf16 v[94:97], v[114:117], v[200:203], v[94:97]
	v_mfma_f32_16x16x32_bf16 v[90:93], v[130:133], v[200:203], v[90:93]
	v_mfma_f32_16x16x32_bf16 v[78:81], v[114:117], v[214:217], v[78:81]
	v_mfma_f32_16x16x32_bf16 v[74:77], v[130:133], v[214:217], v[74:77]
	v_mfma_f32_16x16x32_bf16 v[138:141], v[126:129], v[188:191], v[138:141]
	v_mfma_f32_16x16x32_bf16 v[134:137], v[176:179], v[188:191], v[134:137]
	v_mfma_f32_16x16x32_bf16 v[110:113], v[126:129], v[196:199], v[110:113]
	v_mfma_f32_16x16x32_bf16 v[106:109], v[176:179], v[196:199], v[106:109]
	v_mfma_f32_16x16x32_bf16 v[94:97], v[126:129], v[204:207], v[94:97]
	v_mfma_f32_16x16x32_bf16 v[90:93], v[176:179], v[204:207], v[90:93]
	v_mfma_f32_16x16x32_bf16 v[78:81], v[126:129], v[218:221], v[78:81]
	v_mfma_f32_16x16x32_bf16 v[74:77], v[176:179], v[218:221], v[74:77]
	s_barrier
	s_add_i32 s40, 0, 0x14000
	v_add_u32_e32 v152, s40, v185
	s_add_i32 s38, s38, s47
	ds_read_b128 v[222:225], v152
	ds_read_b128 v[226:229], v152 offset:1024
	ds_read_b128 v[230:233], v152 offset:2048
	ds_read_b128 v[234:237], v152 offset:3072
	v_lshl_add_u64 v[152:153], s[14:15], 0, v[8:9]
	s_mov_b32 m0, s38
	v_lshl_add_u64 v[162:163], s[14:15], 0, v[146:147]
	global_load_lds_dwordx4 v[152:153], off
	s_add_i32 m0, s38, 0x2000
	s_nop 0
	global_load_lds_dwordx4 v[162:163], off
	s_barrier
	s_waitcnt lgkmcnt(0)
	v_mfma_f32_16x16x32_bf16 v[122:125], v[222:225], v[180:183], v[122:125]
	v_mfma_f32_16x16x32_bf16 v[118:121], v[230:233], v[180:183], v[118:121]
	v_mfma_f32_16x16x32_bf16 v[102:105], v[222:225], v[192:195], v[102:105]
	v_mfma_f32_16x16x32_bf16 v[98:101], v[230:233], v[192:195], v[98:101]
	v_mfma_f32_16x16x32_bf16 v[86:89], v[222:225], v[200:203], v[86:89]
	v_mfma_f32_16x16x32_bf16 v[82:85], v[230:233], v[200:203], v[82:85]
	v_mfma_f32_16x16x32_bf16 v[70:73], v[222:225], v[214:217], v[70:73]
	v_mfma_f32_16x16x32_bf16 v[66:69], v[230:233], v[214:217], v[66:69]
	v_mfma_f32_16x16x32_bf16 v[122:125], v[226:229], v[188:191], v[122:125]
	v_mfma_f32_16x16x32_bf16 v[118:121], v[234:237], v[188:191], v[118:121]
	v_mfma_f32_16x16x32_bf16 v[102:105], v[226:229], v[196:199], v[102:105]
	v_mfma_f32_16x16x32_bf16 v[98:101], v[234:237], v[196:199], v[98:101]
	v_mfma_f32_16x16x32_bf16 v[86:89], v[226:229], v[204:207], v[86:89]
	v_mfma_f32_16x16x32_bf16 v[82:85], v[234:237], v[204:207], v[82:85]
	v_mfma_f32_16x16x32_bf16 v[70:73], v[226:229], v[218:221], v[70:73]
	v_mfma_f32_16x16x32_bf16 v[66:69], v[234:237], v[218:221], v[66:69]
	s_barrier
	s_mov_b32 m0, s11
	v_lshl_add_u64 v[164:165], s[16:17], 0, v[142:143]
	ds_read_b128 v[180:183], v187 offset:16384
	ds_read_b128 v[188:191], v187 offset:17408
	ds_read_b128 v[192:195], v187 offset:18432
	ds_read_b128 v[196:199], v187 offset:19456
	ds_read_b128 v[200:203], v187 offset:20480
	ds_read_b128 v[204:207], v187 offset:21504
	ds_read_b128 v[214:217], v187 offset:22528
	ds_read_b128 v[218:221], v187 offset:23552
	global_load_lds_dwordx4 v[164:165], off
	s_mov_b32 m0, s66
	v_lshl_add_u64 v[208:209], s[16:17], 0, v[144:145]
	global_load_lds_dwordx4 v[208:209], off
	s_barrier
	s_waitcnt lgkmcnt(0)
	v_mfma_f32_16x16x32_bf16 v[62:65], v[114:117], v[180:183], v[62:65]
	v_mfma_f32_16x16x32_bf16 v[58:61], v[130:133], v[180:183], v[58:61]
	v_mfma_f32_16x16x32_bf16 v[46:49], v[114:117], v[192:195], v[46:49]
	v_mfma_f32_16x16x32_bf16 v[42:45], v[130:133], v[192:195], v[42:45]
	v_mfma_f32_16x16x32_bf16 v[30:33], v[114:117], v[200:203], v[30:33]
	v_mfma_f32_16x16x32_bf16 v[26:29], v[130:133], v[200:203], v[26:29]
	v_mfma_f32_16x16x32_bf16 v[14:17], v[114:117], v[214:217], v[14:17]
	v_mfma_f32_16x16x32_bf16 v[10:13], v[130:133], v[214:217], v[10:13]
	v_mfma_f32_16x16x32_bf16 v[62:65], v[126:129], v[188:191], v[62:65]
	v_mfma_f32_16x16x32_bf16 v[58:61], v[176:179], v[188:191], v[58:61]
	v_mfma_f32_16x16x32_bf16 v[46:49], v[126:129], v[196:199], v[46:49]
	v_mfma_f32_16x16x32_bf16 v[42:45], v[176:179], v[196:199], v[42:45]
	v_mfma_f32_16x16x32_bf16 v[30:33], v[126:129], v[204:207], v[30:33]
	v_mfma_f32_16x16x32_bf16 v[26:29], v[176:179], v[204:207], v[26:29]
	v_mfma_f32_16x16x32_bf16 v[14:17], v[126:129], v[218:221], v[14:17]
	v_mfma_f32_16x16x32_bf16 v[10:13], v[176:179], v[218:221], v[10:13]
	s_barrier
; #define PG8_STAGE(bufoff, gbase, voff) do { _Pragma("unroll") for (int _i = 0; _i < 2; ++_i) \
;         __builtin_amdgcn_global_load_lds((const unsigned*)((const char*)(gbase) + (voff)[_i]), (LAS unsigned*)(lds + (bufoff) + ldsw + _i * 8192), 16, 0, 0); } while (0)
; #define PG8_LDA(dst, b, h) do { _Pragma("unroll") for (int m = 0; m < 4; ++m) _Pragma("unroll") for (int k = 0; k < 2; ++k) dst[m][k] = *(const LAS bf16x8*)(lds + PG8_SA(b, h) + aoff + m * 2048 + k * 1024); } while (0)
; #define PG8_WAIT_V(n) asm volatile("s_waitcnt vmcnt(" #n ")" ::: "memory")
; #define PG8_WAIT_L(n) asm volatile("s_waitcnt lgkmcnt(" #n ")" ::: "memory")
; template <class Epi>
; DEVI void gemm_phase(LAS unsigned char* lds, const Gemm g, const Epi& E) {
;     ...
;         for (int t = 0; t < nt; t += 2) {
;             const bool last = (t == nt - 2);
;             const char* a1 = cA + (size_t)(t + 1) * kstep;
;             const char* a2 = last ? nA : cA + (size_t)(t + 2) * kstep; const char* b2 = last ? nB : cB + (size_t)(t + 2) * kstep;
;             const char* a3 = a2 + kstep; const char* b3 = b2 + kstep;
;             PG8_LDB(B0, 0, 0); PG8_SCHED; PG8_LDA(At, 0, 0); PG8_STAGE(PG8_SA(1, 1), a1 + hstepA, voffA);
;             PG8_WAIT_L(8); PG8_BAR; PG8_WAIT_L(0); PG8_MMA(0, 0, At, B0); PG8_BAR; PG8_SCHED;
;             PG8_LDB(B1, 0, 1); PG8_STAGE(PG8_SB(0, 0), b2, voffB);
;             PG8_BAR; PG8_WAIT_L(0); PG8_MMA(0, 1, At, B1); PG8_BAR;
;             PG8_LDA(At, 0, 1); PG8_STAGE(PG8_SA(0, 0), a2, voffA);
;             PG8_BAR; PG8_WAIT_L(0); PG8_MMA(1, 0, At, B0); PG8_BAR; PG8_SCHED;
;             PG8_STAGE(PG8_SB(0, 1), b2 + hstepB, voffB);
;             PG8_WAIT_V(6); PG8_BAR; PG8_MMA(1, 1, At, B1); PG8_BAR;
;             PG8_LDB(B0, 1, 0); PG8_SCHED; PG8_LDA(At, 1, 0); PG8_STAGE(PG8_SA(0, 1), a2 + hstepA, voffA);
;             PG8_WAIT_L(8); PG8_BAR; PG8_WAIT_L(0); PG8_MMA(0, 0, At, B0); PG8_BAR; PG8_SCHED;
;             PG8_LDB(B1, 1, 1); PG8_STAGE(PG8_SB(1, 0), b3, voffB);
;             PG8_BAR; PG8_WAIT_L(0); PG8_MMA(0, 1, At, B1); PG8_BAR;
;             PG8_LDA(At, 1, 1); PG8_STAGE(PG8_SA(1, 0), a3, voffA);
;             PG8_BAR; PG8_WAIT_L(0); PG8_MMA(1, 0, At, B0); PG8_BAR; PG8_SCHED;
;             PG8_STAGE(PG8_SB(1, 1), b3 + hstepB, voffB);
;             PG8_WAIT_V(6); PG8_BAR; PG8_MMA(1, 1, At, B1); PG8_BAR;
;         }
	s_add_u32 s38, s14, 0x40000
	s_addc_u32 s39, s15, 0
	s_add_i32 s40, s40, s47
	s_mov_b32 m0, s40
	v_lshl_add_u64 v[114:115], s[38:39], 0, v[8:9]
	global_load_lds_dwordx4 v[114:115], off
	s_add_i32 m0, s40, 0x2000
	v_lshl_add_u64 v[114:115], s[38:39], 0, v[146:147]
	global_load_lds_dwordx4 v[114:115], off
	s_waitcnt vmcnt(6)
	s_barrier
	v_mfma_f32_16x16x32_bf16 v[54:57], v[222:225], v[180:183], v[54:57]
	v_mfma_f32_16x16x32_bf16 v[50:53], v[230:233], v[180:183], v[50:53]
	v_mfma_f32_16x16x32_bf16 v[38:41], v[222:225], v[192:195], v[38:41]
	v_mfma_f32_16x16x32_bf16 v[34:37], v[230:233], v[192:195], v[34:37]
	v_mfma_f32_16x16x32_bf16 v[22:25], v[222:225], v[200:203], v[22:25]
	v_mfma_f32_16x16x32_bf16 v[18:21], v[230:233], v[200:203], v[18:21]
	v_mfma_f32_16x16x32_bf16 v[4:7], v[222:225], v[214:217], v[4:7]
	v_mfma_f32_16x16x32_bf16 v[0:3], v[230:233], v[214:217], v[0:3]
	v_mfma_f32_16x16x32_bf16 v[54:57], v[226:229], v[188:191], v[54:57]
	v_mfma_f32_16x16x32_bf16 v[50:53], v[234:237], v[188:191], v[50:53]
	v_mfma_f32_16x16x32_bf16 v[38:41], v[226:229], v[196:199], v[38:41]
	v_mfma_f32_16x16x32_bf16 v[34:37], v[234:237], v[196:199], v[34:37]
	v_mfma_f32_16x16x32_bf16 v[22:25], v[226:229], v[204:207], v[22:25]
	v_mfma_f32_16x16x32_bf16 v[18:21], v[234:237], v[204:207], v[18:21]
	v_mfma_f32_16x16x32_bf16 v[4:7], v[226:229], v[218:221], v[4:7]
	v_mfma_f32_16x16x32_bf16 v[0:3], v[234:237], v[218:221], v[0:3]
	s_barrier
	s_add_i32 s38, 0, 0x18000
	v_add_u32_e32 v176, s38, v185
	ds_read_b128 v[114:117], v176
	ds_read_b128 v[126:129], v176 offset:1024
	ds_read_b128 v[130:133], v176 offset:2048
	ds_read_b128 v[176:179], v176 offset:3072
	s_add_u32 s16, s16, 0x40000
	s_addc_u32 s17, s17, 0
	s_mov_b32 m0, s68
	v_lshl_add_u64 v[222:223], s[16:17], 0, v[142:143]
	ds_read_b128 v[180:183], v187 offset:32768
	ds_read_b128 v[188:191], v187 offset:33792
	ds_read_b128 v[192:195], v187 offset:34816
	ds_read_b128 v[196:199], v187 offset:35840
	ds_read_b128 v[200:203], v187 offset:36864
	ds_read_b128 v[204:207], v187 offset:37888
	ds_read_b128 v[214:217], v187 offset:38912
	ds_read_b128 v[218:221], v187 offset:39936
	global_load_lds_dwordx4 v[222:223], off
	s_mov_b32 m0, s69
	v_lshl_add_u64 v[222:223], s[16:17], 0, v[144:145]
	global_load_lds_dwordx4 v[222:223], off
	s_waitcnt lgkmcnt(8)
	s_barrier
	s_waitcnt lgkmcnt(0)
	v_mfma_f32_16x16x32_bf16 v[138:141], v[114:117], v[180:183], v[138:141]
	v_mfma_f32_16x16x32_bf16 v[134:137], v[130:133], v[180:183], v[134:137]
	v_mfma_f32_16x16x32_bf16 v[110:113], v[114:117], v[192:195], v[110:113]
	v_mfma_f32_16x16x32_bf16 v[106:109], v[130:133], v[192:195], v[106:109]
	v_mfma_f32_16x16x32_bf16 v[94:97], v[114:117], v[200:203], v[94:97]
	v_mfma_f32_16x16x32_bf16 v[90:93], v[130:133], v[200:203], v[90:93]
	v_mfma_f32_16x16x32_bf16 v[78:81], v[114:117], v[214:217], v[78:81]
	v_mfma_f32_16x16x32_bf16 v[74:77], v[130:133], v[214:217], v[74:77]
	v_mfma_f32_16x16x32_bf16 v[138:141], v[126:129], v[188:191], v[138:141]
	v_mfma_f32_16x16x32_bf16 v[134:137], v[176:179], v[188:191], v[134:137]
	v_mfma_f32_16x16x32_bf16 v[110:113], v[126:129], v[196:199], v[110:113]
	v_mfma_f32_16x16x32_bf16 v[106:109], v[176:179], v[196:199], v[106:109]
	v_mfma_f32_16x16x32_bf16 v[94:97], v[126:129], v[204:207], v[94:97]
	v_mfma_f32_16x16x32_bf16 v[90:93], v[176:179], v[204:207], v[90:93]
	v_mfma_f32_16x16x32_bf16 v[78:81], v[126:129], v[218:221], v[78:81]
	v_mfma_f32_16x16x32_bf16 v[74:77], v[176:179], v[218:221], v[74:77]
	s_barrier
	s_add_i32 s16, 0, 0x1c000
	s_add_i32 s17, s38, s47
	v_add_u32_e32 v213, s16, v185
	v_lshl_add_u64 v[152:153], v[152:153], 0, s[70:71]
	s_mov_b32 m0, s17
	ds_read_b128 v[222:225], v213
	ds_read_b128 v[226:229], v213 offset:1024
	ds_read_b128 v[230:233], v213 offset:2048
	ds_read_b128 v[234:237], v213 offset:3072
	global_load_lds_dwordx4 v[152:153], off
	s_add_i32 m0, s17, 0x2000
	v_lshl_add_u64 v[152:153], v[162:163], 0, s[70:71]
	global_load_lds_dwordx4 v[152:153], off
	s_barrier
	s_waitcnt lgkmcnt(0)
	v_mfma_f32_16x16x32_bf16 v[122:125], v[222:225], v[180:183], v[122:125]
	v_mfma_f32_16x16x32_bf16 v[118:121], v[230:233], v[180:183], v[118:121]
	v_mfma_f32_16x16x32_bf16 v[102:105], v[222:225], v[192:195], v[102:105]
	v_mfma_f32_16x16x32_bf16 v[98:101], v[230:233], v[192:195], v[98:101]
	v_mfma_f32_16x16x32_bf16 v[86:89], v[222:225], v[200:203], v[86:89]
	v_mfma_f32_16x16x32_bf16 v[82:85], v[230:233], v[200:203], v[82:85]
	v_mfma_f32_16x16x32_bf16 v[70:73], v[222:225], v[214:217], v[70:73]
	v_mfma_f32_16x16x32_bf16 v[66:69], v[230:233], v[214:217], v[66:69]
	v_mfma_f32_16x16x32_bf16 v[122:125], v[226:229], v[188:191], v[122:125]
	v_mfma_f32_16x16x32_bf16 v[118:121], v[234:237], v[188:191], v[118:121]
	v_mfma_f32_16x16x32_bf16 v[102:105], v[226:229], v[196:199], v[102:105]
	v_mfma_f32_16x16x32_bf16 v[98:101], v[234:237], v[196:199], v[98:101]
	v_mfma_f32_16x16x32_bf16 v[86:89], v[226:229], v[204:207], v[86:89]
	v_mfma_f32_16x16x32_bf16 v[82:85], v[234:237], v[204:207], v[82:85]
	v_mfma_f32_16x16x32_bf16 v[70:73], v[226:229], v[218:221], v[70:73]
	v_mfma_f32_16x16x32_bf16 v[66:69], v[234:237], v[218:221], v[66:69]
	s_barrier
	s_mov_b32 m0, s80
	v_lshl_add_u64 v[152:153], v[164:165], 0, s[70:71]
	ds_read_b128 v[180:183], v187 offset:49152
	ds_read_b128 v[188:191], v187 offset:50176
	ds_read_b128 v[192:195], v187 offset:51200
	ds_read_b128 v[196:199], v187 offset:52224
	ds_read_b128 v[200:203], v187 offset:53248
	ds_read_b128 v[204:207], v187 offset:54272
	ds_read_b128 v[214:217], v187 offset:55296
	ds_read_b128 v[218:221], v187 offset:56320
	global_load_lds_dwordx4 v[152:153], off
	s_mov_b32 m0, s81
	v_lshl_add_u64 v[152:153], v[208:209], 0, s[70:71]
	global_load_lds_dwordx4 v[152:153], off
	s_barrier
; #define PG8_STAGE(bufoff, gbase, voff) do { _Pragma("unroll") for (int _i = 0; _i < 2; ++_i) \
;         __builtin_amdgcn_global_load_lds((const unsigned*)((const char*)(gbase) + (voff)[_i]), (LAS unsigned*)(lds + (bufoff) + ldsw + _i * 8192), 16, 0, 0); } while (0)
; #define PG8_BAR __builtin_amdgcn_s_barrier()
; template <class Epi>
; DEVI void gemm_phase(LAS unsigned char* lds, const Gemm g, const Epi& E) {
;     ...
;         for (int t = 0; t < nt; t += 2) {
;             const bool last = (t == nt - 2);
;             const char* a1 = cA + (size_t)(t + 1) * kstep;
;             const char* a2 = last ? nA : cA + (size_t)(t + 2) * kstep; const char* b2 = last ? nB : cB + (size_t)(t + 2) * kstep;
;             const char* a3 = a2 + kstep; const char* b3 = b2 + kstep;
;             PG8_LDB(B0, 0, 0); PG8_SCHED; PG8_LDA(At, 0, 0); PG8_STAGE(PG8_SA(1, 1), a1 + hstepA, voffA);
;             PG8_WAIT_L(8); PG8_BAR; PG8_WAIT_L(0); PG8_MMA(0, 0, At, B0); PG8_BAR; PG8_SCHED;
;             PG8_LDB(B1, 0, 1); PG8_STAGE(PG8_SB(0, 0), b2, voffB);
;             PG8_BAR; PG8_WAIT_L(0); PG8_MMA(0, 1, At, B1); PG8_BAR;
;             PG8_LDA(At, 0, 1); PG8_STAGE(PG8_SA(0, 0), a2, voffA);
;             PG8_BAR; PG8_WAIT_L(0); PG8_MMA(1, 0, At, B0); PG8_BAR; PG8_SCHED;
;             PG8_STAGE(PG8_SB(0, 1), b2 + hstepB, voffB);
;             PG8_WAIT_V(6); PG8_BAR; PG8_MMA(1, 1, At, B1); PG8_BAR;
;             PG8_LDB(B0, 1, 0); PG8_SCHED; PG8_LDA(At, 1, 0); PG8_STAGE(PG8_SA(0, 1), a2 + hstepA, voffA);
;             PG8_WAIT_L(8); PG8_BAR; PG8_WAIT_L(0); PG8_MMA(0, 0, At, B0); PG8_BAR; PG8_SCHED;
;             PG8_LDB(B1, 1, 1); PG8_STAGE(PG8_SB(1, 0), b3, voffB);
;             PG8_BAR; PG8_WAIT_L(0); PG8_MMA(0, 1, At, B1); PG8_BAR;
;             PG8_LDA(At, 1, 1); PG8_STAGE(PG8_SA(1, 0), a3, voffA);
;             PG8_BAR; PG8_WAIT_L(0); PG8_MMA(1, 0, At, B0); PG8_BAR; PG8_SCHED;
;             PG8_STAGE(PG8_SB(1, 1), b3 + hstepB, voffB);
;             PG8_WAIT_V(6); PG8_BAR; PG8_MMA(1, 1, At, B1); PG8_BAR;
;         }
;     ...
;                 if constexpr (Epi::PRE) {
; #pragma unroll
;                     for (int m = 0; m < 2; ++m)
; #pragma unroll
;                         for (int bj = 0; bj < 2; ++bj)
; #pragma unroll
;                             for (int n = 0; n < 2; ++n) pre[m][bj][n] = E.load(row0 + ai * HALF + (m0 + m) * 16, col0 + bj * HALF + n * NST);
	s_waitcnt lgkmcnt(0)
	v_mfma_f32_16x16x32_bf16 v[62:65], v[114:117], v[180:183], v[62:65]
	v_mfma_f32_16x16x32_bf16 v[58:61], v[130:133], v[180:183], v[58:61]
	v_mfma_f32_16x16x32_bf16 v[46:49], v[114:117], v[192:195], v[46:49]
	v_mfma_f32_16x16x32_bf16 v[42:45], v[130:133], v[192:195], v[42:45]
	v_mfma_f32_16x16x32_bf16 v[30:33], v[114:117], v[200:203], v[30:33]
	v_mfma_f32_16x16x32_bf16 v[26:29], v[130:133], v[200:203], v[26:29]
	v_mfma_f32_16x16x32_bf16 v[14:17], v[114:117], v[214:217], v[14:17]
	v_mfma_f32_16x16x32_bf16 v[10:13], v[130:133], v[214:217], v[10:13]
	v_mfma_f32_16x16x32_bf16 v[62:65], v[126:129], v[188:191], v[62:65]
	v_mfma_f32_16x16x32_bf16 v[58:61], v[176:179], v[188:191], v[58:61]
	v_mfma_f32_16x16x32_bf16 v[46:49], v[126:129], v[196:199], v[46:49]
	v_mfma_f32_16x16x32_bf16 v[42:45], v[176:179], v[196:199], v[42:45]
	v_mfma_f32_16x16x32_bf16 v[30:33], v[126:129], v[204:207], v[30:33]
	v_mfma_f32_16x16x32_bf16 v[26:29], v[176:179], v[204:207], v[26:29]
	v_mfma_f32_16x16x32_bf16 v[14:17], v[126:129], v[218:221], v[14:17]
	v_mfma_f32_16x16x32_bf16 v[10:13], v[176:179], v[218:221], v[10:13]
	s_barrier
	s_add_u32 s14, s14, 0x40080
	s_addc_u32 s15, s15, 0
	s_add_i32 s16, s16, s47
	s_mov_b32 m0, s16
	v_lshl_add_u64 v[114:115], s[14:15], 0, v[8:9]
	global_load_lds_dwordx4 v[114:115], off
	s_add_i32 m0, s16, 0x2000
	v_lshl_add_u64 v[114:115], s[14:15], 0, v[146:147]
	global_load_lds_dwordx4 v[114:115], off
	s_waitcnt vmcnt(6)
	s_barrier
	v_mfma_f32_16x16x32_bf16 v[54:57], v[222:225], v[180:183], v[54:57]
	v_mfma_f32_16x16x32_bf16 v[50:53], v[230:233], v[180:183], v[50:53]
	v_mfma_f32_16x16x32_bf16 v[38:41], v[222:225], v[192:195], v[38:41]
	v_mfma_f32_16x16x32_bf16 v[34:37], v[230:233], v[192:195], v[34:37]
	v_mfma_f32_16x16x32_bf16 v[22:25], v[222:225], v[200:203], v[22:25]
	v_mfma_f32_16x16x32_bf16 v[18:21], v[230:233], v[200:203], v[18:21]
	v_mfma_f32_16x16x32_bf16 v[4:7], v[222:225], v[214:217], v[4:7]
	v_mfma_f32_16x16x32_bf16 v[0:3], v[230:233], v[214:217], v[0:3]
	v_mfma_f32_16x16x32_bf16 v[54:57], v[226:229], v[188:191], v[54:57]
	v_mfma_f32_16x16x32_bf16 v[50:53], v[234:237], v[188:191], v[50:53]
	v_mfma_f32_16x16x32_bf16 v[38:41], v[226:229], v[196:199], v[38:41]
	v_mfma_f32_16x16x32_bf16 v[34:37], v[234:237], v[196:199], v[34:37]
	v_mfma_f32_16x16x32_bf16 v[22:25], v[226:229], v[204:207], v[22:25]
	v_mfma_f32_16x16x32_bf16 v[18:21], v[234:237], v[204:207], v[18:21]
	v_mfma_f32_16x16x32_bf16 v[4:7], v[226:229], v[218:221], v[4:7]
	v_mfma_f32_16x16x32_bf16 v[0:3], v[234:237], v[218:221], v[0:3]
	s_barrier
	s_add_i32 s27, s27, 2
	s_add_u32 s12, s12, 0x100
	s_addc_u32 s13, s13, 0
	s_add_u32 s19, s19, 0x100
	s_addc_u32 s26, s26, 0
	s_cmp_gt_u32 s27, 13
	s_cbranch_scc0 .LBB0_1346
	s_setprio 0
	v_lshl_add_u32 v180, s10, 8, v184
	v_lshl_or_b32 v152, s0, 8, v186
	v_ashrrev_i32_e32 v181, 31, v180
	v_lshlrev_b64 v[178:179], 11, v[180:181]
	v_ashrrev_i32_e32 v153, 31, v152
	v_lshl_add_u64 v[114:115], s[24:25], 0, v[178:179]
	v_lshlrev_b64 v[176:177], 1, v[152:153]
	v_lshl_add_u64 v[114:115], v[114:115], 0, v[176:177]
	global_load_dwordx4 v[188:191], v[114:115], off
	global_load_dwordx4 v[130:133], v[114:115], off offset:256
	v_or_b32_e32 v114, 16, v180
	v_ashrrev_i32_e32 v115, 31, v114
	v_lshlrev_b64 v[182:183], 11, v[114:115]
	v_readlane_b32 s48, v251, 40
	v_lshl_add_u64 v[114:115], s[24:25], 0, v[182:183]
	v_readlane_b32 s54, v251, 46
	v_readlane_b32 s55, v251, 47
	v_lshl_add_u64 v[114:115], v[114:115], 0, v[176:177]
	global_load_dwordx4 v[126:129], v[114:115], off
	s_nop 0
	global_load_dwordx4 v[114:117], v[114:115], off offset:256
	v_lshl_add_u64 v[152:153], v[152:153], 2, s[54:55]
	global_load_dwordx4 v[214:217], v[152:153], off
	global_load_dwordx4 v[218:221], v[152:153], off offset:16
	global_load_dwordx4 v[222:225], v[152:153], off offset:512
	global_load_dwordx4 v[226:229], v[152:153], off offset:528
	s_mov_b64 s[0:1], 0x40000
	v_readlane_b32 s52, v251, 44
	v_readlane_b32 s56, v251, 48
	v_readlane_b32 s57, v251, 49
	v_readlane_b32 s58, v251, 50
	v_readlane_b32 s59, v251, 51
	v_readlane_b32 s60, v251, 52
	v_readlane_b32 s61, v251, 53
	v_readlane_b32 s62, v251, 54
	v_readlane_b32 s63, v251, 55
	s_and_b64 vcc, exec, s[36:37]
	s_mov_b32 s10, s2
	s_mov_b64 s[14:15], s[8:9]
	s_mov_b64 s[12:13], s[6:7]
	s_mov_b64 s[56:57], s[42:43]
	s_mov_b64 s[58:59], s[44:45]
	s_mov_b32 s60, s41
	s_mov_b32 s61, s83
	s_mov_b32 s62, s84
	s_mov_b32 s63, s85
	v_readlane_b32 s55, v254, 0
	s_movk_i32 s52, 0x110
	v_readlane_b32 s49, v251, 41
	v_readlane_b32 s50, v251, 42
	v_readlane_b32 s51, v251, 43
	v_readlane_b32 s53, v251, 45
	v_readlane_b32 s40, v254, 1
	s_waitcnt vmcnt(0)
; DEVI float bf2f(u16 b) { return __uint_as_float(((unsigned)b) << 16); }
; template <class Epi>
; DEVI void gemm_phase(LAS unsigned char* lds, const Gemm g, const Epi& E) {
;     ...
;                 if constexpr (Epi::PRE) {
; #pragma unroll
;                     for (int m = 0; m < 2; ++m)
; #pragma unroll
;                         for (int bj = 0; bj < 2; ++bj)
; #pragma unroll
;                             for (int n = 0; n < 2; ++n) pre[m][bj][n] = E.load(row0 + ai * HALF + (m0 + m) * 16, col0 + bj * HALF + n * NST);
;                 }
; #pragma unroll
;                 for (int mm = 0; mm < 2; ++mm) {
;                     const int m = m0 + mm;
;                     const int r = row0 + ai * HALF + m * 16; float rs = 1.f, part = 0.f;
;                     if constexpr (Epi::RS) rs = rsv[ai * 4 + m];
;                     if constexpr (Epi::PAIR) E.pair8(cur.b, r, cur.pn * HALF + wc * 32 + 8 * fq, acc[ai][0][m][0] * rs, acc[ai][0][m][1] * rs, acc[ai][1][m][0] * rs, acc[ai][1][m][1] * rs);
;                     else
; #pragma unroll
;                     for (int bj = 0; bj < 2; ++bj) {
;                         const int c = col0 + bj * HALF; f32x4 v0 = acc[ai][bj][m][0], v1 = acc[ai][bj][m][1];
;                         if constexpr (Epi::RS) { v0 = v0 * rs; v1 = v1 * rs; }
;                         if constexpr (Epi::PRE) part += E.frag_pre8(cur.b, r, c, v0, v1, pre[mm][bj][0], pre[mm][bj][1]);
;                         else if constexpr (Epi::PERM) E.frag8(cur.b, r, c, v0, v1);
;     DEVI f32x4 load(int r, int c) const { const bf16x4 y = *(const bf16x4*)(Y + (size_t)r * DM + c); return (f32x4){bf2f((u16)y[0]), bf2f((u16)y[1]), bf2f((u16)y[2]), bf2f((u16)y[3])}; }
	v_and_b32_e32 v163, 0xffff0000, v188
	v_lshlrev_b32_e32 v162, 16, v188
	v_add_f32_e32 v134, v134, v218
	v_add_f32_e32 v138, v138, v214
	v_add_f32_e32 v139, v139, v215
	v_mul_f32_e32 v138, 0xbfb8aa3b, v138
	v_mul_f32_e32 v139, 0xbfb8aa3b, v139
	v_add_f32_e32 v135, v135, v219
	v_exp_f32_e32 v138, v138
	v_mul_f32_e32 v134, 0xbfb8aa3b, v134
	v_exp_f32_e32 v139, v139
	v_mul_f32_e32 v135, 0xbfb8aa3b, v135
	v_exp_f32_e32 v134, v134
	v_exp_f32_e32 v135, v135
	v_add_f32_e32 v138, 1.0, v138
	v_add_f32_e32 v139, 1.0, v139
	v_rcp_f32_e32 v138, v138
	v_add_f32_e32 v134, 1.0, v134
	v_rcp_f32_e32 v139, v139
	v_add_f32_e32 v135, 1.0, v135
	v_rcp_f32_e32 v134, v134
	v_rcp_f32_e32 v135, v135
	v_pk_mul_f32 v[138:139], v[138:139], v[162:163]
	v_and_b32_e32 v163, 0xffff0000, v190
	v_lshlrev_b32_e32 v162, 16, v190
	v_pk_mul_f32 v[162:163], v[134:135], v[162:163]
	v_add_f32_e32 v135, v136, v220
	v_mul_f32_e32 v135, 0xbfb8aa3b, v135
	v_exp_f32_e32 v135, v135
	v_add_f32_e32 v134, v140, v216
	v_mul_f32_e32 v134, 0xbfb8aa3b, v134
	v_exp_f32_e32 v134, v134
	v_add_f32_e32 v135, 1.0, v135
	v_rcp_f32_e32 v136, v135
	v_add_f32_e32 v135, v141, v217
	v_mul_f32_e32 v135, 0xbfb8aa3b, v135
	v_exp_f32_e32 v135, v135
	v_add_f32_e32 v134, 1.0, v134
	v_rcp_f32_e32 v134, v134
	v_and_b32_e32 v141, 0xffff0000, v189
	v_add_f32_e32 v135, 1.0, v135
	v_rcp_f32_e32 v135, v135
	v_lshlrev_b32_e32 v140, 16, v189
	v_pk_mul_f32 v[140:141], v[134:135], v[140:141]
	v_add_f32_e32 v134, v137, v221
	v_mul_f32_e32 v134, 0xbfb8aa3b, v134
	v_exp_f32_e32 v134, v134
	v_and_b32_e32 v135, 0xffff0000, v191
	v_add_f32_e32 v134, 1.0, v134
	v_rcp_f32_e32 v137, v134
	v_lshlrev_b32_e32 v134, 16, v191
	v_pk_mul_f32 v[164:165], v[136:137], v[134:135]
	v_cvt_pk_bf16_f32 v134, v138, v139
	v_lshl_add_u64 v[138:139], s[64:65], 0, v[178:179]
	v_cvt_pk_bf16_f32 v135, v140, v141
	v_cvt_pk_bf16_f32 v136, v162, v163
	v_cvt_pk_bf16_f32 v137, v164, v165
	v_lshl_add_u64 v[138:139], v[138:139], 0, v[176:177]
	global_store_dwordx4 v[138:139], v[134:137], off
	s_nop 0
	v_and_b32_e32 v141, 0xffff0000, v130
	v_lshlrev_b32_e32 v140, 16, v130
	v_lshlrev_b32_e32 v130, 16, v133
	v_add_f32_e32 v118, v118, v226
	v_add_f32_e32 v119, v119, v227
	v_add_f32_e32 v122, v122, v222
	v_mul_f32_e32 v118, 0xbfb8aa3b, v118
	v_add_f32_e32 v123, v123, v223
	v_mul_f32_e32 v119, 0xbfb8aa3b, v119
	v_add_f32_e32 v124, v124, v224
	v_add_f32_e32 v120, v120, v228
	v_add_f32_e32 v125, v125, v225
	v_add_f32_e32 v121, v121, v229
	v_mul_f32_e32 v122, 0xbfb8aa3b, v122
	v_exp_f32_e32 v118, v118
	v_mul_f32_e32 v123, 0xbfb8aa3b, v123
	v_exp_f32_e32 v119, v119
	v_mul_f32_e32 v124, 0xbfb8aa3b, v124
	v_mul_f32_e32 v120, 0xbfb8aa3b, v120
	v_mul_f32_e32 v125, 0xbfb8aa3b, v125
	v_mul_f32_e32 v121, 0xbfb8aa3b, v121
	v_exp_f32_e32 v122, v122
	v_exp_f32_e32 v123, v123
	v_exp_f32_e32 v124, v124
	v_exp_f32_e32 v120, v120
	v_exp_f32_e32 v125, v125
	v_exp_f32_e32 v121, v121
	v_add_f32_e32 v118, 1.0, v118
	v_add_f32_e32 v119, 1.0, v119
	v_add_f32_e32 v122, 1.0, v122
	v_rcp_f32_e32 v118, v118
	v_add_f32_e32 v123, 1.0, v123
	v_rcp_f32_e32 v119, v119
	v_add_f32_e32 v124, 1.0, v124
	v_add_f32_e32 v120, 1.0, v120
	v_add_f32_e32 v125, 1.0, v125
	v_add_f32_e32 v121, 1.0, v121
	v_rcp_f32_e32 v122, v122
	v_rcp_f32_e32 v123, v123
	v_rcp_f32_e32 v124, v124
	v_rcp_f32_e32 v120, v120
	v_rcp_f32_e32 v125, v125
	v_rcp_f32_e32 v121, v121
	v_and_b32_e32 v135, 0xffff0000, v132
	v_lshlrev_b32_e32 v134, 16, v132
	v_pk_mul_f32 v[118:119], v[118:119], v[134:135]
	v_and_b32_e32 v135, 0xffff0000, v131
	v_lshlrev_b32_e32 v134, 16, v131
	v_and_b32_e32 v131, 0xffff0000, v133
	v_pk_mul_f32 v[122:123], v[122:123], v[140:141]
	v_pk_mul_f32 v[124:125], v[124:125], v[134:135]
	v_pk_mul_f32 v[130:131], v[120:121], v[130:131]
	v_cvt_pk_bf16_f32 v120, v122, v123
	v_cvt_pk_bf16_f32 v121, v124, v125
	v_cvt_pk_bf16_f32 v122, v118, v119
	v_cvt_pk_bf16_f32 v123, v130, v131
	global_store_dwordx4 v[138:139], v[120:123], off offset:256
	s_nop 0
	v_add_f32_e32 v106, v106, v218
	v_add_f32_e32 v107, v107, v219
	v_mul_f32_e32 v106, 0xbfb8aa3b, v106
	v_mul_f32_e32 v107, 0xbfb8aa3b, v107
	v_exp_f32_e32 v106, v106
	v_exp_f32_e32 v107, v107
	v_and_b32_e32 v119, 0xffff0000, v128
	v_lshlrev_b32_e32 v118, 16, v128
	v_add_f32_e32 v106, 1.0, v106
	v_add_f32_e32 v107, 1.0, v107
	v_rcp_f32_e32 v106, v106
	v_rcp_f32_e32 v107, v107
	v_add_f32_e32 v110, v110, v214
	v_add_f32_e32 v111, v111, v215
	v_mul_f32_e32 v110, 0xbfb8aa3b, v110
	v_pk_mul_f32 v[118:119], v[106:107], v[118:119]
	v_add_f32_e32 v107, v108, v220
	v_mul_f32_e32 v107, 0xbfb8aa3b, v107
	v_exp_f32_e32 v107, v107
	v_add_f32_e32 v106, v112, v216
	v_mul_f32_e32 v106, 0xbfb8aa3b, v106
	v_exp_f32_e32 v106, v106
	v_add_f32_e32 v107, 1.0, v107
	v_rcp_f32_e32 v108, v107
	v_add_f32_e32 v107, v113, v217
	v_mul_f32_e32 v107, 0xbfb8aa3b, v107
	v_exp_f32_e32 v107, v107
	v_add_f32_e32 v106, 1.0, v106
	v_rcp_f32_e32 v106, v106
	v_and_b32_e32 v113, 0xffff0000, v127
	v_add_f32_e32 v107, 1.0, v107
	v_rcp_f32_e32 v107, v107
	v_lshlrev_b32_e32 v112, 16, v127
	v_mul_f32_e32 v111, 0xbfb8aa3b, v111
	v_exp_f32_e32 v110, v110
	v_pk_mul_f32 v[112:113], v[106:107], v[112:113]
	v_add_f32_e32 v106, v109, v221
	v_exp_f32_e32 v111, v111
	v_mul_f32_e32 v106, 0xbfb8aa3b, v106
	v_exp_f32_e32 v106, v106
	v_add_f32_e32 v110, 1.0, v110
	v_add_f32_e32 v111, 1.0, v111
	v_rcp_f32_e32 v110, v110
	v_rcp_f32_e32 v111, v111
	v_add_f32_e32 v106, 1.0, v106
	v_rcp_f32_e32 v109, v106
	v_and_b32_e32 v123, 0xffff0000, v126
	v_lshlrev_b32_e32 v122, 16, v126
	v_pk_mul_f32 v[110:111], v[110:111], v[122:123]
	v_and_b32_e32 v107, 0xffff0000, v129
	v_lshlrev_b32_e32 v106, 16, v129
	v_pk_mul_f32 v[120:121], v[108:109], v[106:107]
; DEVI float bf2f(u16 b) { return __uint_as_float(((unsigned)b) << 16); }
; template <class Epi>
; DEVI void gemm_phase(LAS unsigned char* lds, const Gemm g, const Epi& E) {
;     ...
;                 if constexpr (Epi::PRE) {
; #pragma unroll
;                     for (int m = 0; m < 2; ++m)
; #pragma unroll
;                         for (int bj = 0; bj < 2; ++bj)
; #pragma unroll
;                             for (int n = 0; n < 2; ++n) pre[m][bj][n] = E.load(row0 + ai * HALF + (m0 + m) * 16, col0 + bj * HALF + n * NST);
;                 }
; #pragma unroll
;                 for (int mm = 0; mm < 2; ++mm) {
;                     const int m = m0 + mm;
;                     const int r = row0 + ai * HALF + m * 16; float rs = 1.f, part = 0.f;
;                     if constexpr (Epi::RS) rs = rsv[ai * 4 + m];
;                     if constexpr (Epi::PAIR) E.pair8(cur.b, r, cur.pn * HALF + wc * 32 + 8 * fq, acc[ai][0][m][0] * rs, acc[ai][0][m][1] * rs, acc[ai][1][m][0] * rs, acc[ai][1][m][1] * rs);
;                     else
; #pragma unroll
;                     for (int bj = 0; bj < 2; ++bj) {
;                         const int c = col0 + bj * HALF; f32x4 v0 = acc[ai][bj][m][0], v1 = acc[ai][bj][m][1];
;                         if constexpr (Epi::RS) { v0 = v0 * rs; v1 = v1 * rs; }
;                         if constexpr (Epi::PRE) part += E.frag_pre8(cur.b, r, c, v0, v1, pre[mm][bj][0], pre[mm][bj][1]);
;                         else if constexpr (Epi::PERM) E.frag8(cur.b, r, c, v0, v1);
;     DEVI f32x4 load(int r, int c) const { const bf16x4 y = *(const bf16x4*)(Y + (size_t)r * DM + c); return (f32x4){bf2f((u16)y[0]), bf2f((u16)y[1]), bf2f((u16)y[2]), bf2f((u16)y[3])}; }
	v_cvt_pk_bf16_f32 v106, v110, v111
	v_lshl_add_u64 v[110:111], s[64:65], 0, v[182:183]
	v_cvt_pk_bf16_f32 v107, v112, v113
	v_cvt_pk_bf16_f32 v108, v118, v119
	v_cvt_pk_bf16_f32 v109, v120, v121
	v_lshl_add_u64 v[110:111], v[110:111], 0, v[176:177]
	global_store_dwordx4 v[110:111], v[106:109], off
	s_nop 0
	v_and_b32_e32 v113, 0xffff0000, v114
	v_lshlrev_b32_e32 v112, 16, v114
	v_add_f32_e32 v98, v98, v226
	v_add_f32_e32 v99, v99, v227
	v_mul_f32_e32 v98, 0xbfb8aa3b, v98
	v_mul_f32_e32 v99, 0xbfb8aa3b, v99
	v_exp_f32_e32 v98, v98
	v_exp_f32_e32 v99, v99
	v_and_b32_e32 v107, 0xffff0000, v116
	v_lshlrev_b32_e32 v106, 16, v116
	v_add_f32_e32 v98, 1.0, v98
	v_add_f32_e32 v99, 1.0, v99
	v_rcp_f32_e32 v98, v98
	v_rcp_f32_e32 v99, v99
	v_add_f32_e32 v102, v102, v222
	v_add_f32_e32 v103, v103, v223
	v_mul_f32_e32 v102, 0xbfb8aa3b, v102
	v_pk_mul_f32 v[106:107], v[98:99], v[106:107]
	v_add_f32_e32 v99, v100, v228
	v_mul_f32_e32 v99, 0xbfb8aa3b, v99
	v_exp_f32_e32 v99, v99
	v_add_f32_e32 v98, v104, v224
	v_mul_f32_e32 v98, 0xbfb8aa3b, v98
	v_exp_f32_e32 v98, v98
	v_add_f32_e32 v99, 1.0, v99
	v_rcp_f32_e32 v100, v99
	v_add_f32_e32 v99, v105, v225
	v_mul_f32_e32 v99, 0xbfb8aa3b, v99
	v_exp_f32_e32 v99, v99
	v_add_f32_e32 v98, 1.0, v98
	v_rcp_f32_e32 v98, v98
	v_and_b32_e32 v105, 0xffff0000, v115
	v_add_f32_e32 v99, 1.0, v99
	v_rcp_f32_e32 v99, v99
	v_lshlrev_b32_e32 v104, 16, v115
	v_mul_f32_e32 v103, 0xbfb8aa3b, v103
	v_exp_f32_e32 v102, v102
	v_pk_mul_f32 v[104:105], v[98:99], v[104:105]
	v_add_f32_e32 v98, v101, v229
	v_mul_f32_e32 v98, 0xbfb8aa3b, v98
	v_exp_f32_e32 v103, v103
	v_exp_f32_e32 v98, v98
	v_add_f32_e32 v102, 1.0, v102
	v_rcp_f32_e32 v102, v102
	v_add_f32_e32 v103, 1.0, v103
	v_add_f32_e32 v98, 1.0, v98
	v_rcp_f32_e32 v103, v103
	v_rcp_f32_e32 v101, v98
	v_and_b32_e32 v99, 0xffff0000, v117
	v_lshlrev_b32_e32 v98, 16, v117
	v_pk_mul_f32 v[102:103], v[102:103], v[112:113]
	v_pk_mul_f32 v[108:109], v[100:101], v[98:99]
	v_cvt_pk_bf16_f32 v98, v102, v103
	v_cvt_pk_bf16_f32 v99, v104, v105
	v_cvt_pk_bf16_f32 v100, v106, v107
	v_cvt_pk_bf16_f32 v101, v108, v109
	global_store_dwordx4 v[110:111], v[98:101], off offset:256
	s_nop 1
	v_or_b32_e32 v98, 32, v180
	v_ashrrev_i32_e32 v99, 31, v98
	v_lshlrev_b64 v[120:121], 11, v[98:99]
	v_lshl_add_u64 v[98:99], s[24:25], 0, v[120:121]
	v_lshl_add_u64 v[98:99], v[98:99], 0, v[176:177]
	global_load_dwordx4 v[110:113], v[98:99], off
	global_load_dwordx4 v[106:109], v[98:99], off offset:256
	v_or_b32_e32 v98, 48, v180
	v_ashrrev_i32_e32 v99, 31, v98
	v_lshlrev_b64 v[118:119], 11, v[98:99]
	v_lshl_add_u64 v[98:99], s[24:25], 0, v[118:119]
	v_lshl_add_u64 v[98:99], v[98:99], 0, v[176:177]
	global_load_dwordx4 v[102:105], v[98:99], off
	s_nop 0
	global_load_dwordx4 v[98:101], v[98:99], off offset:256
	s_nop 0
	s_waitcnt vmcnt(0)
	v_add_f32_e32 v90, v90, v218
	v_add_f32_e32 v91, v91, v219
	v_mul_f32_e32 v90, 0xbfb8aa3b, v90
	v_mul_f32_e32 v91, 0xbfb8aa3b, v91
	v_exp_f32_e32 v90, v90
	v_exp_f32_e32 v91, v91
	v_and_b32_e32 v115, 0xffff0000, v112
	v_lshlrev_b32_e32 v114, 16, v112
	v_add_f32_e32 v90, 1.0, v90
	v_add_f32_e32 v91, 1.0, v91
	v_rcp_f32_e32 v90, v90
	v_rcp_f32_e32 v91, v91
	v_add_f32_e32 v94, v94, v214
	v_add_f32_e32 v95, v95, v215
	v_mul_f32_e32 v94, 0xbfb8aa3b, v94
	v_pk_mul_f32 v[114:115], v[90:91], v[114:115]
	v_add_f32_e32 v91, v92, v220
	v_mul_f32_e32 v91, 0xbfb8aa3b, v91
	v_exp_f32_e32 v91, v91
	v_add_f32_e32 v90, v96, v216
	v_mul_f32_e32 v90, 0xbfb8aa3b, v90
	v_exp_f32_e32 v90, v90
	v_add_f32_e32 v91, 1.0, v91
	v_rcp_f32_e32 v92, v91
	v_add_f32_e32 v91, v97, v217
	v_mul_f32_e32 v91, 0xbfb8aa3b, v91
	v_exp_f32_e32 v91, v91
	v_add_f32_e32 v90, 1.0, v90
	v_rcp_f32_e32 v90, v90
	v_and_b32_e32 v97, 0xffff0000, v111
	v_add_f32_e32 v91, 1.0, v91
	v_rcp_f32_e32 v91, v91
	v_lshlrev_b32_e32 v96, 16, v111
	v_mul_f32_e32 v95, 0xbfb8aa3b, v95
	v_exp_f32_e32 v94, v94
	v_pk_mul_f32 v[96:97], v[90:91], v[96:97]
	v_add_f32_e32 v90, v93, v221
	v_exp_f32_e32 v95, v95
	v_mul_f32_e32 v90, 0xbfb8aa3b, v90
	v_exp_f32_e32 v90, v90
	v_add_f32_e32 v94, 1.0, v94
	v_add_f32_e32 v95, 1.0, v95
	v_rcp_f32_e32 v94, v94
	v_rcp_f32_e32 v95, v95
	v_add_f32_e32 v90, 1.0, v90
	v_rcp_f32_e32 v93, v90
	v_and_b32_e32 v123, 0xffff0000, v110
	v_lshlrev_b32_e32 v122, 16, v110
	v_pk_mul_f32 v[94:95], v[94:95], v[122:123]
	v_and_b32_e32 v91, 0xffff0000, v113
	v_lshlrev_b32_e32 v90, 16, v113
	v_pk_mul_f32 v[110:111], v[92:93], v[90:91]
	v_cvt_pk_bf16_f32 v90, v94, v95
	v_lshl_add_u64 v[94:95], s[64:65], 0, v[120:121]
	v_cvt_pk_bf16_f32 v91, v96, v97
	v_cvt_pk_bf16_f32 v92, v114, v115
	v_cvt_pk_bf16_f32 v93, v110, v111
	v_lshl_add_u64 v[94:95], v[94:95], 0, v[176:177]
	global_store_dwordx4 v[94:95], v[90:93], off
	s_nop 0
	v_and_b32_e32 v97, 0xffff0000, v106
	v_lshlrev_b32_e32 v96, 16, v106
	v_add_f32_e32 v82, v82, v226
	v_add_f32_e32 v83, v83, v227
	v_mul_f32_e32 v82, 0xbfb8aa3b, v82
	v_mul_f32_e32 v83, 0xbfb8aa3b, v83
	v_add_f32_e32 v88, v88, v224
	v_add_f32_e32 v89, v89, v225
	v_add_f32_e32 v86, v86, v222
	v_exp_f32_e32 v82, v82
	v_add_f32_e32 v87, v87, v223
	v_exp_f32_e32 v83, v83
	v_mul_f32_e32 v88, 0xbfb8aa3b, v88
	v_add_f32_e32 v84, v84, v228
	v_mul_f32_e32 v89, 0xbfb8aa3b, v89
	v_add_f32_e32 v85, v85, v229
	v_mul_f32_e32 v86, 0xbfb8aa3b, v86
	v_mul_f32_e32 v87, 0xbfb8aa3b, v87
	v_exp_f32_e32 v88, v88
	v_mul_f32_e32 v84, 0xbfb8aa3b, v84
	v_exp_f32_e32 v89, v89
	v_mul_f32_e32 v85, 0xbfb8aa3b, v85
	v_exp_f32_e32 v86, v86
	v_exp_f32_e32 v87, v87
	v_exp_f32_e32 v84, v84
	v_exp_f32_e32 v85, v85
	v_add_f32_e32 v82, 1.0, v82
	v_add_f32_e32 v83, 1.0, v83
	v_rcp_f32_e32 v82, v82
	v_rcp_f32_e32 v83, v83
	v_add_f32_e32 v88, 1.0, v88
; DEVI float bf2f(u16 b) { return __uint_as_float(((unsigned)b) << 16); }
; template <class Epi>
; DEVI void gemm_phase(LAS unsigned char* lds, const Gemm g, const Epi& E) {
;     ...
;                 if constexpr (Epi::PRE) {
; #pragma unroll
;                     for (int m = 0; m < 2; ++m)
; #pragma unroll
;                         for (int bj = 0; bj < 2; ++bj)
; #pragma unroll
;                             for (int n = 0; n < 2; ++n) pre[m][bj][n] = E.load(row0 + ai * HALF + (m0 + m) * 16, col0 + bj * HALF + n * NST);
;                 }
; #pragma unroll
;                 for (int mm = 0; mm < 2; ++mm) {
;                     const int m = m0 + mm;
;                     const int r = row0 + ai * HALF + m * 16; float rs = 1.f, part = 0.f;
;                     if constexpr (Epi::RS) rs = rsv[ai * 4 + m];
;                     if constexpr (Epi::PAIR) E.pair8(cur.b, r, cur.pn * HALF + wc * 32 + 8 * fq, acc[ai][0][m][0] * rs, acc[ai][0][m][1] * rs, acc[ai][1][m][0] * rs, acc[ai][1][m][1] * rs);
;                     else
; #pragma unroll
;                     for (int bj = 0; bj < 2; ++bj) {
;                         const int c = col0 + bj * HALF; f32x4 v0 = acc[ai][bj][m][0], v1 = acc[ai][bj][m][1];
;                         if constexpr (Epi::RS) { v0 = v0 * rs; v1 = v1 * rs; }
;                         if constexpr (Epi::PRE) part += E.frag_pre8(cur.b, r, c, v0, v1, pre[mm][bj][0], pre[mm][bj][1]);
;                         else if constexpr (Epi::PERM) E.frag8(cur.b, r, c, v0, v1);
;     DEVI f32x4 load(int r, int c) const { const bf16x4 y = *(const bf16x4*)(Y + (size_t)r * DM + c); return (f32x4){bf2f((u16)y[0]), bf2f((u16)y[1]), bf2f((u16)y[2]), bf2f((u16)y[3])}; }
	v_add_f32_e32 v89, 1.0, v89
	v_add_f32_e32 v86, 1.0, v86
	v_add_f32_e32 v87, 1.0, v87
	v_rcp_f32_e32 v88, v88
	v_add_f32_e32 v84, 1.0, v84
	v_rcp_f32_e32 v89, v89
	v_add_f32_e32 v85, 1.0, v85
	v_rcp_f32_e32 v86, v86
	v_rcp_f32_e32 v87, v87
	v_rcp_f32_e32 v84, v84
	v_rcp_f32_e32 v85, v85
	v_and_b32_e32 v91, 0xffff0000, v108
	v_lshlrev_b32_e32 v90, 16, v108
	v_pk_mul_f32 v[82:83], v[82:83], v[90:91]
	v_and_b32_e32 v91, 0xffff0000, v107
	v_lshlrev_b32_e32 v90, 16, v107
	v_pk_mul_f32 v[88:89], v[88:89], v[90:91]
	v_and_b32_e32 v91, 0xffff0000, v109
	v_lshlrev_b32_e32 v90, 16, v109
	v_pk_mul_f32 v[86:87], v[86:87], v[96:97]
	v_pk_mul_f32 v[90:91], v[84:85], v[90:91]
	v_cvt_pk_bf16_f32 v84, v86, v87
	v_cvt_pk_bf16_f32 v85, v88, v89
	v_cvt_pk_bf16_f32 v86, v82, v83
	v_cvt_pk_bf16_f32 v87, v90, v91
	global_store_dwordx4 v[94:95], v[84:87], off offset:256
	s_nop 0
	v_add_f32_e32 v74, v74, v218
	v_add_f32_e32 v75, v75, v219
	v_mul_f32_e32 v74, 0xbfb8aa3b, v74
	v_mul_f32_e32 v75, 0xbfb8aa3b, v75
	v_exp_f32_e32 v74, v74
	v_exp_f32_e32 v75, v75
	v_and_b32_e32 v83, 0xffff0000, v104
	v_lshlrev_b32_e32 v82, 16, v104
	v_add_f32_e32 v74, 1.0, v74
	v_add_f32_e32 v75, 1.0, v75
	v_rcp_f32_e32 v74, v74
	v_rcp_f32_e32 v75, v75
	v_add_f32_e32 v78, v78, v214
	v_add_f32_e32 v79, v79, v215
	v_mul_f32_e32 v78, 0xbfb8aa3b, v78
	v_pk_mul_f32 v[82:83], v[74:75], v[82:83]
	v_add_f32_e32 v75, v76, v220
	v_mul_f32_e32 v75, 0xbfb8aa3b, v75
	v_exp_f32_e32 v75, v75
	v_add_f32_e32 v74, v80, v216
	v_mul_f32_e32 v74, 0xbfb8aa3b, v74
	v_exp_f32_e32 v74, v74
	v_add_f32_e32 v75, 1.0, v75
	v_rcp_f32_e32 v76, v75
	v_add_f32_e32 v75, v81, v217
	v_mul_f32_e32 v75, 0xbfb8aa3b, v75
	v_exp_f32_e32 v75, v75
	v_add_f32_e32 v74, 1.0, v74
	v_rcp_f32_e32 v74, v74
	v_and_b32_e32 v81, 0xffff0000, v103
	v_add_f32_e32 v75, 1.0, v75
	v_rcp_f32_e32 v75, v75
	v_lshlrev_b32_e32 v80, 16, v103
	v_mul_f32_e32 v79, 0xbfb8aa3b, v79
	v_exp_f32_e32 v78, v78
	v_pk_mul_f32 v[80:81], v[74:75], v[80:81]
	v_add_f32_e32 v74, v77, v221
	v_exp_f32_e32 v79, v79
	v_mul_f32_e32 v74, 0xbfb8aa3b, v74
	v_exp_f32_e32 v74, v74
	v_add_f32_e32 v78, 1.0, v78
	v_add_f32_e32 v79, 1.0, v79
	v_rcp_f32_e32 v78, v78
	v_rcp_f32_e32 v79, v79
	v_add_f32_e32 v74, 1.0, v74
	v_rcp_f32_e32 v77, v74
	v_and_b32_e32 v87, 0xffff0000, v102
	v_lshlrev_b32_e32 v86, 16, v102
	v_pk_mul_f32 v[78:79], v[78:79], v[86:87]
	v_and_b32_e32 v75, 0xffff0000, v105
	v_lshlrev_b32_e32 v74, 16, v105
	v_pk_mul_f32 v[84:85], v[76:77], v[74:75]
	v_cvt_pk_bf16_f32 v74, v78, v79
	v_lshl_add_u64 v[78:79], s[64:65], 0, v[118:119]
	v_cvt_pk_bf16_f32 v75, v80, v81
	v_cvt_pk_bf16_f32 v76, v82, v83
	v_cvt_pk_bf16_f32 v77, v84, v85
	v_lshl_add_u64 v[78:79], v[78:79], 0, v[176:177]
	global_store_dwordx4 v[78:79], v[74:77], off
	s_nop 0
	v_lshl_add_u64 v[88:89], v[178:179], 0, s[0:1]
	s_mov_b64 s[0:1], 0x48000
	v_lshl_add_u64 v[86:87], v[178:179], 0, s[0:1]
	s_mov_b64 s[0:1], 0x50000
	v_add_f32_e32 v66, v66, v226
	v_add_f32_e32 v67, v67, v227
	v_mul_f32_e32 v66, 0xbfb8aa3b, v66
	v_mul_f32_e32 v67, 0xbfb8aa3b, v67
	v_exp_f32_e32 v66, v66
	v_exp_f32_e32 v67, v67
	v_and_b32_e32 v75, 0xffff0000, v100
	v_lshlrev_b32_e32 v74, 16, v100
	v_add_f32_e32 v66, 1.0, v66
	v_add_f32_e32 v67, 1.0, v67
	v_rcp_f32_e32 v66, v66
	v_rcp_f32_e32 v67, v67
	v_add_f32_e32 v70, v70, v222
	v_add_f32_e32 v71, v71, v223
	v_mul_f32_e32 v70, 0xbfb8aa3b, v70
	v_pk_mul_f32 v[74:75], v[66:67], v[74:75]
	v_add_f32_e32 v67, v68, v228
	v_mul_f32_e32 v67, 0xbfb8aa3b, v67
	v_exp_f32_e32 v67, v67
	v_add_f32_e32 v66, v72, v224
	v_mul_f32_e32 v66, 0xbfb8aa3b, v66
	v_exp_f32_e32 v66, v66
	v_add_f32_e32 v67, 1.0, v67
	v_rcp_f32_e32 v68, v67
	v_add_f32_e32 v67, v73, v225
	v_mul_f32_e32 v67, 0xbfb8aa3b, v67
	v_exp_f32_e32 v67, v67
	v_add_f32_e32 v66, 1.0, v66
	v_rcp_f32_e32 v66, v66
	v_and_b32_e32 v73, 0xffff0000, v99
	v_add_f32_e32 v67, 1.0, v67
	v_rcp_f32_e32 v67, v67
	v_lshlrev_b32_e32 v72, 16, v99
	v_mul_f32_e32 v71, 0xbfb8aa3b, v71
	v_exp_f32_e32 v70, v70
	v_pk_mul_f32 v[72:73], v[66:67], v[72:73]
	v_add_f32_e32 v66, v69, v229
	v_mul_f32_e32 v66, 0xbfb8aa3b, v66
	v_exp_f32_e32 v71, v71
	v_exp_f32_e32 v66, v66
	v_add_f32_e32 v70, 1.0, v70
	v_rcp_f32_e32 v70, v70
	v_add_f32_e32 v71, 1.0, v71
	v_add_f32_e32 v66, 1.0, v66
	v_rcp_f32_e32 v71, v71
	v_rcp_f32_e32 v69, v66
	v_and_b32_e32 v81, 0xffff0000, v98
	v_lshlrev_b32_e32 v80, 16, v98
	v_and_b32_e32 v67, 0xffff0000, v101
	v_lshlrev_b32_e32 v66, 16, v101
	v_pk_mul_f32 v[70:71], v[70:71], v[80:81]
	v_pk_mul_f32 v[76:77], v[68:69], v[66:67]
	v_cvt_pk_bf16_f32 v66, v70, v71
	v_cvt_pk_bf16_f32 v67, v72, v73
	v_cvt_pk_bf16_f32 v68, v74, v75
	v_cvt_pk_bf16_f32 v69, v76, v77
	global_store_dwordx4 v[78:79], v[66:69], off offset:256
	s_nop 1
	v_lshl_add_u64 v[66:67], s[24:25], 0, v[88:89]
	v_lshl_add_u64 v[66:67], v[66:67], 0, v[176:177]
	global_load_dwordx4 v[78:81], v[66:67], off
	global_load_dwordx4 v[74:77], v[66:67], off offset:256
	v_lshl_add_u64 v[66:67], s[24:25], 0, v[86:87]
	v_lshl_add_u64 v[66:67], v[66:67], 0, v[176:177]
	global_load_dwordx4 v[70:73], v[66:67], off
	s_nop 0
	global_load_dwordx4 v[66:69], v[66:67], off offset:256
	s_nop 0
	s_waitcnt vmcnt(0)
; DEVI float bf2f(u16 b) { return __uint_as_float(((unsigned)b) << 16); }
; template <class Epi>
; DEVI void gemm_phase(LAS unsigned char* lds, const Gemm g, const Epi& E) {
;     ...
;                 if constexpr (Epi::PRE) {
; #pragma unroll
;                     for (int m = 0; m < 2; ++m)
; #pragma unroll
;                         for (int bj = 0; bj < 2; ++bj)
; #pragma unroll
;                             for (int n = 0; n < 2; ++n) pre[m][bj][n] = E.load(row0 + ai * HALF + (m0 + m) * 16, col0 + bj * HALF + n * NST);
;                 }
; #pragma unroll
;                 for (int mm = 0; mm < 2; ++mm) {
;                     const int m = m0 + mm;
;                     const int r = row0 + ai * HALF + m * 16; float rs = 1.f, part = 0.f;
;                     if constexpr (Epi::RS) rs = rsv[ai * 4 + m];
;                     if constexpr (Epi::PAIR) E.pair8(cur.b, r, cur.pn * HALF + wc * 32 + 8 * fq, acc[ai][0][m][0] * rs, acc[ai][0][m][1] * rs, acc[ai][1][m][0] * rs, acc[ai][1][m][1] * rs);
;                     else
; #pragma unroll
;                     for (int bj = 0; bj < 2; ++bj) {
;                         const int c = col0 + bj * HALF; f32x4 v0 = acc[ai][bj][m][0], v1 = acc[ai][bj][m][1];
;                         if constexpr (Epi::RS) { v0 = v0 * rs; v1 = v1 * rs; }
;                         if constexpr (Epi::PRE) part += E.frag_pre8(cur.b, r, c, v0, v1, pre[mm][bj][0], pre[mm][bj][1]);
;                         else if constexpr (Epi::PERM) E.frag8(cur.b, r, c, v0, v1);
;     DEVI f32x4 load(int r, int c) const { const bf16x4 y = *(const bf16x4*)(Y + (size_t)r * DM + c); return (f32x4){bf2f((u16)y[0]), bf2f((u16)y[1]), bf2f((u16)y[2]), bf2f((u16)y[3])}; }
	v_add_f32_e32 v58, v58, v218
	v_add_f32_e32 v59, v59, v219
	v_mul_f32_e32 v58, 0xbfb8aa3b, v58
	v_mul_f32_e32 v59, 0xbfb8aa3b, v59
	v_exp_f32_e32 v58, v58
	v_exp_f32_e32 v59, v59
	v_and_b32_e32 v83, 0xffff0000, v80
	v_lshlrev_b32_e32 v82, 16, v80
	v_add_f32_e32 v58, 1.0, v58
	v_add_f32_e32 v59, 1.0, v59
	v_rcp_f32_e32 v58, v58
	v_rcp_f32_e32 v59, v59
	v_add_f32_e32 v62, v62, v214
	v_add_f32_e32 v63, v63, v215
	v_mul_f32_e32 v62, 0xbfb8aa3b, v62
	v_pk_mul_f32 v[82:83], v[58:59], v[82:83]
	v_add_f32_e32 v59, v60, v220
	v_mul_f32_e32 v59, 0xbfb8aa3b, v59
	v_exp_f32_e32 v59, v59
	v_add_f32_e32 v58, v64, v216
	v_mul_f32_e32 v58, 0xbfb8aa3b, v58
	v_exp_f32_e32 v58, v58
	v_add_f32_e32 v59, 1.0, v59
	v_rcp_f32_e32 v60, v59
	v_add_f32_e32 v59, v65, v217
	v_mul_f32_e32 v59, 0xbfb8aa3b, v59
	v_exp_f32_e32 v59, v59
	v_add_f32_e32 v58, 1.0, v58
	v_rcp_f32_e32 v58, v58
	v_and_b32_e32 v65, 0xffff0000, v79
	v_add_f32_e32 v59, 1.0, v59
	v_rcp_f32_e32 v59, v59
	v_lshlrev_b32_e32 v64, 16, v79
	v_mul_f32_e32 v63, 0xbfb8aa3b, v63
	v_exp_f32_e32 v62, v62
	v_pk_mul_f32 v[64:65], v[58:59], v[64:65]
	v_add_f32_e32 v58, v61, v221
	v_exp_f32_e32 v63, v63
	v_mul_f32_e32 v58, 0xbfb8aa3b, v58
	v_exp_f32_e32 v58, v58
	v_add_f32_e32 v62, 1.0, v62
	v_add_f32_e32 v63, 1.0, v63
	v_rcp_f32_e32 v62, v62
	v_rcp_f32_e32 v63, v63
	v_add_f32_e32 v58, 1.0, v58
	v_rcp_f32_e32 v61, v58
	v_and_b32_e32 v91, 0xffff0000, v78
	v_lshlrev_b32_e32 v90, 16, v78
	v_pk_mul_f32 v[62:63], v[62:63], v[90:91]
	v_and_b32_e32 v59, 0xffff0000, v81
	v_lshlrev_b32_e32 v58, 16, v81
	v_pk_mul_f32 v[78:79], v[60:61], v[58:59]
	v_cvt_pk_bf16_f32 v58, v62, v63
	v_lshl_add_u64 v[62:63], s[64:65], 0, v[88:89]
	v_cvt_pk_bf16_f32 v59, v64, v65
	v_cvt_pk_bf16_f32 v60, v82, v83
	v_cvt_pk_bf16_f32 v61, v78, v79
	v_lshl_add_u64 v[62:63], v[62:63], 0, v[176:177]
	global_store_dwordx4 v[62:63], v[58:61], off
	s_nop 0
	v_and_b32_e32 v65, 0xffff0000, v74
	v_lshlrev_b32_e32 v64, 16, v74
	v_add_f32_e32 v50, v50, v226
	v_add_f32_e32 v51, v51, v227
	v_mul_f32_e32 v50, 0xbfb8aa3b, v50
	v_mul_f32_e32 v51, 0xbfb8aa3b, v51
	v_add_f32_e32 v56, v56, v224
	v_add_f32_e32 v57, v57, v225
	v_add_f32_e32 v54, v54, v222
	v_exp_f32_e32 v50, v50
	v_add_f32_e32 v55, v55, v223
	v_exp_f32_e32 v51, v51
	v_mul_f32_e32 v56, 0xbfb8aa3b, v56
	v_add_f32_e32 v52, v52, v228
	v_mul_f32_e32 v57, 0xbfb8aa3b, v57
	v_add_f32_e32 v53, v53, v229
	v_mul_f32_e32 v54, 0xbfb8aa3b, v54
	v_mul_f32_e32 v55, 0xbfb8aa3b, v55
	v_exp_f32_e32 v56, v56
	v_mul_f32_e32 v52, 0xbfb8aa3b, v52
	v_exp_f32_e32 v57, v57
	v_mul_f32_e32 v53, 0xbfb8aa3b, v53
	v_exp_f32_e32 v54, v54
	v_exp_f32_e32 v55, v55
	v_exp_f32_e32 v52, v52
	v_exp_f32_e32 v53, v53
	v_add_f32_e32 v50, 1.0, v50
	v_add_f32_e32 v51, 1.0, v51
	v_rcp_f32_e32 v50, v50
	v_rcp_f32_e32 v51, v51
	v_add_f32_e32 v56, 1.0, v56
	v_add_f32_e32 v57, 1.0, v57
	v_add_f32_e32 v54, 1.0, v54
	v_add_f32_e32 v55, 1.0, v55
	v_rcp_f32_e32 v56, v56
	v_add_f32_e32 v52, 1.0, v52
	v_rcp_f32_e32 v57, v57
	v_add_f32_e32 v53, 1.0, v53
	v_rcp_f32_e32 v54, v54
	v_rcp_f32_e32 v55, v55
	v_rcp_f32_e32 v52, v52
	v_rcp_f32_e32 v53, v53
	v_and_b32_e32 v59, 0xffff0000, v76
	v_lshlrev_b32_e32 v58, 16, v76
	v_pk_mul_f32 v[50:51], v[50:51], v[58:59]
	v_and_b32_e32 v59, 0xffff0000, v75
	v_lshlrev_b32_e32 v58, 16, v75
	v_pk_mul_f32 v[56:57], v[56:57], v[58:59]
	v_and_b32_e32 v59, 0xffff0000, v77
	v_lshlrev_b32_e32 v58, 16, v77
	v_pk_mul_f32 v[54:55], v[54:55], v[64:65]
	v_pk_mul_f32 v[58:59], v[52:53], v[58:59]
	v_cvt_pk_bf16_f32 v52, v54, v55
	v_cvt_pk_bf16_f32 v53, v56, v57
	v_cvt_pk_bf16_f32 v54, v50, v51
	v_cvt_pk_bf16_f32 v55, v58, v59
	global_store_dwordx4 v[62:63], v[52:55], off offset:256
	s_nop 0
	v_add_f32_e32 v42, v42, v218
	v_add_f32_e32 v43, v43, v219
	v_mul_f32_e32 v42, 0xbfb8aa3b, v42
	v_mul_f32_e32 v43, 0xbfb8aa3b, v43
	v_exp_f32_e32 v42, v42
	v_exp_f32_e32 v43, v43
	v_and_b32_e32 v51, 0xffff0000, v72
	v_lshlrev_b32_e32 v50, 16, v72
	v_add_f32_e32 v42, 1.0, v42
	v_add_f32_e32 v43, 1.0, v43
	v_rcp_f32_e32 v42, v42
	v_rcp_f32_e32 v43, v43
	v_add_f32_e32 v46, v46, v214
	v_add_f32_e32 v47, v47, v215
	v_mul_f32_e32 v46, 0xbfb8aa3b, v46
	v_pk_mul_f32 v[50:51], v[42:43], v[50:51]
	v_add_f32_e32 v43, v44, v220
	v_mul_f32_e32 v43, 0xbfb8aa3b, v43
	v_exp_f32_e32 v43, v43
	v_add_f32_e32 v42, v48, v216
	v_mul_f32_e32 v42, 0xbfb8aa3b, v42
	v_exp_f32_e32 v42, v42
	v_add_f32_e32 v43, 1.0, v43
	v_rcp_f32_e32 v44, v43
	v_add_f32_e32 v43, v49, v217
	v_mul_f32_e32 v43, 0xbfb8aa3b, v43
	v_exp_f32_e32 v43, v43
	v_add_f32_e32 v42, 1.0, v42
	v_rcp_f32_e32 v42, v42
	v_and_b32_e32 v49, 0xffff0000, v71
	v_add_f32_e32 v43, 1.0, v43
	v_rcp_f32_e32 v43, v43
	v_lshlrev_b32_e32 v48, 16, v71
	v_mul_f32_e32 v47, 0xbfb8aa3b, v47
	v_exp_f32_e32 v46, v46
	v_pk_mul_f32 v[48:49], v[42:43], v[48:49]
	v_add_f32_e32 v42, v45, v221
	v_exp_f32_e32 v47, v47
	v_mul_f32_e32 v42, 0xbfb8aa3b, v42
	v_exp_f32_e32 v42, v42
	v_add_f32_e32 v46, 1.0, v46
	v_add_f32_e32 v47, 1.0, v47
	v_rcp_f32_e32 v46, v46
	v_rcp_f32_e32 v47, v47
	v_add_f32_e32 v42, 1.0, v42
	v_rcp_f32_e32 v45, v42
	v_and_b32_e32 v55, 0xffff0000, v70
	v_lshlrev_b32_e32 v54, 16, v70
	v_pk_mul_f32 v[46:47], v[46:47], v[54:55]
	v_and_b32_e32 v43, 0xffff0000, v73
	v_lshlrev_b32_e32 v42, 16, v73
	v_pk_mul_f32 v[52:53], v[44:45], v[42:43]
	v_cvt_pk_bf16_f32 v42, v46, v47
	v_lshl_add_u64 v[46:47], s[64:65], 0, v[86:87]
	v_cvt_pk_bf16_f32 v43, v48, v49
	v_cvt_pk_bf16_f32 v44, v50, v51
	v_cvt_pk_bf16_f32 v45, v52, v53
	v_lshl_add_u64 v[46:47], v[46:47], 0, v[176:177]
	global_store_dwordx4 v[46:47], v[42:45], off
	s_nop 0
	v_lshl_add_u64 v[56:57], v[178:179], 0, s[0:1]
	s_mov_b64 s[0:1], 0x58000
	v_lshl_add_u64 v[54:55], v[178:179], 0, s[0:1]
; DEVI float bf2f(u16 b) { return __uint_as_float(((unsigned)b) << 16); }
; template <class Epi>
; DEVI void gemm_phase(LAS unsigned char* lds, const Gemm g, const Epi& E) {
;     ...
;                 if constexpr (Epi::PRE) {
; #pragma unroll
;                     for (int m = 0; m < 2; ++m)
; #pragma unroll
;                         for (int bj = 0; bj < 2; ++bj)
; #pragma unroll
;                             for (int n = 0; n < 2; ++n) pre[m][bj][n] = E.load(row0 + ai * HALF + (m0 + m) * 16, col0 + bj * HALF + n * NST);
;                 }
; #pragma unroll
;                 for (int mm = 0; mm < 2; ++mm) {
;                     const int m = m0 + mm;
;                     const int r = row0 + ai * HALF + m * 16; float rs = 1.f, part = 0.f;
;                     if constexpr (Epi::RS) rs = rsv[ai * 4 + m];
;                     if constexpr (Epi::PAIR) E.pair8(cur.b, r, cur.pn * HALF + wc * 32 + 8 * fq, acc[ai][0][m][0] * rs, acc[ai][0][m][1] * rs, acc[ai][1][m][0] * rs, acc[ai][1][m][1] * rs);
;                     else
; #pragma unroll
;                     for (int bj = 0; bj < 2; ++bj) {
;                         const int c = col0 + bj * HALF; f32x4 v0 = acc[ai][bj][m][0], v1 = acc[ai][bj][m][1];
;                         if constexpr (Epi::RS) { v0 = v0 * rs; v1 = v1 * rs; }
;                         if constexpr (Epi::PRE) part += E.frag_pre8(cur.b, r, c, v0, v1, pre[mm][bj][0], pre[mm][bj][1]);
;                         else if constexpr (Epi::PERM) E.frag8(cur.b, r, c, v0, v1);
;     DEVI f32x4 load(int r, int c) const { const bf16x4 y = *(const bf16x4*)(Y + (size_t)r * DM + c); return (f32x4){bf2f((u16)y[0]), bf2f((u16)y[1]), bf2f((u16)y[2]), bf2f((u16)y[3])}; }
	s_mov_b32 s0, s4
	v_add_f32_e32 v34, v34, v226
	v_add_f32_e32 v35, v35, v227
	v_mul_f32_e32 v34, 0xbfb8aa3b, v34
	v_mul_f32_e32 v35, 0xbfb8aa3b, v35
	v_exp_f32_e32 v34, v34
	v_exp_f32_e32 v35, v35
	v_and_b32_e32 v43, 0xffff0000, v68
	v_lshlrev_b32_e32 v42, 16, v68
	v_add_f32_e32 v34, 1.0, v34
	v_add_f32_e32 v35, 1.0, v35
	v_rcp_f32_e32 v34, v34
	v_rcp_f32_e32 v35, v35
	v_add_f32_e32 v38, v38, v222
	v_add_f32_e32 v39, v39, v223
	v_mul_f32_e32 v38, 0xbfb8aa3b, v38
	v_pk_mul_f32 v[42:43], v[34:35], v[42:43]
	v_add_f32_e32 v35, v36, v228
	v_mul_f32_e32 v35, 0xbfb8aa3b, v35
	v_exp_f32_e32 v35, v35
	v_add_f32_e32 v34, v40, v224
	v_mul_f32_e32 v34, 0xbfb8aa3b, v34
	v_exp_f32_e32 v34, v34
	v_add_f32_e32 v35, 1.0, v35
	v_rcp_f32_e32 v36, v35
	v_add_f32_e32 v35, v41, v225
	v_mul_f32_e32 v35, 0xbfb8aa3b, v35
	v_exp_f32_e32 v35, v35
	v_add_f32_e32 v34, 1.0, v34
	v_rcp_f32_e32 v34, v34
	v_and_b32_e32 v41, 0xffff0000, v67
	v_add_f32_e32 v35, 1.0, v35
	v_rcp_f32_e32 v35, v35
	v_lshlrev_b32_e32 v40, 16, v67
	v_mul_f32_e32 v39, 0xbfb8aa3b, v39
	v_exp_f32_e32 v38, v38
	v_pk_mul_f32 v[40:41], v[34:35], v[40:41]
	v_add_f32_e32 v34, v37, v229
	v_mul_f32_e32 v34, 0xbfb8aa3b, v34
	v_exp_f32_e32 v39, v39
	v_exp_f32_e32 v34, v34
	v_add_f32_e32 v38, 1.0, v38
	v_rcp_f32_e32 v38, v38
	v_add_f32_e32 v39, 1.0, v39
	v_add_f32_e32 v34, 1.0, v34
	v_rcp_f32_e32 v39, v39
	v_rcp_f32_e32 v37, v34
	v_and_b32_e32 v49, 0xffff0000, v66
	v_lshlrev_b32_e32 v48, 16, v66
	v_and_b32_e32 v35, 0xffff0000, v69
	v_lshlrev_b32_e32 v34, 16, v69
	v_pk_mul_f32 v[38:39], v[38:39], v[48:49]
	v_pk_mul_f32 v[44:45], v[36:37], v[34:35]
	v_cvt_pk_bf16_f32 v34, v38, v39
	v_cvt_pk_bf16_f32 v35, v40, v41
	v_cvt_pk_bf16_f32 v36, v42, v43
	v_cvt_pk_bf16_f32 v37, v44, v45
	global_store_dwordx4 v[46:47], v[34:37], off offset:256
	s_nop 1
	v_lshl_add_u64 v[34:35], s[24:25], 0, v[56:57]
	v_lshl_add_u64 v[34:35], v[34:35], 0, v[176:177]
	global_load_dwordx4 v[46:49], v[34:35], off
	global_load_dwordx4 v[42:45], v[34:35], off offset:256
	v_lshl_add_u64 v[34:35], s[24:25], 0, v[54:55]
	v_lshl_add_u64 v[34:35], v[34:35], 0, v[176:177]
	global_load_dwordx4 v[38:41], v[34:35], off
	s_nop 0
	global_load_dwordx4 v[34:37], v[34:35], off offset:256
	s_nop 0
	s_waitcnt vmcnt(0)
	v_add_f32_e32 v26, v26, v218
	v_add_f32_e32 v27, v27, v219
	v_mul_f32_e32 v26, 0xbfb8aa3b, v26
	v_mul_f32_e32 v27, 0xbfb8aa3b, v27
	v_exp_f32_e32 v26, v26
	v_exp_f32_e32 v27, v27
	v_and_b32_e32 v51, 0xffff0000, v48
	v_lshlrev_b32_e32 v50, 16, v48
	v_add_f32_e32 v26, 1.0, v26
	v_add_f32_e32 v27, 1.0, v27
	v_rcp_f32_e32 v26, v26
	v_rcp_f32_e32 v27, v27
	v_add_f32_e32 v30, v30, v214
	v_add_f32_e32 v31, v31, v215
	v_mul_f32_e32 v30, 0xbfb8aa3b, v30
	v_pk_mul_f32 v[50:51], v[26:27], v[50:51]
	v_add_f32_e32 v27, v28, v220
	v_mul_f32_e32 v27, 0xbfb8aa3b, v27
	v_exp_f32_e32 v27, v27
	v_add_f32_e32 v26, v32, v216
	v_mul_f32_e32 v26, 0xbfb8aa3b, v26
	v_exp_f32_e32 v26, v26
	v_add_f32_e32 v27, 1.0, v27
	v_rcp_f32_e32 v28, v27
	v_add_f32_e32 v27, v33, v217
	v_mul_f32_e32 v27, 0xbfb8aa3b, v27
	v_exp_f32_e32 v27, v27
	v_add_f32_e32 v26, 1.0, v26
	v_rcp_f32_e32 v26, v26
	v_and_b32_e32 v33, 0xffff0000, v47
	v_add_f32_e32 v27, 1.0, v27
	v_rcp_f32_e32 v27, v27
	v_lshlrev_b32_e32 v32, 16, v47
	v_mul_f32_e32 v31, 0xbfb8aa3b, v31
	v_exp_f32_e32 v30, v30
	v_pk_mul_f32 v[32:33], v[26:27], v[32:33]
	v_add_f32_e32 v26, v29, v221
	v_exp_f32_e32 v31, v31
	v_mul_f32_e32 v26, 0xbfb8aa3b, v26
	v_exp_f32_e32 v26, v26
	v_add_f32_e32 v30, 1.0, v30
	v_add_f32_e32 v31, 1.0, v31
	v_rcp_f32_e32 v30, v30
	v_rcp_f32_e32 v31, v31
	v_add_f32_e32 v26, 1.0, v26
	v_rcp_f32_e32 v29, v26
	v_and_b32_e32 v59, 0xffff0000, v46
	v_lshlrev_b32_e32 v58, 16, v46
	v_pk_mul_f32 v[30:31], v[30:31], v[58:59]
	v_and_b32_e32 v27, 0xffff0000, v49
	v_lshlrev_b32_e32 v26, 16, v49
	v_pk_mul_f32 v[46:47], v[28:29], v[26:27]
	v_cvt_pk_bf16_f32 v26, v30, v31
	v_lshl_add_u64 v[30:31], s[64:65], 0, v[56:57]
	v_cvt_pk_bf16_f32 v27, v32, v33
	v_cvt_pk_bf16_f32 v28, v50, v51
	v_cvt_pk_bf16_f32 v29, v46, v47
	v_lshl_add_u64 v[30:31], v[30:31], 0, v[176:177]
	global_store_dwordx4 v[30:31], v[26:29], off
	s_nop 0
	v_and_b32_e32 v33, 0xffff0000, v42
	v_lshlrev_b32_e32 v32, 16, v42
	v_add_f32_e32 v18, v18, v226
	v_add_f32_e32 v19, v19, v227
	v_mul_f32_e32 v18, 0xbfb8aa3b, v18
	v_mul_f32_e32 v19, 0xbfb8aa3b, v19
	v_add_f32_e32 v24, v24, v224
	v_add_f32_e32 v25, v25, v225
	v_add_f32_e32 v22, v22, v222
	v_exp_f32_e32 v18, v18
	v_add_f32_e32 v23, v23, v223
	v_exp_f32_e32 v19, v19
	v_mul_f32_e32 v24, 0xbfb8aa3b, v24
	v_add_f32_e32 v20, v20, v228
	v_mul_f32_e32 v25, 0xbfb8aa3b, v25
	v_add_f32_e32 v21, v21, v229
	v_mul_f32_e32 v22, 0xbfb8aa3b, v22
	v_mul_f32_e32 v23, 0xbfb8aa3b, v23
	v_exp_f32_e32 v24, v24
	v_mul_f32_e32 v20, 0xbfb8aa3b, v20
	v_exp_f32_e32 v25, v25
; DEVI float bf2f(u16 b) { return __uint_as_float(((unsigned)b) << 16); }
; #define PG8_WAIT_V(n) asm volatile("s_waitcnt vmcnt(" #n ")" ::: "memory")
; #define PG8_BAR __builtin_amdgcn_s_barrier()
; template <class Epi>
; DEVI void gemm_phase(LAS unsigned char* lds, const Gemm g, const Epi& E) {
;     ...
;         if (!has_next) break;
; #pragma unroll
;         for (int a = 0; a < 2; ++a)
; #pragma unroll
;             for (int b = 0; b < 2; ++b)
; #pragma unroll
;                 for (int m = 0; m < 4; ++m)
; #pragma unroll
;                     for (int n = 0; n < 2; ++n) acc[a][b][m][n] = (f32x4){0.f, 0.f, 0.f, 0.f};
;         cur = nxt; cA = nA; cB = nB; ++ui;
;     }
;     PG8_WAIT_V(0);
;     if (wr == 0) PG8_BAR;
;     PG8_BAR;
;     DEVI f32x4 load(int r, int c) const { const bf16x4 y = *(const bf16x4*)(Y + (size_t)r * DM + c); return (f32x4){bf2f((u16)y[0]), bf2f((u16)y[1]), bf2f((u16)y[2]), bf2f((u16)y[3])}; }
	v_mul_f32_e32 v21, 0xbfb8aa3b, v21
	v_exp_f32_e32 v22, v22
	v_exp_f32_e32 v23, v23
	v_exp_f32_e32 v20, v20
	v_exp_f32_e32 v21, v21
	v_add_f32_e32 v18, 1.0, v18
	v_add_f32_e32 v19, 1.0, v19
	v_rcp_f32_e32 v18, v18
	v_rcp_f32_e32 v19, v19
	v_add_f32_e32 v24, 1.0, v24
	v_add_f32_e32 v25, 1.0, v25
	v_add_f32_e32 v22, 1.0, v22
	v_add_f32_e32 v23, 1.0, v23
	v_rcp_f32_e32 v24, v24
	v_add_f32_e32 v20, 1.0, v20
	v_rcp_f32_e32 v25, v25
	v_add_f32_e32 v21, 1.0, v21
	v_rcp_f32_e32 v22, v22
	v_rcp_f32_e32 v23, v23
	v_rcp_f32_e32 v20, v20
	v_rcp_f32_e32 v21, v21
	v_and_b32_e32 v27, 0xffff0000, v44
	v_lshlrev_b32_e32 v26, 16, v44
	v_pk_mul_f32 v[18:19], v[18:19], v[26:27]
	v_and_b32_e32 v27, 0xffff0000, v43
	v_lshlrev_b32_e32 v26, 16, v43
	v_pk_mul_f32 v[24:25], v[24:25], v[26:27]
	v_and_b32_e32 v27, 0xffff0000, v45
	v_lshlrev_b32_e32 v26, 16, v45
	v_pk_mul_f32 v[22:23], v[22:23], v[32:33]
	v_pk_mul_f32 v[26:27], v[20:21], v[26:27]
	v_cvt_pk_bf16_f32 v20, v22, v23
	v_cvt_pk_bf16_f32 v21, v24, v25
	v_cvt_pk_bf16_f32 v22, v18, v19
	v_cvt_pk_bf16_f32 v23, v26, v27
	global_store_dwordx4 v[30:31], v[20:23], off offset:256
	s_nop 0
	v_add_f32_e32 v10, v10, v218
	v_add_f32_e32 v11, v11, v219
	v_mul_f32_e32 v10, 0xbfb8aa3b, v10
	v_mul_f32_e32 v11, 0xbfb8aa3b, v11
	v_exp_f32_e32 v10, v10
	v_exp_f32_e32 v11, v11
	v_and_b32_e32 v19, 0xffff0000, v40
	v_lshlrev_b32_e32 v18, 16, v40
	v_add_f32_e32 v10, 1.0, v10
	v_add_f32_e32 v11, 1.0, v11
	v_rcp_f32_e32 v10, v10
	v_rcp_f32_e32 v11, v11
	v_add_f32_e32 v14, v14, v214
	v_add_f32_e32 v15, v15, v215
	v_mul_f32_e32 v14, 0xbfb8aa3b, v14
	v_pk_mul_f32 v[18:19], v[10:11], v[18:19]
	v_add_f32_e32 v11, v12, v220
	v_mul_f32_e32 v11, 0xbfb8aa3b, v11
	v_exp_f32_e32 v11, v11
	v_add_f32_e32 v10, v16, v216
	v_mul_f32_e32 v10, 0xbfb8aa3b, v10
	v_exp_f32_e32 v10, v10
	v_add_f32_e32 v11, 1.0, v11
	v_rcp_f32_e32 v12, v11
	v_add_f32_e32 v11, v17, v217
	v_mul_f32_e32 v11, 0xbfb8aa3b, v11
	v_exp_f32_e32 v11, v11
	v_add_f32_e32 v10, 1.0, v10
	v_rcp_f32_e32 v10, v10
	v_and_b32_e32 v17, 0xffff0000, v39
	v_add_f32_e32 v11, 1.0, v11
	v_rcp_f32_e32 v11, v11
	v_lshlrev_b32_e32 v16, 16, v39
	v_mul_f32_e32 v15, 0xbfb8aa3b, v15
	v_exp_f32_e32 v14, v14
	v_pk_mul_f32 v[16:17], v[10:11], v[16:17]
	v_add_f32_e32 v10, v13, v221
	v_exp_f32_e32 v15, v15
	v_mul_f32_e32 v10, 0xbfb8aa3b, v10
	v_exp_f32_e32 v10, v10
	v_add_f32_e32 v14, 1.0, v14
	v_add_f32_e32 v15, 1.0, v15
	v_rcp_f32_e32 v14, v14
	v_rcp_f32_e32 v15, v15
	v_add_f32_e32 v10, 1.0, v10
	v_rcp_f32_e32 v13, v10
	v_and_b32_e32 v23, 0xffff0000, v38
	v_lshlrev_b32_e32 v22, 16, v38
	v_pk_mul_f32 v[14:15], v[14:15], v[22:23]
	v_and_b32_e32 v11, 0xffff0000, v41
	v_lshlrev_b32_e32 v10, 16, v41
	v_pk_mul_f32 v[20:21], v[12:13], v[10:11]
	v_cvt_pk_bf16_f32 v10, v14, v15
	v_lshl_add_u64 v[14:15], s[64:65], 0, v[54:55]
	v_cvt_pk_bf16_f32 v11, v16, v17
	v_cvt_pk_bf16_f32 v12, v18, v19
	v_cvt_pk_bf16_f32 v13, v20, v21
	v_lshl_add_u64 v[14:15], v[14:15], 0, v[176:177]
	global_store_dwordx4 v[14:15], v[10:13], off
	s_nop 0
	v_add_f32_e32 v0, v0, v226
	v_add_f32_e32 v1, v1, v227
	v_mul_f32_e32 v0, 0xbfb8aa3b, v0
	v_mul_f32_e32 v1, 0xbfb8aa3b, v1
	v_exp_f32_e32 v0, v0
	v_exp_f32_e32 v1, v1
	v_and_b32_e32 v11, 0xffff0000, v36
	v_lshlrev_b32_e32 v10, 16, v36
	v_add_f32_e32 v0, 1.0, v0
	v_add_f32_e32 v1, 1.0, v1
	v_rcp_f32_e32 v0, v0
	v_rcp_f32_e32 v1, v1
	v_add_f32_e32 v4, v4, v222
	v_add_f32_e32 v5, v5, v223
	v_mul_f32_e32 v4, 0xbfb8aa3b, v4
	v_pk_mul_f32 v[10:11], v[0:1], v[10:11]
	v_add_f32_e32 v1, v2, v228
	v_mul_f32_e32 v1, 0xbfb8aa3b, v1
	v_exp_f32_e32 v1, v1
	v_add_f32_e32 v0, v6, v224
	v_mul_f32_e32 v0, 0xbfb8aa3b, v0
	v_exp_f32_e32 v0, v0
	v_add_f32_e32 v1, 1.0, v1
	v_rcp_f32_e32 v2, v1
	v_add_f32_e32 v1, v7, v225
	v_mul_f32_e32 v1, 0xbfb8aa3b, v1
	v_exp_f32_e32 v1, v1
	v_add_f32_e32 v0, 1.0, v0
	v_rcp_f32_e32 v0, v0
	v_and_b32_e32 v7, 0xffff0000, v35
	v_add_f32_e32 v1, 1.0, v1
	v_rcp_f32_e32 v1, v1
	v_lshlrev_b32_e32 v6, 16, v35
	v_mul_f32_e32 v5, 0xbfb8aa3b, v5
	v_exp_f32_e32 v4, v4
	v_pk_mul_f32 v[6:7], v[0:1], v[6:7]
	v_add_f32_e32 v0, v3, v229
	v_mul_f32_e32 v0, 0xbfb8aa3b, v0
	v_exp_f32_e32 v5, v5
	v_exp_f32_e32 v0, v0
	v_add_f32_e32 v4, 1.0, v4
	v_rcp_f32_e32 v4, v4
	v_add_f32_e32 v5, 1.0, v5
	v_add_f32_e32 v0, 1.0, v0
	v_rcp_f32_e32 v5, v5
	v_rcp_f32_e32 v3, v0
	v_and_b32_e32 v17, 0xffff0000, v34
	v_lshlrev_b32_e32 v16, 16, v34
	v_and_b32_e32 v1, 0xffff0000, v37
	v_lshlrev_b32_e32 v0, 16, v37
	v_pk_mul_f32 v[4:5], v[4:5], v[16:17]
	v_pk_mul_f32 v[12:13], v[2:3], v[0:1]
	v_cvt_pk_bf16_f32 v0, v4, v5
	v_cvt_pk_bf16_f32 v1, v6, v7
	v_cvt_pk_bf16_f32 v2, v10, v11
	v_cvt_pk_bf16_f32 v3, v12, v13
	global_store_dwordx4 v[14:15], v[0:3], off offset:256
	s_cbranch_vccz .LBB0_1339
	s_waitcnt vmcnt(0)
	s_cmpk_gt_u32 s46, 0xff
	s_cbranch_scc1 .LBB0_1350
	s_barrier

; #define PG8_STAGE(bufoff, gbase, voff) do { _Pragma("unroll") for (int _i = 0; _i < 2; ++_i) \
;         __builtin_amdgcn_global_load_lds((const unsigned*)((const char*)(gbase) + (voff)[_i]), (LAS unsigned*)(lds + (bufoff) + ldsw + _i * 8192), 16, 0, 0); } while (0)
; #define PG8_LDA(dst, b, h) do { _Pragma("unroll") for (int m = 0; m < 4; ++m) _Pragma("unroll") for (int k = 0; k < 2; ++k) dst[m][k] = *(const LAS bf16x8*)(lds + PG8_SA(b, h) + aoff + m * 2048 + k * 1024); } while (0)
; #define PG8_WAIT_V(n) asm volatile("s_waitcnt vmcnt(" #n ")" ::: "memory")
; #define PG8_WAIT_L(n) asm volatile("s_waitcnt lgkmcnt(" #n ")" ::: "memory")
; template <class Epi>
; DEVI void gemm_phase(LAS unsigned char* lds, const Gemm g, const Epi& E) {
;     ...
;         for (int t = 0; t < nt; t += 2) {
;             const bool last = (t == nt - 2);
;             const char* a1 = cA + (size_t)(t + 1) * kstep;
;             const char* a2 = last ? nA : cA + (size_t)(t + 2) * kstep; const char* b2 = last ? nB : cB + (size_t)(t + 2) * kstep;
;             const char* a3 = a2 + kstep; const char* b3 = b2 + kstep;
;             PG8_LDB(B0, 0, 0); PG8_SCHED; PG8_LDA(At, 0, 0); PG8_STAGE(PG8_SA(1, 1), a1 + hstepA, voffA);
;             PG8_WAIT_L(8); PG8_BAR; PG8_WAIT_L(0); PG8_MMA(0, 0, At, B0); PG8_BAR; PG8_SCHED;
;             PG8_LDB(B1, 0, 1); PG8_STAGE(PG8_SB(0, 0), b2, voffB);
;             PG8_BAR; PG8_WAIT_L(0); PG8_MMA(0, 1, At, B1); PG8_BAR;
;             PG8_LDA(At, 0, 1); PG8_STAGE(PG8_SA(0, 0), a2, voffA);
;             PG8_BAR; PG8_WAIT_L(0); PG8_MMA(1, 0, At, B0); PG8_BAR; PG8_SCHED;
;             PG8_STAGE(PG8_SB(0, 1), b2 + hstepB, voffB);
;             PG8_WAIT_V(6); PG8_BAR; PG8_MMA(1, 1, At, B1); PG8_BAR;
;             PG8_LDB(B0, 1, 0); PG8_SCHED; PG8_LDA(At, 1, 0); PG8_STAGE(PG8_SA(0, 1), a2 + hstepA, voffA);
;             PG8_WAIT_L(8); PG8_BAR; PG8_WAIT_L(0); PG8_MMA(0, 0, At, B0); PG8_BAR; PG8_SCHED;
;             PG8_LDB(B1, 1, 1); PG8_STAGE(PG8_SB(1, 0), b3, voffB);
;             PG8_BAR; PG8_WAIT_L(0); PG8_MMA(0, 1, At, B1); PG8_BAR;
;             PG8_LDA(At, 1, 1); PG8_STAGE(PG8_SA(1, 0), a3, voffA);
;             PG8_BAR; PG8_WAIT_L(0); PG8_MMA(1, 0, At, B0); PG8_BAR; PG8_SCHED;
;             PG8_STAGE(PG8_SB(1, 1), b3 + hstepB, voffB);
;             PG8_WAIT_V(6); PG8_BAR; PG8_MMA(1, 1, At, B1); PG8_BAR;
;         }
.LBB0_1507:
	s_add_u32 s19, s6, 0xfffc0080
	s_addc_u32 s26, s7, -1
	s_add_i32 s27, 0, 0x10000
	v_add_u32_e32 v142, s27, v199
	ds_read_b128 v[130:133], v142
	ds_read_b128 v[134:137], v142 offset:1024
	ds_read_b128 v[138:141], v142 offset:2048
	ds_read_b128 v[142:145], v142 offset:3072
	s_cmp_eq_u32 s18, 12
	s_cselect_b32 s79, s0, s26
	s_cselect_b32 s78, s1, s19
	s_cselect_b32 s69, s15, s13
	s_cselect_b32 s68, s14, s11
	v_lshl_add_u64 v[162:163], s[6:7], 0, v[182:183]
	s_add_i32 m0, s37, 0xc000
	ds_read_b128 v[146:149], v202
	ds_read_b128 v[150:153], v202 offset:1024
	ds_read_b128 v[186:189], v202 offset:2048
	ds_read_b128 v[190:193], v202 offset:3072
	ds_read_b128 v[194:197], v202 offset:4096
	ds_read_b128 v[204:207], v202 offset:5120
	ds_read_b128 v[214:217], v202 offset:6144
	ds_read_b128 v[218:221], v202 offset:7168
	global_load_lds_dwordx4 v[162:163], off
	s_add_i32 m0, s37, 0xe000
	v_lshl_add_u64 v[162:163], s[6:7], 0, v[184:185]
	global_load_lds_dwordx4 v[162:163], off
	s_waitcnt lgkmcnt(8)
	s_barrier
	s_waitcnt lgkmcnt(0)
	v_mfma_f32_16x16x32_bf16 v[126:129], v[130:133], v[146:149], v[126:129]
	v_mfma_f32_16x16x32_bf16 v[122:125], v[138:141], v[146:149], v[122:125]
	v_mfma_f32_16x16x32_bf16 v[110:113], v[130:133], v[186:189], v[110:113]
	v_mfma_f32_16x16x32_bf16 v[106:109], v[138:141], v[186:189], v[106:109]
	v_mfma_f32_16x16x32_bf16 v[94:97], v[130:133], v[194:197], v[94:97]
	v_mfma_f32_16x16x32_bf16 v[90:93], v[138:141], v[194:197], v[90:93]
	v_mfma_f32_16x16x32_bf16 v[78:81], v[130:133], v[214:217], v[78:81]
	v_mfma_f32_16x16x32_bf16 v[74:77], v[138:141], v[214:217], v[74:77]
	v_mfma_f32_16x16x32_bf16 v[126:129], v[134:137], v[150:153], v[126:129]
	v_mfma_f32_16x16x32_bf16 v[122:125], v[142:145], v[150:153], v[122:125]
	v_mfma_f32_16x16x32_bf16 v[110:113], v[134:137], v[190:193], v[110:113]
	v_mfma_f32_16x16x32_bf16 v[106:109], v[142:145], v[190:193], v[106:109]
	v_mfma_f32_16x16x32_bf16 v[94:97], v[134:137], v[204:207], v[94:97]
	v_mfma_f32_16x16x32_bf16 v[90:93], v[142:145], v[204:207], v[90:93]
	v_mfma_f32_16x16x32_bf16 v[78:81], v[134:137], v[218:221], v[78:81]
	v_mfma_f32_16x16x32_bf16 v[74:77], v[142:145], v[218:221], v[74:77]
	s_barrier
	s_add_i32 s19, 0, 0x14000
	v_add_u32_e32 v162, s19, v199
	s_add_i32 s26, s27, s80
	ds_read_b128 v[222:225], v162
	ds_read_b128 v[226:229], v162 offset:1024
	ds_read_b128 v[230:233], v162 offset:2048
	ds_read_b128 v[234:237], v162 offset:3072
	v_lshl_add_u64 v[162:163], s[68:69], 0, v[8:9]
	s_mov_b32 m0, s26
	v_lshl_add_u64 v[164:165], s[68:69], 0, v[180:181]
	global_load_lds_dwordx4 v[162:163], off
	s_add_i32 m0, s26, 0x2000
	s_nop 0
	global_load_lds_dwordx4 v[164:165], off
	s_barrier
	s_waitcnt lgkmcnt(0)
	v_mfma_f32_16x16x32_bf16 v[118:121], v[222:225], v[146:149], v[118:121]
	v_mfma_f32_16x16x32_bf16 v[114:117], v[230:233], v[146:149], v[114:117]
	v_mfma_f32_16x16x32_bf16 v[102:105], v[222:225], v[186:189], v[102:105]
	v_mfma_f32_16x16x32_bf16 v[98:101], v[230:233], v[186:189], v[98:101]
	v_mfma_f32_16x16x32_bf16 v[86:89], v[222:225], v[194:197], v[86:89]
	v_mfma_f32_16x16x32_bf16 v[82:85], v[230:233], v[194:197], v[82:85]
	v_mfma_f32_16x16x32_bf16 v[70:73], v[222:225], v[214:217], v[70:73]
	v_mfma_f32_16x16x32_bf16 v[62:65], v[230:233], v[214:217], v[62:65]
	v_mfma_f32_16x16x32_bf16 v[118:121], v[226:229], v[150:153], v[118:121]
	v_mfma_f32_16x16x32_bf16 v[114:117], v[234:237], v[150:153], v[114:117]
	v_mfma_f32_16x16x32_bf16 v[102:105], v[226:229], v[190:193], v[102:105]
	v_mfma_f32_16x16x32_bf16 v[98:101], v[234:237], v[190:193], v[98:101]
	v_mfma_f32_16x16x32_bf16 v[86:89], v[226:229], v[204:207], v[86:89]
	v_mfma_f32_16x16x32_bf16 v[82:85], v[234:237], v[204:207], v[82:85]
	v_mfma_f32_16x16x32_bf16 v[70:73], v[226:229], v[218:221], v[70:73]
	v_mfma_f32_16x16x32_bf16 v[62:65], v[234:237], v[218:221], v[62:65]
	s_barrier
	s_mov_b32 m0, s37
	v_lshl_add_u64 v[208:209], s[78:79], 0, v[176:177]
	ds_read_b128 v[146:149], v202 offset:16384
	ds_read_b128 v[150:153], v202 offset:17408
	ds_read_b128 v[186:189], v202 offset:18432
	ds_read_b128 v[190:193], v202 offset:19456
	ds_read_b128 v[194:197], v202 offset:20480
	ds_read_b128 v[204:207], v202 offset:21504
	ds_read_b128 v[214:217], v202 offset:22528
	ds_read_b128 v[218:221], v202 offset:23552
	global_load_lds_dwordx4 v[208:209], off
	s_mov_b32 m0, s47
	v_lshl_add_u64 v[238:239], s[78:79], 0, v[178:179]
	global_load_lds_dwordx4 v[238:239], off
	s_barrier
	s_waitcnt lgkmcnt(0)
	v_mfma_f32_16x16x32_bf16 v[66:69], v[130:133], v[146:149], v[66:69]
	v_mfma_f32_16x16x32_bf16 v[54:57], v[138:141], v[146:149], v[54:57]
	v_mfma_f32_16x16x32_bf16 v[46:49], v[130:133], v[186:189], v[46:49]
	v_mfma_f32_16x16x32_bf16 v[38:41], v[138:141], v[186:189], v[38:41]
	v_mfma_f32_16x16x32_bf16 v[30:33], v[130:133], v[194:197], v[30:33]
	v_mfma_f32_16x16x32_bf16 v[22:25], v[138:141], v[194:197], v[22:25]
	v_mfma_f32_16x16x32_bf16 v[14:17], v[130:133], v[214:217], v[14:17]
	v_mfma_f32_16x16x32_bf16 v[4:7], v[138:141], v[214:217], v[4:7]
	v_mfma_f32_16x16x32_bf16 v[66:69], v[134:137], v[150:153], v[66:69]
	v_mfma_f32_16x16x32_bf16 v[54:57], v[142:145], v[150:153], v[54:57]
	v_mfma_f32_16x16x32_bf16 v[46:49], v[134:137], v[190:193], v[46:49]
	v_mfma_f32_16x16x32_bf16 v[38:41], v[142:145], v[190:193], v[38:41]
	v_mfma_f32_16x16x32_bf16 v[30:33], v[134:137], v[204:207], v[30:33]
	v_mfma_f32_16x16x32_bf16 v[22:25], v[142:145], v[204:207], v[22:25]
	v_mfma_f32_16x16x32_bf16 v[14:17], v[134:137], v[218:221], v[14:17]
	v_mfma_f32_16x16x32_bf16 v[4:7], v[142:145], v[218:221], v[4:7]
	s_barrier
; #define PG8_STAGE(bufoff, gbase, voff) do { _Pragma("unroll") for (int _i = 0; _i < 2; ++_i) \
;         __builtin_amdgcn_global_load_lds((const unsigned*)((const char*)(gbase) + (voff)[_i]), (LAS unsigned*)(lds + (bufoff) + ldsw + _i * 8192), 16, 0, 0); } while (0)
; #define PG8_LDA(dst, b, h) do { _Pragma("unroll") for (int m = 0; m < 4; ++m) _Pragma("unroll") for (int k = 0; k < 2; ++k) dst[m][k] = *(const LAS bf16x8*)(lds + PG8_SA(b, h) + aoff + m * 2048 + k * 1024); } while (0)
; #define PG8_WAIT_V(n) asm volatile("s_waitcnt vmcnt(" #n ")" ::: "memory")
; #define PG8_WAIT_L(n) asm volatile("s_waitcnt lgkmcnt(" #n ")" ::: "memory")
; template <class Epi>
; DEVI void gemm_phase(LAS unsigned char* lds, const Gemm g, const Epi& E) {
;     ...
;         for (int t = 0; t < nt; t += 2) {
;             const bool last = (t == nt - 2);
;             const char* a1 = cA + (size_t)(t + 1) * kstep;
;             const char* a2 = last ? nA : cA + (size_t)(t + 2) * kstep; const char* b2 = last ? nB : cB + (size_t)(t + 2) * kstep;
;             const char* a3 = a2 + kstep; const char* b3 = b2 + kstep;
;             PG8_LDB(B0, 0, 0); PG8_SCHED; PG8_LDA(At, 0, 0); PG8_STAGE(PG8_SA(1, 1), a1 + hstepA, voffA);
;             PG8_WAIT_L(8); PG8_BAR; PG8_WAIT_L(0); PG8_MMA(0, 0, At, B0); PG8_BAR; PG8_SCHED;
;             PG8_LDB(B1, 0, 1); PG8_STAGE(PG8_SB(0, 0), b2, voffB);
;             PG8_BAR; PG8_WAIT_L(0); PG8_MMA(0, 1, At, B1); PG8_BAR;
;             PG8_LDA(At, 0, 1); PG8_STAGE(PG8_SA(0, 0), a2, voffA);
;             PG8_BAR; PG8_WAIT_L(0); PG8_MMA(1, 0, At, B0); PG8_BAR; PG8_SCHED;
;             PG8_STAGE(PG8_SB(0, 1), b2 + hstepB, voffB);
;             PG8_WAIT_V(6); PG8_BAR; PG8_MMA(1, 1, At, B1); PG8_BAR;
;             PG8_LDB(B0, 1, 0); PG8_SCHED; PG8_LDA(At, 1, 0); PG8_STAGE(PG8_SA(0, 1), a2 + hstepA, voffA);
;             PG8_WAIT_L(8); PG8_BAR; PG8_WAIT_L(0); PG8_MMA(0, 0, At, B0); PG8_BAR; PG8_SCHED;
;             PG8_LDB(B1, 1, 1); PG8_STAGE(PG8_SB(1, 0), b3, voffB);
;             PG8_BAR; PG8_WAIT_L(0); PG8_MMA(0, 1, At, B1); PG8_BAR;
;             PG8_LDA(At, 1, 1); PG8_STAGE(PG8_SA(1, 0), a3, voffA);
;             PG8_BAR; PG8_WAIT_L(0); PG8_MMA(1, 0, At, B0); PG8_BAR; PG8_SCHED;
;             PG8_STAGE(PG8_SB(1, 1), b3 + hstepB, voffB);
;             PG8_WAIT_V(6); PG8_BAR; PG8_MMA(1, 1, At, B1); PG8_BAR;
;         }
	s_add_u32 s26, s68, 0x40000
	s_addc_u32 s27, s69, 0
	s_add_i32 s19, s19, s80
	s_mov_b32 m0, s19
	v_lshl_add_u64 v[130:131], s[26:27], 0, v[8:9]
	global_load_lds_dwordx4 v[130:131], off
	s_add_i32 m0, s19, 0x2000
	v_lshl_add_u64 v[130:131], s[26:27], 0, v[180:181]
	global_load_lds_dwordx4 v[130:131], off
	s_waitcnt vmcnt(6)
	s_barrier
	v_mfma_f32_16x16x32_bf16 v[58:61], v[222:225], v[146:149], v[58:61]
	v_mfma_f32_16x16x32_bf16 v[50:53], v[230:233], v[146:149], v[50:53]
	v_mfma_f32_16x16x32_bf16 v[42:45], v[222:225], v[186:189], v[42:45]
	v_mfma_f32_16x16x32_bf16 v[34:37], v[230:233], v[186:189], v[34:37]
	v_mfma_f32_16x16x32_bf16 v[26:29], v[222:225], v[194:197], v[26:29]
	v_mfma_f32_16x16x32_bf16 v[18:21], v[230:233], v[194:197], v[18:21]
	v_mfma_f32_16x16x32_bf16 v[10:13], v[222:225], v[214:217], v[10:13]
	v_mfma_f32_16x16x32_bf16 v[0:3], v[230:233], v[214:217], v[0:3]
	v_mfma_f32_16x16x32_bf16 v[58:61], v[226:229], v[150:153], v[58:61]
	v_mfma_f32_16x16x32_bf16 v[50:53], v[234:237], v[150:153], v[50:53]
	v_mfma_f32_16x16x32_bf16 v[42:45], v[226:229], v[190:193], v[42:45]
	v_mfma_f32_16x16x32_bf16 v[34:37], v[234:237], v[190:193], v[34:37]
	v_mfma_f32_16x16x32_bf16 v[26:29], v[226:229], v[204:207], v[26:29]
	v_mfma_f32_16x16x32_bf16 v[18:21], v[234:237], v[204:207], v[18:21]
	v_mfma_f32_16x16x32_bf16 v[10:13], v[226:229], v[218:221], v[10:13]
	v_mfma_f32_16x16x32_bf16 v[0:3], v[234:237], v[218:221], v[0:3]
	s_barrier
	s_add_i32 s19, 0, 0x18000
	v_add_u32_e32 v142, s19, v199
	ds_read_b128 v[130:133], v142
	ds_read_b128 v[134:137], v142 offset:1024
	ds_read_b128 v[138:141], v142 offset:2048
	ds_read_b128 v[142:145], v142 offset:3072
	s_add_u32 s26, s78, 0x40000
	s_addc_u32 s27, s79, 0
	s_mov_b32 m0, s81
	v_lshl_add_u64 v[222:223], s[26:27], 0, v[176:177]
	ds_read_b128 v[146:149], v202 offset:32768
	ds_read_b128 v[150:153], v202 offset:33792
	ds_read_b128 v[186:189], v202 offset:34816
	ds_read_b128 v[190:193], v202 offset:35840
	ds_read_b128 v[194:197], v202 offset:36864
	ds_read_b128 v[204:207], v202 offset:37888
	ds_read_b128 v[214:217], v202 offset:38912
	ds_read_b128 v[218:221], v202 offset:39936
	global_load_lds_dwordx4 v[222:223], off
	s_mov_b32 m0, s82
	v_lshl_add_u64 v[222:223], s[26:27], 0, v[178:179]
	global_load_lds_dwordx4 v[222:223], off
	s_waitcnt lgkmcnt(8)
	s_barrier
	s_waitcnt lgkmcnt(0)
	v_mfma_f32_16x16x32_bf16 v[126:129], v[130:133], v[146:149], v[126:129]
	v_mfma_f32_16x16x32_bf16 v[122:125], v[138:141], v[146:149], v[122:125]
	v_mfma_f32_16x16x32_bf16 v[110:113], v[130:133], v[186:189], v[110:113]
	v_mfma_f32_16x16x32_bf16 v[106:109], v[138:141], v[186:189], v[106:109]
	v_mfma_f32_16x16x32_bf16 v[94:97], v[130:133], v[194:197], v[94:97]
	v_mfma_f32_16x16x32_bf16 v[90:93], v[138:141], v[194:197], v[90:93]
	v_mfma_f32_16x16x32_bf16 v[78:81], v[130:133], v[214:217], v[78:81]
	v_mfma_f32_16x16x32_bf16 v[74:77], v[138:141], v[214:217], v[74:77]
	v_mfma_f32_16x16x32_bf16 v[126:129], v[134:137], v[150:153], v[126:129]
	v_mfma_f32_16x16x32_bf16 v[122:125], v[142:145], v[150:153], v[122:125]
	v_mfma_f32_16x16x32_bf16 v[110:113], v[134:137], v[190:193], v[110:113]
	v_mfma_f32_16x16x32_bf16 v[106:109], v[142:145], v[190:193], v[106:109]
	v_mfma_f32_16x16x32_bf16 v[94:97], v[134:137], v[204:207], v[94:97]
	v_mfma_f32_16x16x32_bf16 v[90:93], v[142:145], v[204:207], v[90:93]
	v_mfma_f32_16x16x32_bf16 v[78:81], v[134:137], v[218:221], v[78:81]
	v_mfma_f32_16x16x32_bf16 v[74:77], v[142:145], v[218:221], v[74:77]
	s_barrier
	s_add_i32 s38, 0, 0x1c000
	s_add_i32 s19, s19, s80
	v_add_u32_e32 v213, s38, v199
	v_lshl_add_u64 v[162:163], v[162:163], 0, s[70:71]
	s_mov_b32 m0, s19
	ds_read_b128 v[222:225], v213
	ds_read_b128 v[226:229], v213 offset:1024
	ds_read_b128 v[230:233], v213 offset:2048
	ds_read_b128 v[234:237], v213 offset:3072
	global_load_lds_dwordx4 v[162:163], off
	s_add_i32 m0, s19, 0x2000
	v_lshl_add_u64 v[162:163], v[164:165], 0, s[70:71]
	global_load_lds_dwordx4 v[162:163], off
	s_barrier
	s_waitcnt lgkmcnt(0)
	v_mfma_f32_16x16x32_bf16 v[118:121], v[222:225], v[146:149], v[118:121]
	v_mfma_f32_16x16x32_bf16 v[114:117], v[230:233], v[146:149], v[114:117]
	v_mfma_f32_16x16x32_bf16 v[102:105], v[222:225], v[186:189], v[102:105]
	v_mfma_f32_16x16x32_bf16 v[98:101], v[230:233], v[186:189], v[98:101]
	v_mfma_f32_16x16x32_bf16 v[86:89], v[222:225], v[194:197], v[86:89]
	v_mfma_f32_16x16x32_bf16 v[82:85], v[230:233], v[194:197], v[82:85]
	v_mfma_f32_16x16x32_bf16 v[70:73], v[222:225], v[214:217], v[70:73]
	v_mfma_f32_16x16x32_bf16 v[62:65], v[230:233], v[214:217], v[62:65]
	v_mfma_f32_16x16x32_bf16 v[118:121], v[226:229], v[150:153], v[118:121]
	v_mfma_f32_16x16x32_bf16 v[114:117], v[234:237], v[150:153], v[114:117]
	v_mfma_f32_16x16x32_bf16 v[102:105], v[226:229], v[190:193], v[102:105]
	v_mfma_f32_16x16x32_bf16 v[98:101], v[234:237], v[190:193], v[98:101]
	v_mfma_f32_16x16x32_bf16 v[86:89], v[226:229], v[204:207], v[86:89]
	v_mfma_f32_16x16x32_bf16 v[82:85], v[234:237], v[204:207], v[82:85]
	v_mfma_f32_16x16x32_bf16 v[70:73], v[226:229], v[218:221], v[70:73]
	v_mfma_f32_16x16x32_bf16 v[62:65], v[234:237], v[218:221], v[62:65]
	s_barrier
	s_mov_b32 m0, s83
	v_lshl_add_u64 v[162:163], v[208:209], 0, s[70:71]
	ds_read_b128 v[146:149], v202 offset:49152
	ds_read_b128 v[150:153], v202 offset:50176
	ds_read_b128 v[186:189], v202 offset:51200
	ds_read_b128 v[190:193], v202 offset:52224
	ds_read_b128 v[194:197], v202 offset:53248
	ds_read_b128 v[204:207], v202 offset:54272
	ds_read_b128 v[214:217], v202 offset:55296
	ds_read_b128 v[218:221], v202 offset:56320
	global_load_lds_dwordx4 v[162:163], off
	s_mov_b32 m0, s84
	v_lshl_add_u64 v[162:163], v[238:239], 0, s[70:71]
	global_load_lds_dwordx4 v[162:163], off
	s_barrier
; #define PG8_STAGE(bufoff, gbase, voff) do { _Pragma("unroll") for (int _i = 0; _i < 2; ++_i) \
;         __builtin_amdgcn_global_load_lds((const unsigned*)((const char*)(gbase) + (voff)[_i]), (LAS unsigned*)(lds + (bufoff) + ldsw + _i * 8192), 16, 0, 0); } while (0)
; #define PG8_LDA(dst, b, h) do { _Pragma("unroll") for (int m = 0; m < 4; ++m) _Pragma("unroll") for (int k = 0; k < 2; ++k) dst[m][k] = *(const LAS bf16x8*)(lds + PG8_SA(b, h) + aoff + m * 2048 + k * 1024); } while (0)
; #define PG8_WAIT_V(n) asm volatile("s_waitcnt vmcnt(" #n ")" ::: "memory")
; #define PG8_WAIT_L(n) asm volatile("s_waitcnt lgkmcnt(" #n ")" ::: "memory")
; template <class Epi>
; DEVI void gemm_phase(LAS unsigned char* lds, const Gemm g, const Epi& E) {
;     ...
;         for (int t = 0; t < nt; t += 2) {
;             const bool last = (t == nt - 2);
;             const char* a1 = cA + (size_t)(t + 1) * kstep;
;             const char* a2 = last ? nA : cA + (size_t)(t + 2) * kstep; const char* b2 = last ? nB : cB + (size_t)(t + 2) * kstep;
;             const char* a3 = a2 + kstep; const char* b3 = b2 + kstep;
;             PG8_LDB(B0, 0, 0); PG8_SCHED; PG8_LDA(At, 0, 0); PG8_STAGE(PG8_SA(1, 1), a1 + hstepA, voffA);
;             PG8_WAIT_L(8); PG8_BAR; PG8_WAIT_L(0); PG8_MMA(0, 0, At, B0); PG8_BAR; PG8_SCHED;
;             PG8_LDB(B1, 0, 1); PG8_STAGE(PG8_SB(0, 0), b2, voffB);
;             PG8_BAR; PG8_WAIT_L(0); PG8_MMA(0, 1, At, B1); PG8_BAR;
;             PG8_LDA(At, 0, 1); PG8_STAGE(PG8_SA(0, 0), a2, voffA);
;             PG8_BAR; PG8_WAIT_L(0); PG8_MMA(1, 0, At, B0); PG8_BAR; PG8_SCHED;
;             PG8_STAGE(PG8_SB(0, 1), b2 + hstepB, voffB);
;             PG8_WAIT_V(6); PG8_BAR; PG8_MMA(1, 1, At, B1); PG8_BAR;
;             PG8_LDB(B0, 1, 0); PG8_SCHED; PG8_LDA(At, 1, 0); PG8_STAGE(PG8_SA(0, 1), a2 + hstepA, voffA);
;             PG8_WAIT_L(8); PG8_BAR; PG8_WAIT_L(0); PG8_MMA(0, 0, At, B0); PG8_BAR; PG8_SCHED;
;             PG8_LDB(B1, 1, 1); PG8_STAGE(PG8_SB(1, 0), b3, voffB);
;             PG8_BAR; PG8_WAIT_L(0); PG8_MMA(0, 1, At, B1); PG8_BAR;
;             PG8_LDA(At, 1, 1); PG8_STAGE(PG8_SA(1, 0), a3, voffA);
;             PG8_BAR; PG8_WAIT_L(0); PG8_MMA(1, 0, At, B0); PG8_BAR; PG8_SCHED;
;             PG8_STAGE(PG8_SB(1, 1), b3 + hstepB, voffB);
;             PG8_WAIT_V(6); PG8_BAR; PG8_MMA(1, 1, At, B1); PG8_BAR;
;         }
	s_waitcnt lgkmcnt(0)
	v_mfma_f32_16x16x32_bf16 v[66:69], v[130:133], v[146:149], v[66:69]
	v_mfma_f32_16x16x32_bf16 v[54:57], v[138:141], v[146:149], v[54:57]
	v_mfma_f32_16x16x32_bf16 v[46:49], v[130:133], v[186:189], v[46:49]
	v_mfma_f32_16x16x32_bf16 v[38:41], v[138:141], v[186:189], v[38:41]
	v_mfma_f32_16x16x32_bf16 v[30:33], v[130:133], v[194:197], v[30:33]
	v_mfma_f32_16x16x32_bf16 v[22:25], v[138:141], v[194:197], v[22:25]
	v_mfma_f32_16x16x32_bf16 v[14:17], v[130:133], v[214:217], v[14:17]
	v_mfma_f32_16x16x32_bf16 v[4:7], v[138:141], v[214:217], v[4:7]
	v_mfma_f32_16x16x32_bf16 v[66:69], v[134:137], v[150:153], v[66:69]
	v_mfma_f32_16x16x32_bf16 v[54:57], v[142:145], v[150:153], v[54:57]
	v_mfma_f32_16x16x32_bf16 v[46:49], v[134:137], v[190:193], v[46:49]
	v_mfma_f32_16x16x32_bf16 v[38:41], v[142:145], v[190:193], v[38:41]
	v_mfma_f32_16x16x32_bf16 v[30:33], v[134:137], v[204:207], v[30:33]
	v_mfma_f32_16x16x32_bf16 v[22:25], v[142:145], v[204:207], v[22:25]
	v_mfma_f32_16x16x32_bf16 v[14:17], v[134:137], v[218:221], v[14:17]
	v_mfma_f32_16x16x32_bf16 v[4:7], v[142:145], v[218:221], v[4:7]
	s_barrier
	s_add_u32 s26, s68, 0x40080
	s_addc_u32 s27, s69, 0
	s_add_i32 s19, s38, s80
	s_mov_b32 m0, s19
	v_lshl_add_u64 v[130:131], s[26:27], 0, v[8:9]
	global_load_lds_dwordx4 v[130:131], off
	s_add_i32 m0, s19, 0x2000
	v_lshl_add_u64 v[130:131], s[26:27], 0, v[180:181]
	global_load_lds_dwordx4 v[130:131], off
	s_waitcnt vmcnt(6)
	s_barrier
	v_mfma_f32_16x16x32_bf16 v[58:61], v[222:225], v[146:149], v[58:61]
	v_mfma_f32_16x16x32_bf16 v[50:53], v[230:233], v[146:149], v[50:53]
	v_mfma_f32_16x16x32_bf16 v[42:45], v[222:225], v[186:189], v[42:45]
	v_mfma_f32_16x16x32_bf16 v[34:37], v[230:233], v[186:189], v[34:37]
	v_mfma_f32_16x16x32_bf16 v[26:29], v[222:225], v[194:197], v[26:29]
	v_mfma_f32_16x16x32_bf16 v[18:21], v[230:233], v[194:197], v[18:21]
	v_mfma_f32_16x16x32_bf16 v[10:13], v[222:225], v[214:217], v[10:13]
	v_mfma_f32_16x16x32_bf16 v[0:3], v[230:233], v[214:217], v[0:3]
	v_mfma_f32_16x16x32_bf16 v[58:61], v[226:229], v[150:153], v[58:61]
	v_mfma_f32_16x16x32_bf16 v[50:53], v[234:237], v[150:153], v[50:53]
	v_mfma_f32_16x16x32_bf16 v[42:45], v[226:229], v[190:193], v[42:45]
	v_mfma_f32_16x16x32_bf16 v[34:37], v[234:237], v[190:193], v[34:37]
	v_mfma_f32_16x16x32_bf16 v[26:29], v[226:229], v[204:207], v[26:29]
	v_mfma_f32_16x16x32_bf16 v[18:21], v[234:237], v[204:207], v[18:21]
	v_mfma_f32_16x16x32_bf16 v[10:13], v[226:229], v[218:221], v[10:13]
	v_mfma_f32_16x16x32_bf16 v[0:3], v[234:237], v[218:221], v[0:3]
	s_barrier
	s_add_i32 s18, s18, 2
	s_add_u32 s6, s6, 0x100
	s_addc_u32 s7, s7, 0
	s_add_u32 s11, s11, 0x100
	s_addc_u32 s13, s13, 0
	s_cmp_gt_u32 s18, 13
	s_cbranch_scc0 .LBB0_1507
; #define LAS __attribute__((address_space(3)))
; template <class Epi>
; DEVI void gemm_phase(LAS unsigned char* lds, const Gemm g, const Epi& E) {
;     ...
;             const int row0 = cur.pm * BM + wr * 64 + fr, col0 = cur.pn * BM + wc * 32 + (Epi::PERM ? 8 : 4) * fq; constexpr int NST = Epi::PERM ? 4 : 16;
;             float rsv[8];
;             if constexpr (Epi::RS) { f32x4 q4[8];
; #pragma unroll
;                 for (int i = 0; i < 8; ++i) q4[i] = *(const f32x4*)(E.ssq_in + (size_t)(row0 + (i >> 2) * HALF + (i & 3) * 16) * 4);
; #pragma unroll
;                 for (int i = 0; i < 8; ++i) rsv[i] = rsqrtf((((q4[i][0] + q4[i][1]) + q4[i][2]) + q4[i][3]) * (1.f / DM) + 1e-6f); }
;             if constexpr (Epi::SOFTMAX) {
;                 LAS float* red = (LAS float*)(lds + 131072);
; #pragma unroll
;                 for (int ai = 0; ai < 2; ++ai)
; #pragma unroll
;                     for (int m = 0; m < 4; ++m) { const float sc = rsv[ai * 4 + m] * 0.0625f; float part = 0.f;
; #pragma unroll
;                         for (int bj = 0; bj < 2; ++bj)
; #pragma unroll
;                             for (int n = 0; n < 2; ++n)
; #pragma unroll
;                                 for (int j = 0; j < 4; ++j) { const float e = __expf(fmaxf(fminf(acc[ai][bj][m][n][j] * sc, 80.f), -80.f)); acc[ai][bj][m][n][j] = e; part += e; }
;                         part += __shfl_xor(part, 16); part += __shfl_xor(part, 32);
;                         if (fq == 0) red[(wr * 4 + wc) * 128 + ai * 64 + m * 16 + fr] = part; }
	s_setprio 0
	v_lshl_add_u32 v194, s46, 8, v198
	v_or_b32_e32 v192, 16, v194
	v_ashrrev_i32_e32 v195, 31, v194
	v_ashrrev_i32_e32 v193, 31, v192
	v_lshl_add_u64 v[130:131], v[194:195], 4, s[8:9]
	v_lshl_add_u64 v[134:135], v[192:193], 4, s[8:9]
	global_load_dwordx4 v[130:133], v[130:131], off
	v_and_b32_e32 v139, 64, v155
	global_load_dwordx4 v[134:137], v[134:135], off
	v_add_u32_e32 v138, 0x90, v194
	v_add_u32_e32 v140, 0xa0, v194
	v_add_u32_e32 v205, 64, v139
	v_ashrrev_i32_e32 v139, 31, v138
	v_ashrrev_i32_e32 v141, 31, v140
	v_lshl_add_u64 v[164:165], v[138:139], 4, s[8:9]
	v_lshl_add_u64 v[206:207], v[140:141], 4, s[8:9]
	v_xor_b32_e32 v144, 16, v155
	v_or_b32_e32 v190, 32, v194
	v_or_b32_e32 v188, 48, v194
	v_add_u32_e32 v186, 0x80, v194
	v_cmp_lt_i32_e32 vcc, v144, v205
	v_add_u32_e32 v142, 0xb0, v194
	v_ashrrev_i32_e32 v191, 31, v190
	v_ashrrev_i32_e32 v189, 31, v188
	v_ashrrev_i32_e32 v187, 31, v186
	v_cndmask_b32_e32 v146, v155, v144, vcc
	v_ashrrev_i32_e32 v143, 31, v142
	v_lshl_add_u64 v[144:145], v[190:191], 4, s[8:9]
	v_lshl_add_u64 v[150:151], v[188:189], 4, s[8:9]
	v_lshl_add_u64 v[162:163], v[186:187], 4, s[8:9]
	v_lshl_add_u64 v[208:209], v[142:143], 4, s[8:9]
	v_lshlrev_b32_e32 v204, 2, v146
	global_load_dwordx4 v[146:149], v[144:145], off
	s_nop 0
	global_load_dwordx4 v[150:153], v[150:151], off
	s_waitcnt vmcnt(0)
	v_mov_b32_e32 v139, v130
	v_mov_b32_e32 v141, v132
	v_mov_b32_e32 v138, v134
	v_mov_b32_e32 v130, v135
	v_mov_b32_e32 v140, v136
	v_pk_add_f32 v[130:131], v[138:139], v[130:131]
	v_mov_b32_e32 v132, v137
	v_pk_add_f32 v[130:131], v[140:141], v[130:131]
	s_nop 0
	v_pk_add_f32 v[130:131], v[132:133], v[130:131]
	s_nop 0
	v_pk_fma_f32 v[196:197], v[130:131], s[72:73], v[160:161] op_sel_hi:[1,0,0]
	s_nop 0
	v_mul_f32_e32 v130, 0x4b800000, v197
	v_cmp_gt_f32_e32 vcc, s94, v197
	s_nop 1
	v_cndmask_b32_e32 v130, v197, v130, vcc
	v_rsq_f32_e32 v197, v130
	global_load_dwordx4 v[138:141], v[162:163], off
	global_load_dwordx4 v[142:145], v[164:165], off
	global_load_dwordx4 v[130:133], v[206:207], off
	global_load_dwordx4 v[134:137], v[208:209], off
	v_mul_f32_e32 v162, 0x45800000, v197
	v_cndmask_b32_e32 v162, v197, v162, vcc
	v_mul_f32_e32 v162, 0x3d800000, v162
	v_mul_f32_e32 v126, v126, v162
	v_mul_f32_e32 v127, v127, v162
	v_mul_f32_e32 v124, v124, v162
	v_min_f32_e32 v126, 0x42a00000, v126
	v_mul_f32_e32 v128, v128, v162
	v_mul_f32_e32 v125, v125, v162
	v_min_f32_e32 v127, 0x42a00000, v127
	v_min_f32_e32 v124, 0x42a00000, v124
	v_max_f32_e32 v126, 0xc2a00000, v126
	v_mul_f32_e32 v129, v129, v162
	v_min_f32_e32 v128, 0x42a00000, v128
	v_min_f32_e32 v125, 0x42a00000, v125
	v_max_f32_e32 v127, 0xc2a00000, v127
	v_max_f32_e32 v124, 0xc2a00000, v124
	v_mul_f32_e32 v126, 0x3fb8aa3b, v126
	v_mul_f32_e32 v122, v122, v162
	v_min_f32_e32 v129, 0x42a00000, v129
	v_max_f32_e32 v128, 0xc2a00000, v128
	v_max_f32_e32 v125, 0xc2a00000, v125
	v_mul_f32_e32 v127, 0x3fb8aa3b, v127
	v_mul_f32_e32 v163, 0x3fb8aa3b, v124
	v_exp_f32_e32 v124, v126
	v_mul_f32_e32 v123, v123, v162
	v_min_f32_e32 v122, 0x42a00000, v122
	v_max_f32_e32 v129, 0xc2a00000, v129
	v_mul_f32_e32 v128, 0x3fb8aa3b, v128
	v_mul_f32_e32 v164, 0x3fb8aa3b, v125
	v_exp_f32_e32 v125, v127
	v_min_f32_e32 v123, 0x42a00000, v123
	v_max_f32_e32 v122, 0xc2a00000, v122
	v_mul_f32_e32 v129, 0x3fb8aa3b, v129
	v_exp_f32_e32 v128, v128
	v_max_f32_e32 v123, 0xc2a00000, v123
	v_mul_f32_e32 v122, 0x3fb8aa3b, v122
	v_exp_f32_e32 v129, v129
	v_mul_f32_e32 v118, v118, v162
	v_mul_f32_e32 v123, 0x3fb8aa3b, v123
	v_exp_f32_e32 v122, v122
	v_exp_f32_e32 v126, v163
	v_add_f32_e32 v163, 0, v124
	v_mul_f32_e32 v119, v119, v162
	v_min_f32_e32 v118, 0x42a00000, v118
	v_exp_f32_e32 v123, v123
	v_add_f32_e32 v163, v125, v163
	v_mul_f32_e32 v120, v120, v162
	v_min_f32_e32 v119, 0x42a00000, v119
	v_max_f32_e32 v118, 0xc2a00000, v118
	v_add_f32_e32 v163, v128, v163
	v_max_f32_e32 v119, 0xc2a00000, v119
	v_mul_f32_e32 v118, 0x3fb8aa3b, v118
	v_exp_f32_e32 v127, v164
	v_add_f32_e32 v163, v129, v163
	v_min_f32_e32 v120, 0x42a00000, v120
	v_mul_f32_e32 v121, v121, v162
	v_mul_f32_e32 v119, 0x3fb8aa3b, v119
	v_exp_f32_e32 v118, v118
	v_add_f32_e32 v163, v122, v163
	v_max_f32_e32 v120, 0xc2a00000, v120
	v_min_f32_e32 v121, 0x42a00000, v121
	v_mul_f32_e32 v114, v114, v162
	v_exp_f32_e32 v119, v119
	v_add_f32_e32 v163, v123, v163
	v_mul_f32_e32 v120, 0x3fb8aa3b, v120
	v_max_f32_e32 v121, 0xc2a00000, v121
	v_min_f32_e32 v114, 0x42a00000, v114
	v_mul_f32_e32 v115, v115, v162
	v_add_f32_e32 v163, v126, v163
	v_exp_f32_e32 v120, v120
	v_mul_f32_e32 v121, 0x3fb8aa3b, v121
	v_max_f32_e32 v114, 0xc2a00000, v114
	v_min_f32_e32 v115, 0x42a00000, v115
	v_mul_f32_e32 v116, v116, v162
	v_add_f32_e32 v163, v127, v163
	v_exp_f32_e32 v121, v121
	v_mul_f32_e32 v114, 0x3fb8aa3b, v114
	v_max_f32_e32 v115, 0xc2a00000, v115
	v_min_f32_e32 v116, 0x42a00000, v116
	v_mul_f32_e32 v117, v117, v162
	v_add_f32_e32 v163, v118, v163
	v_exp_f32_e32 v114, v114
	v_mul_f32_e32 v115, 0x3fb8aa3b, v115
	v_max_f32_e32 v116, 0xc2a00000, v116
	v_min_f32_e32 v117, 0x42a00000, v117
	v_add_f32_e32 v163, v119, v163
	v_exp_f32_e32 v115, v115
	v_mul_f32_e32 v116, 0x3fb8aa3b, v116
	v_max_f32_e32 v117, 0xc2a00000, v117
	v_add_f32_e32 v163, v120, v163
	v_exp_f32_e32 v116, v116
	v_mul_f32_e32 v117, 0x3fb8aa3b, v117
	v_add_f32_e32 v163, v121, v163
	v_exp_f32_e32 v117, v117
	v_add_f32_e32 v162, v114, v163
	v_add_f32_e32 v162, v115, v162
	v_add_f32_e32 v162, v116, v162
	v_add_f32_e32 v162, v117, v162
	ds_bpermute_b32 v163, v204, v162
	v_xor_b32_e32 v164, 32, v155
	v_cmp_lt_i32_e32 vcc, v164, v205
	s_waitcnt lgkmcnt(0)
	v_add_f32_e32 v205, v162, v163
	v_cndmask_b32_e32 v164, v155, v164, vcc
	v_lshlrev_b32_e32 v197, 2, v164
	ds_bpermute_b32 v206, v197, v205
	v_cmp_gt_f32_e32 vcc, s94, v196
	s_and_saveexec_b64 s[6:7], s[2:3]
	s_cbranch_execz .LBB0_1510
	s_waitcnt lgkmcnt(0)
	v_add_f32_e32 v162, v205, v206
	ds_write_b32 v201, v162

; #define PG8_STAGE(bufoff, gbase, voff) do { _Pragma("unroll") for (int _i = 0; _i < 2; ++_i) \
;         __builtin_amdgcn_global_load_lds((const unsigned*)((const char*)(gbase) + (voff)[_i]), (LAS unsigned*)(lds + (bufoff) + ldsw + _i * 8192), 16, 0, 0); } while (0)
; #define PG8_LDA(dst, b, h) do { _Pragma("unroll") for (int m = 0; m < 4; ++m) _Pragma("unroll") for (int k = 0; k < 2; ++k) dst[m][k] = *(const LAS bf16x8*)(lds + PG8_SA(b, h) + aoff + m * 2048 + k * 1024); } while (0)
; #define PG8_WAIT_V(n) asm volatile("s_waitcnt vmcnt(" #n ")" ::: "memory")
; #define PG8_WAIT_L(n) asm volatile("s_waitcnt lgkmcnt(" #n ")" ::: "memory")
; template <class Epi>
; DEVI void gemm_phase(LAS unsigned char* lds, const Gemm g, const Epi& E) {
;     ...
;         for (int t = 0; t < nt; t += 2) {
;             const bool last = (t == nt - 2);
;             const char* a1 = cA + (size_t)(t + 1) * kstep;
;             const char* a2 = last ? nA : cA + (size_t)(t + 2) * kstep; const char* b2 = last ? nB : cB + (size_t)(t + 2) * kstep;
;             const char* a3 = a2 + kstep; const char* b3 = b2 + kstep;
;             PG8_LDB(B0, 0, 0); PG8_SCHED; PG8_LDA(At, 0, 0); PG8_STAGE(PG8_SA(1, 1), a1 + hstepA, voffA);
;             PG8_WAIT_L(8); PG8_BAR; PG8_WAIT_L(0); PG8_MMA(0, 0, At, B0); PG8_BAR; PG8_SCHED;
;             PG8_LDB(B1, 0, 1); PG8_STAGE(PG8_SB(0, 0), b2, voffB);
;             PG8_BAR; PG8_WAIT_L(0); PG8_MMA(0, 1, At, B1); PG8_BAR;
;             PG8_LDA(At, 0, 1); PG8_STAGE(PG8_SA(0, 0), a2, voffA);
;             PG8_BAR; PG8_WAIT_L(0); PG8_MMA(1, 0, At, B0); PG8_BAR; PG8_SCHED;
;             PG8_STAGE(PG8_SB(0, 1), b2 + hstepB, voffB);
;             PG8_WAIT_V(6); PG8_BAR; PG8_MMA(1, 1, At, B1); PG8_BAR;
;             PG8_LDB(B0, 1, 0); PG8_SCHED; PG8_LDA(At, 1, 0); PG8_STAGE(PG8_SA(0, 1), a2 + hstepA, voffA);
;             PG8_WAIT_L(8); PG8_BAR; PG8_WAIT_L(0); PG8_MMA(0, 0, At, B0); PG8_BAR; PG8_SCHED;
;             PG8_LDB(B1, 1, 1); PG8_STAGE(PG8_SB(1, 0), b3, voffB);
;             PG8_BAR; PG8_WAIT_L(0); PG8_MMA(0, 1, At, B1); PG8_BAR;
;             PG8_LDA(At, 1, 1); PG8_STAGE(PG8_SA(1, 0), a3, voffA);
;             PG8_BAR; PG8_WAIT_L(0); PG8_MMA(1, 0, At, B0); PG8_BAR; PG8_SCHED;
;             PG8_STAGE(PG8_SB(1, 1), b3 + hstepB, voffB);
;             PG8_WAIT_V(6); PG8_BAR; PG8_MMA(1, 1, At, B1); PG8_BAR;
;         }
.LBB0_1595:
	s_add_u32 s18, s8, 0xfffc0080
	s_addc_u32 s19, s9, -1
	s_add_i32 s26, 0, 0x10000
	v_add_u32_e32 v142, s26, v191
	ds_read_b128 v[130:133], v142
	ds_read_b128 v[134:137], v142 offset:1024
	ds_read_b128 v[138:141], v142 offset:2048
	ds_read_b128 v[142:145], v142 offset:3072
	s_cmp_eq_u32 s17, 12
	s_cselect_b32 s81, s0, s19
	s_cselect_b32 s80, s1, s18
	s_cselect_b32 s79, s37, s15
	s_cselect_b32 s78, s36, s13
	v_lshl_add_u64 v[162:163], s[8:9], 0, v[152:153]
	s_add_i32 m0, s69, 0xc000
	ds_read_b128 v[178:181], v196
	ds_read_b128 v[182:185], v196 offset:1024
	ds_read_b128 v[186:189], v196 offset:2048
	ds_read_b128 v[198:201], v196 offset:3072
	ds_read_b128 v[202:205], v196 offset:4096
	ds_read_b128 v[206:209], v196 offset:5120
	ds_read_b128 v[214:217], v196 offset:6144
	ds_read_b128 v[218:221], v196 offset:7168
	global_load_lds_dwordx4 v[162:163], off
	s_add_i32 m0, s69, 0xe000
	v_lshl_add_u64 v[162:163], s[8:9], 0, v[176:177]
	global_load_lds_dwordx4 v[162:163], off
	s_waitcnt lgkmcnt(8)
	s_barrier
	s_waitcnt lgkmcnt(0)
	v_mfma_f32_16x16x32_bf16 v[126:129], v[130:133], v[178:181], v[126:129]
	v_mfma_f32_16x16x32_bf16 v[122:125], v[138:141], v[178:181], v[122:125]
	v_mfma_f32_16x16x32_bf16 v[110:113], v[130:133], v[186:189], v[110:113]
	v_mfma_f32_16x16x32_bf16 v[106:109], v[138:141], v[186:189], v[106:109]
	v_mfma_f32_16x16x32_bf16 v[94:97], v[130:133], v[202:205], v[94:97]
	v_mfma_f32_16x16x32_bf16 v[90:93], v[138:141], v[202:205], v[90:93]
	v_mfma_f32_16x16x32_bf16 v[78:81], v[130:133], v[214:217], v[78:81]
	v_mfma_f32_16x16x32_bf16 v[74:77], v[138:141], v[214:217], v[74:77]
	v_mfma_f32_16x16x32_bf16 v[126:129], v[134:137], v[182:185], v[126:129]
	v_mfma_f32_16x16x32_bf16 v[122:125], v[142:145], v[182:185], v[122:125]
	v_mfma_f32_16x16x32_bf16 v[110:113], v[134:137], v[198:201], v[110:113]
	v_mfma_f32_16x16x32_bf16 v[106:109], v[142:145], v[198:201], v[106:109]
	v_mfma_f32_16x16x32_bf16 v[94:97], v[134:137], v[206:209], v[94:97]
	v_mfma_f32_16x16x32_bf16 v[90:93], v[142:145], v[206:209], v[90:93]
	v_mfma_f32_16x16x32_bf16 v[78:81], v[134:137], v[218:221], v[78:81]
	v_mfma_f32_16x16x32_bf16 v[74:77], v[142:145], v[218:221], v[74:77]
	s_barrier
	s_add_i32 s27, 0, 0x14000
	v_add_u32_e32 v162, s27, v191
	s_add_i32 s18, s26, s82
	ds_read_b128 v[222:225], v162
	ds_read_b128 v[226:229], v162 offset:1024
	ds_read_b128 v[230:233], v162 offset:2048
	ds_read_b128 v[234:237], v162 offset:3072
	v_lshl_add_u64 v[162:163], s[78:79], 0, v[8:9]
	s_mov_b32 m0, s18
	v_lshl_add_u64 v[164:165], s[78:79], 0, v[150:151]
	global_load_lds_dwordx4 v[162:163], off
	s_add_i32 m0, s18, 0x2000
	s_nop 0
	global_load_lds_dwordx4 v[164:165], off
	s_barrier
	s_waitcnt lgkmcnt(0)
	v_mfma_f32_16x16x32_bf16 v[118:121], v[222:225], v[178:181], v[118:121]
	v_mfma_f32_16x16x32_bf16 v[114:117], v[230:233], v[178:181], v[114:117]
	v_mfma_f32_16x16x32_bf16 v[102:105], v[222:225], v[186:189], v[102:105]
	v_mfma_f32_16x16x32_bf16 v[98:101], v[230:233], v[186:189], v[98:101]
	v_mfma_f32_16x16x32_bf16 v[86:89], v[222:225], v[202:205], v[86:89]
	v_mfma_f32_16x16x32_bf16 v[82:85], v[230:233], v[202:205], v[82:85]
	v_mfma_f32_16x16x32_bf16 v[70:73], v[222:225], v[214:217], v[70:73]
	v_mfma_f32_16x16x32_bf16 v[66:69], v[230:233], v[214:217], v[66:69]
	v_mfma_f32_16x16x32_bf16 v[118:121], v[226:229], v[182:185], v[118:121]
	v_mfma_f32_16x16x32_bf16 v[114:117], v[234:237], v[182:185], v[114:117]
	v_mfma_f32_16x16x32_bf16 v[102:105], v[226:229], v[198:201], v[102:105]
	v_mfma_f32_16x16x32_bf16 v[98:101], v[234:237], v[198:201], v[98:101]
	v_mfma_f32_16x16x32_bf16 v[86:89], v[226:229], v[206:209], v[86:89]
	v_mfma_f32_16x16x32_bf16 v[82:85], v[234:237], v[206:209], v[82:85]
	v_mfma_f32_16x16x32_bf16 v[70:73], v[226:229], v[218:221], v[70:73]
	v_mfma_f32_16x16x32_bf16 v[66:69], v[234:237], v[218:221], v[66:69]
	s_barrier
	s_mov_b32 m0, s69
	v_lshl_add_u64 v[238:239], s[80:81], 0, v[146:147]
	ds_read_b128 v[178:181], v196 offset:16384
	ds_read_b128 v[182:185], v196 offset:17408
	ds_read_b128 v[186:189], v196 offset:18432
	ds_read_b128 v[198:201], v196 offset:19456
	ds_read_b128 v[202:205], v196 offset:20480
	ds_read_b128 v[206:209], v196 offset:21504
	ds_read_b128 v[214:217], v196 offset:22528
	ds_read_b128 v[218:221], v196 offset:23552
	global_load_lds_dwordx4 v[238:239], off
	s_mov_b32 m0, s83
	v_lshl_add_u64 v[240:241], s[80:81], 0, v[148:149]
	global_load_lds_dwordx4 v[240:241], off
	s_barrier
	s_waitcnt lgkmcnt(0)
	v_mfma_f32_16x16x32_bf16 v[62:65], v[130:133], v[178:181], v[62:65]
	v_mfma_f32_16x16x32_bf16 v[58:61], v[138:141], v[178:181], v[58:61]
	v_mfma_f32_16x16x32_bf16 v[46:49], v[130:133], v[186:189], v[46:49]
	v_mfma_f32_16x16x32_bf16 v[42:45], v[138:141], v[186:189], v[42:45]
	v_mfma_f32_16x16x32_bf16 v[30:33], v[130:133], v[202:205], v[30:33]
	v_mfma_f32_16x16x32_bf16 v[26:29], v[138:141], v[202:205], v[26:29]
	v_mfma_f32_16x16x32_bf16 v[14:17], v[130:133], v[214:217], v[14:17]
	v_mfma_f32_16x16x32_bf16 v[10:13], v[138:141], v[214:217], v[10:13]
	v_mfma_f32_16x16x32_bf16 v[62:65], v[134:137], v[182:185], v[62:65]
	v_mfma_f32_16x16x32_bf16 v[58:61], v[142:145], v[182:185], v[58:61]
	v_mfma_f32_16x16x32_bf16 v[46:49], v[134:137], v[198:201], v[46:49]
	v_mfma_f32_16x16x32_bf16 v[42:45], v[142:145], v[198:201], v[42:45]
	v_mfma_f32_16x16x32_bf16 v[30:33], v[134:137], v[206:209], v[30:33]
	v_mfma_f32_16x16x32_bf16 v[26:29], v[142:145], v[206:209], v[26:29]
	v_mfma_f32_16x16x32_bf16 v[14:17], v[134:137], v[218:221], v[14:17]
	v_mfma_f32_16x16x32_bf16 v[10:13], v[142:145], v[218:221], v[10:13]
	s_barrier
; #define PG8_STAGE(bufoff, gbase, voff) do { _Pragma("unroll") for (int _i = 0; _i < 2; ++_i) \
;         __builtin_amdgcn_global_load_lds((const unsigned*)((const char*)(gbase) + (voff)[_i]), (LAS unsigned*)(lds + (bufoff) + ldsw + _i * 8192), 16, 0, 0); } while (0)
; #define PG8_LDA(dst, b, h) do { _Pragma("unroll") for (int m = 0; m < 4; ++m) _Pragma("unroll") for (int k = 0; k < 2; ++k) dst[m][k] = *(const LAS bf16x8*)(lds + PG8_SA(b, h) + aoff + m * 2048 + k * 1024); } while (0)
; #define PG8_WAIT_V(n) asm volatile("s_waitcnt vmcnt(" #n ")" ::: "memory")
; #define PG8_WAIT_L(n) asm volatile("s_waitcnt lgkmcnt(" #n ")" ::: "memory")
; template <class Epi>
; DEVI void gemm_phase(LAS unsigned char* lds, const Gemm g, const Epi& E) {
;     ...
;         for (int t = 0; t < nt; t += 2) {
;             const bool last = (t == nt - 2);
;             const char* a1 = cA + (size_t)(t + 1) * kstep;
;             const char* a2 = last ? nA : cA + (size_t)(t + 2) * kstep; const char* b2 = last ? nB : cB + (size_t)(t + 2) * kstep;
;             const char* a3 = a2 + kstep; const char* b3 = b2 + kstep;
;             PG8_LDB(B0, 0, 0); PG8_SCHED; PG8_LDA(At, 0, 0); PG8_STAGE(PG8_SA(1, 1), a1 + hstepA, voffA);
;             PG8_WAIT_L(8); PG8_BAR; PG8_WAIT_L(0); PG8_MMA(0, 0, At, B0); PG8_BAR; PG8_SCHED;
;             PG8_LDB(B1, 0, 1); PG8_STAGE(PG8_SB(0, 0), b2, voffB);
;             PG8_BAR; PG8_WAIT_L(0); PG8_MMA(0, 1, At, B1); PG8_BAR;
;             PG8_LDA(At, 0, 1); PG8_STAGE(PG8_SA(0, 0), a2, voffA);
;             PG8_BAR; PG8_WAIT_L(0); PG8_MMA(1, 0, At, B0); PG8_BAR; PG8_SCHED;
;             PG8_STAGE(PG8_SB(0, 1), b2 + hstepB, voffB);
;             PG8_WAIT_V(6); PG8_BAR; PG8_MMA(1, 1, At, B1); PG8_BAR;
;             PG8_LDB(B0, 1, 0); PG8_SCHED; PG8_LDA(At, 1, 0); PG8_STAGE(PG8_SA(0, 1), a2 + hstepA, voffA);
;             PG8_WAIT_L(8); PG8_BAR; PG8_WAIT_L(0); PG8_MMA(0, 0, At, B0); PG8_BAR; PG8_SCHED;
;             PG8_LDB(B1, 1, 1); PG8_STAGE(PG8_SB(1, 0), b3, voffB);
;             PG8_BAR; PG8_WAIT_L(0); PG8_MMA(0, 1, At, B1); PG8_BAR;
;             PG8_LDA(At, 1, 1); PG8_STAGE(PG8_SA(1, 0), a3, voffA);
;             PG8_BAR; PG8_WAIT_L(0); PG8_MMA(1, 0, At, B0); PG8_BAR; PG8_SCHED;
;             PG8_STAGE(PG8_SB(1, 1), b3 + hstepB, voffB);
;             PG8_WAIT_V(6); PG8_BAR; PG8_MMA(1, 1, At, B1); PG8_BAR;
;         }
	s_add_u32 s18, s78, 0x40000
	s_addc_u32 s19, s79, 0
	s_add_i32 s26, s27, s82
	s_mov_b32 m0, s26
	v_lshl_add_u64 v[130:131], s[18:19], 0, v[8:9]
	global_load_lds_dwordx4 v[130:131], off
	s_add_i32 m0, s26, 0x2000
	v_lshl_add_u64 v[130:131], s[18:19], 0, v[150:151]
	global_load_lds_dwordx4 v[130:131], off
	s_waitcnt vmcnt(6)
	s_barrier
	v_mfma_f32_16x16x32_bf16 v[54:57], v[222:225], v[178:181], v[54:57]
	v_mfma_f32_16x16x32_bf16 v[50:53], v[230:233], v[178:181], v[50:53]
	v_mfma_f32_16x16x32_bf16 v[38:41], v[222:225], v[186:189], v[38:41]
	v_mfma_f32_16x16x32_bf16 v[34:37], v[230:233], v[186:189], v[34:37]
	v_mfma_f32_16x16x32_bf16 v[22:25], v[222:225], v[202:205], v[22:25]
	v_mfma_f32_16x16x32_bf16 v[18:21], v[230:233], v[202:205], v[18:21]
	v_mfma_f32_16x16x32_bf16 v[4:7], v[222:225], v[214:217], v[4:7]
	v_mfma_f32_16x16x32_bf16 v[0:3], v[230:233], v[214:217], v[0:3]
	v_mfma_f32_16x16x32_bf16 v[54:57], v[226:229], v[182:185], v[54:57]
	v_mfma_f32_16x16x32_bf16 v[50:53], v[234:237], v[182:185], v[50:53]
	v_mfma_f32_16x16x32_bf16 v[38:41], v[226:229], v[198:201], v[38:41]
	v_mfma_f32_16x16x32_bf16 v[34:37], v[234:237], v[198:201], v[34:37]
	v_mfma_f32_16x16x32_bf16 v[22:25], v[226:229], v[206:209], v[22:25]
	v_mfma_f32_16x16x32_bf16 v[18:21], v[234:237], v[206:209], v[18:21]
	v_mfma_f32_16x16x32_bf16 v[4:7], v[226:229], v[218:221], v[4:7]
	v_mfma_f32_16x16x32_bf16 v[0:3], v[234:237], v[218:221], v[0:3]
	s_barrier
	s_add_i32 s26, 0, 0x18000
	v_add_u32_e32 v142, s26, v191
	ds_read_b128 v[130:133], v142
	ds_read_b128 v[134:137], v142 offset:1024
	ds_read_b128 v[138:141], v142 offset:2048
	ds_read_b128 v[142:145], v142 offset:3072
	s_add_u32 s18, s80, 0x40000
	s_addc_u32 s19, s81, 0
	s_mov_b32 m0, s84
	v_lshl_add_u64 v[222:223], s[18:19], 0, v[146:147]
	ds_read_b128 v[178:181], v196 offset:32768
	ds_read_b128 v[182:185], v196 offset:33792
	ds_read_b128 v[186:189], v196 offset:34816
	ds_read_b128 v[198:201], v196 offset:35840
	ds_read_b128 v[202:205], v196 offset:36864
	ds_read_b128 v[206:209], v196 offset:37888
	ds_read_b128 v[214:217], v196 offset:38912
	ds_read_b128 v[218:221], v196 offset:39936
	global_load_lds_dwordx4 v[222:223], off
	s_mov_b32 m0, s85
	v_lshl_add_u64 v[222:223], s[18:19], 0, v[148:149]
	global_load_lds_dwordx4 v[222:223], off
	s_waitcnt lgkmcnt(8)
	s_barrier
	s_waitcnt lgkmcnt(0)
	v_mfma_f32_16x16x32_bf16 v[126:129], v[130:133], v[178:181], v[126:129]
	v_mfma_f32_16x16x32_bf16 v[122:125], v[138:141], v[178:181], v[122:125]
	v_mfma_f32_16x16x32_bf16 v[110:113], v[130:133], v[186:189], v[110:113]
	v_mfma_f32_16x16x32_bf16 v[106:109], v[138:141], v[186:189], v[106:109]
	v_mfma_f32_16x16x32_bf16 v[94:97], v[130:133], v[202:205], v[94:97]
	v_mfma_f32_16x16x32_bf16 v[90:93], v[138:141], v[202:205], v[90:93]
	v_mfma_f32_16x16x32_bf16 v[78:81], v[130:133], v[214:217], v[78:81]
	v_mfma_f32_16x16x32_bf16 v[74:77], v[138:141], v[214:217], v[74:77]
	v_mfma_f32_16x16x32_bf16 v[126:129], v[134:137], v[182:185], v[126:129]
	v_mfma_f32_16x16x32_bf16 v[122:125], v[142:145], v[182:185], v[122:125]
	v_mfma_f32_16x16x32_bf16 v[110:113], v[134:137], v[198:201], v[110:113]
	v_mfma_f32_16x16x32_bf16 v[106:109], v[142:145], v[198:201], v[106:109]
	v_mfma_f32_16x16x32_bf16 v[94:97], v[134:137], v[206:209], v[94:97]
	v_mfma_f32_16x16x32_bf16 v[90:93], v[142:145], v[206:209], v[90:93]
	v_mfma_f32_16x16x32_bf16 v[78:81], v[134:137], v[218:221], v[78:81]
	v_mfma_f32_16x16x32_bf16 v[74:77], v[142:145], v[218:221], v[74:77]
	s_barrier
	s_add_i32 s27, 0, 0x1c000
	s_add_i32 s18, s26, s82
	v_add_u32_e32 v197, s27, v191
	v_lshl_add_u64 v[162:163], v[162:163], 0, s[70:71]
	s_mov_b32 m0, s18
	ds_read_b128 v[222:225], v197
	ds_read_b128 v[226:229], v197 offset:1024
	ds_read_b128 v[230:233], v197 offset:2048
	ds_read_b128 v[234:237], v197 offset:3072
	global_load_lds_dwordx4 v[162:163], off
	s_add_i32 m0, s18, 0x2000
	v_lshl_add_u64 v[162:163], v[164:165], 0, s[70:71]
	global_load_lds_dwordx4 v[162:163], off
	s_barrier
	s_waitcnt lgkmcnt(0)
	v_mfma_f32_16x16x32_bf16 v[118:121], v[222:225], v[178:181], v[118:121]
	v_mfma_f32_16x16x32_bf16 v[114:117], v[230:233], v[178:181], v[114:117]
	v_mfma_f32_16x16x32_bf16 v[102:105], v[222:225], v[186:189], v[102:105]
	v_mfma_f32_16x16x32_bf16 v[98:101], v[230:233], v[186:189], v[98:101]
	v_mfma_f32_16x16x32_bf16 v[86:89], v[222:225], v[202:205], v[86:89]
	v_mfma_f32_16x16x32_bf16 v[82:85], v[230:233], v[202:205], v[82:85]
	v_mfma_f32_16x16x32_bf16 v[70:73], v[222:225], v[214:217], v[70:73]
	v_mfma_f32_16x16x32_bf16 v[66:69], v[230:233], v[214:217], v[66:69]
	v_mfma_f32_16x16x32_bf16 v[118:121], v[226:229], v[182:185], v[118:121]
	v_mfma_f32_16x16x32_bf16 v[114:117], v[234:237], v[182:185], v[114:117]
	v_mfma_f32_16x16x32_bf16 v[102:105], v[226:229], v[198:201], v[102:105]
	v_mfma_f32_16x16x32_bf16 v[98:101], v[234:237], v[198:201], v[98:101]
	v_mfma_f32_16x16x32_bf16 v[86:89], v[226:229], v[206:209], v[86:89]
	v_mfma_f32_16x16x32_bf16 v[82:85], v[234:237], v[206:209], v[82:85]
	v_mfma_f32_16x16x32_bf16 v[70:73], v[226:229], v[218:221], v[70:73]
	v_mfma_f32_16x16x32_bf16 v[66:69], v[234:237], v[218:221], v[66:69]
	s_barrier
	s_mov_b32 m0, s86
	v_lshl_add_u64 v[162:163], v[238:239], 0, s[70:71]
	ds_read_b128 v[178:181], v196 offset:49152
	ds_read_b128 v[182:185], v196 offset:50176
	ds_read_b128 v[186:189], v196 offset:51200
	ds_read_b128 v[198:201], v196 offset:52224
	ds_read_b128 v[202:205], v196 offset:53248
	ds_read_b128 v[206:209], v196 offset:54272
	ds_read_b128 v[214:217], v196 offset:55296
	ds_read_b128 v[218:221], v196 offset:56320
	global_load_lds_dwordx4 v[162:163], off
	s_mov_b32 m0, s87
	v_lshl_add_u64 v[162:163], v[240:241], 0, s[70:71]
	global_load_lds_dwordx4 v[162:163], off
	s_barrier
; #define PG8_BAR __builtin_amdgcn_s_barrier()
; template <class Epi>
; DEVI void gemm_phase(LAS unsigned char* lds, const Gemm g, const Epi& E) {
;     ...
;         for (int t = 0; t < nt; t += 2) {
;             const bool last = (t == nt - 2);
;             const char* a1 = cA + (size_t)(t + 1) * kstep;
;             const char* a2 = last ? nA : cA + (size_t)(t + 2) * kstep; const char* b2 = last ? nB : cB + (size_t)(t + 2) * kstep;
;             const char* a3 = a2 + kstep; const char* b3 = b2 + kstep;
;             PG8_LDB(B0, 0, 0); PG8_SCHED; PG8_LDA(At, 0, 0); PG8_STAGE(PG8_SA(1, 1), a1 + hstepA, voffA);
;             PG8_WAIT_L(8); PG8_BAR; PG8_WAIT_L(0); PG8_MMA(0, 0, At, B0); PG8_BAR; PG8_SCHED;
;             PG8_LDB(B1, 0, 1); PG8_STAGE(PG8_SB(0, 0), b2, voffB);
;             PG8_BAR; PG8_WAIT_L(0); PG8_MMA(0, 1, At, B1); PG8_BAR;
;             PG8_LDA(At, 0, 1); PG8_STAGE(PG8_SA(0, 0), a2, voffA);
;             PG8_BAR; PG8_WAIT_L(0); PG8_MMA(1, 0, At, B0); PG8_BAR; PG8_SCHED;
;             PG8_STAGE(PG8_SB(0, 1), b2 + hstepB, voffB);
;             PG8_WAIT_V(6); PG8_BAR; PG8_MMA(1, 1, At, B1); PG8_BAR;
;             PG8_LDB(B0, 1, 0); PG8_SCHED; PG8_LDA(At, 1, 0); PG8_STAGE(PG8_SA(0, 1), a2 + hstepA, voffA);
;             PG8_WAIT_L(8); PG8_BAR; PG8_WAIT_L(0); PG8_MMA(0, 0, At, B0); PG8_BAR; PG8_SCHED;
;             PG8_LDB(B1, 1, 1); PG8_STAGE(PG8_SB(1, 0), b3, voffB);
;             PG8_BAR; PG8_WAIT_L(0); PG8_MMA(0, 1, At, B1); PG8_BAR;
;             PG8_LDA(At, 1, 1); PG8_STAGE(PG8_SA(1, 0), a3, voffA);
;             PG8_BAR; PG8_WAIT_L(0); PG8_MMA(1, 0, At, B0); PG8_BAR; PG8_SCHED;
;             PG8_STAGE(PG8_SB(1, 1), b3 + hstepB, voffB);
;             PG8_WAIT_V(6); PG8_BAR; PG8_MMA(1, 1, At, B1); PG8_BAR;
;         }
;     ...
;                 if constexpr (Epi::PRE) {
; #pragma unroll
;                     for (int m = 0; m < 2; ++m)
; #pragma unroll
;                         for (int bj = 0; bj < 2; ++bj)
; #pragma unroll
;                             for (int n = 0; n < 2; ++n) pre[m][bj][n] = E.load(row0 + ai * HALF + (m0 + m) * 16, col0 + bj * HALF + n * NST);
;                 }
; #pragma unroll
;                 for (int mm = 0; mm < 2; ++mm) {
;                     const int m = m0 + mm;
;                     const int r = row0 + ai * HALF + m * 16; float rs = 1.f, part = 0.f;
;                     if constexpr (Epi::RS) rs = rsv[ai * 4 + m];
	s_waitcnt lgkmcnt(0)
	v_mfma_f32_16x16x32_bf16 v[62:65], v[130:133], v[178:181], v[62:65]
	v_mfma_f32_16x16x32_bf16 v[58:61], v[138:141], v[178:181], v[58:61]
	v_mfma_f32_16x16x32_bf16 v[46:49], v[130:133], v[186:189], v[46:49]
	v_mfma_f32_16x16x32_bf16 v[42:45], v[138:141], v[186:189], v[42:45]
	v_mfma_f32_16x16x32_bf16 v[30:33], v[130:133], v[202:205], v[30:33]
	v_mfma_f32_16x16x32_bf16 v[26:29], v[138:141], v[202:205], v[26:29]
	v_mfma_f32_16x16x32_bf16 v[14:17], v[130:133], v[214:217], v[14:17]
	v_mfma_f32_16x16x32_bf16 v[10:13], v[138:141], v[214:217], v[10:13]
	v_mfma_f32_16x16x32_bf16 v[62:65], v[134:137], v[182:185], v[62:65]
	v_mfma_f32_16x16x32_bf16 v[58:61], v[142:145], v[182:185], v[58:61]
	v_mfma_f32_16x16x32_bf16 v[46:49], v[134:137], v[198:201], v[46:49]
	v_mfma_f32_16x16x32_bf16 v[42:45], v[142:145], v[198:201], v[42:45]
	v_mfma_f32_16x16x32_bf16 v[30:33], v[134:137], v[206:209], v[30:33]
	v_mfma_f32_16x16x32_bf16 v[26:29], v[142:145], v[206:209], v[26:29]
	v_mfma_f32_16x16x32_bf16 v[14:17], v[134:137], v[218:221], v[14:17]
	v_mfma_f32_16x16x32_bf16 v[10:13], v[142:145], v[218:221], v[10:13]
	s_barrier
	s_add_u32 s18, s78, 0x40080
	s_addc_u32 s19, s79, 0
	s_add_i32 s26, s27, s82
	s_mov_b32 m0, s26
	v_lshl_add_u64 v[130:131], s[18:19], 0, v[8:9]
	global_load_lds_dwordx4 v[130:131], off
	s_add_i32 m0, s26, 0x2000
	v_lshl_add_u64 v[130:131], s[18:19], 0, v[150:151]
	global_load_lds_dwordx4 v[130:131], off
	s_waitcnt vmcnt(6)
	s_barrier
	v_mfma_f32_16x16x32_bf16 v[54:57], v[222:225], v[178:181], v[54:57]
	v_mfma_f32_16x16x32_bf16 v[50:53], v[230:233], v[178:181], v[50:53]
	v_mfma_f32_16x16x32_bf16 v[38:41], v[222:225], v[186:189], v[38:41]
	v_mfma_f32_16x16x32_bf16 v[34:37], v[230:233], v[186:189], v[34:37]
	v_mfma_f32_16x16x32_bf16 v[22:25], v[222:225], v[202:205], v[22:25]
	v_mfma_f32_16x16x32_bf16 v[18:21], v[230:233], v[202:205], v[18:21]
	v_mfma_f32_16x16x32_bf16 v[4:7], v[222:225], v[214:217], v[4:7]
	v_mfma_f32_16x16x32_bf16 v[0:3], v[230:233], v[214:217], v[0:3]
	v_mfma_f32_16x16x32_bf16 v[54:57], v[226:229], v[182:185], v[54:57]
	v_mfma_f32_16x16x32_bf16 v[50:53], v[234:237], v[182:185], v[50:53]
	v_mfma_f32_16x16x32_bf16 v[38:41], v[226:229], v[198:201], v[38:41]
	v_mfma_f32_16x16x32_bf16 v[34:37], v[234:237], v[198:201], v[34:37]
	v_mfma_f32_16x16x32_bf16 v[22:25], v[226:229], v[206:209], v[22:25]
	v_mfma_f32_16x16x32_bf16 v[18:21], v[234:237], v[206:209], v[18:21]
	v_mfma_f32_16x16x32_bf16 v[4:7], v[226:229], v[218:221], v[4:7]
	v_mfma_f32_16x16x32_bf16 v[0:3], v[234:237], v[218:221], v[0:3]
	s_barrier
	s_add_i32 s17, s17, 2
	s_add_u32 s8, s8, 0x100
	s_addc_u32 s9, s9, 0
	s_add_u32 s13, s13, 0x100
	s_addc_u32 s15, s15, 0
	s_cmp_gt_u32 s17, 13
	s_cbranch_scc0 .LBB0_1595
	s_setprio 0
	s_lshl_b32 s0, s68, 8
	v_add_u32_e32 v182, s0, v190
	v_lshl_or_b32 v180, s12, 8, v195
	v_ashrrev_i32_e32 v183, 31, v182
	v_lshlrev_b64 v[130:131], 12, v[182:183]
	v_ashrrev_i32_e32 v181, 31, v180
	v_lshl_add_u64 v[130:131], s[30:31], 0, v[130:131]
	v_lshlrev_b64 v[184:185], 2, v[180:181]
	v_lshl_add_u64 v[162:163], v[130:131], 0, v[184:185]
	global_load_dwordx4 v[200:203], v[162:163], off
	global_load_dwordx4 v[204:207], v[162:163], off offset:16
	global_load_dwordx4 v[214:217], v[162:163], off offset:512
	global_load_dwordx4 v[218:221], v[162:163], off offset:528
	v_or_b32_e32 v188, 16, v182
	v_ashrrev_i32_e32 v189, 31, v188
	v_lshlrev_b64 v[130:131], 12, v[188:189]
	v_lshl_add_u64 v[130:131], s[30:31], 0, v[130:131]
	v_lshl_add_u64 v[186:187], v[130:131], 0, v[184:185]
	global_load_dwordx4 v[138:141], v[186:187], off offset:16
	global_load_dwordx4 v[142:145], v[186:187], off
	global_load_dwordx4 v[130:133], v[186:187], off offset:528
	global_load_dwordx4 v[134:137], v[186:187], off offset:512
	v_and_b32_e32 v165, 64, v155
	v_xor_b32_e32 v164, 16, v155
	v_add_u32_e32 v165, 64, v165
	v_xor_b32_e32 v179, 32, v155
	v_cmp_lt_i32_e32 vcc, v164, v165
	v_or_b32_e32 v178, 0x80, v180
	s_waitcnt vmcnt(0)
	v_pk_add_f32 v[128:129], v[128:129], v[202:203]
	v_cndmask_b32_e32 v164, v155, v164, vcc
	v_cmp_lt_i32_e32 vcc, v179, v165
	v_lshlrev_b32_e32 v198, 2, v164
	v_pk_add_f32 v[126:127], v[126:127], v[200:201]
	v_cndmask_b32_e32 v165, v155, v179, vcc
	v_lshlrev_b32_e32 v197, 2, v165
	v_lshlrev_b64 v[164:165], 10, v[182:183]
	v_pk_add_f32 v[124:125], v[124:125], v[206:207]
	v_pk_add_f32 v[122:123], v[122:123], v[204:205]
	v_pk_add_f32 v[120:121], v[120:121], v[216:217]
	v_pk_add_f32 v[118:119], v[118:119], v[214:215]
	v_pk_add_f32 v[202:203], v[116:117], v[220:221]
	v_pk_add_f32 v[200:201], v[114:115], v[218:219]
	v_lshl_add_u64 v[208:209], v[164:165], 0, v[180:181]
	global_store_dwordx4 v[162:163], v[126:129], off
	global_store_dwordx4 v[162:163], v[122:125], off offset:16
	v_cvt_pk_bf16_f32 v114, v126, v127
	v_cvt_pk_bf16_f32 v115, v128, v129
	v_cvt_pk_bf16_f32 v116, v122, v123
	v_cvt_pk_bf16_f32 v117, v124, v125
	v_mul_f32_e32 v127, v127, v127
	v_mul_f32_e32 v129, v129, v129
	v_mul_f32_e32 v123, v123, v123
	v_mul_f32_e32 v125, v125, v125
	v_mul_f32_e32 v183, v119, v119
	v_mul_f32_e32 v199, v121, v121
	v_mul_f32_e32 v204, v201, v201
	v_mul_f32_e32 v205, v203, v203
	v_lshl_add_u64 v[208:209], v[208:209], 1, s[24:25]
	v_fmac_f32_e32 v127, v126, v126
	v_fmac_f32_e32 v129, v128, v128
	v_fmac_f32_e32 v123, v122, v122
	v_fmac_f32_e32 v125, v124, v124
	v_fmac_f32_e32 v183, v118, v118
	v_fmac_f32_e32 v199, v120, v120
	v_fmac_f32_e32 v204, v200, v200
	v_fmac_f32_e32 v205, v202, v202
	global_store_dwordx4 v[208:209], v[114:117], off
	v_ashrrev_i32_e32 v179, 31, v178
	v_lshl_add_u64 v[164:165], v[164:165], 0, v[178:179]
	v_add_f32_e32 v114, v127, v129
	v_add_f32_e32 v115, v123, v125
	v_add_f32_e32 v116, v183, v199
	v_add_f32_e32 v117, v204, v205
	v_add_f32_e32 v114, v114, v115
	v_add_f32_e32 v115, v116, v117
	v_add_f32_e32 v114, v114, v115
	ds_bpermute_b32 v115, v198, v114
	global_store_dwordx4 v[162:163], v[118:121], off offset:512
	global_store_dwordx4 v[162:163], v[200:203], off offset:528
	v_cvt_pk_bf16_f32 v116, v118, v119
	v_cvt_pk_bf16_f32 v117, v120, v121
	v_cvt_pk_bf16_f32 v118, v200, v201
	s_waitcnt lgkmcnt(0)
	v_add_f32_e32 v114, v114, v115
	ds_bpermute_b32 v115, v197, v114
	v_cvt_pk_bf16_f32 v119, v202, v203
	v_lshl_add_u64 v[120:121], v[164:165], 1, s[24:25]
	global_store_dwordx4 v[120:121], v[116:119], off
	s_and_saveexec_b64 s[8:9], s[2:3]
	s_cbranch_execz .LBB0_1598
	s_waitcnt lgkmcnt(0)
	v_add_f32_e32 v114, v114, v115
	ds_write_b32 v192, v114

; #define PG8_STAGE(bufoff, gbase, voff) do { _Pragma("unroll") for (int _i = 0; _i < 2; ++_i) \
;         __builtin_amdgcn_global_load_lds((const unsigned*)((const char*)(gbase) + (voff)[_i]), (LAS unsigned*)(lds + (bufoff) + ldsw + _i * 8192), 16, 0, 0); } while (0)
; #define PG8_LDA(dst, b, h) do { _Pragma("unroll") for (int m = 0; m < 4; ++m) _Pragma("unroll") for (int k = 0; k < 2; ++k) dst[m][k] = *(const LAS bf16x8*)(lds + PG8_SA(b, h) + aoff + m * 2048 + k * 1024); } while (0)
; #define PG8_WAIT_V(n) asm volatile("s_waitcnt vmcnt(" #n ")" ::: "memory")
; #define PG8_WAIT_L(n) asm volatile("s_waitcnt lgkmcnt(" #n ")" ::: "memory")
; template <class Epi>
; DEVI void gemm_phase(LAS unsigned char* lds, const Gemm g, const Epi& E) {
;     ...
;         for (int t = 0; t < nt; t += 2) {
;             const bool last = (t == nt - 2);
;             const char* a1 = cA + (size_t)(t + 1) * kstep;
;             const char* a2 = last ? nA : cA + (size_t)(t + 2) * kstep; const char* b2 = last ? nB : cB + (size_t)(t + 2) * kstep;
;             const char* a3 = a2 + kstep; const char* b3 = b2 + kstep;
;             PG8_LDB(B0, 0, 0); PG8_SCHED; PG8_LDA(At, 0, 0); PG8_STAGE(PG8_SA(1, 1), a1 + hstepA, voffA);
;             PG8_WAIT_L(8); PG8_BAR; PG8_WAIT_L(0); PG8_MMA(0, 0, At, B0); PG8_BAR; PG8_SCHED;
;             PG8_LDB(B1, 0, 1); PG8_STAGE(PG8_SB(0, 0), b2, voffB);
;             PG8_BAR; PG8_WAIT_L(0); PG8_MMA(0, 1, At, B1); PG8_BAR;
;             PG8_LDA(At, 0, 1); PG8_STAGE(PG8_SA(0, 0), a2, voffA);
;             PG8_BAR; PG8_WAIT_L(0); PG8_MMA(1, 0, At, B0); PG8_BAR; PG8_SCHED;
;             PG8_STAGE(PG8_SB(0, 1), b2 + hstepB, voffB);
;             PG8_WAIT_V(6); PG8_BAR; PG8_MMA(1, 1, At, B1); PG8_BAR;
;             PG8_LDB(B0, 1, 0); PG8_SCHED; PG8_LDA(At, 1, 0); PG8_STAGE(PG8_SA(0, 1), a2 + hstepA, voffA);
;             PG8_WAIT_L(8); PG8_BAR; PG8_WAIT_L(0); PG8_MMA(0, 0, At, B0); PG8_BAR; PG8_SCHED;
;             PG8_LDB(B1, 1, 1); PG8_STAGE(PG8_SB(1, 0), b3, voffB);
;             PG8_BAR; PG8_WAIT_L(0); PG8_MMA(0, 1, At, B1); PG8_BAR;
;             PG8_LDA(At, 1, 1); PG8_STAGE(PG8_SA(1, 0), a3, voffA);
;             PG8_BAR; PG8_WAIT_L(0); PG8_MMA(1, 0, At, B0); PG8_BAR; PG8_SCHED;
;             PG8_STAGE(PG8_SB(1, 1), b3 + hstepB, voffB);
;             PG8_WAIT_V(6); PG8_BAR; PG8_MMA(1, 1, At, B1); PG8_BAR;
;         }
.LBB0_1672:
	s_add_u32 s26, s16, 0xfffc0080
	s_addc_u32 s27, s17, -1
	s_add_i32 s38, 0, 0x10000
	v_add_u32_e32 v142, s38, v197
	ds_read_b128 v[130:133], v142
	ds_read_b128 v[134:137], v142 offset:1024
	ds_read_b128 v[138:141], v142 offset:2048
	ds_read_b128 v[142:145], v142 offset:3072
	s_cmp_eq_u32 s19, 12
	s_cselect_b32 s47, s0, s27
	s_cselect_b32 s46, s1, s26
	s_cselect_b32 s37, s5, s18
	s_cselect_b32 s36, s7, s9
	v_lshl_add_u64 v[162:163], s[16:17], 0, v[152:153]
	s_add_i32 m0, s79, 0xc000
	ds_read_b128 v[178:181], v201
	ds_read_b128 v[182:185], v201 offset:1024
	ds_read_b128 v[186:189], v201 offset:2048
	ds_read_b128 v[202:205], v201 offset:3072
	ds_read_b128 v[206:209], v201 offset:4096
	ds_read_b128 v[214:217], v201 offset:5120
	ds_read_b128 v[218:221], v201 offset:6144
	ds_read_b128 v[222:225], v201 offset:7168
	global_load_lds_dwordx4 v[162:163], off
	s_add_i32 m0, s79, 0xe000
	v_lshl_add_u64 v[162:163], s[16:17], 0, v[176:177]
	global_load_lds_dwordx4 v[162:163], off
	s_waitcnt lgkmcnt(8)
	s_barrier
	s_waitcnt lgkmcnt(0)
	v_mfma_f32_16x16x32_bf16 v[126:129], v[130:133], v[178:181], v[126:129]
	v_mfma_f32_16x16x32_bf16 v[122:125], v[138:141], v[178:181], v[122:125]
	v_mfma_f32_16x16x32_bf16 v[110:113], v[130:133], v[186:189], v[110:113]
	v_mfma_f32_16x16x32_bf16 v[106:109], v[138:141], v[186:189], v[106:109]
	v_mfma_f32_16x16x32_bf16 v[94:97], v[130:133], v[206:209], v[94:97]
	v_mfma_f32_16x16x32_bf16 v[90:93], v[138:141], v[206:209], v[90:93]
	v_mfma_f32_16x16x32_bf16 v[78:81], v[130:133], v[218:221], v[78:81]
	v_mfma_f32_16x16x32_bf16 v[74:77], v[138:141], v[218:221], v[74:77]
	v_mfma_f32_16x16x32_bf16 v[126:129], v[134:137], v[182:185], v[126:129]
	v_mfma_f32_16x16x32_bf16 v[122:125], v[142:145], v[182:185], v[122:125]
	v_mfma_f32_16x16x32_bf16 v[110:113], v[134:137], v[202:205], v[110:113]
	v_mfma_f32_16x16x32_bf16 v[106:109], v[142:145], v[202:205], v[106:109]
	v_mfma_f32_16x16x32_bf16 v[94:97], v[134:137], v[214:217], v[94:97]
	v_mfma_f32_16x16x32_bf16 v[90:93], v[142:145], v[214:217], v[90:93]
	v_mfma_f32_16x16x32_bf16 v[78:81], v[134:137], v[222:225], v[78:81]
	v_mfma_f32_16x16x32_bf16 v[74:77], v[142:145], v[222:225], v[74:77]
	s_barrier
	s_add_i32 s39, 0, 0x14000
	v_add_u32_e32 v162, s39, v197
	s_add_i32 s26, s38, s78
	ds_read_b128 v[226:229], v162
	ds_read_b128 v[230:233], v162 offset:1024
	ds_read_b128 v[234:237], v162 offset:2048
	ds_read_b128 v[238:241], v162 offset:3072
	v_lshl_add_u64 v[162:163], s[36:37], 0, v[8:9]
	s_mov_b32 m0, s26
	v_lshl_add_u64 v[164:165], s[36:37], 0, v[146:147]
	global_load_lds_dwordx4 v[162:163], off
	s_add_i32 m0, s26, 0x2000
	s_nop 0
	global_load_lds_dwordx4 v[164:165], off
	s_barrier
	s_waitcnt lgkmcnt(0)
	v_mfma_f32_16x16x32_bf16 v[118:121], v[226:229], v[178:181], v[118:121]
	v_mfma_f32_16x16x32_bf16 v[114:117], v[234:237], v[178:181], v[114:117]
	v_mfma_f32_16x16x32_bf16 v[102:105], v[226:229], v[186:189], v[102:105]
	v_mfma_f32_16x16x32_bf16 v[98:101], v[234:237], v[186:189], v[98:101]
	v_mfma_f32_16x16x32_bf16 v[86:89], v[226:229], v[206:209], v[86:89]
	v_mfma_f32_16x16x32_bf16 v[82:85], v[234:237], v[206:209], v[82:85]
	v_mfma_f32_16x16x32_bf16 v[70:73], v[226:229], v[218:221], v[70:73]
	v_mfma_f32_16x16x32_bf16 v[66:69], v[234:237], v[218:221], v[66:69]
	v_mfma_f32_16x16x32_bf16 v[118:121], v[230:233], v[182:185], v[118:121]
	v_mfma_f32_16x16x32_bf16 v[114:117], v[238:241], v[182:185], v[114:117]
	v_mfma_f32_16x16x32_bf16 v[102:105], v[230:233], v[202:205], v[102:105]
	v_mfma_f32_16x16x32_bf16 v[98:101], v[238:241], v[202:205], v[98:101]
	v_mfma_f32_16x16x32_bf16 v[86:89], v[230:233], v[214:217], v[86:89]
	v_mfma_f32_16x16x32_bf16 v[82:85], v[238:241], v[214:217], v[82:85]
	v_mfma_f32_16x16x32_bf16 v[70:73], v[230:233], v[222:225], v[70:73]
	v_mfma_f32_16x16x32_bf16 v[66:69], v[238:241], v[222:225], v[66:69]
	s_barrier
	s_mov_b32 m0, s79
	v_lshl_add_u64 v[190:191], s[46:47], 0, v[150:151]
	ds_read_b128 v[178:181], v201 offset:16384
	ds_read_b128 v[182:185], v201 offset:17408
	ds_read_b128 v[186:189], v201 offset:18432
	ds_read_b128 v[202:205], v201 offset:19456
	ds_read_b128 v[206:209], v201 offset:20480
	ds_read_b128 v[214:217], v201 offset:21504
	ds_read_b128 v[218:221], v201 offset:22528
	ds_read_b128 v[222:225], v201 offset:23552
	global_load_lds_dwordx4 v[190:191], off
	s_mov_b32 m0, s80
	v_lshl_add_u64 v[194:195], s[46:47], 0, v[148:149]
	global_load_lds_dwordx4 v[194:195], off
	s_barrier
	s_waitcnt lgkmcnt(0)
	v_mfma_f32_16x16x32_bf16 v[50:53], v[130:133], v[178:181], v[50:53]
	v_mfma_f32_16x16x32_bf16 v[54:57], v[138:141], v[178:181], v[54:57]
	v_mfma_f32_16x16x32_bf16 v[34:37], v[130:133], v[186:189], v[34:37]
	v_mfma_f32_16x16x32_bf16 v[38:41], v[138:141], v[186:189], v[38:41]
	v_mfma_f32_16x16x32_bf16 v[18:21], v[130:133], v[206:209], v[18:21]
	v_mfma_f32_16x16x32_bf16 v[22:25], v[138:141], v[206:209], v[22:25]
	v_mfma_f32_16x16x32_bf16 v[0:3], v[130:133], v[218:221], v[0:3]
	v_mfma_f32_16x16x32_bf16 v[4:7], v[138:141], v[218:221], v[4:7]
	v_mfma_f32_16x16x32_bf16 v[50:53], v[134:137], v[182:185], v[50:53]
	v_mfma_f32_16x16x32_bf16 v[54:57], v[142:145], v[182:185], v[54:57]
	v_mfma_f32_16x16x32_bf16 v[34:37], v[134:137], v[202:205], v[34:37]
	v_mfma_f32_16x16x32_bf16 v[38:41], v[142:145], v[202:205], v[38:41]
	v_mfma_f32_16x16x32_bf16 v[18:21], v[134:137], v[214:217], v[18:21]
	v_mfma_f32_16x16x32_bf16 v[22:25], v[142:145], v[214:217], v[22:25]
	v_mfma_f32_16x16x32_bf16 v[0:3], v[134:137], v[222:225], v[0:3]
	v_mfma_f32_16x16x32_bf16 v[4:7], v[142:145], v[222:225], v[4:7]
	s_barrier
; #define PG8_STAGE(bufoff, gbase, voff) do { _Pragma("unroll") for (int _i = 0; _i < 2; ++_i) \
;         __builtin_amdgcn_global_load_lds((const unsigned*)((const char*)(gbase) + (voff)[_i]), (LAS unsigned*)(lds + (bufoff) + ldsw + _i * 8192), 16, 0, 0); } while (0)
; #define PG8_LDA(dst, b, h) do { _Pragma("unroll") for (int m = 0; m < 4; ++m) _Pragma("unroll") for (int k = 0; k < 2; ++k) dst[m][k] = *(const LAS bf16x8*)(lds + PG8_SA(b, h) + aoff + m * 2048 + k * 1024); } while (0)
; #define PG8_WAIT_V(n) asm volatile("s_waitcnt vmcnt(" #n ")" ::: "memory")
; #define PG8_WAIT_L(n) asm volatile("s_waitcnt lgkmcnt(" #n ")" ::: "memory")
; template <class Epi>
; DEVI void gemm_phase(LAS unsigned char* lds, const Gemm g, const Epi& E) {
;     ...
;         for (int t = 0; t < nt; t += 2) {
;             const bool last = (t == nt - 2);
;             const char* a1 = cA + (size_t)(t + 1) * kstep;
;             const char* a2 = last ? nA : cA + (size_t)(t + 2) * kstep; const char* b2 = last ? nB : cB + (size_t)(t + 2) * kstep;
;             const char* a3 = a2 + kstep; const char* b3 = b2 + kstep;
;             PG8_LDB(B0, 0, 0); PG8_SCHED; PG8_LDA(At, 0, 0); PG8_STAGE(PG8_SA(1, 1), a1 + hstepA, voffA);
;             PG8_WAIT_L(8); PG8_BAR; PG8_WAIT_L(0); PG8_MMA(0, 0, At, B0); PG8_BAR; PG8_SCHED;
;             PG8_LDB(B1, 0, 1); PG8_STAGE(PG8_SB(0, 0), b2, voffB);
;             PG8_BAR; PG8_WAIT_L(0); PG8_MMA(0, 1, At, B1); PG8_BAR;
;             PG8_LDA(At, 0, 1); PG8_STAGE(PG8_SA(0, 0), a2, voffA);
;             PG8_BAR; PG8_WAIT_L(0); PG8_MMA(1, 0, At, B0); PG8_BAR; PG8_SCHED;
;             PG8_STAGE(PG8_SB(0, 1), b2 + hstepB, voffB);
;             PG8_WAIT_V(6); PG8_BAR; PG8_MMA(1, 1, At, B1); PG8_BAR;
;             PG8_LDB(B0, 1, 0); PG8_SCHED; PG8_LDA(At, 1, 0); PG8_STAGE(PG8_SA(0, 1), a2 + hstepA, voffA);
;             PG8_WAIT_L(8); PG8_BAR; PG8_WAIT_L(0); PG8_MMA(0, 0, At, B0); PG8_BAR; PG8_SCHED;
;             PG8_LDB(B1, 1, 1); PG8_STAGE(PG8_SB(1, 0), b3, voffB);
;             PG8_BAR; PG8_WAIT_L(0); PG8_MMA(0, 1, At, B1); PG8_BAR;
;             PG8_LDA(At, 1, 1); PG8_STAGE(PG8_SA(1, 0), a3, voffA);
;             PG8_BAR; PG8_WAIT_L(0); PG8_MMA(1, 0, At, B0); PG8_BAR; PG8_SCHED;
;             PG8_STAGE(PG8_SB(1, 1), b3 + hstepB, voffB);
;             PG8_WAIT_V(6); PG8_BAR; PG8_MMA(1, 1, At, B1); PG8_BAR;
;         }
	s_add_u32 s26, s36, 0x40000
	s_addc_u32 s27, s37, 0
	s_add_i32 s38, s39, s78
	s_mov_b32 m0, s38
	v_lshl_add_u64 v[130:131], s[26:27], 0, v[8:9]
	global_load_lds_dwordx4 v[130:131], off
	s_add_i32 m0, s38, 0x2000
	v_lshl_add_u64 v[130:131], s[26:27], 0, v[146:147]
	global_load_lds_dwordx4 v[130:131], off
	s_waitcnt vmcnt(6)
	s_barrier
	v_mfma_f32_16x16x32_bf16 v[58:61], v[226:229], v[178:181], v[58:61]
	v_mfma_f32_16x16x32_bf16 v[62:65], v[234:237], v[178:181], v[62:65]
	v_mfma_f32_16x16x32_bf16 v[42:45], v[226:229], v[186:189], v[42:45]
	v_mfma_f32_16x16x32_bf16 v[46:49], v[234:237], v[186:189], v[46:49]
	v_mfma_f32_16x16x32_bf16 v[26:29], v[226:229], v[206:209], v[26:29]
	v_mfma_f32_16x16x32_bf16 v[30:33], v[234:237], v[206:209], v[30:33]
	v_mfma_f32_16x16x32_bf16 v[10:13], v[226:229], v[218:221], v[10:13]
	v_mfma_f32_16x16x32_bf16 v[14:17], v[234:237], v[218:221], v[14:17]
	v_mfma_f32_16x16x32_bf16 v[58:61], v[230:233], v[182:185], v[58:61]
	v_mfma_f32_16x16x32_bf16 v[62:65], v[238:241], v[182:185], v[62:65]
	v_mfma_f32_16x16x32_bf16 v[42:45], v[230:233], v[202:205], v[42:45]
	v_mfma_f32_16x16x32_bf16 v[46:49], v[238:241], v[202:205], v[46:49]
	v_mfma_f32_16x16x32_bf16 v[26:29], v[230:233], v[214:217], v[26:29]
	v_mfma_f32_16x16x32_bf16 v[30:33], v[238:241], v[214:217], v[30:33]
	v_mfma_f32_16x16x32_bf16 v[10:13], v[230:233], v[222:225], v[10:13]
	v_mfma_f32_16x16x32_bf16 v[14:17], v[238:241], v[222:225], v[14:17]
	s_barrier
	s_add_i32 s38, 0, 0x18000
	v_add_u32_e32 v142, s38, v197
	ds_read_b128 v[130:133], v142
	ds_read_b128 v[134:137], v142 offset:1024
	ds_read_b128 v[138:141], v142 offset:2048
	ds_read_b128 v[142:145], v142 offset:3072
	s_add_u32 s26, s46, 0x40000
	s_addc_u32 s27, s47, 0
	s_mov_b32 m0, s81
	v_lshl_add_u64 v[226:227], s[26:27], 0, v[150:151]
	ds_read_b128 v[178:181], v201 offset:32768
	ds_read_b128 v[182:185], v201 offset:33792
	ds_read_b128 v[186:189], v201 offset:34816
	ds_read_b128 v[202:205], v201 offset:35840
	ds_read_b128 v[206:209], v201 offset:36864
	ds_read_b128 v[214:217], v201 offset:37888
	ds_read_b128 v[218:221], v201 offset:38912
	ds_read_b128 v[222:225], v201 offset:39936
	global_load_lds_dwordx4 v[226:227], off
	s_mov_b32 m0, s82
	v_lshl_add_u64 v[226:227], s[26:27], 0, v[148:149]
	global_load_lds_dwordx4 v[226:227], off
	s_waitcnt lgkmcnt(8)
	s_barrier
	s_waitcnt lgkmcnt(0)
	v_mfma_f32_16x16x32_bf16 v[126:129], v[130:133], v[178:181], v[126:129]
	v_mfma_f32_16x16x32_bf16 v[122:125], v[138:141], v[178:181], v[122:125]
	v_mfma_f32_16x16x32_bf16 v[110:113], v[130:133], v[186:189], v[110:113]
	v_mfma_f32_16x16x32_bf16 v[106:109], v[138:141], v[186:189], v[106:109]
	v_mfma_f32_16x16x32_bf16 v[94:97], v[130:133], v[206:209], v[94:97]
	v_mfma_f32_16x16x32_bf16 v[90:93], v[138:141], v[206:209], v[90:93]
	v_mfma_f32_16x16x32_bf16 v[78:81], v[130:133], v[218:221], v[78:81]
	v_mfma_f32_16x16x32_bf16 v[74:77], v[138:141], v[218:221], v[74:77]
	v_mfma_f32_16x16x32_bf16 v[126:129], v[134:137], v[182:185], v[126:129]
	v_mfma_f32_16x16x32_bf16 v[122:125], v[142:145], v[182:185], v[122:125]
	v_mfma_f32_16x16x32_bf16 v[110:113], v[134:137], v[202:205], v[110:113]
	v_mfma_f32_16x16x32_bf16 v[106:109], v[142:145], v[202:205], v[106:109]
	v_mfma_f32_16x16x32_bf16 v[94:97], v[134:137], v[214:217], v[94:97]
	v_mfma_f32_16x16x32_bf16 v[90:93], v[142:145], v[214:217], v[90:93]
	v_mfma_f32_16x16x32_bf16 v[78:81], v[134:137], v[222:225], v[78:81]
	v_mfma_f32_16x16x32_bf16 v[74:77], v[142:145], v[222:225], v[74:77]
	s_barrier
	s_add_i32 s39, 0, 0x1c000
	s_add_i32 s26, s38, s78
	v_add_u32_e32 v192, s39, v197
	v_lshl_add_u64 v[162:163], v[162:163], 0, s[70:71]
	s_mov_b32 m0, s26
	ds_read_b128 v[226:229], v192
	ds_read_b128 v[230:233], v192 offset:1024
	ds_read_b128 v[234:237], v192 offset:2048
	ds_read_b128 v[238:241], v192 offset:3072
	global_load_lds_dwordx4 v[162:163], off
	s_add_i32 m0, s26, 0x2000
	v_lshl_add_u64 v[162:163], v[164:165], 0, s[70:71]
	global_load_lds_dwordx4 v[162:163], off
	s_barrier
	s_waitcnt lgkmcnt(0)
	v_mfma_f32_16x16x32_bf16 v[118:121], v[226:229], v[178:181], v[118:121]
	v_mfma_f32_16x16x32_bf16 v[114:117], v[234:237], v[178:181], v[114:117]
	v_mfma_f32_16x16x32_bf16 v[102:105], v[226:229], v[186:189], v[102:105]
	v_mfma_f32_16x16x32_bf16 v[98:101], v[234:237], v[186:189], v[98:101]
	v_mfma_f32_16x16x32_bf16 v[86:89], v[226:229], v[206:209], v[86:89]
	v_mfma_f32_16x16x32_bf16 v[82:85], v[234:237], v[206:209], v[82:85]
	v_mfma_f32_16x16x32_bf16 v[70:73], v[226:229], v[218:221], v[70:73]
	v_mfma_f32_16x16x32_bf16 v[66:69], v[234:237], v[218:221], v[66:69]
	v_mfma_f32_16x16x32_bf16 v[118:121], v[230:233], v[182:185], v[118:121]
	v_mfma_f32_16x16x32_bf16 v[114:117], v[238:241], v[182:185], v[114:117]
	v_mfma_f32_16x16x32_bf16 v[102:105], v[230:233], v[202:205], v[102:105]
	v_mfma_f32_16x16x32_bf16 v[98:101], v[238:241], v[202:205], v[98:101]
	v_mfma_f32_16x16x32_bf16 v[86:89], v[230:233], v[214:217], v[86:89]
	v_mfma_f32_16x16x32_bf16 v[82:85], v[238:241], v[214:217], v[82:85]
	v_mfma_f32_16x16x32_bf16 v[70:73], v[230:233], v[222:225], v[70:73]
	v_mfma_f32_16x16x32_bf16 v[66:69], v[238:241], v[222:225], v[66:69]
	s_barrier
	s_mov_b32 m0, s83
	v_lshl_add_u64 v[162:163], v[190:191], 0, s[70:71]
	ds_read_b128 v[178:181], v201 offset:49152
	ds_read_b128 v[182:185], v201 offset:50176
	ds_read_b128 v[186:189], v201 offset:51200
	ds_read_b128 v[202:205], v201 offset:52224
	ds_read_b128 v[206:209], v201 offset:53248
	ds_read_b128 v[214:217], v201 offset:54272
	ds_read_b128 v[218:221], v201 offset:55296
	ds_read_b128 v[222:225], v201 offset:56320
	global_load_lds_dwordx4 v[162:163], off
	s_mov_b32 m0, s84
	v_lshl_add_u64 v[162:163], v[194:195], 0, s[70:71]
	global_load_lds_dwordx4 v[162:163], off
	s_barrier
; #define PG8_STAGE(bufoff, gbase, voff) do { _Pragma("unroll") for (int _i = 0; _i < 2; ++_i) \
;         __builtin_amdgcn_global_load_lds((const unsigned*)((const char*)(gbase) + (voff)[_i]), (LAS unsigned*)(lds + (bufoff) + ldsw + _i * 8192), 16, 0, 0); } while (0)
; #define PG8_LDA(dst, b, h) do { _Pragma("unroll") for (int m = 0; m < 4; ++m) _Pragma("unroll") for (int k = 0; k < 2; ++k) dst[m][k] = *(const LAS bf16x8*)(lds + PG8_SA(b, h) + aoff + m * 2048 + k * 1024); } while (0)
; #define PG8_MMA(ai, bj, At, Bt) do { __builtin_amdgcn_s_setprio(1); _Pragma("unroll") for (int m = 0; m < 4; ++m) _Pragma("unroll") for (int n = 0; n < 2; ++n) _Pragma("unroll") for (int k = 0; k < 2; ++k) \
;         acc[ai][bj][m][n] = __builtin_amdgcn_mfma_f32_16x16x32_bf16(Bt[n][k], At[m][k], acc[ai][bj][m][n], 0, 0, 0); __builtin_amdgcn_s_setprio(0); } while (0)
; #define PG8_WAIT_V(n) asm volatile("s_waitcnt vmcnt(" #n ")" ::: "memory")
; #define PG8_WAIT_L(n) asm volatile("s_waitcnt lgkmcnt(" #n ")" ::: "memory")
; #define PG8_BAR __builtin_amdgcn_s_barrier()
; #define PG8_SCHED __builtin_amdgcn_sched_barrier(0)
; template <class Epi>
; DEVI void gemm_phase(LAS unsigned char* lds, const Gemm g, const Epi& E) {
;     ...
;             PG8_LDA(At, 1, 1); PG8_STAGE(PG8_SA(1, 0), a3, voffA);
;             PG8_BAR; PG8_WAIT_L(0); PG8_MMA(1, 0, At, B0); PG8_BAR; PG8_SCHED;
;             PG8_STAGE(PG8_SB(1, 1), b3 + hstepB, voffB);
;             PG8_WAIT_V(6); PG8_BAR; PG8_MMA(1, 1, At, B1); PG8_BAR;
;         }
;         {
;             const int row0 = cur.pm * BM + wr * 64 + fr, col0 = cur.pn * BM + wc * 32 + (Epi::PERM ? 8 : 4) * fq; constexpr int NST = Epi::PERM ? 4 : 16;
;             float rsv[8];
;             if constexpr (Epi::RS) { f32x4 q4[8];
; #pragma unroll
;                 for (int i = 0; i < 8; ++i) q4[i] = *(const f32x4*)(E.ssq_in + (size_t)(row0 + (i >> 2) * HALF + (i & 3) * 16) * 4);
; #pragma unroll
;                 for (int i = 0; i < 8; ++i) rsv[i] = rsqrtf((((q4[i][0] + q4[i][1]) + q4[i][2]) + q4[i][3]) * (1.f / DM) + 1e-6f); }
	s_waitcnt lgkmcnt(0)
	v_mfma_f32_16x16x32_bf16 v[50:53], v[130:133], v[178:181], v[50:53]
	v_mfma_f32_16x16x32_bf16 v[54:57], v[138:141], v[178:181], v[54:57]
	v_mfma_f32_16x16x32_bf16 v[34:37], v[130:133], v[186:189], v[34:37]
	v_mfma_f32_16x16x32_bf16 v[38:41], v[138:141], v[186:189], v[38:41]
	v_mfma_f32_16x16x32_bf16 v[18:21], v[130:133], v[206:209], v[18:21]
	v_mfma_f32_16x16x32_bf16 v[22:25], v[138:141], v[206:209], v[22:25]
	v_mfma_f32_16x16x32_bf16 v[0:3], v[130:133], v[218:221], v[0:3]
	v_mfma_f32_16x16x32_bf16 v[4:7], v[138:141], v[218:221], v[4:7]
	v_mfma_f32_16x16x32_bf16 v[50:53], v[134:137], v[182:185], v[50:53]
	v_mfma_f32_16x16x32_bf16 v[54:57], v[142:145], v[182:185], v[54:57]
	v_mfma_f32_16x16x32_bf16 v[34:37], v[134:137], v[202:205], v[34:37]
	v_mfma_f32_16x16x32_bf16 v[38:41], v[142:145], v[202:205], v[38:41]
	v_mfma_f32_16x16x32_bf16 v[18:21], v[134:137], v[214:217], v[18:21]
	v_mfma_f32_16x16x32_bf16 v[22:25], v[142:145], v[214:217], v[22:25]
	v_mfma_f32_16x16x32_bf16 v[0:3], v[134:137], v[222:225], v[0:3]
	v_mfma_f32_16x16x32_bf16 v[4:7], v[142:145], v[222:225], v[4:7]
	s_barrier
	s_add_u32 s26, s36, 0x40080
	s_addc_u32 s27, s37, 0
	s_add_i32 s36, s39, s78
	s_mov_b32 m0, s36
	v_lshl_add_u64 v[130:131], s[26:27], 0, v[8:9]
	global_load_lds_dwordx4 v[130:131], off
	s_add_i32 m0, s36, 0x2000
	v_lshl_add_u64 v[130:131], s[26:27], 0, v[146:147]
	global_load_lds_dwordx4 v[130:131], off
	s_waitcnt vmcnt(6)
	s_barrier
	v_mfma_f32_16x16x32_bf16 v[58:61], v[226:229], v[178:181], v[58:61]
	v_mfma_f32_16x16x32_bf16 v[62:65], v[234:237], v[178:181], v[62:65]
	v_mfma_f32_16x16x32_bf16 v[42:45], v[226:229], v[186:189], v[42:45]
	v_mfma_f32_16x16x32_bf16 v[46:49], v[234:237], v[186:189], v[46:49]
	v_mfma_f32_16x16x32_bf16 v[26:29], v[226:229], v[206:209], v[26:29]
	v_mfma_f32_16x16x32_bf16 v[30:33], v[234:237], v[206:209], v[30:33]
	v_mfma_f32_16x16x32_bf16 v[10:13], v[226:229], v[218:221], v[10:13]
	v_mfma_f32_16x16x32_bf16 v[14:17], v[234:237], v[218:221], v[14:17]
	v_mfma_f32_16x16x32_bf16 v[58:61], v[230:233], v[182:185], v[58:61]
	v_mfma_f32_16x16x32_bf16 v[62:65], v[238:241], v[182:185], v[62:65]
	v_mfma_f32_16x16x32_bf16 v[42:45], v[230:233], v[202:205], v[42:45]
	v_mfma_f32_16x16x32_bf16 v[46:49], v[238:241], v[202:205], v[46:49]
	v_mfma_f32_16x16x32_bf16 v[26:29], v[230:233], v[214:217], v[26:29]
	v_mfma_f32_16x16x32_bf16 v[30:33], v[238:241], v[214:217], v[30:33]
	v_mfma_f32_16x16x32_bf16 v[10:13], v[230:233], v[222:225], v[10:13]
	v_mfma_f32_16x16x32_bf16 v[14:17], v[238:241], v[222:225], v[14:17]
	s_barrier
	s_add_i32 s19, s19, 2
	s_add_u32 s16, s16, 0x100
	s_addc_u32 s17, s17, 0
	s_add_u32 s9, s9, 0x100
	s_addc_u32 s18, s18, 0
	s_cmp_gt_u32 s19, 13
	s_cbranch_scc0 .LBB0_1672
	s_setprio 0
	v_lshl_add_u32 v194, s4, 8, v193
	v_add_u32_e32 v178, 0xb0, v194
	v_ashrrev_i32_e32 v195, 31, v194
	v_or_b32_e32 v190, 16, v194
	v_ashrrev_i32_e32 v179, 31, v178
	v_lshl_add_u64 v[130:131], v[194:195], 4, s[10:11]
	v_ashrrev_i32_e32 v191, 31, v190
	v_lshl_add_u64 v[134:135], v[178:179], 4, s[10:11]
	global_load_dwordx4 v[202:205], v[130:131], off
	v_or_b32_e32 v188, 32, v194
	global_load_dwordx4 v[134:137], v[134:135], off
	v_lshl_add_u64 v[130:131], v[190:191], 4, s[10:11]
	global_load_dwordx4 v[206:209], v[130:131], off
	v_ashrrev_i32_e32 v189, 31, v188
	v_or_b32_e32 v186, 48, v194
	v_lshl_add_u64 v[130:131], v[188:189], 4, s[10:11]
	v_ashrrev_i32_e32 v187, 31, v186
	global_load_dwordx4 v[214:217], v[130:131], off
	v_lshl_add_u64 v[130:131], v[186:187], 4, s[10:11]
	global_load_dwordx4 v[218:221], v[130:131], off
	v_add_u32_e32 v184, 0x80, v194
	v_ashrrev_i32_e32 v185, 31, v184
	v_add_u32_e32 v182, 0x90, v194
	v_lshl_add_u64 v[130:131], v[184:185], 4, s[10:11]
	v_ashrrev_i32_e32 v183, 31, v182
	global_load_dwordx4 v[138:141], v[130:131], off
	v_lshl_add_u64 v[130:131], v[182:183], 4, s[10:11]
	v_add_u32_e32 v180, 0xa0, v194
	global_load_dwordx4 v[142:145], v[130:131], off
	v_ashrrev_i32_e32 v181, 31, v180
	v_lshl_add_u64 v[130:131], v[180:181], 4, s[10:11]
	global_load_dwordx4 v[130:133], v[130:131], off
	s_mov_b32 s0, 0x358637bd
	s_mov_b64 s[36:37], s[14:15]
	s_mov_b64 s[16:17], s[12:13]
	s_waitcnt vmcnt(0)
	v_mov_b32_e32 v163, v202
	v_mov_b32_e32 v165, v204
	v_mov_b32_e32 v162, v206
	v_mov_b32_e32 v202, v207
	v_pk_add_f32 v[162:163], v[162:163], v[202:203]
	v_mov_b32_e32 v164, v208
	v_pk_add_f32 v[162:163], v[164:165], v[162:163]
	v_mov_b32_e32 v204, v209
	v_pk_add_f32 v[162:163], v[204:205], v[162:163]
	v_mov_b64_e32 v[202:203], s[0:1]
	v_pk_fma_f32 v[162:163], v[162:163], s[72:73], v[202:203] op_sel_hi:[1,0,0]
	v_mov_b32_e32 v165, v216
	v_mul_f32_e32 v164, 0x4b800000, v163
	v_cmp_gt_f32_e64 s[4:5], s94, v163
	v_cmp_gt_f32_e32 vcc, s94, v162
	v_mov_b32_e32 v216, v221
	v_cndmask_b32_e64 v163, v163, v164, s[4:5]
	v_rsq_f32_e32 v163, v163
	s_nop 0
	v_mul_f32_e32 v164, 0x45800000, v163
	v_cndmask_b32_e64 v200, v163, v164, s[4:5]
	v_mul_f32_e32 v163, 0x4b800000, v162
	v_cndmask_b32_e32 v162, v162, v163, vcc
	v_rsq_f32_e32 v162, v162
	v_mov_b32_e32 v164, v220
	v_pk_mul_f32 v[126:127], v[126:127], v[200:201] op_sel_hi:[1,0]
	v_pk_mul_f32 v[122:123], v[122:123], v[200:201] op_sel_hi:[1,0]
	v_mul_f32_e32 v163, 0x45800000, v162
	v_cndmask_b32_e32 v198, v162, v163, vcc
	v_mov_b32_e32 v162, v218
	v_mov_b32_e32 v163, v214
	v_mov_b32_e32 v214, v219
	v_pk_add_f32 v[162:163], v[162:163], v[214:215]
	v_pk_mul_f32 v[118:119], v[118:119], v[200:201] op_sel_hi:[1,0]
	v_pk_add_f32 v[162:163], v[164:165], v[162:163]
	v_pk_mul_f32 v[124:125], v[124:125], v[200:201] op_sel_hi:[1,0]
	v_pk_add_f32 v[162:163], v[216:217], v[162:163]
; template <class Epi>
; DEVI void gemm_phase(LAS unsigned char* lds, const Gemm g, const Epi& E) {
;     ...
;                 for (int i = 0; i < 8; ++i) q4[i] = *(const f32x4*)(E.ssq_in + (size_t)(row0 + (i >> 2) * HALF + (i & 3) * 16) * 4);
; #pragma unroll
;                 for (int i = 0; i < 8; ++i) rsv[i] = rsqrtf((((q4[i][0] + q4[i][1]) + q4[i][2]) + q4[i][3]) * (1.f / DM) + 1e-6f); }
;             if constexpr (Epi::SOFTMAX) {
;                 LAS float* red = (LAS float*)(lds + 131072);
; #pragma unroll
;                 for (int ai = 0; ai < 2; ++ai)
; #pragma unroll
;                     for (int m = 0; m < 4; ++m) { const float sc = rsv[ai * 4 + m] * 0.0625f; float part = 0.f;
; #pragma unroll
;                         for (int bj = 0; bj < 2; ++bj)
; #pragma unroll
;                             for (int n = 0; n < 2; ++n)
; #pragma unroll
;                                 for (int j = 0; j < 4; ++j) { const float e = __expf(fmaxf(fminf(acc[ai][bj][m][n][j] * sc, 80.f), -80.f)); acc[ai][bj][m][n][j] = e; part += e; }
;                         part += __shfl_xor(part, 16); part += __shfl_xor(part, 32);
;                         if (fq == 0) red[(wr * 4 + wc) * 128 + ai * 64 + m * 16 + fr] = part; }
;                 PG8_WAIT_L(0); PG8_BAR;
; #pragma unroll
;                 for (int ai = 0; ai < 2; ++ai)
; #pragma unroll
;                     for (int m = 0; m < 4; ++m) { const LAS float* rr = red + wr * 512 + ai * 64 + m * 16 + fr;
;                         const float inv = __builtin_amdgcn_rcpf(((rr[0] + rr[128]) + rr[256]) + rr[384]); const int r = row0 + ai * HALF + m * 16;
; #pragma unroll
;                         for (int bj = 0; bj < 2; ++bj) *(u32x4*)(E.P + (size_t)r * DM + col0 + bj * HALF) = pk8(acc[ai][bj][m][0] * inv, acc[ai][bj][m][1] * inv); }
;             } else
; #pragma unroll
;             for (int am = 0; am < 4; ++am) {
;                 const int ai = am >> 1, m0 = (am & 1) * 2;
;                 f32x4 pre[2][2][2];
;                 if constexpr (Epi::PRE) {
; #pragma unroll
;                     for (int m = 0; m < 2; ++m)
; #pragma unroll
;                         for (int bj = 0; bj < 2; ++bj)
; #pragma unroll
;                             for (int n = 0; n < 2; ++n) pre[m][bj][n] = E.load(row0 + ai * HALF + (m0 + m) * 16, col0 + bj * HALF + n * NST);
;                 }
; #pragma unroll
	v_pk_mul_f32 v[114:115], v[114:115], v[200:201] op_sel_hi:[1,0]
	v_pk_fma_f32 v[162:163], v[162:163], s[72:73], v[202:203] op_sel_hi:[1,0,0]
	v_pk_mul_f32 v[128:129], v[128:129], v[200:201] op_sel_hi:[1,0]
	v_mul_f32_e32 v164, 0x4b800000, v163
	v_cmp_gt_f32_e64 s[4:5], s94, v163
	v_cmp_gt_f32_e32 vcc, s94, v162
	v_pk_mul_f32 v[120:121], v[120:121], v[200:201] op_sel_hi:[1,0]
	v_cndmask_b32_e64 v163, v163, v164, s[4:5]
	v_rsq_f32_e32 v163, v163
	v_pk_mul_f32 v[116:117], v[116:117], v[200:201] op_sel_hi:[1,0]
	v_pk_mul_f32 v[106:107], v[106:107], v[198:199] op_sel_hi:[1,0]
	v_pk_mul_f32 v[110:111], v[110:111], v[198:199] op_sel_hi:[1,0]
	v_mul_f32_e32 v164, 0x45800000, v163
	v_cndmask_b32_e64 v196, v163, v164, s[4:5]
	v_mul_f32_e32 v163, 0x4b800000, v162
	v_cndmask_b32_e32 v162, v162, v163, vcc
	v_rsq_f32_e32 v162, v162
	v_pk_mul_f32 v[102:103], v[102:103], v[198:199] op_sel_hi:[1,0]
	v_pk_mul_f32 v[108:109], v[108:109], v[198:199] op_sel_hi:[1,0]
	v_pk_mul_f32 v[98:99], v[98:99], v[198:199] op_sel_hi:[1,0]
	v_mul_f32_e32 v163, 0x45800000, v162
	v_cndmask_b32_e32 v192, v162, v163, vcc
	v_mov_b32_e32 v162, v142
	v_mov_b32_e32 v163, v138
	v_mov_b32_e32 v138, v143
	v_pk_add_f32 v[138:139], v[162:163], v[138:139]
	v_mov_b32_e32 v142, v144
	v_mov_b32_e32 v143, v140
	v_pk_add_f32 v[138:139], v[142:143], v[138:139]
	v_mov_b32_e32 v142, v134
	v_mov_b32_e32 v143, v130
	v_mov_b32_e32 v130, v135
	v_pk_add_f32 v[130:131], v[142:143], v[130:131]
	v_mov_b32_e32 v134, v136
	v_mov_b32_e32 v135, v132
	v_pk_add_f32 v[130:131], v[134:135], v[130:131]
	v_mov_b32_e32 v132, v137
	v_pk_add_f32 v[130:131], v[132:133], v[130:131]
	v_mul_f32_e32 v133, 0xbfb8aa3b, v126
	v_exp_f32_e32 v133, v133
	v_mov_b32_e32 v140, v145
	v_pk_add_f32 v[138:139], v[140:141], v[138:139]
	v_pk_fma_f32 v[130:131], v[130:131], s[72:73], v[202:203] op_sel_hi:[1,0,0]
	v_add_f32_e32 v133, 1.0, v133
	v_rcp_f32_e32 v136, v133
	v_mul_f32_e32 v133, 0xbfb8aa3b, v122
	v_exp_f32_e32 v133, v133
	v_pk_fma_f32 v[138:139], v[138:139], s[72:73], v[202:203] op_sel_hi:[1,0,0]
	v_mul_f32_e32 v132, 0x4b800000, v131
	v_mul_f32_e32 v140, 0x4b800000, v139
	v_add_f32_e32 v133, 1.0, v133
	v_rcp_f32_e32 v142, v133
	v_mul_f32_e32 v133, 0xbfb8aa3b, v127
	v_exp_f32_e32 v133, v133
	v_cmp_gt_f32_e64 s[4:5], s94, v139
	v_cmp_gt_f32_e32 vcc, s94, v138
	v_pk_mul_f32 v[112:113], v[112:113], v[198:199] op_sel_hi:[1,0]
	v_add_f32_e32 v133, 1.0, v133
	v_rcp_f32_e32 v137, v133
	v_cndmask_b32_e64 v139, v139, v140, s[4:5]
	v_rsq_f32_e32 v139, v139
	v_pk_mul_f32 v[104:105], v[104:105], v[198:199] op_sel_hi:[1,0]
	v_pk_mul_f32 v[126:127], v[126:127], v[136:137]
	v_pk_mul_f32 v[100:101], v[100:101], v[198:199] op_sel_hi:[1,0]
	v_pk_mul_f32 v[118:119], v[118:119], v[126:127]
	v_mul_f32_e32 v126, 0xbfb8aa3b, v123
	v_exp_f32_e32 v126, v126
	v_mul_f32_e32 v140, 0x45800000, v139
	v_cndmask_b32_e64 v140, v139, v140, s[4:5]
	v_mul_f32_e32 v139, 0x4b800000, v138
	v_add_f32_e32 v126, 1.0, v126
	v_rcp_f32_e32 v143, v126
	v_cmp_gt_f32_e64 s[4:5], s94, v131
	v_cndmask_b32_e32 v138, v138, v139, vcc
	v_rsq_f32_e32 v138, v138
	v_pk_mul_f32 v[122:123], v[122:123], v[142:143]
	v_cndmask_b32_e64 v131, v131, v132, s[4:5]
	v_pk_mul_f32 v[122:123], v[114:115], v[122:123]
	v_mul_f32_e32 v115, 0xbfb8aa3b, v124
	v_exp_f32_e32 v115, v115
	v_mul_f32_e32 v114, 0xbfb8aa3b, v128
	v_exp_f32_e32 v114, v114
	v_rsq_f32_e32 v131, v131
	v_add_f32_e32 v115, 1.0, v115
	v_rcp_f32_e32 v126, v115
	v_mul_f32_e32 v115, 0xbfb8aa3b, v129
	v_exp_f32_e32 v115, v115
	v_add_f32_e32 v114, 1.0, v114
	v_rcp_f32_e32 v114, v114
	v_mul_f32_e32 v139, 0x45800000, v138
	v_add_f32_e32 v115, 1.0, v115
	v_rcp_f32_e32 v115, v115
	v_mul_f32_e32 v132, 0x45800000, v131
	v_cndmask_b32_e32 v138, v138, v139, vcc
	v_cmp_gt_f32_e32 vcc, s94, v130
	v_pk_mul_f32 v[114:115], v[128:129], v[114:115]
	v_cndmask_b32_e64 v134, v131, v132, s[4:5]
	v_pk_mul_f32 v[120:121], v[120:121], v[114:115]
	v_mul_f32_e32 v114, 0xbfb8aa3b, v125
	v_exp_f32_e32 v114, v114
	v_mul_f32_e32 v131, 0x4b800000, v130
	v_cndmask_b32_e32 v130, v130, v131, vcc
	v_rsq_f32_e32 v130, v130
	v_add_f32_e32 v114, 1.0, v114
	v_rcp_f32_e32 v127, v114
	v_pk_mul_f32 v[90:91], v[90:91], v[196:197] op_sel_hi:[1,0]
	v_mul_f32_e32 v131, 0x45800000, v130
	v_cndmask_b32_e32 v132, v130, v131, vcc
	v_lshl_or_b32 v130, s86, 7, v199
	v_ashrrev_i32_e32 v131, 31, v130
	v_pk_mul_f32 v[114:115], v[124:125], v[126:127]
	v_lshl_add_u64 v[130:131], v[130:131], 1, s[28:29]
	v_pk_mul_f32 v[124:125], v[116:117], v[114:115]
	v_cvt_pk_bf16_f32 v114, v118, v119
	v_cvt_pk_bf16_f32 v115, v120, v121
	v_cvt_pk_bf16_f32 v116, v122, v123
	v_cvt_pk_bf16_f32 v117, v124, v125
	v_mad_i64_i32 v[118:119], s[0:1], v194, s35, v[130:131]
	global_store_dwordx4 v[118:119], v[114:117], off
	v_pk_mul_f32 v[94:95], v[94:95], v[196:197] op_sel_hi:[1,0]
	v_pk_mul_f32 v[86:87], v[86:87], v[196:197] op_sel_hi:[1,0]
	v_mul_f32_e32 v115, 0xbfb8aa3b, v106
	v_exp_f32_e32 v115, v115
	v_mul_f32_e32 v114, 0xbfb8aa3b, v110
	v_exp_f32_e32 v114, v114
	v_pk_mul_f32 v[92:93], v[92:93], v[196:197] op_sel_hi:[1,0]
	v_add_f32_e32 v115, 1.0, v115
	v_rcp_f32_e32 v116, v115
	v_mul_f32_e32 v115, 0xbfb8aa3b, v111
	v_exp_f32_e32 v115, v115
	v_add_f32_e32 v114, 1.0, v114
	v_rcp_f32_e32 v114, v114
	v_pk_mul_f32 v[82:83], v[82:83], v[196:197] op_sel_hi:[1,0]
	v_add_f32_e32 v115, 1.0, v115
	v_rcp_f32_e32 v115, v115
	v_pk_mul_f32 v[96:97], v[96:97], v[196:197] op_sel_hi:[1,0]
	v_pk_mul_f32 v[88:89], v[88:89], v[196:197] op_sel_hi:[1,0]
	v_pk_mul_f32 v[84:85], v[84:85], v[196:197] op_sel_hi:[1,0]
	v_pk_mul_f32 v[110:111], v[110:111], v[114:115]
	v_pk_mul_f32 v[74:75], v[74:75], v[192:193] op_sel_hi:[1,0]
; template <class Epi>
; DEVI void gemm_phase(LAS unsigned char* lds, const Gemm g, const Epi& E) {
;     ...
;                 for (int mm = 0; mm < 2; ++mm) {
;                     const int m = m0 + mm;
;                     const int r = row0 + ai * HALF + m * 16; float rs = 1.f, part = 0.f;
;                     if constexpr (Epi::RS) rs = rsv[ai * 4 + m];
;                     if constexpr (Epi::PAIR) E.pair8(cur.b, r, cur.pn * HALF + wc * 32 + 8 * fq, acc[ai][0][m][0] * rs, acc[ai][0][m][1] * rs, acc[ai][1][m][0] * rs, acc[ai][1][m][1] * rs);
	v_pk_mul_f32 v[102:103], v[102:103], v[110:111]
	v_mul_f32_e32 v110, 0xbfb8aa3b, v107
	v_exp_f32_e32 v110, v110
	v_pk_mul_f32 v[78:79], v[78:79], v[192:193] op_sel_hi:[1,0]
	v_pk_mul_f32 v[70:71], v[70:71], v[192:193] op_sel_hi:[1,0]
	v_pk_mul_f32 v[76:77], v[76:77], v[192:193] op_sel_hi:[1,0]
	v_add_f32_e32 v110, 1.0, v110
	v_rcp_f32_e32 v117, v110
	v_pk_mul_f32 v[66:67], v[66:67], v[192:193] op_sel_hi:[1,0]
	v_pk_mul_f32 v[80:81], v[80:81], v[192:193] op_sel_hi:[1,0]
	v_pk_mul_f32 v[72:73], v[72:73], v[192:193] op_sel_hi:[1,0]
	v_pk_mul_f32 v[106:107], v[106:107], v[116:117]
	v_pk_mul_f32 v[68:69], v[68:69], v[192:193] op_sel_hi:[1,0]
	v_pk_mul_f32 v[106:107], v[98:99], v[106:107]
	v_mul_f32_e32 v99, 0xbfb8aa3b, v108
	v_exp_f32_e32 v99, v99
	v_mul_f32_e32 v98, 0xbfb8aa3b, v112
	v_exp_f32_e32 v98, v98
	v_pk_mul_f32 v[54:55], v[54:55], v[140:141] op_sel_hi:[1,0]
	v_add_f32_e32 v99, 1.0, v99
	v_rcp_f32_e32 v110, v99
	v_mul_f32_e32 v99, 0xbfb8aa3b, v113
	v_exp_f32_e32 v99, v99
	v_add_f32_e32 v98, 1.0, v98
	v_rcp_f32_e32 v98, v98
	v_pk_mul_f32 v[50:51], v[50:51], v[140:141] op_sel_hi:[1,0]
	v_add_f32_e32 v99, 1.0, v99
	v_rcp_f32_e32 v99, v99
	v_pk_mul_f32 v[58:59], v[58:59], v[140:141] op_sel_hi:[1,0]
	v_pk_mul_f32 v[56:57], v[56:57], v[140:141] op_sel_hi:[1,0]
	v_pk_mul_f32 v[52:53], v[52:53], v[140:141] op_sel_hi:[1,0]
	v_pk_mul_f32 v[98:99], v[112:113], v[98:99]
	v_pk_mul_f32 v[62:63], v[62:63], v[140:141] op_sel_hi:[1,0]
	v_pk_mul_f32 v[104:105], v[104:105], v[98:99]
	v_mul_f32_e32 v98, 0xbfb8aa3b, v109
	v_exp_f32_e32 v98, v98
	v_pk_mul_f32 v[60:61], v[60:61], v[140:141] op_sel_hi:[1,0]
	v_pk_mul_f32 v[64:65], v[64:65], v[140:141] op_sel_hi:[1,0]
	v_pk_mul_f32 v[38:39], v[38:39], v[138:139] op_sel_hi:[1,0]
	v_add_f32_e32 v98, 1.0, v98
	v_rcp_f32_e32 v111, v98
	v_pk_mul_f32 v[34:35], v[34:35], v[138:139] op_sel_hi:[1,0]
	v_pk_mul_f32 v[42:43], v[42:43], v[138:139] op_sel_hi:[1,0]
	v_pk_mul_f32 v[40:41], v[40:41], v[138:139] op_sel_hi:[1,0]
	v_pk_mul_f32 v[98:99], v[108:109], v[110:111]
	v_pk_mul_f32 v[36:37], v[36:37], v[138:139] op_sel_hi:[1,0]
	v_pk_mul_f32 v[108:109], v[100:101], v[98:99]
	v_cvt_pk_bf16_f32 v98, v102, v103
	v_cvt_pk_bf16_f32 v99, v104, v105
	v_cvt_pk_bf16_f32 v100, v106, v107
	v_cvt_pk_bf16_f32 v101, v108, v109
	v_mad_i64_i32 v[102:103], s[0:1], v190, s35, v[130:131]
	global_store_dwordx4 v[102:103], v[98:101], off
	v_pk_mul_f32 v[46:47], v[46:47], v[138:139] op_sel_hi:[1,0]
	v_pk_mul_f32 v[44:45], v[44:45], v[138:139] op_sel_hi:[1,0]
	v_mul_f32_e32 v99, 0xbfb8aa3b, v90
	v_exp_f32_e32 v99, v99
	v_mul_f32_e32 v98, 0xbfb8aa3b, v94
	v_exp_f32_e32 v98, v98
	v_pk_mul_f32 v[48:49], v[48:49], v[138:139] op_sel_hi:[1,0]
	v_add_f32_e32 v99, 1.0, v99
	v_rcp_f32_e32 v100, v99
	v_mul_f32_e32 v99, 0xbfb8aa3b, v95
	v_exp_f32_e32 v99, v99
	v_add_f32_e32 v98, 1.0, v98
	v_rcp_f32_e32 v98, v98
	v_pk_mul_f32 v[22:23], v[22:23], v[134:135] op_sel_hi:[1,0]
	v_add_f32_e32 v99, 1.0, v99
	v_rcp_f32_e32 v99, v99
	v_pk_mul_f32 v[18:19], v[18:19], v[134:135] op_sel_hi:[1,0]
	v_pk_mul_f32 v[26:27], v[26:27], v[134:135] op_sel_hi:[1,0]
	v_pk_mul_f32 v[24:25], v[24:25], v[134:135] op_sel_hi:[1,0]
	v_pk_mul_f32 v[94:95], v[94:95], v[98:99]
	v_pk_mul_f32 v[20:21], v[20:21], v[134:135] op_sel_hi:[1,0]
	v_pk_mul_f32 v[86:87], v[86:87], v[94:95]
	v_mul_f32_e32 v94, 0xbfb8aa3b, v91
	v_exp_f32_e32 v94, v94
	v_pk_mul_f32 v[30:31], v[30:31], v[134:135] op_sel_hi:[1,0]
	v_pk_mul_f32 v[28:29], v[28:29], v[134:135] op_sel_hi:[1,0]
	v_pk_mul_f32 v[32:33], v[32:33], v[134:135] op_sel_hi:[1,0]
	v_add_f32_e32 v94, 1.0, v94
	v_rcp_f32_e32 v101, v94
	v_pk_mul_f32 v[4:5], v[4:5], v[132:133] op_sel_hi:[1,0]
	v_pk_mul_f32 v[0:1], v[0:1], v[132:133] op_sel_hi:[1,0]
	v_pk_mul_f32 v[10:11], v[10:11], v[132:133] op_sel_hi:[1,0]
	v_pk_mul_f32 v[90:91], v[90:91], v[100:101]
	v_pk_mul_f32 v[6:7], v[6:7], v[132:133] op_sel_hi:[1,0]
	v_pk_mul_f32 v[90:91], v[82:83], v[90:91]
	v_mul_f32_e32 v83, 0xbfb8aa3b, v92
	v_exp_f32_e32 v83, v83
	v_mul_f32_e32 v82, 0xbfb8aa3b, v96
	v_exp_f32_e32 v82, v82
	v_pk_mul_f32 v[2:3], v[2:3], v[132:133] op_sel_hi:[1,0]
	v_add_f32_e32 v83, 1.0, v83
	v_rcp_f32_e32 v94, v83
	v_mul_f32_e32 v83, 0xbfb8aa3b, v97
	v_exp_f32_e32 v83, v83
	v_add_f32_e32 v82, 1.0, v82
	v_rcp_f32_e32 v82, v82
	v_pk_mul_f32 v[14:15], v[14:15], v[132:133] op_sel_hi:[1,0]
	v_add_f32_e32 v83, 1.0, v83
	v_rcp_f32_e32 v83, v83
	v_pk_mul_f32 v[12:13], v[12:13], v[132:133] op_sel_hi:[1,0]
	v_pk_mul_f32 v[16:17], v[16:17], v[132:133] op_sel_hi:[1,0]
	s_and_b64 vcc, exec, s[2:3]
	v_pk_mul_f32 v[82:83], v[96:97], v[82:83]
	s_mov_b32 s86, s8
	v_pk_mul_f32 v[88:89], v[88:89], v[82:83]
	v_mul_f32_e32 v82, 0xbfb8aa3b, v93
	v_exp_f32_e32 v82, v82
	s_mov_b32 s4, s6
	v_add_f32_e32 v82, 1.0, v82
	v_rcp_f32_e32 v95, v82
	s_nop 0
	v_pk_mul_f32 v[82:83], v[92:93], v[94:95]
	s_nop 0
	v_pk_mul_f32 v[92:93], v[84:85], v[82:83]
	v_cvt_pk_bf16_f32 v82, v86, v87
	v_cvt_pk_bf16_f32 v83, v88, v89
	v_cvt_pk_bf16_f32 v84, v90, v91
	v_cvt_pk_bf16_f32 v85, v92, v93
	v_mad_i64_i32 v[86:87], s[0:1], v188, s35, v[130:131]
	global_store_dwordx4 v[86:87], v[82:85], off
	s_nop 1
	v_mul_f32_e32 v83, 0xbfb8aa3b, v74
	v_exp_f32_e32 v83, v83
	v_mul_f32_e32 v82, 0xbfb8aa3b, v78
	v_exp_f32_e32 v82, v82
	v_add_f32_e32 v83, 1.0, v83
	v_rcp_f32_e32 v84, v83
	v_mul_f32_e32 v83, 0xbfb8aa3b, v79
	v_exp_f32_e32 v83, v83
	v_add_f32_e32 v82, 1.0, v82
	v_rcp_f32_e32 v82, v82
	v_add_f32_e32 v83, 1.0, v83
	v_rcp_f32_e32 v83, v83
	s_nop 0
	v_pk_mul_f32 v[78:79], v[78:79], v[82:83]
	s_nop 0
	v_pk_mul_f32 v[70:71], v[70:71], v[78:79]
	v_mul_f32_e32 v78, 0xbfb8aa3b, v75
	v_exp_f32_e32 v78, v78
	s_nop 0
	v_add_f32_e32 v78, 1.0, v78
; template <class Epi>
; DEVI void gemm_phase(LAS unsigned char* lds, const Gemm g, const Epi& E) {
;     ...
;                 for (int mm = 0; mm < 2; ++mm) {
;                     const int m = m0 + mm;
;                     const int r = row0 + ai * HALF + m * 16; float rs = 1.f, part = 0.f;
;                     if constexpr (Epi::RS) rs = rsv[ai * 4 + m];
;                     if constexpr (Epi::PAIR) E.pair8(cur.b, r, cur.pn * HALF + wc * 32 + 8 * fq, acc[ai][0][m][0] * rs, acc[ai][0][m][1] * rs, acc[ai][1][m][0] * rs, acc[ai][1][m][1] * rs);
	v_rcp_f32_e32 v85, v78
	s_nop 0
	v_pk_mul_f32 v[74:75], v[74:75], v[84:85]
	s_nop 0
	v_pk_mul_f32 v[74:75], v[66:67], v[74:75]
	v_mul_f32_e32 v67, 0xbfb8aa3b, v76
	v_exp_f32_e32 v67, v67
	v_mul_f32_e32 v66, 0xbfb8aa3b, v80
	v_exp_f32_e32 v66, v66
	v_add_f32_e32 v67, 1.0, v67
	v_rcp_f32_e32 v78, v67
	v_mul_f32_e32 v67, 0xbfb8aa3b, v81
	v_exp_f32_e32 v67, v67
	v_add_f32_e32 v66, 1.0, v66
	v_rcp_f32_e32 v66, v66
	v_add_f32_e32 v67, 1.0, v67
	v_rcp_f32_e32 v67, v67
	s_nop 0
	v_pk_mul_f32 v[66:67], v[80:81], v[66:67]
	s_nop 0
	v_pk_mul_f32 v[72:73], v[72:73], v[66:67]
	v_mul_f32_e32 v66, 0xbfb8aa3b, v77
	v_exp_f32_e32 v66, v66
	s_nop 0
	v_add_f32_e32 v66, 1.0, v66
	v_rcp_f32_e32 v79, v66
	s_nop 0
	v_pk_mul_f32 v[66:67], v[76:77], v[78:79]
	s_nop 0
	v_pk_mul_f32 v[76:77], v[68:69], v[66:67]
	v_cvt_pk_bf16_f32 v66, v70, v71
	v_cvt_pk_bf16_f32 v67, v72, v73
	v_cvt_pk_bf16_f32 v68, v74, v75
	v_cvt_pk_bf16_f32 v69, v76, v77
	v_mad_i64_i32 v[70:71], s[0:1], v186, s35, v[130:131]
	global_store_dwordx4 v[70:71], v[66:69], off
	s_nop 1
	v_mul_f32_e32 v67, 0xbfb8aa3b, v54
	v_exp_f32_e32 v67, v67
	v_mul_f32_e32 v66, 0xbfb8aa3b, v50
	v_exp_f32_e32 v66, v66
	v_add_f32_e32 v67, 1.0, v67
	v_rcp_f32_e32 v68, v67
	v_mul_f32_e32 v67, 0xbfb8aa3b, v51
	v_exp_f32_e32 v67, v67
	v_add_f32_e32 v66, 1.0, v66
	v_rcp_f32_e32 v66, v66
	v_add_f32_e32 v67, 1.0, v67
	v_rcp_f32_e32 v67, v67
	s_nop 0
	v_pk_mul_f32 v[50:51], v[50:51], v[66:67]
	s_nop 0
	v_pk_mul_f32 v[50:51], v[58:59], v[50:51]
	v_mul_f32_e32 v58, 0xbfb8aa3b, v55
	v_exp_f32_e32 v58, v58
	v_mul_f32_e32 v59, 0xbfb8aa3b, v56
	v_exp_f32_e32 v59, v59
	v_cvt_pk_bf16_f32 v50, v50, v51
	v_add_f32_e32 v58, 1.0, v58
	v_rcp_f32_e32 v69, v58
	v_add_f32_e32 v59, 1.0, v59
	v_mul_f32_e32 v58, 0xbfb8aa3b, v52
	v_exp_f32_e32 v58, v58
	v_pk_mul_f32 v[54:55], v[54:55], v[68:69]
	v_add_f32_e32 v58, 1.0, v58
	v_pk_mul_f32 v[54:55], v[62:63], v[54:55]
	v_rcp_f32_e32 v62, v59
	v_mul_f32_e32 v59, 0xbfb8aa3b, v53
	v_exp_f32_e32 v59, v59
	v_rcp_f32_e32 v58, v58
	v_add_f32_e32 v59, 1.0, v59
	v_rcp_f32_e32 v59, v59
	s_nop 0
	v_pk_mul_f32 v[52:53], v[52:53], v[58:59]
	v_mul_f32_e32 v58, 0xbfb8aa3b, v57
	v_exp_f32_e32 v58, v58
	v_pk_mul_f32 v[52:53], v[60:61], v[52:53]
	v_add_f32_e32 v58, 1.0, v58
	v_rcp_f32_e32 v63, v58
	v_cvt_pk_bf16_f32 v51, v52, v53
	v_cvt_pk_bf16_f32 v52, v54, v55
	v_mad_i64_i32 v[54:55], s[0:1], v184, s35, v[130:131]
	v_pk_mul_f32 v[56:57], v[56:57], v[62:63]
	s_nop 0
	v_pk_mul_f32 v[56:57], v[64:65], v[56:57]
	s_nop 0
	v_cvt_pk_bf16_f32 v53, v56, v57
	global_store_dwordx4 v[54:55], v[50:53], off
	s_nop 1
	v_mul_f32_e32 v51, 0xbfb8aa3b, v38
	v_exp_f32_e32 v51, v51
	v_mul_f32_e32 v50, 0xbfb8aa3b, v34
	v_exp_f32_e32 v50, v50
	v_add_f32_e32 v51, 1.0, v51
	v_rcp_f32_e32 v52, v51
	v_mul_f32_e32 v51, 0xbfb8aa3b, v35
	v_exp_f32_e32 v51, v51
	v_add_f32_e32 v50, 1.0, v50
	v_rcp_f32_e32 v50, v50
	v_add_f32_e32 v51, 1.0, v51
	v_rcp_f32_e32 v51, v51
	s_nop 0
	v_pk_mul_f32 v[34:35], v[34:35], v[50:51]
	s_nop 0
	v_pk_mul_f32 v[34:35], v[42:43], v[34:35]
	v_mul_f32_e32 v42, 0xbfb8aa3b, v39
	v_exp_f32_e32 v42, v42
	v_mul_f32_e32 v43, 0xbfb8aa3b, v40
	v_exp_f32_e32 v43, v43
	v_cvt_pk_bf16_f32 v34, v34, v35
	v_add_f32_e32 v42, 1.0, v42
	v_rcp_f32_e32 v53, v42
	v_add_f32_e32 v43, 1.0, v43
	v_mul_f32_e32 v42, 0xbfb8aa3b, v36
	v_exp_f32_e32 v42, v42
	v_pk_mul_f32 v[38:39], v[38:39], v[52:53]
	v_add_f32_e32 v42, 1.0, v42
	v_pk_mul_f32 v[38:39], v[46:47], v[38:39]
	v_rcp_f32_e32 v46, v43
	v_mul_f32_e32 v43, 0xbfb8aa3b, v37
	v_exp_f32_e32 v43, v43
	v_rcp_f32_e32 v42, v42
	v_add_f32_e32 v43, 1.0, v43
	v_rcp_f32_e32 v43, v43
	s_nop 0
; #define PG8_WAIT_V(n) asm volatile("s_waitcnt vmcnt(" #n ")" ::: "memory")
; #define PG8_BAR __builtin_amdgcn_s_barrier()
; template <class Epi>
; DEVI void gemm_phase(LAS unsigned char* lds, const Gemm g, const Epi& E) {
;     ...
;                 for (int mm = 0; mm < 2; ++mm) {
;                     const int m = m0 + mm;
;                     const int r = row0 + ai * HALF + m * 16; float rs = 1.f, part = 0.f;
;                     if constexpr (Epi::RS) rs = rsv[ai * 4 + m];
;                     if constexpr (Epi::PAIR) E.pair8(cur.b, r, cur.pn * HALF + wc * 32 + 8 * fq, acc[ai][0][m][0] * rs, acc[ai][0][m][1] * rs, acc[ai][1][m][0] * rs, acc[ai][1][m][1] * rs);
;     ...
;         if (!has_next) break;
; #pragma unroll
;         for (int a = 0; a < 2; ++a)
; #pragma unroll
;             for (int b = 0; b < 2; ++b)
; #pragma unroll
;                 for (int m = 0; m < 4; ++m)
; #pragma unroll
;                     for (int n = 0; n < 2; ++n) acc[a][b][m][n] = (f32x4){0.f, 0.f, 0.f, 0.f};
;         cur = nxt; cA = nA; cB = nB; ++ui;
;     }
;     PG8_WAIT_V(0);
;     if (wr == 0) PG8_BAR;
;     PG8_BAR;
	v_pk_mul_f32 v[36:37], v[36:37], v[42:43]
	v_mul_f32_e32 v42, 0xbfb8aa3b, v41
	v_exp_f32_e32 v42, v42
	v_pk_mul_f32 v[36:37], v[44:45], v[36:37]
	v_add_f32_e32 v42, 1.0, v42
	v_rcp_f32_e32 v47, v42
	v_cvt_pk_bf16_f32 v35, v36, v37
	v_cvt_pk_bf16_f32 v36, v38, v39
	v_mad_i64_i32 v[38:39], s[0:1], v182, s35, v[130:131]
	v_pk_mul_f32 v[40:41], v[40:41], v[46:47]
	s_nop 0
	v_pk_mul_f32 v[40:41], v[48:49], v[40:41]
	s_nop 0
	v_cvt_pk_bf16_f32 v37, v40, v41
	global_store_dwordx4 v[38:39], v[34:37], off
	s_nop 1
	v_mul_f32_e32 v35, 0xbfb8aa3b, v22
	v_exp_f32_e32 v35, v35
	v_mul_f32_e32 v34, 0xbfb8aa3b, v18
	v_exp_f32_e32 v34, v34
	v_add_f32_e32 v35, 1.0, v35
	v_rcp_f32_e32 v36, v35
	v_mul_f32_e32 v35, 0xbfb8aa3b, v19
	v_exp_f32_e32 v35, v35
	v_add_f32_e32 v34, 1.0, v34
	v_rcp_f32_e32 v34, v34
	v_add_f32_e32 v35, 1.0, v35
	v_rcp_f32_e32 v35, v35
	s_nop 0
	v_pk_mul_f32 v[18:19], v[18:19], v[34:35]
	s_nop 0
	v_pk_mul_f32 v[18:19], v[26:27], v[18:19]
	v_mul_f32_e32 v26, 0xbfb8aa3b, v23
	v_exp_f32_e32 v26, v26
	v_mul_f32_e32 v27, 0xbfb8aa3b, v24
	v_exp_f32_e32 v27, v27
	v_cvt_pk_bf16_f32 v18, v18, v19
	v_add_f32_e32 v26, 1.0, v26
	v_rcp_f32_e32 v37, v26
	v_add_f32_e32 v27, 1.0, v27
	v_mul_f32_e32 v26, 0xbfb8aa3b, v20
	v_exp_f32_e32 v26, v26
	v_pk_mul_f32 v[22:23], v[22:23], v[36:37]
	v_add_f32_e32 v26, 1.0, v26
	v_pk_mul_f32 v[22:23], v[30:31], v[22:23]
	v_rcp_f32_e32 v30, v27
	v_mul_f32_e32 v27, 0xbfb8aa3b, v21
	v_exp_f32_e32 v27, v27
	v_rcp_f32_e32 v26, v26
	v_add_f32_e32 v27, 1.0, v27
	v_rcp_f32_e32 v27, v27
	s_nop 0
	v_pk_mul_f32 v[20:21], v[20:21], v[26:27]
	v_mul_f32_e32 v26, 0xbfb8aa3b, v25
	v_exp_f32_e32 v26, v26
	v_pk_mul_f32 v[20:21], v[28:29], v[20:21]
	v_add_f32_e32 v26, 1.0, v26
	v_rcp_f32_e32 v31, v26
	v_cvt_pk_bf16_f32 v19, v20, v21
	v_cvt_pk_bf16_f32 v20, v22, v23
	v_mad_i64_i32 v[22:23], s[0:1], v180, s35, v[130:131]
	v_pk_mul_f32 v[24:25], v[24:25], v[30:31]
	s_nop 0
	v_pk_mul_f32 v[24:25], v[32:33], v[24:25]
	s_nop 0
	v_cvt_pk_bf16_f32 v21, v24, v25
	global_store_dwordx4 v[22:23], v[18:21], off
	s_nop 1
	v_mul_f32_e32 v19, 0xbfb8aa3b, v4
	v_exp_f32_e32 v19, v19
	v_mul_f32_e32 v18, 0xbfb8aa3b, v0
	v_exp_f32_e32 v18, v18
	v_add_f32_e32 v19, 1.0, v19
	v_rcp_f32_e32 v20, v19
	v_mul_f32_e32 v19, 0xbfb8aa3b, v1
	v_exp_f32_e32 v19, v19
	v_add_f32_e32 v18, 1.0, v18
	v_rcp_f32_e32 v18, v18
	v_add_f32_e32 v19, 1.0, v19
	v_rcp_f32_e32 v19, v19
	s_nop 0
	v_pk_mul_f32 v[0:1], v[0:1], v[18:19]
	s_nop 0
	v_pk_mul_f32 v[0:1], v[10:11], v[0:1]
	v_mul_f32_e32 v10, 0xbfb8aa3b, v5
	v_exp_f32_e32 v10, v10
	v_mul_f32_e32 v11, 0xbfb8aa3b, v6
	v_exp_f32_e32 v11, v11
	v_cvt_pk_bf16_f32 v0, v0, v1
	v_add_f32_e32 v10, 1.0, v10
	v_rcp_f32_e32 v21, v10
	v_add_f32_e32 v11, 1.0, v11
	v_mul_f32_e32 v10, 0xbfb8aa3b, v2
	v_exp_f32_e32 v10, v10
	v_pk_mul_f32 v[4:5], v[4:5], v[20:21]
	v_add_f32_e32 v10, 1.0, v10
	v_pk_mul_f32 v[4:5], v[14:15], v[4:5]
	v_rcp_f32_e32 v14, v11
	v_mul_f32_e32 v11, 0xbfb8aa3b, v3
	v_exp_f32_e32 v11, v11
	v_rcp_f32_e32 v10, v10
	v_add_f32_e32 v11, 1.0, v11
	v_rcp_f32_e32 v11, v11
	s_nop 0
	v_pk_mul_f32 v[2:3], v[2:3], v[10:11]
	v_mul_f32_e32 v10, 0xbfb8aa3b, v7
	v_exp_f32_e32 v10, v10
	v_pk_mul_f32 v[2:3], v[12:13], v[2:3]
	v_add_f32_e32 v10, 1.0, v10
	v_rcp_f32_e32 v15, v10
	v_cvt_pk_bf16_f32 v1, v2, v3
	v_cvt_pk_bf16_f32 v2, v4, v5
	v_mad_i64_i32 v[4:5], s[0:1], v178, s35, v[130:131]
	v_pk_mul_f32 v[6:7], v[6:7], v[14:15]
	s_nop 0
	v_pk_mul_f32 v[6:7], v[16:17], v[6:7]
	s_nop 0
	v_cvt_pk_bf16_f32 v3, v6, v7
	global_store_dwordx4 v[4:5], v[0:3], off
	s_cbranch_vccz .LBB0_1669
	s_waitcnt vmcnt(0)
	s_cmpk_gt_u32 s66, 0xff
	s_cbranch_scc1 .LBB0_1676
	s_barrier

; #define PG8_STAGE(bufoff, gbase, voff) do { _Pragma("unroll") for (int _i = 0; _i < 2; ++_i) \
;         __builtin_amdgcn_global_load_lds((const unsigned*)((const char*)(gbase) + (voff)[_i]), (LAS unsigned*)(lds + (bufoff) + ldsw + _i * 8192), 16, 0, 0); } while (0)
; #define PG8_LDA(dst, b, h) do { _Pragma("unroll") for (int m = 0; m < 4; ++m) _Pragma("unroll") for (int k = 0; k < 2; ++k) dst[m][k] = *(const LAS bf16x8*)(lds + PG8_SA(b, h) + aoff + m * 2048 + k * 1024); } while (0)
; #define PG8_LDB(dst, b, h) do { _Pragma("unroll") for (int n = 0; n < 2; ++n) _Pragma("unroll") for (int k = 0; k < 2; ++k) dst[n][k] = *(const LAS bf16x8*)(lds + PG8_SB(b, h) + boff + n * 2048 + k * 1024); } while (0)
; #define PG8_MMA(ai, bj, At, Bt) do { __builtin_amdgcn_s_setprio(1); _Pragma("unroll") for (int m = 0; m < 4; ++m) _Pragma("unroll") for (int n = 0; n < 2; ++n) _Pragma("unroll") for (int k = 0; k < 2; ++k) \
;         acc[ai][bj][m][n] = __builtin_amdgcn_mfma_f32_16x16x32_bf16(Bt[n][k], At[m][k], acc[ai][bj][m][n], 0, 0, 0); __builtin_amdgcn_s_setprio(0); } while (0)
; #define PG8_WAIT_V(n) asm volatile("s_waitcnt vmcnt(" #n ")" ::: "memory")
; #define PG8_WAIT_L(n) asm volatile("s_waitcnt lgkmcnt(" #n ")" ::: "memory")
; #define PG8_BAR __builtin_amdgcn_s_barrier()
; #define PG8_SCHED __builtin_amdgcn_sched_barrier(0)
; template <class Epi>
; DEVI void gemm_phase(LAS unsigned char* lds, const Gemm g, const Epi& E) {
;     ...
;             PG8_LDB(B0, 0, 0); PG8_SCHED; PG8_LDA(At, 0, 0); PG8_STAGE(PG8_SA(1, 1), a1 + hstepA, voffA);
;             PG8_WAIT_L(8); PG8_BAR; PG8_WAIT_L(0); PG8_MMA(0, 0, At, B0); PG8_BAR; PG8_SCHED;
;             PG8_LDB(B1, 0, 1); PG8_STAGE(PG8_SB(0, 0), b2, voffB);
;             PG8_BAR; PG8_WAIT_L(0); PG8_MMA(0, 1, At, B1); PG8_BAR;
;             PG8_LDA(At, 0, 1); PG8_STAGE(PG8_SA(0, 0), a2, voffA);
;             PG8_BAR; PG8_WAIT_L(0); PG8_MMA(1, 0, At, B0); PG8_BAR; PG8_SCHED;
;             PG8_STAGE(PG8_SB(0, 1), b2 + hstepB, voffB);
;             PG8_WAIT_V(6); PG8_BAR; PG8_MMA(1, 1, At, B1); PG8_BAR;
.LBB0_1747:
	s_add_u32 s36, s16, 0x100
	s_addc_u32 s37, s17, 0
	s_add_i32 s19, 0, 0x10000
	v_add_u32_e32 v142, s19, v191
	ds_read_b128 v[130:133], v142
	ds_read_b128 v[134:137], v142 offset:1024
	ds_read_b128 v[138:141], v142 offset:2048
	ds_read_b128 v[142:145], v142 offset:3072
	s_cmp_eq_u32 s18, 40
	s_cselect_b32 s69, s9, s37
	s_cselect_b32 s68, s8, s36
	s_cselect_b32 s47, s11, s13
	s_cselect_b32 s46, s10, s1
	v_lshl_add_u64 v[162:163], s[16:17], 0, v[152:153]
	s_add_i32 m0, s81, 0xc000
	ds_read_b128 v[178:181], v196
	ds_read_b128 v[182:185], v196 offset:1024
	ds_read_b128 v[186:189], v196 offset:2048
	ds_read_b128 v[198:201], v196 offset:3072
	ds_read_b128 v[202:205], v196 offset:4096
	ds_read_b128 v[206:209], v196 offset:5120
	ds_read_b128 v[214:217], v196 offset:6144
	ds_read_b128 v[218:221], v196 offset:7168
	global_load_lds_dwordx4 v[162:163], off
	s_add_i32 m0, s81, 0xe000
	v_lshl_add_u64 v[162:163], s[16:17], 0, v[176:177]
	global_load_lds_dwordx4 v[162:163], off
	s_waitcnt lgkmcnt(8)
	s_barrier
	s_waitcnt lgkmcnt(0)
	v_mfma_f32_16x16x32_bf16 v[126:129], v[130:133], v[178:181], v[126:129]
	v_mfma_f32_16x16x32_bf16 v[122:125], v[138:141], v[178:181], v[122:125]
	v_mfma_f32_16x16x32_bf16 v[110:113], v[130:133], v[186:189], v[110:113]
	v_mfma_f32_16x16x32_bf16 v[106:109], v[138:141], v[186:189], v[106:109]
	v_mfma_f32_16x16x32_bf16 v[94:97], v[130:133], v[202:205], v[94:97]
	v_mfma_f32_16x16x32_bf16 v[90:93], v[138:141], v[202:205], v[90:93]
	v_mfma_f32_16x16x32_bf16 v[78:81], v[130:133], v[214:217], v[78:81]
	v_mfma_f32_16x16x32_bf16 v[74:77], v[138:141], v[214:217], v[74:77]
	v_mfma_f32_16x16x32_bf16 v[126:129], v[134:137], v[182:185], v[126:129]
	v_mfma_f32_16x16x32_bf16 v[122:125], v[142:145], v[182:185], v[122:125]
	v_mfma_f32_16x16x32_bf16 v[110:113], v[134:137], v[198:201], v[110:113]
	v_mfma_f32_16x16x32_bf16 v[106:109], v[142:145], v[198:201], v[106:109]
	v_mfma_f32_16x16x32_bf16 v[94:97], v[134:137], v[206:209], v[94:97]
	v_mfma_f32_16x16x32_bf16 v[90:93], v[142:145], v[206:209], v[90:93]
	v_mfma_f32_16x16x32_bf16 v[78:81], v[134:137], v[218:221], v[78:81]
	v_mfma_f32_16x16x32_bf16 v[74:77], v[142:145], v[218:221], v[74:77]
	s_barrier
	s_add_i32 s26, 0, 0x14000
	v_add_u32_e32 v162, s26, v191
	s_add_i32 s16, s19, s80
	ds_read_b128 v[222:225], v162
	ds_read_b128 v[226:229], v162 offset:1024
	ds_read_b128 v[230:233], v162 offset:2048
	ds_read_b128 v[234:237], v162 offset:3072
	v_lshl_add_u64 v[162:163], s[46:47], 0, v[8:9]
	s_mov_b32 m0, s16
	v_lshl_add_u64 v[164:165], s[46:47], 0, v[150:151]
	global_load_lds_dwordx4 v[162:163], off
	s_add_i32 m0, s16, 0x2000
	s_nop 0
	global_load_lds_dwordx4 v[164:165], off
	s_barrier
	s_waitcnt lgkmcnt(0)
	v_mfma_f32_16x16x32_bf16 v[118:121], v[222:225], v[178:181], v[118:121]
	v_mfma_f32_16x16x32_bf16 v[114:117], v[230:233], v[178:181], v[114:117]
	v_mfma_f32_16x16x32_bf16 v[102:105], v[222:225], v[186:189], v[102:105]
	v_mfma_f32_16x16x32_bf16 v[98:101], v[230:233], v[186:189], v[98:101]
	v_mfma_f32_16x16x32_bf16 v[86:89], v[222:225], v[202:205], v[86:89]
	v_mfma_f32_16x16x32_bf16 v[82:85], v[230:233], v[202:205], v[82:85]
	v_mfma_f32_16x16x32_bf16 v[70:73], v[222:225], v[214:217], v[70:73]
	v_mfma_f32_16x16x32_bf16 v[66:69], v[230:233], v[214:217], v[66:69]
	v_mfma_f32_16x16x32_bf16 v[118:121], v[226:229], v[182:185], v[118:121]
	v_mfma_f32_16x16x32_bf16 v[114:117], v[234:237], v[182:185], v[114:117]
	v_mfma_f32_16x16x32_bf16 v[102:105], v[226:229], v[198:201], v[102:105]
	v_mfma_f32_16x16x32_bf16 v[98:101], v[234:237], v[198:201], v[98:101]
	v_mfma_f32_16x16x32_bf16 v[86:89], v[226:229], v[206:209], v[86:89]
	v_mfma_f32_16x16x32_bf16 v[82:85], v[234:237], v[206:209], v[82:85]
	v_mfma_f32_16x16x32_bf16 v[70:73], v[226:229], v[218:221], v[70:73]
	v_mfma_f32_16x16x32_bf16 v[66:69], v[234:237], v[218:221], v[66:69]
	s_barrier
	s_mov_b32 m0, s81
	v_lshl_add_u64 v[238:239], s[68:69], 0, v[146:147]
	ds_read_b128 v[178:181], v196 offset:16384
	ds_read_b128 v[182:185], v196 offset:17408
	ds_read_b128 v[186:189], v196 offset:18432
	ds_read_b128 v[198:201], v196 offset:19456
	ds_read_b128 v[202:205], v196 offset:20480
	ds_read_b128 v[206:209], v196 offset:21504
	ds_read_b128 v[214:217], v196 offset:22528
	ds_read_b128 v[218:221], v196 offset:23552
	global_load_lds_dwordx4 v[238:239], off
	s_mov_b32 m0, s82
	v_lshl_add_u64 v[240:241], s[68:69], 0, v[148:149]
	global_load_lds_dwordx4 v[240:241], off
	s_barrier
	s_waitcnt lgkmcnt(0)
	v_mfma_f32_16x16x32_bf16 v[62:65], v[130:133], v[178:181], v[62:65]
	v_mfma_f32_16x16x32_bf16 v[58:61], v[138:141], v[178:181], v[58:61]
	v_mfma_f32_16x16x32_bf16 v[46:49], v[130:133], v[186:189], v[46:49]
	v_mfma_f32_16x16x32_bf16 v[42:45], v[138:141], v[186:189], v[42:45]
	v_mfma_f32_16x16x32_bf16 v[30:33], v[130:133], v[202:205], v[30:33]
	v_mfma_f32_16x16x32_bf16 v[26:29], v[138:141], v[202:205], v[26:29]
	v_mfma_f32_16x16x32_bf16 v[14:17], v[130:133], v[214:217], v[14:17]
	v_mfma_f32_16x16x32_bf16 v[10:13], v[138:141], v[214:217], v[10:13]
	v_mfma_f32_16x16x32_bf16 v[62:65], v[134:137], v[182:185], v[62:65]
	v_mfma_f32_16x16x32_bf16 v[58:61], v[142:145], v[182:185], v[58:61]
	v_mfma_f32_16x16x32_bf16 v[46:49], v[134:137], v[198:201], v[46:49]
	v_mfma_f32_16x16x32_bf16 v[42:45], v[142:145], v[198:201], v[42:45]
	v_mfma_f32_16x16x32_bf16 v[30:33], v[134:137], v[206:209], v[30:33]
	v_mfma_f32_16x16x32_bf16 v[26:29], v[142:145], v[206:209], v[26:29]
	v_mfma_f32_16x16x32_bf16 v[14:17], v[134:137], v[218:221], v[14:17]
	v_mfma_f32_16x16x32_bf16 v[10:13], v[142:145], v[218:221], v[10:13]
	s_barrier
; #define PG8_STAGE(bufoff, gbase, voff) do { _Pragma("unroll") for (int _i = 0; _i < 2; ++_i) \
;         __builtin_amdgcn_global_load_lds((const unsigned*)((const char*)(gbase) + (voff)[_i]), (LAS unsigned*)(lds + (bufoff) + ldsw + _i * 8192), 16, 0, 0); } while (0)
; #define PG8_LDA(dst, b, h) do { _Pragma("unroll") for (int m = 0; m < 4; ++m) _Pragma("unroll") for (int k = 0; k < 2; ++k) dst[m][k] = *(const LAS bf16x8*)(lds + PG8_SA(b, h) + aoff + m * 2048 + k * 1024); } while (0)
; #define PG8_LDB(dst, b, h) do { _Pragma("unroll") for (int n = 0; n < 2; ++n) _Pragma("unroll") for (int k = 0; k < 2; ++k) dst[n][k] = *(const LAS bf16x8*)(lds + PG8_SB(b, h) + boff + n * 2048 + k * 1024); } while (0)
; #define PG8_MMA(ai, bj, At, Bt) do { __builtin_amdgcn_s_setprio(1); _Pragma("unroll") for (int m = 0; m < 4; ++m) _Pragma("unroll") for (int n = 0; n < 2; ++n) _Pragma("unroll") for (int k = 0; k < 2; ++k) \
;         acc[ai][bj][m][n] = __builtin_amdgcn_mfma_f32_16x16x32_bf16(Bt[n][k], At[m][k], acc[ai][bj][m][n], 0, 0, 0); __builtin_amdgcn_s_setprio(0); } while (0)
; #define PG8_WAIT_V(n) asm volatile("s_waitcnt vmcnt(" #n ")" ::: "memory")
; #define PG8_WAIT_L(n) asm volatile("s_waitcnt lgkmcnt(" #n ")" ::: "memory")
; #define PG8_BAR __builtin_amdgcn_s_barrier()
; #define PG8_SCHED __builtin_amdgcn_sched_barrier(0)
; template <class Epi>
; DEVI void gemm_phase(LAS unsigned char* lds, const Gemm g, const Epi& E) {
;     ...
;             PG8_WAIT_V(6); PG8_BAR; PG8_MMA(1, 1, At, B1); PG8_BAR;
;             PG8_LDB(B0, 1, 0); PG8_SCHED; PG8_LDA(At, 1, 0); PG8_STAGE(PG8_SA(0, 1), a2 + hstepA, voffA);
;             PG8_WAIT_L(8); PG8_BAR; PG8_WAIT_L(0); PG8_MMA(0, 0, At, B0); PG8_BAR; PG8_SCHED;
;             PG8_LDB(B1, 1, 1); PG8_STAGE(PG8_SB(1, 0), b3, voffB);
;             PG8_BAR; PG8_WAIT_L(0); PG8_MMA(0, 1, At, B1); PG8_BAR;
;             PG8_LDA(At, 1, 1); PG8_STAGE(PG8_SA(1, 0), a3, voffA);
;             PG8_BAR; PG8_WAIT_L(0); PG8_MMA(1, 0, At, B0); PG8_BAR; PG8_SCHED;
	s_add_u32 s16, s46, 0xb0000
	s_addc_u32 s17, s47, 0
	s_add_i32 s19, s26, s80
	s_mov_b32 m0, s19
	v_lshl_add_u64 v[130:131], s[16:17], 0, v[8:9]
	global_load_lds_dwordx4 v[130:131], off
	s_add_i32 m0, s19, 0x2000
	v_lshl_add_u64 v[130:131], s[16:17], 0, v[150:151]
	global_load_lds_dwordx4 v[130:131], off
	s_waitcnt vmcnt(6)
	s_barrier
	v_mfma_f32_16x16x32_bf16 v[54:57], v[222:225], v[178:181], v[54:57]
	v_mfma_f32_16x16x32_bf16 v[50:53], v[230:233], v[178:181], v[50:53]
	v_mfma_f32_16x16x32_bf16 v[38:41], v[222:225], v[186:189], v[38:41]
	v_mfma_f32_16x16x32_bf16 v[34:37], v[230:233], v[186:189], v[34:37]
	v_mfma_f32_16x16x32_bf16 v[22:25], v[222:225], v[202:205], v[22:25]
	v_mfma_f32_16x16x32_bf16 v[18:21], v[230:233], v[202:205], v[18:21]
	v_mfma_f32_16x16x32_bf16 v[4:7], v[222:225], v[214:217], v[4:7]
	v_mfma_f32_16x16x32_bf16 v[0:3], v[230:233], v[214:217], v[0:3]
	v_mfma_f32_16x16x32_bf16 v[54:57], v[226:229], v[182:185], v[54:57]
	v_mfma_f32_16x16x32_bf16 v[50:53], v[234:237], v[182:185], v[50:53]
	v_mfma_f32_16x16x32_bf16 v[38:41], v[226:229], v[198:201], v[38:41]
	v_mfma_f32_16x16x32_bf16 v[34:37], v[234:237], v[198:201], v[34:37]
	v_mfma_f32_16x16x32_bf16 v[22:25], v[226:229], v[206:209], v[22:25]
	v_mfma_f32_16x16x32_bf16 v[18:21], v[234:237], v[206:209], v[18:21]
	v_mfma_f32_16x16x32_bf16 v[4:7], v[226:229], v[218:221], v[4:7]
	v_mfma_f32_16x16x32_bf16 v[0:3], v[234:237], v[218:221], v[0:3]
	s_barrier
	s_add_i32 s19, 0, 0x18000
	v_add_u32_e32 v142, s19, v191
	ds_read_b128 v[130:133], v142
	ds_read_b128 v[134:137], v142 offset:1024
	ds_read_b128 v[138:141], v142 offset:2048
	ds_read_b128 v[142:145], v142 offset:3072
	s_add_u32 s16, s68, 0xb0000
	s_addc_u32 s17, s69, 0
	s_mov_b32 m0, s83
	v_lshl_add_u64 v[222:223], s[16:17], 0, v[146:147]
	ds_read_b128 v[178:181], v196 offset:32768
	ds_read_b128 v[182:185], v196 offset:33792
	ds_read_b128 v[186:189], v196 offset:34816
	ds_read_b128 v[198:201], v196 offset:35840
	ds_read_b128 v[202:205], v196 offset:36864
	ds_read_b128 v[206:209], v196 offset:37888
	ds_read_b128 v[214:217], v196 offset:38912
	ds_read_b128 v[218:221], v196 offset:39936
	global_load_lds_dwordx4 v[222:223], off
	s_mov_b32 m0, s84
	v_lshl_add_u64 v[222:223], s[16:17], 0, v[148:149]
	global_load_lds_dwordx4 v[222:223], off
	s_waitcnt lgkmcnt(8)
	s_barrier
	s_waitcnt lgkmcnt(0)
	v_mfma_f32_16x16x32_bf16 v[126:129], v[130:133], v[178:181], v[126:129]
	v_mfma_f32_16x16x32_bf16 v[122:125], v[138:141], v[178:181], v[122:125]
	v_mfma_f32_16x16x32_bf16 v[110:113], v[130:133], v[186:189], v[110:113]
	v_mfma_f32_16x16x32_bf16 v[106:109], v[138:141], v[186:189], v[106:109]
	v_mfma_f32_16x16x32_bf16 v[94:97], v[130:133], v[202:205], v[94:97]
	v_mfma_f32_16x16x32_bf16 v[90:93], v[138:141], v[202:205], v[90:93]
	v_mfma_f32_16x16x32_bf16 v[78:81], v[130:133], v[214:217], v[78:81]
	v_mfma_f32_16x16x32_bf16 v[74:77], v[138:141], v[214:217], v[74:77]
	v_mfma_f32_16x16x32_bf16 v[126:129], v[134:137], v[182:185], v[126:129]
	v_mfma_f32_16x16x32_bf16 v[122:125], v[142:145], v[182:185], v[122:125]
	v_mfma_f32_16x16x32_bf16 v[110:113], v[134:137], v[198:201], v[110:113]
	v_mfma_f32_16x16x32_bf16 v[106:109], v[142:145], v[198:201], v[106:109]
	v_mfma_f32_16x16x32_bf16 v[94:97], v[134:137], v[206:209], v[94:97]
	v_mfma_f32_16x16x32_bf16 v[90:93], v[142:145], v[206:209], v[90:93]
	v_mfma_f32_16x16x32_bf16 v[78:81], v[134:137], v[218:221], v[78:81]
	v_mfma_f32_16x16x32_bf16 v[74:77], v[142:145], v[218:221], v[74:77]
	s_barrier
	s_add_i32 s26, 0, 0x1c000
	s_add_i32 s16, s19, s80
	v_add_u32_e32 v197, s26, v191
	v_lshl_add_u64 v[162:163], v[162:163], 0, s[70:71]
	s_mov_b32 m0, s16
	ds_read_b128 v[222:225], v197
	ds_read_b128 v[226:229], v197 offset:1024
	ds_read_b128 v[230:233], v197 offset:2048
	ds_read_b128 v[234:237], v197 offset:3072
	global_load_lds_dwordx4 v[162:163], off
	s_add_i32 m0, s16, 0x2000
	v_lshl_add_u64 v[162:163], v[164:165], 0, s[70:71]
	global_load_lds_dwordx4 v[162:163], off
	s_barrier
	s_waitcnt lgkmcnt(0)
	v_mfma_f32_16x16x32_bf16 v[118:121], v[222:225], v[178:181], v[118:121]
	v_mfma_f32_16x16x32_bf16 v[114:117], v[230:233], v[178:181], v[114:117]
	v_mfma_f32_16x16x32_bf16 v[102:105], v[222:225], v[186:189], v[102:105]
	v_mfma_f32_16x16x32_bf16 v[98:101], v[230:233], v[186:189], v[98:101]
	v_mfma_f32_16x16x32_bf16 v[86:89], v[222:225], v[202:205], v[86:89]
	v_mfma_f32_16x16x32_bf16 v[82:85], v[230:233], v[202:205], v[82:85]
	v_mfma_f32_16x16x32_bf16 v[70:73], v[222:225], v[214:217], v[70:73]
	v_mfma_f32_16x16x32_bf16 v[66:69], v[230:233], v[214:217], v[66:69]
	v_mfma_f32_16x16x32_bf16 v[118:121], v[226:229], v[182:185], v[118:121]
	v_mfma_f32_16x16x32_bf16 v[114:117], v[234:237], v[182:185], v[114:117]
	v_mfma_f32_16x16x32_bf16 v[102:105], v[226:229], v[198:201], v[102:105]
	v_mfma_f32_16x16x32_bf16 v[98:101], v[234:237], v[198:201], v[98:101]
	v_mfma_f32_16x16x32_bf16 v[86:89], v[226:229], v[206:209], v[86:89]
	v_mfma_f32_16x16x32_bf16 v[82:85], v[234:237], v[206:209], v[82:85]
	v_mfma_f32_16x16x32_bf16 v[70:73], v[226:229], v[218:221], v[70:73]
	v_mfma_f32_16x16x32_bf16 v[66:69], v[234:237], v[218:221], v[66:69]
	s_barrier
	s_mov_b32 m0, s76
	v_lshl_add_u64 v[162:163], v[238:239], 0, s[70:71]
	ds_read_b128 v[178:181], v196 offset:49152
	ds_read_b128 v[182:185], v196 offset:50176
	ds_read_b128 v[186:189], v196 offset:51200
	ds_read_b128 v[198:201], v196 offset:52224
	ds_read_b128 v[202:205], v196 offset:53248
	ds_read_b128 v[206:209], v196 offset:54272
	ds_read_b128 v[214:217], v196 offset:55296
	ds_read_b128 v[218:221], v196 offset:56320
	global_load_lds_dwordx4 v[162:163], off
	s_mov_b32 m0, s77
	v_lshl_add_u64 v[162:163], v[240:241], 0, s[70:71]
	global_load_lds_dwordx4 v[162:163], off
	s_barrier
; #define LAS __attribute__((address_space(3)))
; #define PG8_WAIT_V(n) asm volatile("s_waitcnt vmcnt(" #n ")" ::: "memory")
; #define PG8_WAIT_L(n) asm volatile("s_waitcnt lgkmcnt(" #n ")" ::: "memory")
; template <class Epi>
; DEVI void gemm_phase(LAS unsigned char* lds, const Gemm g, const Epi& E) {
;     ...
;             PG8_LDA(At, 1, 1); PG8_STAGE(PG8_SA(1, 0), a3, voffA);
;             PG8_BAR; PG8_WAIT_L(0); PG8_MMA(1, 0, At, B0); PG8_BAR; PG8_SCHED;
;             PG8_STAGE(PG8_SB(1, 1), b3 + hstepB, voffB);
;             PG8_WAIT_V(6); PG8_BAR; PG8_MMA(1, 1, At, B1); PG8_BAR;
;         }
;     ...
;             for (int am = 0; am < 4; ++am) {
;                 const int ai = am >> 1, m0 = (am & 1) * 2;
;                 f32x4 pre[2][2][2];
;                 if constexpr (Epi::PRE) {
; #pragma unroll
;                     for (int m = 0; m < 2; ++m)
; #pragma unroll
;                         for (int bj = 0; bj < 2; ++bj)
; #pragma unroll
;                             for (int n = 0; n < 2; ++n) pre[m][bj][n] = E.load(row0 + ai * HALF + (m0 + m) * 16, col0 + bj * HALF + n * NST);
;                 }
; #pragma unroll
;                 for (int mm = 0; mm < 2; ++mm) {
;                     const int m = m0 + mm;
;                     const int r = row0 + ai * HALF + m * 16; float rs = 1.f, part = 0.f;
;                     if constexpr (Epi::RS) rs = rsv[ai * 4 + m];
;                     if constexpr (Epi::PAIR) E.pair8(cur.b, r, cur.pn * HALF + wc * 32 + 8 * fq, acc[ai][0][m][0] * rs, acc[ai][0][m][1] * rs, acc[ai][1][m][0] * rs, acc[ai][1][m][1] * rs);
;                     else
; #pragma unroll
;                     for (int bj = 0; bj < 2; ++bj) {
;                         const int c = col0 + bj * HALF; f32x4 v0 = acc[ai][bj][m][0], v1 = acc[ai][bj][m][1];
;                         if constexpr (Epi::RS) { v0 = v0 * rs; v1 = v1 * rs; }
;                         if constexpr (Epi::PRE) part += E.frag_pre8(cur.b, r, c, v0, v1, pre[mm][bj][0], pre[mm][bj][1]);
;                         else if constexpr (Epi::PERM) E.frag8(cur.b, r, c, v0, v1);
;                         else { E.frag(cur.b, r, c, v0); E.frag(cur.b, r, c + 16, v1); }
;                     }
;                     if constexpr (Epi::SSQ) { part += __shfl_xor(part, 16); part += __shfl_xor(part, 32); if (fq == 0) ((LAS float*)(lds + 131072))[(wr * 4 + wc) * 128 + ai * 64 + m * 16 + fr] = part; }
	s_waitcnt lgkmcnt(0)
	v_mfma_f32_16x16x32_bf16 v[62:65], v[130:133], v[178:181], v[62:65]
	v_mfma_f32_16x16x32_bf16 v[58:61], v[138:141], v[178:181], v[58:61]
	v_mfma_f32_16x16x32_bf16 v[46:49], v[130:133], v[186:189], v[46:49]
	v_mfma_f32_16x16x32_bf16 v[42:45], v[138:141], v[186:189], v[42:45]
	v_mfma_f32_16x16x32_bf16 v[30:33], v[130:133], v[202:205], v[30:33]
	v_mfma_f32_16x16x32_bf16 v[26:29], v[138:141], v[202:205], v[26:29]
	v_mfma_f32_16x16x32_bf16 v[14:17], v[130:133], v[214:217], v[14:17]
	v_mfma_f32_16x16x32_bf16 v[10:13], v[138:141], v[214:217], v[10:13]
	v_mfma_f32_16x16x32_bf16 v[62:65], v[134:137], v[182:185], v[62:65]
	v_mfma_f32_16x16x32_bf16 v[58:61], v[142:145], v[182:185], v[58:61]
	v_mfma_f32_16x16x32_bf16 v[46:49], v[134:137], v[198:201], v[46:49]
	v_mfma_f32_16x16x32_bf16 v[42:45], v[142:145], v[198:201], v[42:45]
	v_mfma_f32_16x16x32_bf16 v[30:33], v[134:137], v[206:209], v[30:33]
	v_mfma_f32_16x16x32_bf16 v[26:29], v[142:145], v[206:209], v[26:29]
	v_mfma_f32_16x16x32_bf16 v[14:17], v[134:137], v[218:221], v[14:17]
	v_mfma_f32_16x16x32_bf16 v[10:13], v[142:145], v[218:221], v[10:13]
	s_barrier
	s_add_u32 s16, s46, 0xb0080
	s_addc_u32 s17, s47, 0
	s_add_i32 s19, s26, s80
	s_mov_b32 m0, s19
	v_lshl_add_u64 v[130:131], s[16:17], 0, v[8:9]
	global_load_lds_dwordx4 v[130:131], off
	s_add_i32 m0, s19, 0x2000
	v_lshl_add_u64 v[130:131], s[16:17], 0, v[150:151]
	global_load_lds_dwordx4 v[130:131], off
	s_waitcnt vmcnt(6)
	s_barrier
	v_mfma_f32_16x16x32_bf16 v[54:57], v[222:225], v[178:181], v[54:57]
	v_mfma_f32_16x16x32_bf16 v[50:53], v[230:233], v[178:181], v[50:53]
	v_mfma_f32_16x16x32_bf16 v[38:41], v[222:225], v[186:189], v[38:41]
	v_mfma_f32_16x16x32_bf16 v[34:37], v[230:233], v[186:189], v[34:37]
	v_mfma_f32_16x16x32_bf16 v[22:25], v[222:225], v[202:205], v[22:25]
	v_mfma_f32_16x16x32_bf16 v[18:21], v[230:233], v[202:205], v[18:21]
	v_mfma_f32_16x16x32_bf16 v[4:7], v[222:225], v[214:217], v[4:7]
	v_mfma_f32_16x16x32_bf16 v[0:3], v[230:233], v[214:217], v[0:3]
	v_mfma_f32_16x16x32_bf16 v[54:57], v[226:229], v[182:185], v[54:57]
	v_mfma_f32_16x16x32_bf16 v[50:53], v[234:237], v[182:185], v[50:53]
	v_mfma_f32_16x16x32_bf16 v[38:41], v[226:229], v[198:201], v[38:41]
	v_mfma_f32_16x16x32_bf16 v[34:37], v[234:237], v[198:201], v[34:37]
	v_mfma_f32_16x16x32_bf16 v[22:25], v[226:229], v[206:209], v[22:25]
	v_mfma_f32_16x16x32_bf16 v[18:21], v[234:237], v[206:209], v[18:21]
	v_mfma_f32_16x16x32_bf16 v[4:7], v[226:229], v[218:221], v[4:7]
	v_mfma_f32_16x16x32_bf16 v[0:3], v[234:237], v[218:221], v[0:3]
	s_barrier
	s_add_i32 s18, s18, 2
	s_add_u32 s1, s1, 0x100
	s_addc_u32 s13, s13, 0
	s_cmp_gt_u32 s18, 41
	s_mov_b64 s[16:17], s[36:37]
	s_cbranch_scc0 .LBB0_1747
	s_setprio 0
	s_lshl_b32 s0, s0, 8
	v_add_u32_e32 v182, s0, v190
	v_lshl_or_b32 v180, s12, 8, v195
	v_ashrrev_i32_e32 v183, 31, v182
	v_lshlrev_b64 v[130:131], 12, v[182:183]
	v_ashrrev_i32_e32 v181, 31, v180
	v_lshl_add_u64 v[130:131], s[30:31], 0, v[130:131]
	v_lshlrev_b64 v[184:185], 2, v[180:181]
	v_lshl_add_u64 v[162:163], v[130:131], 0, v[184:185]
	global_load_dwordx4 v[200:203], v[162:163], off
	global_load_dwordx4 v[204:207], v[162:163], off offset:16
	global_load_dwordx4 v[214:217], v[162:163], off offset:512
	global_load_dwordx4 v[218:221], v[162:163], off offset:528
	v_or_b32_e32 v188, 16, v182
	v_ashrrev_i32_e32 v189, 31, v188
	v_lshlrev_b64 v[130:131], 12, v[188:189]
	v_lshl_add_u64 v[130:131], s[30:31], 0, v[130:131]
	v_lshl_add_u64 v[186:187], v[130:131], 0, v[184:185]
	global_load_dwordx4 v[138:141], v[186:187], off offset:16
	global_load_dwordx4 v[142:145], v[186:187], off
	global_load_dwordx4 v[130:133], v[186:187], off offset:528
	global_load_dwordx4 v[134:137], v[186:187], off offset:512
	v_and_b32_e32 v165, 64, v155
	v_xor_b32_e32 v164, 16, v155
	v_add_u32_e32 v165, 64, v165
	v_xor_b32_e32 v179, 32, v155
	v_cmp_lt_i32_e32 vcc, v164, v165
	v_or_b32_e32 v178, 0x80, v180
	s_waitcnt vmcnt(0)
	v_pk_add_f32 v[128:129], v[128:129], v[202:203]
	v_cndmask_b32_e32 v164, v155, v164, vcc
	v_cmp_lt_i32_e32 vcc, v179, v165
	v_lshlrev_b32_e32 v198, 2, v164
	v_pk_add_f32 v[126:127], v[126:127], v[200:201]
	v_cndmask_b32_e32 v165, v155, v179, vcc
	v_lshlrev_b32_e32 v197, 2, v165
	v_lshlrev_b64 v[164:165], 10, v[182:183]
	v_pk_add_f32 v[124:125], v[124:125], v[206:207]
	v_pk_add_f32 v[122:123], v[122:123], v[204:205]
	v_pk_add_f32 v[120:121], v[120:121], v[216:217]
	v_pk_add_f32 v[118:119], v[118:119], v[214:215]
	v_pk_add_f32 v[202:203], v[116:117], v[220:221]
	v_pk_add_f32 v[200:201], v[114:115], v[218:219]
	v_lshl_add_u64 v[208:209], v[164:165], 0, v[180:181]
	global_store_dwordx4 v[162:163], v[126:129], off
	global_store_dwordx4 v[162:163], v[122:125], off offset:16
	v_cvt_pk_bf16_f32 v114, v126, v127
	v_cvt_pk_bf16_f32 v115, v128, v129
	v_cvt_pk_bf16_f32 v116, v122, v123
	v_cvt_pk_bf16_f32 v117, v124, v125
	v_mul_f32_e32 v127, v127, v127
	v_mul_f32_e32 v129, v129, v129
	v_mul_f32_e32 v123, v123, v123
	v_mul_f32_e32 v125, v125, v125
	v_mul_f32_e32 v183, v119, v119
	v_mul_f32_e32 v199, v121, v121
	v_mul_f32_e32 v204, v201, v201
	v_mul_f32_e32 v205, v203, v203
	v_lshl_add_u64 v[208:209], v[208:209], 1, s[24:25]
	v_fmac_f32_e32 v127, v126, v126
	v_fmac_f32_e32 v129, v128, v128
	v_fmac_f32_e32 v123, v122, v122
	v_fmac_f32_e32 v125, v124, v124
	v_fmac_f32_e32 v183, v118, v118
	v_fmac_f32_e32 v199, v120, v120
	v_fmac_f32_e32 v204, v200, v200
	v_fmac_f32_e32 v205, v202, v202
	global_store_dwordx4 v[208:209], v[114:117], off
	v_ashrrev_i32_e32 v179, 31, v178
	v_lshl_add_u64 v[164:165], v[164:165], 0, v[178:179]
	v_add_f32_e32 v114, v127, v129
	v_add_f32_e32 v115, v123, v125
	v_add_f32_e32 v116, v183, v199
	v_add_f32_e32 v117, v204, v205
	v_add_f32_e32 v114, v114, v115
	v_add_f32_e32 v115, v116, v117
	v_add_f32_e32 v114, v114, v115
	ds_bpermute_b32 v115, v198, v114
	global_store_dwordx4 v[162:163], v[118:121], off offset:512
	global_store_dwordx4 v[162:163], v[200:203], off offset:528
	v_cvt_pk_bf16_f32 v116, v118, v119
	v_cvt_pk_bf16_f32 v117, v120, v121
	v_cvt_pk_bf16_f32 v118, v200, v201
	s_waitcnt lgkmcnt(0)
	v_add_f32_e32 v114, v114, v115
	ds_bpermute_b32 v115, v197, v114
	v_cvt_pk_bf16_f32 v119, v202, v203
	v_lshl_add_u64 v[120:121], v[164:165], 1, s[24:25]
	global_store_dwordx4 v[120:121], v[116:119], off
	s_and_saveexec_b64 s[16:17], s[2:3]
	s_cbranch_execz .LBB0_1750
	s_waitcnt lgkmcnt(0)
	v_add_f32_e32 v114, v114, v115
	ds_write_b32 v192, v114
